# bf16 GEMM epilogue dwordx4 stores made write-through (sc1) so the phase barrier L2 writeback has less to flush, on top of v22
# baseline (speedup 1.0000x reference)
;     __device__ __forceinline__ RowPre pre_row(int row, int) const { const float ss = NSLOT == 8 ? sum8(part + (size_t)row * 8) : sum4(part + (size_t)row * 4); return PreRs{rsqrtf(ss * inv_k + EPS)}; }
;     __device__ __forceinline__ void operator()(const pg8::f32x4 (&acc)[2][2][4][2], const pg8::Unit& u, int wr, int wc, int, int, int ui) const {
;     ...
;             for (int j = 0; j < NB; ++j) { const int ai = (g + j) >> 2, mm = (g + j) & 3; const int rl = ai * 128 + wr * 64 + mm * 16 + fr; int row = u.pm * 256 + rl; asm volatile("" : "+v"(row)); rows[j] = row;
;                 rv[j] = F::USE_TAB ? tab[rl] : 0.f; rp[j] = f.pre_row(row, col); }
.LBB0_326:
	v_mbcnt_lo_u32_b32 v140, -1, 0
	v_mbcnt_hi_u32_b32 v140, -1, v140
	s_lshl_b32 s3, s62, 8
	v_ashrrev_i32_e32 v141, 1, v140
	s_or_b32 s3, s3, s69
	v_and_b32_e32 v141, -8, v141
	v_add_u32_e32 v184, s3, v141
	s_lshl_b32 s3, s61, 11
	s_and_b32 s3, s3, 0x800
	s_add_i32 s3, s3, 0
	v_and_or_b32 v140, v140, 15, s68
	v_lshl_add_u32 v141, v140, 2, s3
	s_lshl_b32 s3, s60, 8
	v_add_u32_e32 v152, s3, v140
	v_mov_b32_e32 v144, v152
	v_add_u32_e32 v151, 0x20040, v141
	ds_read_b32 v154, v151
	v_add_u32_e32 v140, 16, v152
	ds_read_b32 v142, v151 offset:64
	v_ashrrev_i32_e32 v150, 8, v184
	v_bfe_u32 v149, v184, 5, 2
	v_cmp_lt_i32_e64 s[36:37], 1, v150
	v_cmp_eq_u32_e32 vcc, 0, v149
	s_waitcnt lgkmcnt(0)
	v_pk_mul_f32 v[126:127], v[126:127], v[154:155] op_sel_hi:[1,0]
	v_pk_mul_f32 v[146:147], v[124:125], v[154:155] op_sel_hi:[1,0]
	v_pk_mul_f32 v[122:123], v[122:123], v[154:155] op_sel_hi:[1,0]
	v_pk_mul_f32 v[124:125], v[120:121], v[154:155] op_sel_hi:[1,0]
	v_pk_mul_f32 v[118:119], v[118:119], v[154:155] op_sel_hi:[1,0]
	v_pk_mul_f32 v[120:121], v[116:117], v[154:155] op_sel_hi:[1,0]
	v_pk_mul_f32 v[114:115], v[114:115], v[154:155] op_sel_hi:[1,0]
	v_pk_mul_f32 v[116:117], v[112:113], v[154:155] op_sel_hi:[1,0]
	s_and_saveexec_b64 s[14:15], s[36:37]
	s_xor_b64 s[58:59], exec, s[14:15]
	s_cbranch_execz .LBB0_344
	v_cmp_lt_i32_e64 s[38:39], 2, v150
	s_and_saveexec_b64 s[14:15], s[38:39]
	s_xor_b64 s[60:61], exec, s[14:15]
	s_cbranch_execz .LBB0_339
	v_cmp_ne_u32_e64 s[38:39], 3, v150
	s_and_saveexec_b64 s[14:15], s[38:39]
	s_xor_b64 s[62:63], exec, s[14:15]
	s_cbranch_execz .LBB0_334
	v_readlane_b32 s6, v251, 0
	v_readlane_b32 s7, v251, 1
	s_movk_i32 s3, 0x300
	v_cvt_pk_bf16_f32 v154, v146, v147
	v_cvt_pk_bf16_f32 v155, v126, v127
	v_cvt_pk_bf16_f32 v156, v124, v125
	v_cvt_pk_bf16_f32 v157, v122, v123
	s_nop 0
	v_mov_b64_e32 v[112:113], s[6:7]
	v_mad_i64_i32 v[112:113], s[14:15], v144, s3, v[112:113]
	v_lshl_add_u64 v[112:113], v[184:185], 1, v[112:113]
	global_store_dwordx4 v[112:113], v[154:157], off offset:-1536 sc1
	v_mul_f32_e32 v112, v147, v147
	v_mul_f32_e32 v113, v127, v127
	v_fmac_f32_e32 v112, v146, v146
	v_fmac_f32_e32 v113, v126, v126
	v_add_f32_e32 v112, v112, v113
	v_mul_f32_e32 v113, v125, v125
	v_fmac_f32_e32 v113, v124, v124
	v_add_f32_e32 v112, v113, v112
	v_mul_f32_e32 v113, v123, v123
	v_fmac_f32_e32 v113, v122, v122
	v_add_f32_e32 v112, v113, v112
	v_mov_b32_e32 v113, v112
	s_nop 1
	v_permlane16_swap_b32_e32 v112, v113
	v_add_f32_e32 v112, v112, v113
	v_mov_b32_e32 v113, v112
	v_ashrrev_i32_e32 v145, 31, v144
	s_nop 0
	v_permlane32_swap_b32_e32 v112, v113
	v_mbcnt_lo_u32_b32 v122, -1, 0
	v_mbcnt_hi_u32_b32 v122, -1, v122
	s_nop 0
	v_cmp_gt_u32_e64 s[38:39], 16, v122
	s_and_saveexec_b64 s[64:65], s[38:39]
	s_cbranch_execz .LBB0_331
	v_add_f32_e32 v124, v112, v113
	v_lshlrev_b64 v[112:113], 5, v[144:145]
	v_lshl_add_u64 v[112:113], s[96:97], 0, v[112:113]
	v_lshlrev_b32_e32 v122, 2, v149
	v_mov_b32_e32 v123, v185
	v_lshl_add_u64 v[112:113], v[112:113], 0, v[122:123]
	global_store_dword v[112:113], v124, off offset:16
.LBB0_331:
	s_or_b64 exec, exec, s[64:65]
	s_and_saveexec_b64 s[38:39], vcc
	s_cbranch_execz .LBB0_333
	v_readlane_b32 s6, v251, 36
	v_lshlrev_b64 v[112:113], 6, v[144:145]
	v_readlane_b32 s7, v251, 37
	v_cvt_pk_bf16_f32 v120, v120, v121
	v_cvt_pk_bf16_f32 v121, v118, v119
	v_cvt_pk_bf16_f32 v122, v116, v117
	v_cvt_pk_bf16_f32 v123, v114, v115
	s_nop 1
	v_lshl_add_u64 v[112:113], s[6:7], 0, v[112:113]
	v_lshl_add_u64 v[112:113], v[184:185], 1, v[112:113]
	global_store_dwordx4 v[112:113], v[120:123], off offset:-2048 sc1

; __device__ __forceinline__ int lane_id_asm() { int l; asm volatile("v_mbcnt_lo_u32_b32 %0, -1, 0\n\tv_mbcnt_hi_u32_b32 %0, -1, %0" : "=v"(l)); return l; }
; __device__ __forceinline__ void row_part_store(float s, float* dst) {
;     { const auto r_ = __builtin_amdgcn_permlane16_swap(__float_as_uint(s), __float_as_uint(s), false, false); s = __uint_as_float(r_[0]) + __uint_as_float(r_[1]); }
;     { const auto r_ = __builtin_amdgcn_permlane32_swap(__float_as_uint(s), __float_as_uint(s), false, false); s = __uint_as_float(r_[0]) + __uint_as_float(r_[1]); }
;     if ((lane_id_asm() >> 4) == 0) *dst = s;
.LBB0_334:
	s_andn2_saveexec_b64 s[62:63], s[62:63]
	s_cbranch_execz .LBB0_338
	v_readlane_b32 s6, v251, 0
	v_readlane_b32 s7, v251, 1
	s_movk_i32 s3, 0x300
	v_cvt_pk_bf16_f32 v154, v146, v147
	v_cvt_pk_bf16_f32 v155, v126, v127
	v_cvt_pk_bf16_f32 v156, v124, v125
	v_cvt_pk_bf16_f32 v157, v122, v123
	s_nop 0
	v_mov_b64_e32 v[112:113], s[6:7]
	v_mad_i64_i32 v[112:113], s[14:15], v144, s3, v[112:113]
	v_lshl_add_u64 v[112:113], v[184:185], 1, v[112:113]
	global_store_dwordx4 v[112:113], v[154:157], off offset:-1536 sc1
	s_nop 1
	v_cvt_pk_bf16_f32 v154, v120, v121
	v_cvt_pk_bf16_f32 v155, v118, v119
	v_cvt_pk_bf16_f32 v156, v116, v117
	v_cvt_pk_bf16_f32 v157, v114, v115
	global_store_dwordx4 v[112:113], v[154:157], off offset:-1280 sc1
	v_mul_f32_e32 v112, v147, v147
	v_mul_f32_e32 v113, v127, v127
	v_fmac_f32_e32 v112, v146, v146
	v_fmac_f32_e32 v113, v126, v126
	v_add_f32_e32 v112, v112, v113
	v_mul_f32_e32 v113, v125, v125
	v_fmac_f32_e32 v113, v124, v124
	v_add_f32_e32 v112, v113, v112
	v_mul_f32_e32 v113, v123, v123
	v_fmac_f32_e32 v113, v122, v122
	v_add_f32_e32 v112, v113, v112
	v_mul_f32_e32 v113, v121, v121
	v_mul_f32_e32 v119, v119, v119
	v_fmac_f32_e32 v113, v120, v120
	v_fmac_f32_e32 v119, v118, v118
	v_mul_f32_e32 v117, v117, v117
	v_add_f32_e32 v113, v113, v119
	v_fmac_f32_e32 v117, v116, v116
	v_mul_f32_e32 v115, v115, v115
	v_add_f32_e32 v113, v117, v113
	v_fmac_f32_e32 v115, v114, v114
	v_add_f32_e32 v113, v115, v113
	v_add_f32_e32 v112, v112, v113
	v_mov_b32_e32 v113, v112
	s_nop 1
	v_permlane16_swap_b32_e32 v112, v113
	v_add_f32_e32 v112, v112, v113
	v_mov_b32_e32 v113, v112
	s_nop 1
	v_permlane32_swap_b32_e32 v112, v113
	v_mbcnt_lo_u32_b32 v114, -1, 0
	v_mbcnt_hi_u32_b32 v114, -1, v114
	s_nop 0
	v_cmp_gt_u32_e64 s[38:39], 16, v114
	s_and_saveexec_b64 s[64:65], s[38:39]
	s_cbranch_execz .LBB0_337
	v_ashrrev_i32_e32 v145, 31, v144
	v_add_f32_e32 v116, v112, v113
	v_lshlrev_b64 v[112:113], 5, v[144:145]
	v_lshl_add_u64 v[112:113], s[96:97], 0, v[112:113]
	v_lshlrev_b32_e32 v114, 2, v149
	v_mov_b32_e32 v115, v185
	v_lshl_add_u64 v[112:113], v[112:113], 0, v[114:115]
	global_store_dword v[112:113], v116, off

; __device__ __forceinline__ int lane_id_asm() { int l; asm volatile("v_mbcnt_lo_u32_b32 %0, -1, 0\n\tv_mbcnt_hi_u32_b32 %0, -1, %0" : "=v"(l)); return l; }
; __device__ __forceinline__ void row_part_store(float s, float* dst) {
;     { const auto r_ = __builtin_amdgcn_permlane16_swap(__float_as_uint(s), __float_as_uint(s), false, false); s = __uint_as_float(r_[0]) + __uint_as_float(r_[1]); }
;     { const auto r_ = __builtin_amdgcn_permlane32_swap(__float_as_uint(s), __float_as_uint(s), false, false); s = __uint_as_float(r_[0]) + __uint_as_float(r_[1]); }
;     if ((lane_id_asm() >> 4) == 0) *dst = s;
.LBB0_339:
	s_andn2_saveexec_b64 s[60:61], s[60:61]
	s_cbranch_execz .LBB0_343
	v_ashrrev_i32_e32 v145, 31, v144
	v_readlane_b32 s6, v255, 30
	v_lshlrev_b64 v[112:113], 9, v[144:145]
	v_readlane_b32 s7, v255, 31
	v_cvt_pk_bf16_f32 v154, v146, v147
	v_cvt_pk_bf16_f32 v155, v126, v127
	v_cvt_pk_bf16_f32 v156, v124, v125
	v_cvt_pk_bf16_f32 v157, v122, v123
	s_nop 1
	v_lshl_add_u64 v[112:113], s[6:7], 0, v[112:113]
	v_lshl_add_u64 v[112:113], v[184:185], 1, v[112:113]
	global_store_dwordx4 v[112:113], v[154:157], off offset:-1024 sc1
	s_nop 1
	v_cvt_pk_bf16_f32 v154, v120, v121
	v_cvt_pk_bf16_f32 v155, v118, v119
	v_cvt_pk_bf16_f32 v156, v116, v117
	v_cvt_pk_bf16_f32 v157, v114, v115
	global_store_dwordx4 v[112:113], v[154:157], off offset:-768 sc1
	v_mul_f32_e32 v112, v147, v147
	v_mul_f32_e32 v113, v127, v127
	v_fmac_f32_e32 v112, v146, v146
	v_fmac_f32_e32 v113, v126, v126
	v_add_f32_e32 v112, v112, v113
	v_mul_f32_e32 v113, v125, v125
	v_fmac_f32_e32 v113, v124, v124
	v_add_f32_e32 v112, v113, v112
	v_mul_f32_e32 v113, v123, v123
	v_fmac_f32_e32 v113, v122, v122
	v_add_f32_e32 v112, v113, v112
	v_mul_f32_e32 v113, v121, v121
	v_mul_f32_e32 v119, v119, v119
	v_fmac_f32_e32 v113, v120, v120
	v_fmac_f32_e32 v119, v118, v118
	v_mul_f32_e32 v117, v117, v117
	v_add_f32_e32 v113, v113, v119
	v_fmac_f32_e32 v117, v116, v116
	v_mul_f32_e32 v115, v115, v115
	v_add_f32_e32 v113, v117, v113
	v_fmac_f32_e32 v115, v114, v114
	v_add_f32_e32 v113, v115, v113
	v_add_f32_e32 v112, v112, v113
	v_mov_b32_e32 v113, v112
	s_nop 1
	v_permlane16_swap_b32_e32 v112, v113
	v_add_f32_e32 v112, v112, v113
	v_mov_b32_e32 v113, v112
	s_nop 1
	v_permlane32_swap_b32_e32 v112, v113
	v_mbcnt_lo_u32_b32 v114, -1, 0
	v_mbcnt_hi_u32_b32 v114, -1, v114
	s_nop 0
	v_cmp_gt_u32_e64 s[38:39], 16, v114
	s_and_saveexec_b64 s[62:63], s[38:39]
	s_cbranch_execz .LBB0_342
	v_add_f32_e32 v116, v112, v113
	v_lshl_add_u64 v[112:113], v[144:145], 4, s[92:93]
	v_lshlrev_b32_e32 v114, 2, v149
	v_mov_b32_e32 v115, v185
	v_lshl_add_u64 v[112:113], v[112:113], 0, v[114:115]
	global_store_dword v[112:113], v116, off

.LBB0_344:
	s_or_saveexec_b64 s[38:39], s[58:59]
	v_ashrrev_i32_e32 v113, 31, v184
	v_mov_b32_e32 v112, v184
	s_xor_b64 exec, exec, s[38:39]
	s_cbranch_execz .LBB0_346
	v_ashrrev_i32_e32 v145, 31, v144
	v_cvt_pk_bf16_f32 v154, v146, v147
	v_cvt_pk_bf16_f32 v155, v126, v127
	v_cvt_pk_bf16_f32 v156, v124, v125
	v_cvt_pk_bf16_f32 v157, v122, v123
	v_lshlrev_b64 v[122:123], 10, v[144:145]
	v_lshl_add_u64 v[122:123], s[4:5], 0, v[122:123]
	v_lshl_add_u64 v[124:125], v[112:113], 1, v[122:123]
	global_store_dwordx4 v[124:125], v[154:157], off sc1
	v_cvt_pk_bf16_f32 v120, v120, v121
	v_cvt_pk_bf16_f32 v121, v118, v119
	v_cvt_pk_bf16_f32 v122, v116, v117
	v_cvt_pk_bf16_f32 v123, v114, v115
	global_store_dwordx4 v[124:125], v[120:123], off offset:256 sc1
.LBB0_346:
	s_or_b64 exec, exec, s[38:39]
	v_pk_mul_f32 v[110:111], v[110:111], v[142:143] op_sel_hi:[1,0]
	v_pk_mul_f32 v[108:109], v[108:109], v[142:143] op_sel_hi:[1,0]
	v_pk_mul_f32 v[106:107], v[106:107], v[142:143] op_sel_hi:[1,0]
	v_pk_mul_f32 v[104:105], v[104:105], v[142:143] op_sel_hi:[1,0]
	v_pk_mul_f32 v[102:103], v[102:103], v[142:143] op_sel_hi:[1,0]
	v_pk_mul_f32 v[100:101], v[100:101], v[142:143] op_sel_hi:[1,0]
	v_pk_mul_f32 v[98:99], v[98:99], v[142:143] op_sel_hi:[1,0]
	v_pk_mul_f32 v[96:97], v[96:97], v[142:143] op_sel_hi:[1,0]
	s_and_saveexec_b64 s[14:15], s[36:37]
	s_xor_b64 s[58:59], exec, s[14:15]
	s_mov_b32 s77, s8
	s_cbranch_execz .LBB0_364
	v_cmp_lt_i32_e64 s[38:39], 2, v150
	s_and_saveexec_b64 s[14:15], s[38:39]
	s_xor_b64 s[60:61], exec, s[14:15]
	s_cbranch_execz .LBB0_359
	v_cmp_ne_u32_e64 s[38:39], 3, v150
	s_and_saveexec_b64 s[14:15], s[38:39]
	s_xor_b64 s[62:63], exec, s[14:15]
	s_cbranch_execz .LBB0_354
	v_cvt_pk_bf16_f32 v114, v108, v109
	v_mul_f32_e32 v109, v109, v109
	v_fmac_f32_e32 v109, v108, v108
	v_mul_f32_e32 v108, v111, v111
	v_cvt_pk_bf16_f32 v115, v110, v111
	v_cvt_pk_bf16_f32 v116, v104, v105
	v_fmac_f32_e32 v108, v110, v110
	v_mul_f32_e32 v105, v105, v105
	v_add_f32_e32 v108, v109, v108
	v_fmac_f32_e32 v105, v104, v104
	v_add_f32_e32 v104, v105, v108
	v_mul_f32_e32 v105, v107, v107
	v_fmac_f32_e32 v105, v106, v106
	v_readlane_b32 s6, v251, 0
	v_add_f32_e32 v104, v105, v104
	v_readlane_b32 s7, v251, 1
	v_mov_b32_e32 v105, v104
	s_movk_i32 s3, 0x300
	v_mov_b64_e32 v[118:119], s[6:7]
	v_permlane16_swap_b32_e32 v104, v105
	v_mad_i64_i32 v[118:119], s[14:15], v140, s3, v[118:119]
	v_add_f32_e32 v104, v104, v105
	v_lshl_add_u64 v[118:119], v[184:185], 1, v[118:119]
	v_mov_b32_e32 v105, v104
	v_cvt_pk_bf16_f32 v117, v106, v107
	v_ashrrev_i32_e32 v141, 31, v140
	global_store_dwordx4 v[118:119], v[114:117], off offset:-1536 sc1
	v_permlane32_swap_b32_e32 v104, v105
	v_mbcnt_lo_u32_b32 v106, -1, 0
	v_mbcnt_hi_u32_b32 v106, -1, v106
	s_nop 0
	v_cmp_gt_u32_e64 s[38:39], 16, v106
	s_and_saveexec_b64 s[64:65], s[38:39]
	s_cbranch_execz .LBB0_351
	v_add_f32_e32 v108, v104, v105
	v_lshlrev_b64 v[104:105], 5, v[140:141]
	v_lshl_add_u64 v[104:105], s[96:97], 0, v[104:105]
	v_lshlrev_b32_e32 v106, 2, v149
	v_mov_b32_e32 v107, v185
	v_lshl_add_u64 v[104:105], v[104:105], 0, v[106:107]
	global_store_dword v[104:105], v108, off offset:16
.LBB0_351:
	s_or_b64 exec, exec, s[64:65]
	s_and_saveexec_b64 s[38:39], vcc
	s_cbranch_execz .LBB0_353
	v_readlane_b32 s6, v251, 36
	v_cvt_pk_bf16_f32 v100, v100, v101
	v_cvt_pk_bf16_f32 v101, v102, v103
	v_cvt_pk_bf16_f32 v102, v96, v97
	v_lshlrev_b64 v[96:97], 6, v[140:141]
	v_readlane_b32 s7, v251, 37
	v_cvt_pk_bf16_f32 v103, v98, v99
	s_nop 1
	v_lshl_add_u64 v[96:97], s[6:7], 0, v[96:97]
	v_lshl_add_u64 v[96:97], v[184:185], 1, v[96:97]
	global_store_dwordx4 v[96:97], v[100:103], off offset:-2048 sc1

; __device__ __forceinline__ int lane_id_asm() { int l; asm volatile("v_mbcnt_lo_u32_b32 %0, -1, 0\n\tv_mbcnt_hi_u32_b32 %0, -1, %0" : "=v"(l)); return l; }
; __device__ __forceinline__ void row_part_store(float s, float* dst) {
;     { const auto r_ = __builtin_amdgcn_permlane16_swap(__float_as_uint(s), __float_as_uint(s), false, false); s = __uint_as_float(r_[0]) + __uint_as_float(r_[1]); }
;     { const auto r_ = __builtin_amdgcn_permlane32_swap(__float_as_uint(s), __float_as_uint(s), false, false); s = __uint_as_float(r_[0]) + __uint_as_float(r_[1]); }
;     if ((lane_id_asm() >> 4) == 0) *dst = s;
.LBB0_354:
	s_andn2_saveexec_b64 s[62:63], s[62:63]
	s_cbranch_execz .LBB0_358
	v_readlane_b32 s6, v251, 0
	v_readlane_b32 s7, v251, 1
	s_movk_i32 s3, 0x300
	s_nop 0
	v_mov_b64_e32 v[114:115], s[6:7]
	v_mad_i64_i32 v[114:115], s[14:15], v140, s3, v[114:115]
	v_lshl_add_u64 v[118:119], v[184:185], 1, v[114:115]
	v_cvt_pk_bf16_f32 v114, v108, v109
	v_cvt_pk_bf16_f32 v115, v110, v111
	v_cvt_pk_bf16_f32 v116, v104, v105
	v_cvt_pk_bf16_f32 v117, v106, v107
	global_store_dwordx4 v[118:119], v[114:117], off offset:-1536 sc1
	v_mul_f32_e32 v109, v109, v109
	v_fmac_f32_e32 v109, v108, v108
	v_cvt_pk_bf16_f32 v114, v100, v101
	v_mul_f32_e32 v101, v101, v101
	v_mul_f32_e32 v108, v111, v111
	v_fmac_f32_e32 v101, v100, v100
	v_mul_f32_e32 v100, v103, v103
	v_cvt_pk_bf16_f32 v115, v102, v103
	v_cvt_pk_bf16_f32 v116, v96, v97
	v_fmac_f32_e32 v108, v110, v110
	v_mul_f32_e32 v105, v105, v105
	v_fmac_f32_e32 v100, v102, v102
	v_mul_f32_e32 v97, v97, v97
	v_add_f32_e32 v108, v109, v108
	v_fmac_f32_e32 v105, v104, v104
	v_add_f32_e32 v100, v101, v100
	v_fmac_f32_e32 v97, v96, v96
	v_add_f32_e32 v104, v105, v108
	v_mul_f32_e32 v105, v107, v107
	v_add_f32_e32 v96, v97, v100
	v_mul_f32_e32 v97, v99, v99
	v_fmac_f32_e32 v105, v106, v106
	v_fmac_f32_e32 v97, v98, v98
	v_add_f32_e32 v104, v105, v104
	v_add_f32_e32 v96, v97, v96
	v_add_f32_e32 v96, v104, v96
	v_mov_b32_e32 v97, v96
	s_nop 1
	v_permlane16_swap_b32_e32 v96, v97
	v_add_f32_e32 v96, v96, v97
	v_mov_b32_e32 v97, v96
	v_cvt_pk_bf16_f32 v117, v98, v99
	global_store_dwordx4 v[118:119], v[114:117], off offset:-1280 sc1
	s_nop 0
	v_permlane32_swap_b32_e32 v96, v97
	v_mbcnt_lo_u32_b32 v98, -1, 0
	v_mbcnt_hi_u32_b32 v98, -1, v98
	s_nop 0
	v_cmp_gt_u32_e64 s[38:39], 16, v98
	s_and_saveexec_b64 s[64:65], s[38:39]
	s_cbranch_execz .LBB0_357
	v_ashrrev_i32_e32 v141, 31, v140
	v_add_f32_e32 v100, v96, v97
	v_lshlrev_b64 v[96:97], 5, v[140:141]
	v_lshl_add_u64 v[96:97], s[96:97], 0, v[96:97]
	v_lshlrev_b32_e32 v98, 2, v149
	v_mov_b32_e32 v99, v185
	v_lshl_add_u64 v[96:97], v[96:97], 0, v[98:99]
	global_store_dword v[96:97], v100, off

; __device__ __forceinline__ int lane_id_asm() { int l; asm volatile("v_mbcnt_lo_u32_b32 %0, -1, 0\n\tv_mbcnt_hi_u32_b32 %0, -1, %0" : "=v"(l)); return l; }
; __device__ __forceinline__ void row_part_store(float s, float* dst) {
;     { const auto r_ = __builtin_amdgcn_permlane16_swap(__float_as_uint(s), __float_as_uint(s), false, false); s = __uint_as_float(r_[0]) + __uint_as_float(r_[1]); }
;     { const auto r_ = __builtin_amdgcn_permlane32_swap(__float_as_uint(s), __float_as_uint(s), false, false); s = __uint_as_float(r_[0]) + __uint_as_float(r_[1]); }
;     if ((lane_id_asm() >> 4) == 0) *dst = s;
.LBB0_359:
	s_andn2_saveexec_b64 s[60:61], s[60:61]
	s_cbranch_execz .LBB0_363
	v_ashrrev_i32_e32 v141, 31, v140
	v_readlane_b32 s6, v255, 30
	v_lshlrev_b64 v[114:115], 9, v[140:141]
	v_readlane_b32 s7, v255, 31
	s_nop 1
	v_lshl_add_u64 v[114:115], s[6:7], 0, v[114:115]
	v_lshl_add_u64 v[118:119], v[184:185], 1, v[114:115]
	v_cvt_pk_bf16_f32 v114, v108, v109
	v_cvt_pk_bf16_f32 v115, v110, v111
	v_cvt_pk_bf16_f32 v116, v104, v105
	v_cvt_pk_bf16_f32 v117, v106, v107
	global_store_dwordx4 v[118:119], v[114:117], off offset:-1024 sc1
	v_mul_f32_e32 v109, v109, v109
	v_fmac_f32_e32 v109, v108, v108
	v_cvt_pk_bf16_f32 v114, v100, v101
	v_mul_f32_e32 v101, v101, v101
	v_mul_f32_e32 v108, v111, v111
	v_fmac_f32_e32 v101, v100, v100
	v_mul_f32_e32 v100, v103, v103
	v_cvt_pk_bf16_f32 v115, v102, v103
	v_cvt_pk_bf16_f32 v116, v96, v97
	v_fmac_f32_e32 v108, v110, v110
	v_mul_f32_e32 v105, v105, v105
	v_fmac_f32_e32 v100, v102, v102
	v_mul_f32_e32 v97, v97, v97
	v_add_f32_e32 v108, v109, v108
	v_fmac_f32_e32 v105, v104, v104
	v_add_f32_e32 v100, v101, v100
	v_fmac_f32_e32 v97, v96, v96
	v_add_f32_e32 v104, v105, v108
	v_mul_f32_e32 v105, v107, v107
	v_add_f32_e32 v96, v97, v100
	v_mul_f32_e32 v97, v99, v99
	v_fmac_f32_e32 v105, v106, v106
	v_fmac_f32_e32 v97, v98, v98
	v_add_f32_e32 v104, v105, v104
	v_add_f32_e32 v96, v97, v96
	v_add_f32_e32 v96, v104, v96
	v_mov_b32_e32 v97, v96
	s_nop 1
	v_permlane16_swap_b32_e32 v96, v97
	v_add_f32_e32 v96, v96, v97
	v_mov_b32_e32 v97, v96
	v_cvt_pk_bf16_f32 v117, v98, v99
	global_store_dwordx4 v[118:119], v[114:117], off offset:-768 sc1
	s_nop 0
	v_permlane32_swap_b32_e32 v96, v97
	v_mbcnt_lo_u32_b32 v98, -1, 0
	v_mbcnt_hi_u32_b32 v98, -1, v98
	s_nop 0
	v_cmp_gt_u32_e64 s[38:39], 16, v98
	s_and_saveexec_b64 s[62:63], s[38:39]
	s_cbranch_execz .LBB0_362
	v_add_f32_e32 v100, v96, v97
	v_lshl_add_u64 v[96:97], v[140:141], 4, s[92:93]
	v_lshlrev_b32_e32 v98, 2, v149
	v_mov_b32_e32 v99, v185
	v_lshl_add_u64 v[96:97], v[96:97], 0, v[98:99]
	global_store_dword v[96:97], v100, off

;     __device__ __forceinline__ RowPre pre_row(int row, int) const { const float ss = NSLOT == 8 ? sum8(part + (size_t)row * 8) : sum4(part + (size_t)row * 4); return PreRs{rsqrtf(ss * inv_k + EPS)}; }
;     __device__ __forceinline__ void operator()(const pg8::f32x4 (&acc)[2][2][4][2], const pg8::Unit& u, int wr, int wc, int, int, int ui) const {
;     ...
;             for (int j = 0; j < NB; ++j) { const int ai = (g + j) >> 2, mm = (g + j) & 3; const int rl = ai * 128 + wr * 64 + mm * 16 + fr; int row = u.pm * 256 + rl; asm volatile("" : "+v"(row)); rows[j] = row;
;                 rv[j] = F::USE_TAB ? tab[rl] : 0.f; rp[j] = f.pre_row(row, col); }
.LBB0_364:
	s_andn2_saveexec_b64 s[38:39], s[58:59]
	s_cbranch_execz .LBB0_366
	v_ashrrev_i32_e32 v141, 31, v140
	v_cvt_pk_bf16_f32 v108, v108, v109
	v_cvt_pk_bf16_f32 v109, v110, v111
	v_cvt_pk_bf16_f32 v110, v104, v105
	v_lshlrev_b64 v[104:105], 10, v[140:141]
	v_lshl_add_u64 v[104:105], s[4:5], 0, v[104:105]
	v_lshl_add_u64 v[104:105], v[112:113], 1, v[104:105]
	v_cvt_pk_bf16_f32 v111, v106, v107
	global_store_dwordx4 v[104:105], v[108:111], off sc1
	v_cvt_pk_bf16_f32 v100, v100, v101
	v_cvt_pk_bf16_f32 v101, v102, v103
	v_cvt_pk_bf16_f32 v102, v96, v97
	v_cvt_pk_bf16_f32 v103, v98, v99
	global_store_dwordx4 v[104:105], v[100:103], off offset:256 sc1
.LBB0_366:
	s_or_b64 exec, exec, s[38:39]
	s_nop 0
	v_add_u32_e32 v100, 32, v152
	ds_read_b32 v102, v151 offset:128
	v_add_u32_e32 v96, 48, v152
	ds_read_b32 v98, v151 offset:192
	s_waitcnt lgkmcnt(0)
	v_pk_mul_f32 v[94:95], v[94:95], v[102:103] op_sel_hi:[1,0]
	v_pk_mul_f32 v[92:93], v[92:93], v[102:103] op_sel_hi:[1,0]
	v_pk_mul_f32 v[90:91], v[90:91], v[102:103] op_sel_hi:[1,0]
	v_pk_mul_f32 v[88:89], v[88:89], v[102:103] op_sel_hi:[1,0]
	v_pk_mul_f32 v[86:87], v[86:87], v[102:103] op_sel_hi:[1,0]
	v_pk_mul_f32 v[84:85], v[84:85], v[102:103] op_sel_hi:[1,0]
	v_pk_mul_f32 v[82:83], v[82:83], v[102:103] op_sel_hi:[1,0]
	v_pk_mul_f32 v[80:81], v[80:81], v[102:103] op_sel_hi:[1,0]
	s_and_saveexec_b64 s[14:15], s[36:37]
	s_xor_b64 s[58:59], exec, s[14:15]
	s_cbranch_execz .LBB0_384
	v_cmp_lt_i32_e64 s[38:39], 2, v150
	s_and_saveexec_b64 s[14:15], s[38:39]
	s_xor_b64 s[60:61], exec, s[14:15]
	s_cbranch_execz .LBB0_379
	v_cmp_ne_u32_e64 s[38:39], 3, v150
	s_and_saveexec_b64 s[14:15], s[38:39]
	s_xor_b64 s[62:63], exec, s[14:15]
	s_cbranch_execz .LBB0_374
	v_cvt_pk_bf16_f32 v102, v92, v93
	v_mul_f32_e32 v93, v93, v93
	v_fmac_f32_e32 v93, v92, v92
	v_mul_f32_e32 v92, v95, v95
	v_cvt_pk_bf16_f32 v103, v94, v95
	v_cvt_pk_bf16_f32 v104, v88, v89
	v_fmac_f32_e32 v92, v94, v94
	v_mul_f32_e32 v89, v89, v89
	v_add_f32_e32 v92, v93, v92
	v_fmac_f32_e32 v89, v88, v88
	v_add_f32_e32 v88, v89, v92
	v_mul_f32_e32 v89, v91, v91
	v_fmac_f32_e32 v89, v90, v90
	v_readlane_b32 s6, v251, 0
	v_add_f32_e32 v88, v89, v88
	v_readlane_b32 s7, v251, 1
	v_mov_b32_e32 v89, v88
	s_movk_i32 s3, 0x300
	v_mov_b64_e32 v[106:107], s[6:7]
	v_permlane16_swap_b32_e32 v88, v89
	v_mad_i64_i32 v[106:107], s[14:15], v100, s3, v[106:107]
	v_add_f32_e32 v88, v88, v89
	v_lshl_add_u64 v[106:107], v[184:185], 1, v[106:107]
	v_mov_b32_e32 v89, v88
	v_cvt_pk_bf16_f32 v105, v90, v91
	v_ashrrev_i32_e32 v101, 31, v100
	global_store_dwordx4 v[106:107], v[102:105], off offset:-1536 sc1
	v_permlane32_swap_b32_e32 v88, v89
	v_mbcnt_lo_u32_b32 v90, -1, 0
	v_mbcnt_hi_u32_b32 v90, -1, v90
	s_nop 0
	v_cmp_gt_u32_e64 s[38:39], 16, v90
	s_and_saveexec_b64 s[64:65], s[38:39]
	s_cbranch_execz .LBB0_371
	v_add_f32_e32 v92, v88, v89
	v_lshlrev_b64 v[88:89], 5, v[100:101]
	v_lshl_add_u64 v[88:89], s[96:97], 0, v[88:89]
	v_lshlrev_b32_e32 v90, 2, v149
	v_mov_b32_e32 v91, v185
	v_lshl_add_u64 v[88:89], v[88:89], 0, v[90:91]
	global_store_dword v[88:89], v92, off offset:16
.LBB0_371:
	s_or_b64 exec, exec, s[64:65]
	s_and_saveexec_b64 s[38:39], vcc
	s_cbranch_execz .LBB0_373
	v_readlane_b32 s6, v251, 36
	v_cvt_pk_bf16_f32 v84, v84, v85
	v_cvt_pk_bf16_f32 v85, v86, v87
	v_cvt_pk_bf16_f32 v86, v80, v81
	v_lshlrev_b64 v[80:81], 6, v[100:101]
	v_readlane_b32 s7, v251, 37
	v_cvt_pk_bf16_f32 v87, v82, v83
	s_nop 1
	v_lshl_add_u64 v[80:81], s[6:7], 0, v[80:81]
	v_lshl_add_u64 v[80:81], v[184:185], 1, v[80:81]
	global_store_dwordx4 v[80:81], v[84:87], off offset:-2048 sc1

; __device__ __forceinline__ int lane_id_asm() { int l; asm volatile("v_mbcnt_lo_u32_b32 %0, -1, 0\n\tv_mbcnt_hi_u32_b32 %0, -1, %0" : "=v"(l)); return l; }
; __device__ __forceinline__ void row_part_store(float s, float* dst) {
;     { const auto r_ = __builtin_amdgcn_permlane16_swap(__float_as_uint(s), __float_as_uint(s), false, false); s = __uint_as_float(r_[0]) + __uint_as_float(r_[1]); }
;     { const auto r_ = __builtin_amdgcn_permlane32_swap(__float_as_uint(s), __float_as_uint(s), false, false); s = __uint_as_float(r_[0]) + __uint_as_float(r_[1]); }
;     if ((lane_id_asm() >> 4) == 0) *dst = s;
.LBB0_374:
	s_andn2_saveexec_b64 s[62:63], s[62:63]
	s_cbranch_execz .LBB0_378
	v_readlane_b32 s6, v251, 0
	v_readlane_b32 s7, v251, 1
	s_movk_i32 s3, 0x300
	s_nop 0
	v_mov_b64_e32 v[102:103], s[6:7]
	v_mad_i64_i32 v[102:103], s[14:15], v100, s3, v[102:103]
	v_lshl_add_u64 v[106:107], v[184:185], 1, v[102:103]
	v_cvt_pk_bf16_f32 v102, v92, v93
	v_cvt_pk_bf16_f32 v103, v94, v95
	v_cvt_pk_bf16_f32 v104, v88, v89
	v_cvt_pk_bf16_f32 v105, v90, v91
	global_store_dwordx4 v[106:107], v[102:105], off offset:-1536 sc1
	v_mul_f32_e32 v93, v93, v93
	v_fmac_f32_e32 v93, v92, v92
	v_cvt_pk_bf16_f32 v102, v84, v85
	v_mul_f32_e32 v85, v85, v85
	v_mul_f32_e32 v92, v95, v95
	v_fmac_f32_e32 v85, v84, v84
	v_mul_f32_e32 v84, v87, v87
	v_cvt_pk_bf16_f32 v103, v86, v87
	v_cvt_pk_bf16_f32 v104, v80, v81
	v_fmac_f32_e32 v92, v94, v94
	v_mul_f32_e32 v89, v89, v89
	v_fmac_f32_e32 v84, v86, v86
	v_mul_f32_e32 v81, v81, v81
	v_add_f32_e32 v92, v93, v92
	v_fmac_f32_e32 v89, v88, v88
	v_add_f32_e32 v84, v85, v84
	v_fmac_f32_e32 v81, v80, v80
	v_add_f32_e32 v88, v89, v92
	v_mul_f32_e32 v89, v91, v91
	v_add_f32_e32 v80, v81, v84
	v_mul_f32_e32 v81, v83, v83
	v_fmac_f32_e32 v89, v90, v90
	v_fmac_f32_e32 v81, v82, v82
	v_add_f32_e32 v88, v89, v88
	v_add_f32_e32 v80, v81, v80
	v_add_f32_e32 v80, v88, v80
	v_mov_b32_e32 v81, v80
	s_nop 1
	v_permlane16_swap_b32_e32 v80, v81
	v_add_f32_e32 v80, v80, v81
	v_mov_b32_e32 v81, v80
	v_cvt_pk_bf16_f32 v105, v82, v83
	global_store_dwordx4 v[106:107], v[102:105], off offset:-1280 sc1
	s_nop 0
	v_permlane32_swap_b32_e32 v80, v81
	v_mbcnt_lo_u32_b32 v82, -1, 0
	v_mbcnt_hi_u32_b32 v82, -1, v82
	s_nop 0
	v_cmp_gt_u32_e64 s[38:39], 16, v82
	s_and_saveexec_b64 s[64:65], s[38:39]
	s_cbranch_execz .LBB0_377
	v_ashrrev_i32_e32 v101, 31, v100
	v_add_f32_e32 v84, v80, v81
	v_lshlrev_b64 v[80:81], 5, v[100:101]
	v_lshl_add_u64 v[80:81], s[96:97], 0, v[80:81]
	v_lshlrev_b32_e32 v82, 2, v149
	v_mov_b32_e32 v83, v185
	v_lshl_add_u64 v[80:81], v[80:81], 0, v[82:83]
	global_store_dword v[80:81], v84, off

; __device__ __forceinline__ int lane_id_asm() { int l; asm volatile("v_mbcnt_lo_u32_b32 %0, -1, 0\n\tv_mbcnt_hi_u32_b32 %0, -1, %0" : "=v"(l)); return l; }
; __device__ __forceinline__ void row_part_store(float s, float* dst) {
;     { const auto r_ = __builtin_amdgcn_permlane16_swap(__float_as_uint(s), __float_as_uint(s), false, false); s = __uint_as_float(r_[0]) + __uint_as_float(r_[1]); }
;     { const auto r_ = __builtin_amdgcn_permlane32_swap(__float_as_uint(s), __float_as_uint(s), false, false); s = __uint_as_float(r_[0]) + __uint_as_float(r_[1]); }
;     if ((lane_id_asm() >> 4) == 0) *dst = s;
.LBB0_379:
	s_andn2_saveexec_b64 s[60:61], s[60:61]
	s_cbranch_execz .LBB0_383
	v_ashrrev_i32_e32 v101, 31, v100
	v_readlane_b32 s6, v255, 30
	v_lshlrev_b64 v[102:103], 9, v[100:101]
	v_readlane_b32 s7, v255, 31
	s_nop 1
	v_lshl_add_u64 v[102:103], s[6:7], 0, v[102:103]
	v_lshl_add_u64 v[106:107], v[184:185], 1, v[102:103]
	v_cvt_pk_bf16_f32 v102, v92, v93
	v_cvt_pk_bf16_f32 v103, v94, v95
	v_cvt_pk_bf16_f32 v104, v88, v89
	v_cvt_pk_bf16_f32 v105, v90, v91
	global_store_dwordx4 v[106:107], v[102:105], off offset:-1024 sc1
	v_mul_f32_e32 v93, v93, v93
	v_fmac_f32_e32 v93, v92, v92
	v_cvt_pk_bf16_f32 v102, v84, v85
	v_mul_f32_e32 v85, v85, v85
	v_mul_f32_e32 v92, v95, v95
	v_fmac_f32_e32 v85, v84, v84
	v_mul_f32_e32 v84, v87, v87
	v_cvt_pk_bf16_f32 v103, v86, v87
	v_cvt_pk_bf16_f32 v104, v80, v81
	v_fmac_f32_e32 v92, v94, v94
	v_mul_f32_e32 v89, v89, v89
	v_fmac_f32_e32 v84, v86, v86
	v_mul_f32_e32 v81, v81, v81
	v_add_f32_e32 v92, v93, v92
	v_fmac_f32_e32 v89, v88, v88
	v_add_f32_e32 v84, v85, v84
	v_fmac_f32_e32 v81, v80, v80
	v_add_f32_e32 v88, v89, v92
	v_mul_f32_e32 v89, v91, v91
	v_add_f32_e32 v80, v81, v84
	v_mul_f32_e32 v81, v83, v83
	v_fmac_f32_e32 v89, v90, v90
	v_fmac_f32_e32 v81, v82, v82
	v_add_f32_e32 v88, v89, v88
	v_add_f32_e32 v80, v81, v80
	v_add_f32_e32 v80, v88, v80
	v_mov_b32_e32 v81, v80
	s_nop 1
	v_permlane16_swap_b32_e32 v80, v81
	v_add_f32_e32 v80, v80, v81
	v_mov_b32_e32 v81, v80
	v_cvt_pk_bf16_f32 v105, v82, v83
	global_store_dwordx4 v[106:107], v[102:105], off offset:-768 sc1
	s_nop 0
	v_permlane32_swap_b32_e32 v80, v81
	v_mbcnt_lo_u32_b32 v82, -1, 0
	v_mbcnt_hi_u32_b32 v82, -1, v82
	s_nop 0
	v_cmp_gt_u32_e64 s[38:39], 16, v82
	s_and_saveexec_b64 s[62:63], s[38:39]
	s_cbranch_execz .LBB0_382
	v_add_f32_e32 v84, v80, v81
	v_lshl_add_u64 v[80:81], v[100:101], 4, s[92:93]
	v_lshlrev_b32_e32 v82, 2, v149
	v_mov_b32_e32 v83, v185
	v_lshl_add_u64 v[80:81], v[80:81], 0, v[82:83]
	global_store_dword v[80:81], v84, off

.LBB0_384:
	s_andn2_saveexec_b64 s[38:39], s[58:59]
	s_cbranch_execz .LBB0_386
	v_ashrrev_i32_e32 v101, 31, v100
	v_cvt_pk_bf16_f32 v92, v92, v93
	v_cvt_pk_bf16_f32 v93, v94, v95
	v_cvt_pk_bf16_f32 v94, v88, v89
	v_lshlrev_b64 v[88:89], 10, v[100:101]
	v_lshl_add_u64 v[88:89], s[4:5], 0, v[88:89]
	v_lshl_add_u64 v[88:89], v[112:113], 1, v[88:89]
	v_cvt_pk_bf16_f32 v95, v90, v91
	global_store_dwordx4 v[88:89], v[92:95], off sc1
	v_cvt_pk_bf16_f32 v84, v84, v85
	v_cvt_pk_bf16_f32 v85, v86, v87
	v_cvt_pk_bf16_f32 v86, v80, v81
	v_cvt_pk_bf16_f32 v87, v82, v83
	global_store_dwordx4 v[88:89], v[84:87], off offset:256 sc1
.LBB0_386:
	s_or_b64 exec, exec, s[38:39]
	v_pk_mul_f32 v[78:79], v[78:79], v[98:99] op_sel_hi:[1,0]
	v_pk_mul_f32 v[76:77], v[76:77], v[98:99] op_sel_hi:[1,0]
	v_pk_mul_f32 v[74:75], v[74:75], v[98:99] op_sel_hi:[1,0]
	v_pk_mul_f32 v[72:73], v[72:73], v[98:99] op_sel_hi:[1,0]
	v_pk_mul_f32 v[70:71], v[70:71], v[98:99] op_sel_hi:[1,0]
	v_pk_mul_f32 v[68:69], v[68:69], v[98:99] op_sel_hi:[1,0]
	v_pk_mul_f32 v[66:67], v[66:67], v[98:99] op_sel_hi:[1,0]
	v_pk_mul_f32 v[64:65], v[64:65], v[98:99] op_sel_hi:[1,0]
	s_and_saveexec_b64 s[14:15], s[36:37]
	s_xor_b64 s[58:59], exec, s[14:15]
	s_cbranch_execz .LBB0_404
	v_cmp_lt_i32_e64 s[38:39], 2, v150
	s_and_saveexec_b64 s[14:15], s[38:39]
	s_xor_b64 s[60:61], exec, s[14:15]
	s_cbranch_execz .LBB0_399
	v_cmp_ne_u32_e64 s[38:39], 3, v150
	s_and_saveexec_b64 s[14:15], s[38:39]
	s_xor_b64 s[62:63], exec, s[14:15]
	s_cbranch_execz .LBB0_394
	v_cvt_pk_bf16_f32 v80, v76, v77
	v_mul_f32_e32 v77, v77, v77
	v_fmac_f32_e32 v77, v76, v76
	v_mul_f32_e32 v76, v79, v79
	v_cvt_pk_bf16_f32 v81, v78, v79
	v_cvt_pk_bf16_f32 v82, v72, v73
	v_fmac_f32_e32 v76, v78, v78
	v_mul_f32_e32 v73, v73, v73
	v_add_f32_e32 v76, v77, v76
	v_fmac_f32_e32 v73, v72, v72
	v_add_f32_e32 v72, v73, v76
	v_mul_f32_e32 v73, v75, v75
	v_fmac_f32_e32 v73, v74, v74
	v_readlane_b32 s6, v251, 0
	v_add_f32_e32 v72, v73, v72
	v_readlane_b32 s7, v251, 1
	v_mov_b32_e32 v73, v72
	s_movk_i32 s3, 0x300
	v_mov_b64_e32 v[84:85], s[6:7]
	v_permlane16_swap_b32_e32 v72, v73
	v_mad_i64_i32 v[84:85], s[14:15], v96, s3, v[84:85]
	v_add_f32_e32 v72, v72, v73
	v_lshl_add_u64 v[84:85], v[184:185], 1, v[84:85]
	v_mov_b32_e32 v73, v72
	v_cvt_pk_bf16_f32 v83, v74, v75
	v_ashrrev_i32_e32 v97, 31, v96
	global_store_dwordx4 v[84:85], v[80:83], off offset:-1536 sc1
	v_permlane32_swap_b32_e32 v72, v73
	v_mbcnt_lo_u32_b32 v74, -1, 0
	v_mbcnt_hi_u32_b32 v74, -1, v74
	s_nop 0
	v_cmp_gt_u32_e64 s[38:39], 16, v74
	s_and_saveexec_b64 s[64:65], s[38:39]
	s_cbranch_execz .LBB0_391
	v_add_f32_e32 v76, v72, v73
	v_lshlrev_b64 v[72:73], 5, v[96:97]
	v_lshl_add_u64 v[72:73], s[96:97], 0, v[72:73]
	v_lshlrev_b32_e32 v74, 2, v149
	v_mov_b32_e32 v75, v185
	v_lshl_add_u64 v[72:73], v[72:73], 0, v[74:75]
	global_store_dword v[72:73], v76, off offset:16
.LBB0_391:
	s_or_b64 exec, exec, s[64:65]
	s_and_saveexec_b64 s[38:39], vcc
	s_cbranch_execz .LBB0_393
	v_readlane_b32 s6, v251, 36
	v_cvt_pk_bf16_f32 v68, v68, v69
	v_cvt_pk_bf16_f32 v69, v70, v71
	v_cvt_pk_bf16_f32 v70, v64, v65
	v_lshlrev_b64 v[64:65], 6, v[96:97]
	v_readlane_b32 s7, v251, 37
	v_cvt_pk_bf16_f32 v71, v66, v67
	s_nop 1
	v_lshl_add_u64 v[64:65], s[6:7], 0, v[64:65]
	v_lshl_add_u64 v[64:65], v[184:185], 1, v[64:65]
	global_store_dwordx4 v[64:65], v[68:71], off offset:-2048 sc1

; __device__ __forceinline__ int lane_id_asm() { int l; asm volatile("v_mbcnt_lo_u32_b32 %0, -1, 0\n\tv_mbcnt_hi_u32_b32 %0, -1, %0" : "=v"(l)); return l; }
; __device__ __forceinline__ void row_part_store(float s, float* dst) {
;     { const auto r_ = __builtin_amdgcn_permlane16_swap(__float_as_uint(s), __float_as_uint(s), false, false); s = __uint_as_float(r_[0]) + __uint_as_float(r_[1]); }
;     { const auto r_ = __builtin_amdgcn_permlane32_swap(__float_as_uint(s), __float_as_uint(s), false, false); s = __uint_as_float(r_[0]) + __uint_as_float(r_[1]); }
;     if ((lane_id_asm() >> 4) == 0) *dst = s;
.LBB0_394:
	s_andn2_saveexec_b64 s[62:63], s[62:63]
	s_cbranch_execz .LBB0_398
	v_readlane_b32 s6, v251, 0
	v_readlane_b32 s7, v251, 1
	s_movk_i32 s3, 0x300
	s_nop 0
	v_mov_b64_e32 v[80:81], s[6:7]
	v_mad_i64_i32 v[80:81], s[14:15], v96, s3, v[80:81]
	v_lshl_add_u64 v[84:85], v[184:185], 1, v[80:81]
	v_cvt_pk_bf16_f32 v80, v76, v77
	v_cvt_pk_bf16_f32 v81, v78, v79
	v_cvt_pk_bf16_f32 v82, v72, v73
	v_cvt_pk_bf16_f32 v83, v74, v75
	global_store_dwordx4 v[84:85], v[80:83], off offset:-1536 sc1
	v_mul_f32_e32 v77, v77, v77
	v_fmac_f32_e32 v77, v76, v76
	v_cvt_pk_bf16_f32 v80, v68, v69
	v_mul_f32_e32 v69, v69, v69
	v_mul_f32_e32 v76, v79, v79
	v_fmac_f32_e32 v69, v68, v68
	v_mul_f32_e32 v68, v71, v71
	v_cvt_pk_bf16_f32 v81, v70, v71
	v_cvt_pk_bf16_f32 v82, v64, v65
	v_fmac_f32_e32 v76, v78, v78
	v_mul_f32_e32 v73, v73, v73
	v_fmac_f32_e32 v68, v70, v70
	v_mul_f32_e32 v65, v65, v65
	v_add_f32_e32 v76, v77, v76
	v_fmac_f32_e32 v73, v72, v72
	v_add_f32_e32 v68, v69, v68
	v_fmac_f32_e32 v65, v64, v64
	v_add_f32_e32 v72, v73, v76
	v_mul_f32_e32 v73, v75, v75
	v_add_f32_e32 v64, v65, v68
	v_mul_f32_e32 v65, v67, v67
	v_fmac_f32_e32 v73, v74, v74
	v_fmac_f32_e32 v65, v66, v66
	v_add_f32_e32 v72, v73, v72
	v_add_f32_e32 v64, v65, v64
	v_add_f32_e32 v64, v72, v64
	v_mov_b32_e32 v65, v64
	s_nop 1
	v_permlane16_swap_b32_e32 v64, v65
	v_add_f32_e32 v64, v64, v65
	v_mov_b32_e32 v65, v64
	v_cvt_pk_bf16_f32 v83, v66, v67
	global_store_dwordx4 v[84:85], v[80:83], off offset:-1280 sc1
	s_nop 0
	v_permlane32_swap_b32_e32 v64, v65
	v_mbcnt_lo_u32_b32 v66, -1, 0
	v_mbcnt_hi_u32_b32 v66, -1, v66
	s_nop 0
	v_cmp_gt_u32_e64 s[38:39], 16, v66
	s_and_saveexec_b64 s[64:65], s[38:39]
	s_cbranch_execz .LBB0_397
	v_ashrrev_i32_e32 v97, 31, v96
	v_add_f32_e32 v68, v64, v65
	v_lshlrev_b64 v[64:65], 5, v[96:97]
	v_lshl_add_u64 v[64:65], s[96:97], 0, v[64:65]
	v_lshlrev_b32_e32 v66, 2, v149
	v_mov_b32_e32 v67, v185
	v_lshl_add_u64 v[64:65], v[64:65], 0, v[66:67]
	global_store_dword v[64:65], v68, off

; __device__ __forceinline__ int lane_id_asm() { int l; asm volatile("v_mbcnt_lo_u32_b32 %0, -1, 0\n\tv_mbcnt_hi_u32_b32 %0, -1, %0" : "=v"(l)); return l; }
; __device__ __forceinline__ void row_part_store(float s, float* dst) {
;     { const auto r_ = __builtin_amdgcn_permlane16_swap(__float_as_uint(s), __float_as_uint(s), false, false); s = __uint_as_float(r_[0]) + __uint_as_float(r_[1]); }
;     { const auto r_ = __builtin_amdgcn_permlane32_swap(__float_as_uint(s), __float_as_uint(s), false, false); s = __uint_as_float(r_[0]) + __uint_as_float(r_[1]); }
;     if ((lane_id_asm() >> 4) == 0) *dst = s;
.LBB0_399:
	s_andn2_saveexec_b64 s[60:61], s[60:61]
	s_cbranch_execz .LBB0_403
	v_ashrrev_i32_e32 v97, 31, v96
	v_readlane_b32 s6, v255, 30
	v_lshlrev_b64 v[80:81], 9, v[96:97]
	v_readlane_b32 s7, v255, 31
	s_nop 1
	v_lshl_add_u64 v[80:81], s[6:7], 0, v[80:81]
	v_lshl_add_u64 v[84:85], v[184:185], 1, v[80:81]
	v_cvt_pk_bf16_f32 v80, v76, v77
	v_cvt_pk_bf16_f32 v81, v78, v79
	v_cvt_pk_bf16_f32 v82, v72, v73
	v_cvt_pk_bf16_f32 v83, v74, v75
	global_store_dwordx4 v[84:85], v[80:83], off offset:-1024 sc1
	v_mul_f32_e32 v77, v77, v77
	v_fmac_f32_e32 v77, v76, v76
	v_cvt_pk_bf16_f32 v80, v68, v69
	v_mul_f32_e32 v69, v69, v69
	v_mul_f32_e32 v76, v79, v79
	v_fmac_f32_e32 v69, v68, v68
	v_mul_f32_e32 v68, v71, v71
	v_cvt_pk_bf16_f32 v81, v70, v71
	v_cvt_pk_bf16_f32 v82, v64, v65
	v_fmac_f32_e32 v76, v78, v78
	v_mul_f32_e32 v73, v73, v73
	v_fmac_f32_e32 v68, v70, v70
	v_mul_f32_e32 v65, v65, v65
	v_add_f32_e32 v76, v77, v76
	v_fmac_f32_e32 v73, v72, v72
	v_add_f32_e32 v68, v69, v68
	v_fmac_f32_e32 v65, v64, v64
	v_add_f32_e32 v72, v73, v76
	v_mul_f32_e32 v73, v75, v75
	v_add_f32_e32 v64, v65, v68
	v_mul_f32_e32 v65, v67, v67
	v_fmac_f32_e32 v73, v74, v74
	v_fmac_f32_e32 v65, v66, v66
	v_add_f32_e32 v72, v73, v72
	v_add_f32_e32 v64, v65, v64
	v_add_f32_e32 v64, v72, v64
	v_mov_b32_e32 v65, v64
	s_nop 1
	v_permlane16_swap_b32_e32 v64, v65
	v_add_f32_e32 v64, v64, v65
	v_mov_b32_e32 v65, v64
	v_cvt_pk_bf16_f32 v83, v66, v67
	global_store_dwordx4 v[84:85], v[80:83], off offset:-768 sc1
	s_nop 0
	v_permlane32_swap_b32_e32 v64, v65
	v_mbcnt_lo_u32_b32 v66, -1, 0
	v_mbcnt_hi_u32_b32 v66, -1, v66
	s_nop 0
	v_cmp_gt_u32_e64 s[38:39], 16, v66
	s_and_saveexec_b64 s[62:63], s[38:39]
	s_cbranch_execz .LBB0_402
	v_add_f32_e32 v68, v64, v65
	v_lshl_add_u64 v[64:65], v[96:97], 4, s[92:93]
	v_lshlrev_b32_e32 v66, 2, v149
	v_mov_b32_e32 v67, v185
	v_lshl_add_u64 v[64:65], v[64:65], 0, v[66:67]
	global_store_dword v[64:65], v68, off

;     __device__ __forceinline__ RowPre pre_row(int row, int) const { const float ss = NSLOT == 8 ? sum8(part + (size_t)row * 8) : sum4(part + (size_t)row * 4); return PreRs{rsqrtf(ss * inv_k + EPS)}; }
;     __device__ __forceinline__ void operator()(const pg8::f32x4 (&acc)[2][2][4][2], const pg8::Unit& u, int wr, int wc, int, int, int ui) const {
;     ...
;             for (int j = 0; j < NB; ++j) { const int ai = (g + j) >> 2, mm = (g + j) & 3; const int rl = ai * 128 + wr * 64 + mm * 16 + fr; int row = u.pm * 256 + rl; asm volatile("" : "+v"(row)); rows[j] = row;
;                 rv[j] = F::USE_TAB ? tab[rl] : 0.f; rp[j] = f.pre_row(row, col); }
.LBB0_404:
	s_andn2_saveexec_b64 s[38:39], s[58:59]
	s_cbranch_execz .LBB0_406
	v_ashrrev_i32_e32 v97, 31, v96
	v_cvt_pk_bf16_f32 v76, v76, v77
	v_cvt_pk_bf16_f32 v77, v78, v79
	v_cvt_pk_bf16_f32 v78, v72, v73
	v_lshlrev_b64 v[72:73], 10, v[96:97]
	v_lshl_add_u64 v[72:73], s[4:5], 0, v[72:73]
	v_lshl_add_u64 v[72:73], v[112:113], 1, v[72:73]
	v_cvt_pk_bf16_f32 v79, v74, v75
	global_store_dwordx4 v[72:73], v[76:79], off sc1
	v_cvt_pk_bf16_f32 v68, v68, v69
	v_cvt_pk_bf16_f32 v69, v70, v71
	v_cvt_pk_bf16_f32 v70, v64, v65
	v_cvt_pk_bf16_f32 v71, v66, v67
	global_store_dwordx4 v[72:73], v[68:71], off offset:256 sc1
.LBB0_406:
	s_or_b64 exec, exec, s[38:39]
	s_nop 0
	v_add_u32_e32 v68, 0x80, v152
	ds_read_b32 v70, v151 offset:512
	v_add_u32_e32 v64, 0x90, v152
	ds_read_b32 v66, v151 offset:576
	s_waitcnt lgkmcnt(0)
	v_pk_mul_f32 v[62:63], v[62:63], v[70:71] op_sel_hi:[1,0]
	v_pk_mul_f32 v[60:61], v[60:61], v[70:71] op_sel_hi:[1,0]
	v_pk_mul_f32 v[58:59], v[58:59], v[70:71] op_sel_hi:[1,0]
	v_pk_mul_f32 v[56:57], v[56:57], v[70:71] op_sel_hi:[1,0]
	v_pk_mul_f32 v[54:55], v[54:55], v[70:71] op_sel_hi:[1,0]
	v_pk_mul_f32 v[52:53], v[52:53], v[70:71] op_sel_hi:[1,0]
	v_pk_mul_f32 v[50:51], v[50:51], v[70:71] op_sel_hi:[1,0]
	v_pk_mul_f32 v[48:49], v[48:49], v[70:71] op_sel_hi:[1,0]
	s_and_saveexec_b64 s[14:15], s[36:37]
	s_xor_b64 s[58:59], exec, s[14:15]
	s_cbranch_execz .LBB0_424
	v_cmp_lt_i32_e64 s[38:39], 2, v150
	s_and_saveexec_b64 s[14:15], s[38:39]
	s_xor_b64 s[60:61], exec, s[14:15]
	s_cbranch_execz .LBB0_419
	v_cmp_ne_u32_e64 s[38:39], 3, v150
	s_and_saveexec_b64 s[14:15], s[38:39]
	s_xor_b64 s[62:63], exec, s[14:15]
	s_cbranch_execz .LBB0_414
	v_cvt_pk_bf16_f32 v70, v60, v61
	v_mul_f32_e32 v61, v61, v61
	v_fmac_f32_e32 v61, v60, v60
	v_mul_f32_e32 v60, v63, v63
	v_cvt_pk_bf16_f32 v71, v62, v63
	v_cvt_pk_bf16_f32 v72, v56, v57
	v_fmac_f32_e32 v60, v62, v62
	v_mul_f32_e32 v57, v57, v57
	v_add_f32_e32 v60, v61, v60
	v_fmac_f32_e32 v57, v56, v56
	v_add_f32_e32 v56, v57, v60
	v_mul_f32_e32 v57, v59, v59
	v_fmac_f32_e32 v57, v58, v58
	v_readlane_b32 s6, v251, 0
	v_add_f32_e32 v56, v57, v56
	v_readlane_b32 s7, v251, 1
	v_mov_b32_e32 v57, v56
	s_movk_i32 s3, 0x300
	v_mov_b64_e32 v[74:75], s[6:7]
	v_permlane16_swap_b32_e32 v56, v57
	v_mad_i64_i32 v[74:75], s[14:15], v68, s3, v[74:75]
	v_add_f32_e32 v56, v56, v57
	v_lshl_add_u64 v[74:75], v[184:185], 1, v[74:75]
	v_mov_b32_e32 v57, v56
	v_cvt_pk_bf16_f32 v73, v58, v59
	v_ashrrev_i32_e32 v69, 31, v68
	global_store_dwordx4 v[74:75], v[70:73], off offset:-1536 sc1
	v_permlane32_swap_b32_e32 v56, v57
	v_mbcnt_lo_u32_b32 v58, -1, 0
	v_mbcnt_hi_u32_b32 v58, -1, v58
	s_nop 0
	v_cmp_gt_u32_e64 s[38:39], 16, v58
	s_and_saveexec_b64 s[64:65], s[38:39]
	s_cbranch_execz .LBB0_411
	v_add_f32_e32 v60, v56, v57
	v_lshlrev_b64 v[56:57], 5, v[68:69]
	v_lshl_add_u64 v[56:57], s[96:97], 0, v[56:57]
	v_lshlrev_b32_e32 v58, 2, v149
	v_mov_b32_e32 v59, v185
	v_lshl_add_u64 v[56:57], v[56:57], 0, v[58:59]
	global_store_dword v[56:57], v60, off offset:16
.LBB0_411:
	s_or_b64 exec, exec, s[64:65]
	s_and_saveexec_b64 s[38:39], vcc
	s_cbranch_execz .LBB0_413
	v_readlane_b32 s6, v251, 36
	v_cvt_pk_bf16_f32 v52, v52, v53
	v_cvt_pk_bf16_f32 v53, v54, v55
	v_cvt_pk_bf16_f32 v54, v48, v49
	v_lshlrev_b64 v[48:49], 6, v[68:69]
	v_readlane_b32 s7, v251, 37
	v_cvt_pk_bf16_f32 v55, v50, v51
	s_nop 1
	v_lshl_add_u64 v[48:49], s[6:7], 0, v[48:49]
	v_lshl_add_u64 v[48:49], v[184:185], 1, v[48:49]
	global_store_dwordx4 v[48:49], v[52:55], off offset:-2048 sc1

; __device__ __forceinline__ int lane_id_asm() { int l; asm volatile("v_mbcnt_lo_u32_b32 %0, -1, 0\n\tv_mbcnt_hi_u32_b32 %0, -1, %0" : "=v"(l)); return l; }
; __device__ __forceinline__ void row_part_store(float s, float* dst) {
;     { const auto r_ = __builtin_amdgcn_permlane16_swap(__float_as_uint(s), __float_as_uint(s), false, false); s = __uint_as_float(r_[0]) + __uint_as_float(r_[1]); }
;     { const auto r_ = __builtin_amdgcn_permlane32_swap(__float_as_uint(s), __float_as_uint(s), false, false); s = __uint_as_float(r_[0]) + __uint_as_float(r_[1]); }
;     if ((lane_id_asm() >> 4) == 0) *dst = s;
.LBB0_414:
	s_andn2_saveexec_b64 s[62:63], s[62:63]
	s_cbranch_execz .LBB0_418
	v_readlane_b32 s6, v251, 0
	v_readlane_b32 s7, v251, 1
	s_movk_i32 s3, 0x300
	s_nop 0
	v_mov_b64_e32 v[70:71], s[6:7]
	v_mad_i64_i32 v[70:71], s[14:15], v68, s3, v[70:71]
	v_lshl_add_u64 v[74:75], v[184:185], 1, v[70:71]
	v_cvt_pk_bf16_f32 v70, v60, v61
	v_cvt_pk_bf16_f32 v71, v62, v63
	v_cvt_pk_bf16_f32 v72, v56, v57
	v_cvt_pk_bf16_f32 v73, v58, v59
	global_store_dwordx4 v[74:75], v[70:73], off offset:-1536 sc1
	v_mul_f32_e32 v61, v61, v61
	v_fmac_f32_e32 v61, v60, v60
	v_cvt_pk_bf16_f32 v70, v52, v53
	v_mul_f32_e32 v53, v53, v53
	v_mul_f32_e32 v60, v63, v63
	v_fmac_f32_e32 v53, v52, v52
	v_mul_f32_e32 v52, v55, v55
	v_cvt_pk_bf16_f32 v71, v54, v55
	v_cvt_pk_bf16_f32 v72, v48, v49
	v_fmac_f32_e32 v60, v62, v62
	v_mul_f32_e32 v57, v57, v57
	v_fmac_f32_e32 v52, v54, v54
	v_mul_f32_e32 v49, v49, v49
	v_add_f32_e32 v60, v61, v60
	v_fmac_f32_e32 v57, v56, v56
	v_add_f32_e32 v52, v53, v52
	v_fmac_f32_e32 v49, v48, v48
	v_add_f32_e32 v56, v57, v60
	v_mul_f32_e32 v57, v59, v59
	v_add_f32_e32 v48, v49, v52
	v_mul_f32_e32 v49, v51, v51
	v_fmac_f32_e32 v57, v58, v58
	v_fmac_f32_e32 v49, v50, v50
	v_add_f32_e32 v56, v57, v56
	v_add_f32_e32 v48, v49, v48
	v_add_f32_e32 v48, v56, v48
	v_mov_b32_e32 v49, v48
	s_nop 1
	v_permlane16_swap_b32_e32 v48, v49
	v_add_f32_e32 v48, v48, v49
	v_mov_b32_e32 v49, v48
	v_cvt_pk_bf16_f32 v73, v50, v51
	global_store_dwordx4 v[74:75], v[70:73], off offset:-1280 sc1
	s_nop 0
	v_permlane32_swap_b32_e32 v48, v49
	v_mbcnt_lo_u32_b32 v50, -1, 0
	v_mbcnt_hi_u32_b32 v50, -1, v50
	s_nop 0
	v_cmp_gt_u32_e64 s[38:39], 16, v50
	s_and_saveexec_b64 s[64:65], s[38:39]
	s_cbranch_execz .LBB0_417
	v_ashrrev_i32_e32 v69, 31, v68
	v_add_f32_e32 v52, v48, v49
	v_lshlrev_b64 v[48:49], 5, v[68:69]
	v_lshl_add_u64 v[48:49], s[96:97], 0, v[48:49]
	v_lshlrev_b32_e32 v50, 2, v149
	v_mov_b32_e32 v51, v185
	v_lshl_add_u64 v[48:49], v[48:49], 0, v[50:51]
	global_store_dword v[48:49], v52, off

; __device__ __forceinline__ int lane_id_asm() { int l; asm volatile("v_mbcnt_lo_u32_b32 %0, -1, 0\n\tv_mbcnt_hi_u32_b32 %0, -1, %0" : "=v"(l)); return l; }
; __device__ __forceinline__ void row_part_store(float s, float* dst) {
;     { const auto r_ = __builtin_amdgcn_permlane16_swap(__float_as_uint(s), __float_as_uint(s), false, false); s = __uint_as_float(r_[0]) + __uint_as_float(r_[1]); }
;     { const auto r_ = __builtin_amdgcn_permlane32_swap(__float_as_uint(s), __float_as_uint(s), false, false); s = __uint_as_float(r_[0]) + __uint_as_float(r_[1]); }
;     if ((lane_id_asm() >> 4) == 0) *dst = s;
.LBB0_419:
	s_andn2_saveexec_b64 s[60:61], s[60:61]
	s_cbranch_execz .LBB0_423
	v_ashrrev_i32_e32 v69, 31, v68
	v_readlane_b32 s6, v255, 30
	v_lshlrev_b64 v[70:71], 9, v[68:69]
	v_readlane_b32 s7, v255, 31
	s_nop 1
	v_lshl_add_u64 v[70:71], s[6:7], 0, v[70:71]
	v_lshl_add_u64 v[74:75], v[184:185], 1, v[70:71]
	v_cvt_pk_bf16_f32 v70, v60, v61
	v_cvt_pk_bf16_f32 v71, v62, v63
	v_cvt_pk_bf16_f32 v72, v56, v57
	v_cvt_pk_bf16_f32 v73, v58, v59
	global_store_dwordx4 v[74:75], v[70:73], off offset:-1024 sc1
	v_mul_f32_e32 v61, v61, v61
	v_fmac_f32_e32 v61, v60, v60
	v_cvt_pk_bf16_f32 v70, v52, v53
	v_mul_f32_e32 v53, v53, v53
	v_mul_f32_e32 v60, v63, v63
	v_fmac_f32_e32 v53, v52, v52
	v_mul_f32_e32 v52, v55, v55
	v_cvt_pk_bf16_f32 v71, v54, v55
	v_cvt_pk_bf16_f32 v72, v48, v49
	v_fmac_f32_e32 v60, v62, v62
	v_mul_f32_e32 v57, v57, v57
	v_fmac_f32_e32 v52, v54, v54
	v_mul_f32_e32 v49, v49, v49
	v_add_f32_e32 v60, v61, v60
	v_fmac_f32_e32 v57, v56, v56
	v_add_f32_e32 v52, v53, v52
	v_fmac_f32_e32 v49, v48, v48
	v_add_f32_e32 v56, v57, v60
	v_mul_f32_e32 v57, v59, v59
	v_add_f32_e32 v48, v49, v52
	v_mul_f32_e32 v49, v51, v51
	v_fmac_f32_e32 v57, v58, v58
	v_fmac_f32_e32 v49, v50, v50
	v_add_f32_e32 v56, v57, v56
	v_add_f32_e32 v48, v49, v48
	v_add_f32_e32 v48, v56, v48
	v_mov_b32_e32 v49, v48
	s_nop 1
	v_permlane16_swap_b32_e32 v48, v49
	v_add_f32_e32 v48, v48, v49
	v_mov_b32_e32 v49, v48
	v_cvt_pk_bf16_f32 v73, v50, v51
	global_store_dwordx4 v[74:75], v[70:73], off offset:-768 sc1
	s_nop 0
	v_permlane32_swap_b32_e32 v48, v49
	v_mbcnt_lo_u32_b32 v50, -1, 0
	v_mbcnt_hi_u32_b32 v50, -1, v50
	s_nop 0
	v_cmp_gt_u32_e64 s[38:39], 16, v50
	s_and_saveexec_b64 s[62:63], s[38:39]
	s_cbranch_execz .LBB0_422
	v_add_f32_e32 v52, v48, v49
	v_lshl_add_u64 v[48:49], v[68:69], 4, s[92:93]
	v_lshlrev_b32_e32 v50, 2, v149
	v_mov_b32_e32 v51, v185
	v_lshl_add_u64 v[48:49], v[48:49], 0, v[50:51]
	global_store_dword v[48:49], v52, off

.LBB0_424:
	s_andn2_saveexec_b64 s[38:39], s[58:59]
	s_cbranch_execz .LBB0_426
	v_ashrrev_i32_e32 v69, 31, v68
	v_cvt_pk_bf16_f32 v60, v60, v61
	v_cvt_pk_bf16_f32 v61, v62, v63
	v_cvt_pk_bf16_f32 v62, v56, v57
	v_lshlrev_b64 v[56:57], 10, v[68:69]
	v_lshl_add_u64 v[56:57], s[4:5], 0, v[56:57]
	v_lshl_add_u64 v[56:57], v[112:113], 1, v[56:57]
	v_cvt_pk_bf16_f32 v63, v58, v59
	global_store_dwordx4 v[56:57], v[60:63], off sc1
	v_cvt_pk_bf16_f32 v52, v52, v53
	v_cvt_pk_bf16_f32 v53, v54, v55
	v_cvt_pk_bf16_f32 v54, v48, v49
	v_cvt_pk_bf16_f32 v55, v50, v51
	global_store_dwordx4 v[56:57], v[52:55], off offset:256 sc1
.LBB0_426:
	s_or_b64 exec, exec, s[38:39]
	v_pk_mul_f32 v[46:47], v[46:47], v[66:67] op_sel_hi:[1,0]
	v_pk_mul_f32 v[44:45], v[44:45], v[66:67] op_sel_hi:[1,0]
	v_pk_mul_f32 v[42:43], v[42:43], v[66:67] op_sel_hi:[1,0]
	v_pk_mul_f32 v[40:41], v[40:41], v[66:67] op_sel_hi:[1,0]
	v_pk_mul_f32 v[38:39], v[38:39], v[66:67] op_sel_hi:[1,0]
	v_pk_mul_f32 v[36:37], v[36:37], v[66:67] op_sel_hi:[1,0]
	v_pk_mul_f32 v[34:35], v[34:35], v[66:67] op_sel_hi:[1,0]
	v_pk_mul_f32 v[32:33], v[32:33], v[66:67] op_sel_hi:[1,0]
	s_and_saveexec_b64 s[14:15], s[36:37]
	s_xor_b64 s[58:59], exec, s[14:15]
	s_cbranch_execz .LBB0_444
	v_cmp_lt_i32_e64 s[38:39], 2, v150
	s_and_saveexec_b64 s[14:15], s[38:39]
	s_xor_b64 s[60:61], exec, s[14:15]
	s_cbranch_execz .LBB0_439
	v_cmp_ne_u32_e64 s[38:39], 3, v150
	s_and_saveexec_b64 s[14:15], s[38:39]
	s_xor_b64 s[62:63], exec, s[14:15]
	s_cbranch_execz .LBB0_434
	v_cvt_pk_bf16_f32 v48, v44, v45
	v_mul_f32_e32 v45, v45, v45
	v_fmac_f32_e32 v45, v44, v44
	v_mul_f32_e32 v44, v47, v47
	v_cvt_pk_bf16_f32 v49, v46, v47
	v_cvt_pk_bf16_f32 v50, v40, v41
	v_fmac_f32_e32 v44, v46, v46
	v_mul_f32_e32 v41, v41, v41
	v_add_f32_e32 v44, v45, v44
	v_fmac_f32_e32 v41, v40, v40
	v_add_f32_e32 v40, v41, v44
	v_mul_f32_e32 v41, v43, v43
	v_fmac_f32_e32 v41, v42, v42
	v_readlane_b32 s6, v251, 0
	v_add_f32_e32 v40, v41, v40
	v_readlane_b32 s7, v251, 1
	v_mov_b32_e32 v41, v40
	s_movk_i32 s3, 0x300
	v_mov_b64_e32 v[52:53], s[6:7]
	v_permlane16_swap_b32_e32 v40, v41
	v_mad_i64_i32 v[52:53], s[14:15], v64, s3, v[52:53]
	v_add_f32_e32 v40, v40, v41
	v_lshl_add_u64 v[52:53], v[184:185], 1, v[52:53]
	v_mov_b32_e32 v41, v40
	v_cvt_pk_bf16_f32 v51, v42, v43
	v_ashrrev_i32_e32 v65, 31, v64
	global_store_dwordx4 v[52:53], v[48:51], off offset:-1536 sc1
	v_permlane32_swap_b32_e32 v40, v41
	v_mbcnt_lo_u32_b32 v42, -1, 0
	v_mbcnt_hi_u32_b32 v42, -1, v42
	s_nop 0
	v_cmp_gt_u32_e64 s[38:39], 16, v42
	s_and_saveexec_b64 s[64:65], s[38:39]
	s_cbranch_execz .LBB0_431
	v_add_f32_e32 v44, v40, v41
	v_lshlrev_b64 v[40:41], 5, v[64:65]
	v_lshl_add_u64 v[40:41], s[96:97], 0, v[40:41]
	v_lshlrev_b32_e32 v42, 2, v149
	v_mov_b32_e32 v43, v185
	v_lshl_add_u64 v[40:41], v[40:41], 0, v[42:43]
	global_store_dword v[40:41], v44, off offset:16
.LBB0_431:
	s_or_b64 exec, exec, s[64:65]
	s_and_saveexec_b64 s[38:39], vcc
	s_cbranch_execz .LBB0_433
	v_readlane_b32 s6, v251, 36
	v_cvt_pk_bf16_f32 v36, v36, v37
	v_cvt_pk_bf16_f32 v37, v38, v39
	v_cvt_pk_bf16_f32 v38, v32, v33
	v_lshlrev_b64 v[32:33], 6, v[64:65]
	v_readlane_b32 s7, v251, 37
	v_cvt_pk_bf16_f32 v39, v34, v35
	s_nop 1
	v_lshl_add_u64 v[32:33], s[6:7], 0, v[32:33]
	v_lshl_add_u64 v[32:33], v[184:185], 1, v[32:33]
	global_store_dwordx4 v[32:33], v[36:39], off offset:-2048 sc1

; __device__ __forceinline__ int lane_id_asm() { int l; asm volatile("v_mbcnt_lo_u32_b32 %0, -1, 0\n\tv_mbcnt_hi_u32_b32 %0, -1, %0" : "=v"(l)); return l; }
; __device__ __forceinline__ void row_part_store(float s, float* dst) {
;     { const auto r_ = __builtin_amdgcn_permlane16_swap(__float_as_uint(s), __float_as_uint(s), false, false); s = __uint_as_float(r_[0]) + __uint_as_float(r_[1]); }
;     { const auto r_ = __builtin_amdgcn_permlane32_swap(__float_as_uint(s), __float_as_uint(s), false, false); s = __uint_as_float(r_[0]) + __uint_as_float(r_[1]); }
;     if ((lane_id_asm() >> 4) == 0) *dst = s;
.LBB0_434:
	s_andn2_saveexec_b64 s[62:63], s[62:63]
	s_cbranch_execz .LBB0_438
	v_readlane_b32 s6, v251, 0
	v_readlane_b32 s7, v251, 1
	s_movk_i32 s3, 0x300
	s_nop 0
	v_mov_b64_e32 v[48:49], s[6:7]
	v_mad_i64_i32 v[48:49], s[14:15], v64, s3, v[48:49]
	v_lshl_add_u64 v[52:53], v[184:185], 1, v[48:49]
	v_cvt_pk_bf16_f32 v48, v44, v45
	v_cvt_pk_bf16_f32 v49, v46, v47
	v_cvt_pk_bf16_f32 v50, v40, v41
	v_cvt_pk_bf16_f32 v51, v42, v43
	global_store_dwordx4 v[52:53], v[48:51], off offset:-1536 sc1
	v_mul_f32_e32 v45, v45, v45
	v_fmac_f32_e32 v45, v44, v44
	v_cvt_pk_bf16_f32 v48, v36, v37
	v_mul_f32_e32 v37, v37, v37
	v_mul_f32_e32 v44, v47, v47
	v_fmac_f32_e32 v37, v36, v36
	v_mul_f32_e32 v36, v39, v39
	v_cvt_pk_bf16_f32 v49, v38, v39
	v_cvt_pk_bf16_f32 v50, v32, v33
	v_fmac_f32_e32 v44, v46, v46
	v_mul_f32_e32 v41, v41, v41
	v_fmac_f32_e32 v36, v38, v38
	v_mul_f32_e32 v33, v33, v33
	v_add_f32_e32 v44, v45, v44
	v_fmac_f32_e32 v41, v40, v40
	v_add_f32_e32 v36, v37, v36
	v_fmac_f32_e32 v33, v32, v32
	v_add_f32_e32 v40, v41, v44
	v_mul_f32_e32 v41, v43, v43
	v_add_f32_e32 v32, v33, v36
	v_mul_f32_e32 v33, v35, v35
	v_fmac_f32_e32 v41, v42, v42
	v_fmac_f32_e32 v33, v34, v34
	v_add_f32_e32 v40, v41, v40
	v_add_f32_e32 v32, v33, v32
	v_add_f32_e32 v32, v40, v32
	v_mov_b32_e32 v33, v32
	s_nop 1
	v_permlane16_swap_b32_e32 v32, v33
	v_add_f32_e32 v32, v32, v33
	v_mov_b32_e32 v33, v32
	v_cvt_pk_bf16_f32 v51, v34, v35
	global_store_dwordx4 v[52:53], v[48:51], off offset:-1280 sc1
	s_nop 0
	v_permlane32_swap_b32_e32 v32, v33
	v_mbcnt_lo_u32_b32 v34, -1, 0
	v_mbcnt_hi_u32_b32 v34, -1, v34
	s_nop 0
	v_cmp_gt_u32_e64 s[38:39], 16, v34
	s_and_saveexec_b64 s[64:65], s[38:39]
	s_cbranch_execz .LBB0_437
	v_ashrrev_i32_e32 v65, 31, v64
	v_add_f32_e32 v36, v32, v33
	v_lshlrev_b64 v[32:33], 5, v[64:65]
	v_lshl_add_u64 v[32:33], s[96:97], 0, v[32:33]
	v_lshlrev_b32_e32 v34, 2, v149
	v_mov_b32_e32 v35, v185
	v_lshl_add_u64 v[32:33], v[32:33], 0, v[34:35]
	global_store_dword v[32:33], v36, off

; __device__ __forceinline__ int lane_id_asm() { int l; asm volatile("v_mbcnt_lo_u32_b32 %0, -1, 0\n\tv_mbcnt_hi_u32_b32 %0, -1, %0" : "=v"(l)); return l; }
; __device__ __forceinline__ void row_part_store(float s, float* dst) {
;     { const auto r_ = __builtin_amdgcn_permlane16_swap(__float_as_uint(s), __float_as_uint(s), false, false); s = __uint_as_float(r_[0]) + __uint_as_float(r_[1]); }
;     { const auto r_ = __builtin_amdgcn_permlane32_swap(__float_as_uint(s), __float_as_uint(s), false, false); s = __uint_as_float(r_[0]) + __uint_as_float(r_[1]); }
;     if ((lane_id_asm() >> 4) == 0) *dst = s;
.LBB0_439:
	s_andn2_saveexec_b64 s[60:61], s[60:61]
	s_cbranch_execz .LBB0_443
	v_ashrrev_i32_e32 v65, 31, v64
	v_readlane_b32 s6, v255, 30
	v_lshlrev_b64 v[48:49], 9, v[64:65]
	v_readlane_b32 s7, v255, 31
	s_nop 1
	v_lshl_add_u64 v[48:49], s[6:7], 0, v[48:49]
	v_lshl_add_u64 v[52:53], v[184:185], 1, v[48:49]
	v_cvt_pk_bf16_f32 v48, v44, v45
	v_cvt_pk_bf16_f32 v49, v46, v47
	v_cvt_pk_bf16_f32 v50, v40, v41
	v_cvt_pk_bf16_f32 v51, v42, v43
	global_store_dwordx4 v[52:53], v[48:51], off offset:-1024 sc1
	v_mul_f32_e32 v45, v45, v45
	v_fmac_f32_e32 v45, v44, v44
	v_cvt_pk_bf16_f32 v48, v36, v37
	v_mul_f32_e32 v37, v37, v37
	v_mul_f32_e32 v44, v47, v47
	v_fmac_f32_e32 v37, v36, v36
	v_mul_f32_e32 v36, v39, v39
	v_cvt_pk_bf16_f32 v49, v38, v39
	v_cvt_pk_bf16_f32 v50, v32, v33
	v_fmac_f32_e32 v44, v46, v46
	v_mul_f32_e32 v41, v41, v41
	v_fmac_f32_e32 v36, v38, v38
	v_mul_f32_e32 v33, v33, v33
	v_add_f32_e32 v44, v45, v44
	v_fmac_f32_e32 v41, v40, v40
	v_add_f32_e32 v36, v37, v36
	v_fmac_f32_e32 v33, v32, v32
	v_add_f32_e32 v40, v41, v44
	v_mul_f32_e32 v41, v43, v43
	v_add_f32_e32 v32, v33, v36
	v_mul_f32_e32 v33, v35, v35
	v_fmac_f32_e32 v41, v42, v42
	v_fmac_f32_e32 v33, v34, v34
	v_add_f32_e32 v40, v41, v40
	v_add_f32_e32 v32, v33, v32
	v_add_f32_e32 v32, v40, v32
	v_mov_b32_e32 v33, v32
	s_nop 1
	v_permlane16_swap_b32_e32 v32, v33
	v_add_f32_e32 v32, v32, v33
	v_mov_b32_e32 v33, v32
	v_cvt_pk_bf16_f32 v51, v34, v35
	global_store_dwordx4 v[52:53], v[48:51], off offset:-768 sc1
	s_nop 0
	v_permlane32_swap_b32_e32 v32, v33
	v_mbcnt_lo_u32_b32 v34, -1, 0
	v_mbcnt_hi_u32_b32 v34, -1, v34
	s_nop 0
	v_cmp_gt_u32_e64 s[38:39], 16, v34
	s_and_saveexec_b64 s[62:63], s[38:39]
	s_cbranch_execz .LBB0_442
	v_add_f32_e32 v36, v32, v33
	v_lshl_add_u64 v[32:33], v[64:65], 4, s[92:93]
	v_lshlrev_b32_e32 v34, 2, v149
	v_mov_b32_e32 v35, v185
	v_lshl_add_u64 v[32:33], v[32:33], 0, v[34:35]
	global_store_dword v[32:33], v36, off

;     __device__ __forceinline__ RowPre pre_row(int row, int) const { const float ss = NSLOT == 8 ? sum8(part + (size_t)row * 8) : sum4(part + (size_t)row * 4); return PreRs{rsqrtf(ss * inv_k + EPS)}; }
;     __device__ __forceinline__ void operator()(const pg8::f32x4 (&acc)[2][2][4][2], const pg8::Unit& u, int wr, int wc, int, int, int ui) const {
;     ...
;             for (int j = 0; j < NB; ++j) { const int ai = (g + j) >> 2, mm = (g + j) & 3; const int rl = ai * 128 + wr * 64 + mm * 16 + fr; int row = u.pm * 256 + rl; asm volatile("" : "+v"(row)); rows[j] = row;
;                 rv[j] = F::USE_TAB ? tab[rl] : 0.f; rp[j] = f.pre_row(row, col); }
.LBB0_444:
	s_andn2_saveexec_b64 s[38:39], s[58:59]
	s_cbranch_execz .LBB0_446
	v_ashrrev_i32_e32 v65, 31, v64
	v_cvt_pk_bf16_f32 v44, v44, v45
	v_cvt_pk_bf16_f32 v45, v46, v47
	v_cvt_pk_bf16_f32 v46, v40, v41
	v_lshlrev_b64 v[40:41], 10, v[64:65]
	v_lshl_add_u64 v[40:41], s[4:5], 0, v[40:41]
	v_lshl_add_u64 v[40:41], v[112:113], 1, v[40:41]
	v_cvt_pk_bf16_f32 v47, v42, v43
	global_store_dwordx4 v[40:41], v[44:47], off sc1
	v_cvt_pk_bf16_f32 v36, v36, v37
	v_cvt_pk_bf16_f32 v37, v38, v39
	v_cvt_pk_bf16_f32 v38, v32, v33
	v_cvt_pk_bf16_f32 v39, v34, v35
	global_store_dwordx4 v[40:41], v[36:39], off offset:256 sc1
.LBB0_446:
	s_or_b64 exec, exec, s[38:39]
	s_nop 0
	v_add_u32_e32 v36, 0xa0, v152
	ds_read_b32 v38, v151 offset:640
	v_add_u32_e32 v32, 0xb0, v152
	ds_read_b32 v34, v151 offset:704
	s_waitcnt lgkmcnt(0)
	v_pk_mul_f32 v[30:31], v[30:31], v[38:39] op_sel_hi:[1,0]
	v_pk_mul_f32 v[28:29], v[28:29], v[38:39] op_sel_hi:[1,0]
	v_pk_mul_f32 v[26:27], v[26:27], v[38:39] op_sel_hi:[1,0]
	v_pk_mul_f32 v[24:25], v[24:25], v[38:39] op_sel_hi:[1,0]
	v_pk_mul_f32 v[22:23], v[22:23], v[38:39] op_sel_hi:[1,0]
	v_pk_mul_f32 v[20:21], v[20:21], v[38:39] op_sel_hi:[1,0]
	v_pk_mul_f32 v[18:19], v[18:19], v[38:39] op_sel_hi:[1,0]
	v_pk_mul_f32 v[16:17], v[16:17], v[38:39] op_sel_hi:[1,0]
	s_and_saveexec_b64 s[14:15], s[36:37]
	s_xor_b64 s[58:59], exec, s[14:15]
	s_cbranch_execz .LBB0_464
	v_cmp_lt_i32_e64 s[38:39], 2, v150
	s_and_saveexec_b64 s[14:15], s[38:39]
	s_xor_b64 s[60:61], exec, s[14:15]
	s_cbranch_execz .LBB0_459
	v_cmp_ne_u32_e64 s[38:39], 3, v150
	s_and_saveexec_b64 s[14:15], s[38:39]
	s_xor_b64 s[62:63], exec, s[14:15]
	s_cbranch_execz .LBB0_454
	v_cvt_pk_bf16_f32 v38, v28, v29
	v_mul_f32_e32 v29, v29, v29
	v_fmac_f32_e32 v29, v28, v28
	v_mul_f32_e32 v28, v31, v31
	v_cvt_pk_bf16_f32 v39, v30, v31
	v_cvt_pk_bf16_f32 v40, v24, v25
	v_fmac_f32_e32 v28, v30, v30
	v_mul_f32_e32 v25, v25, v25
	v_add_f32_e32 v28, v29, v28
	v_fmac_f32_e32 v25, v24, v24
	v_add_f32_e32 v24, v25, v28
	v_mul_f32_e32 v25, v27, v27
	v_fmac_f32_e32 v25, v26, v26
	v_readlane_b32 s6, v251, 0
	v_add_f32_e32 v24, v25, v24
	v_readlane_b32 s7, v251, 1
	v_mov_b32_e32 v25, v24
	s_movk_i32 s3, 0x300
	v_mov_b64_e32 v[42:43], s[6:7]
	v_permlane16_swap_b32_e32 v24, v25
	v_mad_i64_i32 v[42:43], s[14:15], v36, s3, v[42:43]
	v_add_f32_e32 v24, v24, v25
	v_lshl_add_u64 v[42:43], v[184:185], 1, v[42:43]
	v_mov_b32_e32 v25, v24
	v_cvt_pk_bf16_f32 v41, v26, v27
	v_ashrrev_i32_e32 v37, 31, v36
	global_store_dwordx4 v[42:43], v[38:41], off offset:-1536 sc1
	v_permlane32_swap_b32_e32 v24, v25
	v_mbcnt_lo_u32_b32 v26, -1, 0
	v_mbcnt_hi_u32_b32 v26, -1, v26
	s_nop 0
	v_cmp_gt_u32_e64 s[38:39], 16, v26
	s_and_saveexec_b64 s[64:65], s[38:39]
	s_cbranch_execz .LBB0_451
	v_add_f32_e32 v28, v24, v25
	v_lshlrev_b64 v[24:25], 5, v[36:37]
	v_lshl_add_u64 v[24:25], s[96:97], 0, v[24:25]
	v_lshlrev_b32_e32 v26, 2, v149
	v_mov_b32_e32 v27, v185
	v_lshl_add_u64 v[24:25], v[24:25], 0, v[26:27]
	global_store_dword v[24:25], v28, off offset:16
.LBB0_451:
	s_or_b64 exec, exec, s[64:65]
	s_and_saveexec_b64 s[38:39], vcc
	s_cbranch_execz .LBB0_453
	v_readlane_b32 s6, v251, 36
	v_cvt_pk_bf16_f32 v20, v20, v21
	v_cvt_pk_bf16_f32 v21, v22, v23
	v_cvt_pk_bf16_f32 v22, v16, v17
	v_lshlrev_b64 v[16:17], 6, v[36:37]
	v_readlane_b32 s7, v251, 37
	v_cvt_pk_bf16_f32 v23, v18, v19
	s_nop 1
	v_lshl_add_u64 v[16:17], s[6:7], 0, v[16:17]
	v_lshl_add_u64 v[16:17], v[184:185], 1, v[16:17]
	global_store_dwordx4 v[16:17], v[20:23], off offset:-2048 sc1

; __device__ __forceinline__ int lane_id_asm() { int l; asm volatile("v_mbcnt_lo_u32_b32 %0, -1, 0\n\tv_mbcnt_hi_u32_b32 %0, -1, %0" : "=v"(l)); return l; }
; __device__ __forceinline__ void row_part_store(float s, float* dst) {
;     { const auto r_ = __builtin_amdgcn_permlane16_swap(__float_as_uint(s), __float_as_uint(s), false, false); s = __uint_as_float(r_[0]) + __uint_as_float(r_[1]); }
;     { const auto r_ = __builtin_amdgcn_permlane32_swap(__float_as_uint(s), __float_as_uint(s), false, false); s = __uint_as_float(r_[0]) + __uint_as_float(r_[1]); }
;     if ((lane_id_asm() >> 4) == 0) *dst = s;
.LBB0_454:
	s_andn2_saveexec_b64 s[62:63], s[62:63]
	s_cbranch_execz .LBB0_458
	v_readlane_b32 s6, v251, 0
	v_readlane_b32 s7, v251, 1
	s_movk_i32 s3, 0x300
	s_nop 0
	v_mov_b64_e32 v[38:39], s[6:7]
	v_mad_i64_i32 v[38:39], s[14:15], v36, s3, v[38:39]
	v_lshl_add_u64 v[42:43], v[184:185], 1, v[38:39]
	v_cvt_pk_bf16_f32 v38, v28, v29
	v_cvt_pk_bf16_f32 v39, v30, v31
	v_cvt_pk_bf16_f32 v40, v24, v25
	v_cvt_pk_bf16_f32 v41, v26, v27
	global_store_dwordx4 v[42:43], v[38:41], off offset:-1536 sc1
	v_mul_f32_e32 v29, v29, v29
	v_fmac_f32_e32 v29, v28, v28
	v_cvt_pk_bf16_f32 v38, v20, v21
	v_mul_f32_e32 v21, v21, v21
	v_mul_f32_e32 v28, v31, v31
	v_fmac_f32_e32 v21, v20, v20
	v_mul_f32_e32 v20, v23, v23
	v_cvt_pk_bf16_f32 v39, v22, v23
	v_cvt_pk_bf16_f32 v40, v16, v17
	v_fmac_f32_e32 v28, v30, v30
	v_mul_f32_e32 v25, v25, v25
	v_fmac_f32_e32 v20, v22, v22
	v_mul_f32_e32 v17, v17, v17
	v_add_f32_e32 v28, v29, v28
	v_fmac_f32_e32 v25, v24, v24
	v_add_f32_e32 v20, v21, v20
	v_fmac_f32_e32 v17, v16, v16
	v_add_f32_e32 v24, v25, v28
	v_mul_f32_e32 v25, v27, v27
	v_add_f32_e32 v16, v17, v20
	v_mul_f32_e32 v17, v19, v19
	v_fmac_f32_e32 v25, v26, v26
	v_fmac_f32_e32 v17, v18, v18
	v_add_f32_e32 v24, v25, v24
	v_add_f32_e32 v16, v17, v16
	v_add_f32_e32 v16, v24, v16
	v_mov_b32_e32 v17, v16
	s_nop 1
	v_permlane16_swap_b32_e32 v16, v17
	v_add_f32_e32 v16, v16, v17
	v_mov_b32_e32 v17, v16
	v_cvt_pk_bf16_f32 v41, v18, v19
	global_store_dwordx4 v[42:43], v[38:41], off offset:-1280 sc1
	s_nop 0
	v_permlane32_swap_b32_e32 v16, v17
	v_mbcnt_lo_u32_b32 v18, -1, 0
	v_mbcnt_hi_u32_b32 v18, -1, v18
	s_nop 0
	v_cmp_gt_u32_e64 s[38:39], 16, v18
	s_and_saveexec_b64 s[64:65], s[38:39]
	s_cbranch_execz .LBB0_457
	v_ashrrev_i32_e32 v37, 31, v36
	v_add_f32_e32 v20, v16, v17
	v_lshlrev_b64 v[16:17], 5, v[36:37]
	v_lshl_add_u64 v[16:17], s[96:97], 0, v[16:17]
	v_lshlrev_b32_e32 v18, 2, v149
	v_mov_b32_e32 v19, v185
	v_lshl_add_u64 v[16:17], v[16:17], 0, v[18:19]
	global_store_dword v[16:17], v20, off

; __device__ __forceinline__ int lane_id_asm() { int l; asm volatile("v_mbcnt_lo_u32_b32 %0, -1, 0\n\tv_mbcnt_hi_u32_b32 %0, -1, %0" : "=v"(l)); return l; }
; __device__ __forceinline__ void row_part_store(float s, float* dst) {
;     { const auto r_ = __builtin_amdgcn_permlane16_swap(__float_as_uint(s), __float_as_uint(s), false, false); s = __uint_as_float(r_[0]) + __uint_as_float(r_[1]); }
;     { const auto r_ = __builtin_amdgcn_permlane32_swap(__float_as_uint(s), __float_as_uint(s), false, false); s = __uint_as_float(r_[0]) + __uint_as_float(r_[1]); }
;     if ((lane_id_asm() >> 4) == 0) *dst = s;
.LBB0_459:
	s_andn2_saveexec_b64 s[60:61], s[60:61]
	s_cbranch_execz .LBB0_463
	v_ashrrev_i32_e32 v37, 31, v36
	v_readlane_b32 s6, v255, 30
	v_lshlrev_b64 v[38:39], 9, v[36:37]
	v_readlane_b32 s7, v255, 31
	s_nop 1
	v_lshl_add_u64 v[38:39], s[6:7], 0, v[38:39]
	v_lshl_add_u64 v[42:43], v[184:185], 1, v[38:39]
	v_cvt_pk_bf16_f32 v38, v28, v29
	v_cvt_pk_bf16_f32 v39, v30, v31
	v_cvt_pk_bf16_f32 v40, v24, v25
	v_cvt_pk_bf16_f32 v41, v26, v27
	global_store_dwordx4 v[42:43], v[38:41], off offset:-1024 sc1
	v_mul_f32_e32 v29, v29, v29
	v_fmac_f32_e32 v29, v28, v28
	v_cvt_pk_bf16_f32 v38, v20, v21
	v_mul_f32_e32 v21, v21, v21
	v_mul_f32_e32 v28, v31, v31
	v_fmac_f32_e32 v21, v20, v20
	v_mul_f32_e32 v20, v23, v23
	v_cvt_pk_bf16_f32 v39, v22, v23
	v_cvt_pk_bf16_f32 v40, v16, v17
	v_fmac_f32_e32 v28, v30, v30
	v_mul_f32_e32 v25, v25, v25
	v_fmac_f32_e32 v20, v22, v22
	v_mul_f32_e32 v17, v17, v17
	v_add_f32_e32 v28, v29, v28
	v_fmac_f32_e32 v25, v24, v24
	v_add_f32_e32 v20, v21, v20
	v_fmac_f32_e32 v17, v16, v16
	v_add_f32_e32 v24, v25, v28
	v_mul_f32_e32 v25, v27, v27
	v_add_f32_e32 v16, v17, v20
	v_mul_f32_e32 v17, v19, v19
	v_fmac_f32_e32 v25, v26, v26
	v_fmac_f32_e32 v17, v18, v18
	v_add_f32_e32 v24, v25, v24
	v_add_f32_e32 v16, v17, v16
	v_add_f32_e32 v16, v24, v16
	v_mov_b32_e32 v17, v16
	s_nop 1
	v_permlane16_swap_b32_e32 v16, v17
	v_add_f32_e32 v16, v16, v17
	v_mov_b32_e32 v17, v16
	v_cvt_pk_bf16_f32 v41, v18, v19
	global_store_dwordx4 v[42:43], v[38:41], off offset:-768 sc1
	s_nop 0
	v_permlane32_swap_b32_e32 v16, v17
	v_mbcnt_lo_u32_b32 v18, -1, 0
	v_mbcnt_hi_u32_b32 v18, -1, v18
	s_nop 0
	v_cmp_gt_u32_e64 s[38:39], 16, v18
	s_and_saveexec_b64 s[62:63], s[38:39]
	s_cbranch_execz .LBB0_462
	v_add_f32_e32 v20, v16, v17
	v_lshl_add_u64 v[16:17], v[36:37], 4, s[92:93]
	v_lshlrev_b32_e32 v18, 2, v149
	v_mov_b32_e32 v19, v185
	v_lshl_add_u64 v[16:17], v[16:17], 0, v[18:19]
	global_store_dword v[16:17], v20, off

.LBB0_464:
	s_andn2_saveexec_b64 s[38:39], s[58:59]
	s_cbranch_execz .LBB0_466
	v_ashrrev_i32_e32 v37, 31, v36
	v_cvt_pk_bf16_f32 v28, v28, v29
	v_cvt_pk_bf16_f32 v29, v30, v31
	v_cvt_pk_bf16_f32 v30, v24, v25
	v_lshlrev_b64 v[24:25], 10, v[36:37]
	v_lshl_add_u64 v[24:25], s[4:5], 0, v[24:25]
	v_lshl_add_u64 v[24:25], v[112:113], 1, v[24:25]
	v_cvt_pk_bf16_f32 v31, v26, v27
	global_store_dwordx4 v[24:25], v[28:31], off sc1
	v_cvt_pk_bf16_f32 v20, v20, v21
	v_cvt_pk_bf16_f32 v21, v22, v23
	v_cvt_pk_bf16_f32 v22, v16, v17
	v_cvt_pk_bf16_f32 v23, v18, v19
	global_store_dwordx4 v[24:25], v[20:23], off offset:256 sc1
.LBB0_466:
	s_or_b64 exec, exec, s[38:39]
	v_pk_mul_f32 v[14:15], v[14:15], v[34:35] op_sel_hi:[1,0]
	v_pk_mul_f32 v[12:13], v[12:13], v[34:35] op_sel_hi:[1,0]
	v_pk_mul_f32 v[10:11], v[10:11], v[34:35] op_sel_hi:[1,0]
	v_pk_mul_f32 v[8:9], v[8:9], v[34:35] op_sel_hi:[1,0]
	v_pk_mul_f32 v[6:7], v[6:7], v[34:35] op_sel_hi:[1,0]
	v_pk_mul_f32 v[4:5], v[4:5], v[34:35] op_sel_hi:[1,0]
	v_pk_mul_f32 v[2:3], v[2:3], v[34:35] op_sel_hi:[1,0]
	v_pk_mul_f32 v[0:1], v[0:1], v[34:35] op_sel_hi:[1,0]
	s_and_saveexec_b64 s[14:15], s[36:37]
	s_xor_b64 s[38:39], exec, s[14:15]
	s_cbranch_execz .LBB0_484
	v_cmp_lt_i32_e64 s[36:37], 2, v150
	s_and_saveexec_b64 s[14:15], s[36:37]
	s_xor_b64 s[58:59], exec, s[14:15]
	s_cbranch_execz .LBB0_479
	v_cmp_ne_u32_e64 s[36:37], 3, v150
	s_and_saveexec_b64 s[14:15], s[36:37]
	s_xor_b64 s[60:61], exec, s[14:15]
	s_cbranch_execz .LBB0_474
	v_cvt_pk_bf16_f32 v16, v12, v13
	v_mul_f32_e32 v13, v13, v13
	v_fmac_f32_e32 v13, v12, v12
	v_mul_f32_e32 v12, v15, v15
	v_cvt_pk_bf16_f32 v17, v14, v15
	v_cvt_pk_bf16_f32 v18, v8, v9
	v_fmac_f32_e32 v12, v14, v14
	v_mul_f32_e32 v9, v9, v9
	v_add_f32_e32 v12, v13, v12
	v_fmac_f32_e32 v9, v8, v8
	v_add_f32_e32 v8, v9, v12
	v_mul_f32_e32 v9, v11, v11
	v_fmac_f32_e32 v9, v10, v10
	v_readlane_b32 s6, v251, 0
	v_add_f32_e32 v8, v9, v8
	v_readlane_b32 s7, v251, 1
	v_mov_b32_e32 v9, v8
	s_movk_i32 s3, 0x300
	v_mov_b64_e32 v[20:21], s[6:7]
	v_permlane16_swap_b32_e32 v8, v9
	v_mad_i64_i32 v[20:21], s[14:15], v32, s3, v[20:21]
	v_add_f32_e32 v8, v8, v9
	v_lshl_add_u64 v[20:21], v[184:185], 1, v[20:21]
	v_mov_b32_e32 v9, v8
	v_cvt_pk_bf16_f32 v19, v10, v11
	v_ashrrev_i32_e32 v33, 31, v32
	global_store_dwordx4 v[20:21], v[16:19], off offset:-1536 sc1
	v_permlane32_swap_b32_e32 v8, v9
	v_mbcnt_lo_u32_b32 v10, -1, 0
	v_mbcnt_hi_u32_b32 v10, -1, v10
	s_nop 0
	v_cmp_gt_u32_e64 s[36:37], 16, v10
	s_and_saveexec_b64 s[62:63], s[36:37]
	s_cbranch_execz .LBB0_471
	v_add_f32_e32 v12, v8, v9
	v_lshlrev_b64 v[8:9], 5, v[32:33]
	v_lshl_add_u64 v[8:9], s[96:97], 0, v[8:9]
	v_lshlrev_b32_e32 v10, 2, v149
	v_mov_b32_e32 v11, v185
	v_lshl_add_u64 v[8:9], v[8:9], 0, v[10:11]
	global_store_dword v[8:9], v12, off offset:16
.LBB0_471:
	s_or_b64 exec, exec, s[62:63]
	s_and_saveexec_b64 s[36:37], vcc
	s_cbranch_execz .LBB0_473
	v_readlane_b32 s6, v251, 36
	v_cvt_pk_bf16_f32 v4, v4, v5
	v_cvt_pk_bf16_f32 v5, v6, v7
	v_cvt_pk_bf16_f32 v6, v0, v1
	v_lshlrev_b64 v[0:1], 6, v[32:33]
	v_readlane_b32 s7, v251, 37
	v_cvt_pk_bf16_f32 v7, v2, v3
	s_nop 1
	v_lshl_add_u64 v[0:1], s[6:7], 0, v[0:1]
	v_lshl_add_u64 v[0:1], v[184:185], 1, v[0:1]
	global_store_dwordx4 v[0:1], v[4:7], off offset:-2048 sc1

.LBB0_474:
	s_andn2_saveexec_b64 s[36:37], s[60:61]
	s_cbranch_execz .LBB0_478
	v_readlane_b32 s6, v251, 0
	v_readlane_b32 s7, v251, 1
	s_movk_i32 s3, 0x300
	s_nop 0
	v_mov_b64_e32 v[16:17], s[6:7]
	v_mad_i64_i32 v[16:17], s[14:15], v32, s3, v[16:17]
	v_lshl_add_u64 v[20:21], v[184:185], 1, v[16:17]
	v_cvt_pk_bf16_f32 v16, v12, v13
	v_cvt_pk_bf16_f32 v17, v14, v15
	v_cvt_pk_bf16_f32 v18, v8, v9
	v_cvt_pk_bf16_f32 v19, v10, v11
	global_store_dwordx4 v[20:21], v[16:19], off offset:-1536 sc1
	v_mul_f32_e32 v13, v13, v13
	v_fmac_f32_e32 v13, v12, v12
	v_cvt_pk_bf16_f32 v16, v4, v5
	v_mul_f32_e32 v5, v5, v5
	v_mul_f32_e32 v12, v15, v15
	v_fmac_f32_e32 v5, v4, v4
	v_mul_f32_e32 v4, v7, v7
	v_cvt_pk_bf16_f32 v17, v6, v7
	v_cvt_pk_bf16_f32 v18, v0, v1
	v_fmac_f32_e32 v12, v14, v14
	v_mul_f32_e32 v9, v9, v9
	v_fmac_f32_e32 v4, v6, v6
	v_mul_f32_e32 v1, v1, v1
	v_add_f32_e32 v12, v13, v12
	v_fmac_f32_e32 v9, v8, v8
	v_add_f32_e32 v4, v5, v4
	v_fmac_f32_e32 v1, v0, v0
	v_add_f32_e32 v8, v9, v12
	v_mul_f32_e32 v9, v11, v11
	v_add_f32_e32 v0, v1, v4
	v_mul_f32_e32 v1, v3, v3
	v_fmac_f32_e32 v9, v10, v10
	v_fmac_f32_e32 v1, v2, v2
	v_add_f32_e32 v8, v9, v8
	v_add_f32_e32 v0, v1, v0
	v_add_f32_e32 v0, v8, v0
	v_mov_b32_e32 v1, v0
	s_nop 1
	v_permlane16_swap_b32_e32 v0, v1
	v_add_f32_e32 v0, v0, v1
	v_mov_b32_e32 v1, v0
	v_cvt_pk_bf16_f32 v19, v2, v3
	global_store_dwordx4 v[20:21], v[16:19], off offset:-1280 sc1
	s_nop 0
	v_permlane32_swap_b32_e32 v0, v1
	v_mbcnt_lo_u32_b32 v2, -1, 0
	v_mbcnt_hi_u32_b32 v2, -1, v2
	s_nop 0
	v_cmp_gt_u32_e32 vcc, 16, v2
	s_and_saveexec_b64 s[60:61], vcc
	s_cbranch_execz .LBB0_477
	v_ashrrev_i32_e32 v33, 31, v32
	v_add_f32_e32 v2, v0, v1
	v_lshlrev_b64 v[0:1], 5, v[32:33]
	v_lshl_add_u64 v[0:1], s[96:97], 0, v[0:1]
	v_lshlrev_b32_e32 v184, 2, v149
	v_lshl_add_u64 v[0:1], v[0:1], 0, v[184:185]
	global_store_dword v[0:1], v2, off

.LBB0_479:
	s_andn2_saveexec_b64 s[36:37], s[58:59]
	s_cbranch_execz .LBB0_483
	v_ashrrev_i32_e32 v33, 31, v32
	v_readlane_b32 s6, v255, 30
	v_lshlrev_b64 v[16:17], 9, v[32:33]
	v_readlane_b32 s7, v255, 31
	s_nop 1
	v_lshl_add_u64 v[16:17], s[6:7], 0, v[16:17]
	v_lshl_add_u64 v[20:21], v[184:185], 1, v[16:17]
	v_cvt_pk_bf16_f32 v16, v12, v13
	v_cvt_pk_bf16_f32 v17, v14, v15
	v_cvt_pk_bf16_f32 v18, v8, v9
	v_cvt_pk_bf16_f32 v19, v10, v11
	global_store_dwordx4 v[20:21], v[16:19], off offset:-1024 sc1
	v_mul_f32_e32 v13, v13, v13
	v_fmac_f32_e32 v13, v12, v12
	v_cvt_pk_bf16_f32 v16, v4, v5
	v_mul_f32_e32 v5, v5, v5
	v_mul_f32_e32 v12, v15, v15
	v_fmac_f32_e32 v5, v4, v4
	v_mul_f32_e32 v4, v7, v7
	v_cvt_pk_bf16_f32 v17, v6, v7
	v_cvt_pk_bf16_f32 v18, v0, v1
	v_fmac_f32_e32 v12, v14, v14
	v_mul_f32_e32 v9, v9, v9
	v_fmac_f32_e32 v4, v6, v6
	v_mul_f32_e32 v1, v1, v1
	v_add_f32_e32 v12, v13, v12
	v_fmac_f32_e32 v9, v8, v8
	v_add_f32_e32 v4, v5, v4
	v_fmac_f32_e32 v1, v0, v0
	v_add_f32_e32 v8, v9, v12
	v_mul_f32_e32 v9, v11, v11
	v_add_f32_e32 v0, v1, v4
	v_mul_f32_e32 v1, v3, v3
	v_fmac_f32_e32 v9, v10, v10
	v_fmac_f32_e32 v1, v2, v2
	v_add_f32_e32 v8, v9, v8
	v_add_f32_e32 v0, v1, v0
	v_add_f32_e32 v0, v8, v0
	v_mov_b32_e32 v1, v0
	s_nop 1
	v_permlane16_swap_b32_e32 v0, v1
	v_add_f32_e32 v0, v0, v1
	v_mov_b32_e32 v1, v0
	v_cvt_pk_bf16_f32 v19, v2, v3
	global_store_dwordx4 v[20:21], v[16:19], off offset:-768 sc1
	s_nop 0
	v_permlane32_swap_b32_e32 v0, v1
	v_mbcnt_lo_u32_b32 v2, -1, 0
	v_mbcnt_hi_u32_b32 v2, -1, v2
	s_nop 0
	v_cmp_gt_u32_e32 vcc, 16, v2
	s_and_saveexec_b64 s[58:59], vcc
	s_cbranch_execz .LBB0_482
	v_add_f32_e32 v2, v0, v1
	v_lshl_add_u64 v[0:1], v[32:33], 4, s[92:93]
	v_lshlrev_b32_e32 v184, 2, v149
	v_lshl_add_u64 v[0:1], v[0:1], 0, v[184:185]
	global_store_dword v[0:1], v2, off

.LBB0_484:
	s_andn2_saveexec_b64 s[36:37], s[38:39]
	s_cbranch_execz .LBB0_486
	v_ashrrev_i32_e32 v33, 31, v32
	v_cvt_pk_bf16_f32 v12, v12, v13
	v_cvt_pk_bf16_f32 v13, v14, v15
	v_cvt_pk_bf16_f32 v14, v8, v9
	v_lshlrev_b64 v[8:9], 10, v[32:33]
	v_lshl_add_u64 v[8:9], s[4:5], 0, v[8:9]
	v_lshl_add_u64 v[8:9], v[112:113], 1, v[8:9]
	v_cvt_pk_bf16_f32 v15, v10, v11
	global_store_dwordx4 v[8:9], v[12:15], off sc1
	v_cvt_pk_bf16_f32 v4, v4, v5
	v_cvt_pk_bf16_f32 v5, v6, v7
	v_cvt_pk_bf16_f32 v6, v0, v1
	v_cvt_pk_bf16_f32 v7, v2, v3
	global_store_dwordx4 v[8:9], v[4:7], off offset:256 sc1

;     __device__ __forceinline__ RowPre pre_row(int row, int) const { const float ss = NSLOT == 8 ? sum8(part + (size_t)row * 8) : sum4(part + (size_t)row * 4); return PreRs{rsqrtf(ss * inv_k + EPS)}; }
;     __device__ __forceinline__ void operator()(const pg8::f32x4 (&acc)[2][2][4][2], const pg8::Unit& u, int wr, int wc, int, int, int ui) const {
;     ...
;         for (int g = 0; g < 8; g += NB) {
;             typename F::RowPre rp[NB]; int rows[NB]; float rv[NB];
; #pragma unroll
;             for (int j = 0; j < NB; ++j) { const int ai = (g + j) >> 2, mm = (g + j) & 3; const int rl = ai * 128 + wr * 64 + mm * 16 + fr; int row = u.pm * 256 + rl; asm volatile("" : "+v"(row)); rows[j] = row;
;                 rv[j] = F::USE_TAB ? tab[rl] : 0.f; rp[j] = f.pre_row(row, col); }
; #pragma unroll
;             for (int j = 0; j < NB; ++j) { const int ai = (g + j) >> 2, mm = (g + j) & 3; f.apply(rows[j], col, rv[j], cv, rp[j], acc[ai][0][mm][0], acc[ai][0][mm][1], acc[ai][1][mm][0], acc[ai][1][mm][1]); }
;             asm volatile("" ::: "memory");
;         }
.LBB0_561:
	v_mbcnt_lo_u32_b32 v134, -1, 0
	v_mbcnt_hi_u32_b32 v134, -1, v134
	s_lshl_b32 s12, s12, 8
	v_ashrrev_i32_e32 v135, 1, v134
	v_and_or_b32 v134, v134, 15, s63
	s_or_b32 s12, s12, s64
	v_and_b32_e32 v135, -8, v135
	v_lshl_add_u32 v151, s3, 8, v134
	v_add_u32_e32 v138, s12, v135
	v_mov_b32_e32 v154, v151
	s_mov_b32 s6, 0x358637bd
	v_ashrrev_i32_e32 v155, 31, v154
	v_lshlrev_b64 v[134:135], 5, v[154:155]
	v_lshl_add_u64 v[142:143], s[96:97], 0, v[134:135]
	global_load_dwordx4 v[134:137], v[142:143], off
	global_load_dwordx4 v[146:149], v[142:143], off offset:16
	s_mov_b32 s8, 0x3b2aaaab
	v_ashrrev_i32_e32 v139, 31, v138
	s_movk_i32 s3, 0x600
	v_lshlrev_b64 v[138:139], 1, v[138:139]
	v_readlane_b32 s78, v252, 15
	v_readlane_b32 s79, v252, 16
	v_readlane_b32 s77, v251, 5
	s_mov_b32 s55, 0x1a000000
	s_movk_i32 s79, 0x3fff
	s_waitcnt vmcnt(0)
	v_pk_add_f32 v[136:137], v[136:137], v[148:149]
	v_pk_add_f32 v[134:135], v[134:135], v[146:147]
	s_nop 0
	v_pk_mov_b32 v[142:143], v[134:135], v[136:137] op_sel:[1,0]
	v_mov_b32_e32 v135, v137
	v_pk_add_f32 v[152:153], v[142:143], v[134:135]
	v_or_b32_e32 v142, 16, v151
	s_nop 0
	v_ashrrev_i32_e32 v143, 31, v142
	v_lshlrev_b64 v[134:135], 5, v[142:143]
	v_lshl_add_u64 v[146:147], s[96:97], 0, v[134:135]
	global_load_dwordx4 v[134:137], v[146:147], off
	s_nop 0
	global_load_dwordx4 v[146:149], v[146:147], off offset:16
	s_waitcnt vmcnt(0)
	v_pk_add_f32 v[136:137], v[136:137], v[148:149]
	v_pk_add_f32 v[134:135], v[134:135], v[146:147]
	v_or_b32_e32 v148, 32, v151
	v_pk_mov_b32 v[146:147], v[134:135], v[136:137] op_sel:[1,0]
	v_mov_b32_e32 v135, v137
	v_pk_add_f32 v[134:135], v[146:147], v[134:135]
	v_mov_b32_e32 v137, v152
	v_mov_b32_e32 v136, v134
	v_mov_b32_e32 v152, v135
	v_pk_add_f32 v[136:137], v[136:137], v[152:153]
	v_mov_b64_e32 v[134:135], s[6:7]
	v_pk_fma_f32 v[136:137], v[136:137], s[8:9], v[134:135] op_sel_hi:[1,0,0]
	v_readlane_b32 s6, v253, 51
	v_mul_f32_e32 v140, 0x4b800000, v137
	v_cmp_gt_f32_e64 s[36:37], s48, v137
	v_cmp_gt_f32_e32 vcc, s48, v136
	v_ashrrev_i32_e32 v149, 31, v148
	v_cndmask_b32_e64 v137, v137, v140, s[36:37]
	v_rsq_f32_e32 v137, v137
	v_readlane_b32 s7, v253, 52
	v_mul_f32_e32 v140, 0x45800000, v137
	v_cndmask_b32_e64 v150, v137, v140, s[36:37]
	v_mul_f32_e32 v137, 0x4b800000, v136
	v_cndmask_b32_e32 v136, v136, v137, vcc
	v_rsq_f32_e32 v136, v136
	v_pk_mul_f32 v[126:127], v[126:127], v[150:151] op_sel_hi:[1,0]
	v_pk_mul_f32 v[124:125], v[124:125], v[150:151] op_sel_hi:[1,0]
	v_pk_mul_f32 v[118:119], v[118:119], v[150:151] op_sel_hi:[1,0]
	v_mul_f32_e32 v137, 0x45800000, v136
	v_cndmask_b32_e32 v140, v136, v137, vcc
	v_lshlrev_b64 v[136:137], 5, v[148:149]
	v_lshl_add_u64 v[136:137], s[96:97], 0, v[136:137]
	global_load_dwordx4 v[156:159], v[136:137], off
	global_load_dwordx4 v[160:163], v[136:137], off offset:16
	v_pk_mul_f32 v[116:117], v[116:117], v[150:151] op_sel_hi:[1,0]
	v_pk_mul_f32 v[110:111], v[110:111], v[140:141] op_sel_hi:[1,0]
	v_pk_mul_f32 v[108:109], v[108:109], v[140:141] op_sel_hi:[1,0]
	v_pk_mul_f32 v[102:103], v[102:103], v[140:141] op_sel_hi:[1,0]
	v_pk_mul_f32 v[100:101], v[100:101], v[140:141] op_sel_hi:[1,0]
	s_waitcnt vmcnt(0)
	v_pk_add_f32 v[136:137], v[158:159], v[162:163]
	v_pk_add_f32 v[146:147], v[156:157], v[160:161]
	s_nop 0
	v_pk_mov_b32 v[152:153], v[146:147], v[136:137] op_sel:[1,0]
	v_mov_b32_e32 v147, v137
	v_pk_add_f32 v[136:137], v[152:153], v[146:147]
	v_or_b32_e32 v146, 48, v151
	s_nop 0
	v_ashrrev_i32_e32 v147, 31, v146
	v_lshlrev_b64 v[152:153], 5, v[146:147]
	v_lshl_add_u64 v[152:153], s[96:97], 0, v[152:153]
	global_load_dwordx4 v[156:159], v[152:153], off
	global_load_dwordx4 v[160:163], v[152:153], off offset:16
	s_waitcnt vmcnt(0)
	v_pk_add_f32 v[152:153], v[158:159], v[162:163]
	v_pk_add_f32 v[156:157], v[156:157], v[160:161]
	s_nop 0
	v_pk_mov_b32 v[158:159], v[156:157], v[152:153] op_sel:[1,0]
	v_mov_b32_e32 v157, v153
	v_pk_add_f32 v[152:153], v[158:159], v[156:157]
	v_mov_b32_e32 v157, v136
	v_mov_b32_e32 v156, v152
	v_mov_b32_e32 v136, v153
	v_pk_add_f32 v[136:137], v[156:157], v[136:137]
	v_pk_mul_f32 v[156:157], v[122:123], v[150:151] op_sel_hi:[1,0]
	v_pk_fma_f32 v[136:137], v[136:137], s[8:9], v[134:135] op_sel_hi:[1,0,0]
	v_pk_mul_f32 v[122:123], v[120:121], v[150:151] op_sel_hi:[1,0]
	v_mul_f32_e32 v143, 0x4b800000, v137
	v_cmp_gt_f32_e64 s[36:37], s48, v137
	v_cmp_gt_f32_e32 vcc, s48, v136
	v_cvt_pk_bf16_f32 v120, v124, v125
	v_cvt_pk_bf16_f32 v121, v126, v127
	v_cvt_pk_bf16_f32 v122, v122, v123
	v_cvt_pk_bf16_f32 v123, v156, v157
	s_nop 0
	v_cndmask_b32_e64 v137, v137, v143, s[36:37]
	v_rsq_f32_e32 v137, v137
	s_nop 0
	v_mul_f32_e32 v143, 0x45800000, v137
	v_cndmask_b32_e64 v152, v137, v143, s[36:37]
	v_mul_f32_e32 v137, 0x4b800000, v136
	v_cndmask_b32_e32 v136, v136, v137, vcc
	v_rsq_f32_e32 v136, v136
	v_pk_mul_f32 v[94:95], v[94:95], v[152:153] op_sel_hi:[1,0]
	v_pk_mul_f32 v[92:93], v[92:93], v[152:153] op_sel_hi:[1,0]
	v_pk_mul_f32 v[86:87], v[86:87], v[152:153] op_sel_hi:[1,0]
	v_mul_f32_e32 v137, 0x45800000, v136
	v_cndmask_b32_e32 v144, v136, v137, vcc
	v_mov_b64_e32 v[136:137], s[6:7]
	v_mad_i64_i32 v[154:155], s[14:15], v154, s3, v[136:137]
	v_lshl_add_u64 v[154:155], v[154:155], 0, v[138:139]
	global_store_dwordx4 v[154:155], v[120:123], off sc1
	v_pk_mul_f32 v[84:85], v[84:85], v[152:153] op_sel_hi:[1,0]
	v_pk_mul_f32 v[78:79], v[78:79], v[144:145] op_sel_hi:[1,0]
	v_pk_mul_f32 v[120:121], v[114:115], v[150:151] op_sel_hi:[1,0]
	v_pk_mul_f32 v[114:115], v[112:113], v[150:151] op_sel_hi:[1,0]
	v_cvt_pk_bf16_f32 v112, v116, v117
	v_cvt_pk_bf16_f32 v113, v118, v119
;     __device__ __forceinline__ RowPre pre_row(int row, int) const { const float ss = NSLOT == 8 ? sum8(part + (size_t)row * 8) : sum4(part + (size_t)row * 4); return PreRs{rsqrtf(ss * inv_k + EPS)}; }
;     __device__ __forceinline__ void operator()(const pg8::f32x4 (&acc)[2][2][4][2], const pg8::Unit& u, int wr, int wc, int, int, int ui) const {
;     ...
;         for (int g = 0; g < 8; g += NB) {
;             typename F::RowPre rp[NB]; int rows[NB]; float rv[NB];
; #pragma unroll
;             for (int j = 0; j < NB; ++j) { const int ai = (g + j) >> 2, mm = (g + j) & 3; const int rl = ai * 128 + wr * 64 + mm * 16 + fr; int row = u.pm * 256 + rl; asm volatile("" : "+v"(row)); rows[j] = row;
;                 rv[j] = F::USE_TAB ? tab[rl] : 0.f; rp[j] = f.pre_row(row, col); }
; #pragma unroll
;             for (int j = 0; j < NB; ++j) { const int ai = (g + j) >> 2, mm = (g + j) & 3; f.apply(rows[j], col, rv[j], cv, rp[j], acc[ai][0][mm][0], acc[ai][0][mm][1], acc[ai][1][mm][0], acc[ai][1][mm][1]); }
;             asm volatile("" ::: "memory");
;         }
	v_pk_mul_f32 v[76:77], v[76:77], v[144:145] op_sel_hi:[1,0]
	v_cvt_pk_bf16_f32 v114, v114, v115
	v_cvt_pk_bf16_f32 v115, v120, v121
	global_store_dwordx4 v[154:155], v[112:115], off offset:256 sc1
	v_pk_mul_f32 v[68:69], v[68:69], v[144:145] op_sel_hi:[1,0]
	v_pk_mul_f32 v[70:71], v[70:71], v[144:145] op_sel_hi:[1,0]
	v_mad_i64_i32 v[112:113], s[14:15], v142, s3, v[136:137]
	v_lshl_add_u64 v[112:113], v[112:113], 0, v[138:139]
	v_pk_mul_f32 v[114:115], v[106:107], v[140:141] op_sel_hi:[1,0]
	v_pk_mul_f32 v[106:107], v[104:105], v[140:141] op_sel_hi:[1,0]
	v_cvt_pk_bf16_f32 v104, v108, v109
	v_cvt_pk_bf16_f32 v105, v110, v111
	s_nop 0
	v_cvt_pk_bf16_f32 v106, v106, v107
	v_cvt_pk_bf16_f32 v107, v114, v115
	global_store_dwordx4 v[112:113], v[104:107], off sc1
	s_nop 1
	v_pk_mul_f32 v[104:105], v[98:99], v[140:141] op_sel_hi:[1,0]
	v_pk_mul_f32 v[98:99], v[96:97], v[140:141] op_sel_hi:[1,0]
	v_cvt_pk_bf16_f32 v96, v100, v101
	v_cvt_pk_bf16_f32 v97, v102, v103
	s_nop 0
	v_cvt_pk_bf16_f32 v98, v98, v99
	v_cvt_pk_bf16_f32 v99, v104, v105
	global_store_dwordx4 v[112:113], v[96:99], off offset:256 sc1
	s_nop 1
	v_mad_i64_i32 v[96:97], s[14:15], v148, s3, v[136:137]
	v_lshl_add_u64 v[96:97], v[96:97], 0, v[138:139]
	v_pk_mul_f32 v[98:99], v[90:91], v[152:153] op_sel_hi:[1,0]
	v_pk_mul_f32 v[90:91], v[88:89], v[152:153] op_sel_hi:[1,0]
	v_cvt_pk_bf16_f32 v88, v92, v93
	v_cvt_pk_bf16_f32 v89, v94, v95
	s_nop 0
	v_cvt_pk_bf16_f32 v90, v90, v91
	v_cvt_pk_bf16_f32 v91, v98, v99
	global_store_dwordx4 v[96:97], v[88:91], off sc1
	s_nop 1
	v_pk_mul_f32 v[88:89], v[82:83], v[152:153] op_sel_hi:[1,0]
	v_pk_mul_f32 v[82:83], v[80:81], v[152:153] op_sel_hi:[1,0]
	v_cvt_pk_bf16_f32 v80, v84, v85
	v_cvt_pk_bf16_f32 v81, v86, v87
	s_nop 0
	v_cvt_pk_bf16_f32 v82, v82, v83
	v_cvt_pk_bf16_f32 v83, v88, v89
	global_store_dwordx4 v[96:97], v[80:83], off offset:256 sc1
	s_nop 1
	v_mad_i64_i32 v[80:81], s[14:15], v146, s3, v[136:137]
	v_lshl_add_u64 v[80:81], v[80:81], 0, v[138:139]
	v_pk_mul_f32 v[82:83], v[74:75], v[144:145] op_sel_hi:[1,0]
	v_pk_mul_f32 v[74:75], v[72:73], v[144:145] op_sel_hi:[1,0]
	v_cvt_pk_bf16_f32 v72, v76, v77
	v_cvt_pk_bf16_f32 v73, v78, v79
	s_nop 0
	v_cvt_pk_bf16_f32 v74, v74, v75
	v_cvt_pk_bf16_f32 v75, v82, v83
	global_store_dwordx4 v[80:81], v[72:75], off sc1
	s_nop 1
	v_pk_mul_f32 v[72:73], v[66:67], v[144:145] op_sel_hi:[1,0]
	v_pk_mul_f32 v[66:67], v[64:65], v[144:145] op_sel_hi:[1,0]
	v_cvt_pk_bf16_f32 v64, v68, v69
	v_cvt_pk_bf16_f32 v65, v70, v71
	v_add_u32_e32 v68, 0x80, v151
	v_cvt_pk_bf16_f32 v66, v66, v67
	v_cvt_pk_bf16_f32 v67, v72, v73
	global_store_dwordx4 v[80:81], v[64:67], off offset:256 sc1
	s_nop 0
	v_ashrrev_i32_e32 v69, 31, v68
	v_lshlrev_b64 v[64:65], 5, v[68:69]
	v_lshl_add_u64 v[70:71], s[96:97], 0, v[64:65]
	global_load_dwordx4 v[64:67], v[70:71], off
	s_nop 0
	global_load_dwordx4 v[70:73], v[70:71], off offset:16
	v_mad_i64_i32 v[68:69], s[14:15], v68, s3, v[136:137]
	v_lshl_add_u64 v[68:69], v[68:69], 0, v[138:139]
	s_waitcnt vmcnt(0)
	v_pk_add_f32 v[66:67], v[66:67], v[72:73]
	v_pk_add_f32 v[64:65], v[64:65], v[70:71]
	s_nop 0
	v_pk_mov_b32 v[70:71], v[64:65], v[66:67] op_sel:[1,0]
	v_add_u32_e32 v66, 0x90, v151
	v_mov_b32_e32 v65, v67
	v_pk_add_f32 v[64:65], v[70:71], v[64:65]
	v_ashrrev_i32_e32 v67, 31, v66
	v_lshlrev_b64 v[70:71], 5, v[66:67]
	v_lshl_add_u64 v[74:75], s[96:97], 0, v[70:71]
	global_load_dwordx4 v[70:73], v[74:75], off
	s_nop 0
	global_load_dwordx4 v[74:77], v[74:75], off offset:16
	s_waitcnt vmcnt(0)
	v_pk_add_f32 v[72:73], v[72:73], v[76:77]
	v_pk_add_f32 v[70:71], v[70:71], v[74:75]
	s_nop 0
	v_pk_mov_b32 v[74:75], v[70:71], v[72:73] op_sel:[1,0]
	v_mov_b32_e32 v71, v73
	v_pk_add_f32 v[70:71], v[74:75], v[70:71]
	v_add_u32_e32 v74, 0xa0, v151
	v_mov_b32_e32 v72, v70
	v_mov_b32_e32 v73, v64
	v_mov_b32_e32 v64, v71
	v_pk_add_f32 v[64:65], v[72:73], v[64:65]
	v_ashrrev_i32_e32 v75, 31, v74
	v_lshlrev_b64 v[72:73], 5, v[74:75]
	v_lshl_add_u64 v[72:73], s[96:97], 0, v[72:73]
	global_load_dwordx4 v[76:79], v[72:73], off
	global_load_dwordx4 v[80:83], v[72:73], off offset:16
	v_pk_fma_f32 v[64:65], v[64:65], s[8:9], v[134:135] op_sel_hi:[1,0,0]
	s_waitcnt vmcnt(0)
	v_pk_add_f32 v[72:73], v[78:79], v[82:83]
	v_pk_add_f32 v[76:77], v[76:77], v[80:81]
	v_mul_f32_e32 v67, 0x4b800000, v65
	v_pk_mov_b32 v[78:79], v[76:77], v[72:73] op_sel:[1,0]
	v_add_u32_e32 v72, 0xb0, v151
	v_mov_b32_e32 v77, v73
	v_pk_add_f32 v[84:85], v[78:79], v[76:77]
	v_ashrrev_i32_e32 v73, 31, v72
	v_lshlrev_b64 v[76:77], 5, v[72:73]
	v_lshl_add_u64 v[80:81], s[96:97], 0, v[76:77]
	global_load_dwordx4 v[76:79], v[80:81], off
	s_nop 0
	global_load_dwordx4 v[80:83], v[80:81], off offset:16
	v_cmp_gt_f32_e64 s[36:37], s48, v65
	v_cmp_gt_f32_e32 vcc, s48, v64
	s_waitcnt vmcnt(0)
;     __device__ __forceinline__ RowPre pre_row(int row, int) const { const float ss = NSLOT == 8 ? sum8(part + (size_t)row * 8) : sum4(part + (size_t)row * 4); return PreRs{rsqrtf(ss * inv_k + EPS)}; }
;     __device__ __forceinline__ void operator()(const pg8::f32x4 (&acc)[2][2][4][2], const pg8::Unit& u, int wr, int wc, int, int, int ui) const {
;     ...
;         for (int g = 0; g < 8; g += NB) {
;             typename F::RowPre rp[NB]; int rows[NB]; float rv[NB];
; #pragma unroll
;             for (int j = 0; j < NB; ++j) { const int ai = (g + j) >> 2, mm = (g + j) & 3; const int rl = ai * 128 + wr * 64 + mm * 16 + fr; int row = u.pm * 256 + rl; asm volatile("" : "+v"(row)); rows[j] = row;
;                 rv[j] = F::USE_TAB ? tab[rl] : 0.f; rp[j] = f.pre_row(row, col); }
; #pragma unroll
;             for (int j = 0; j < NB; ++j) { const int ai = (g + j) >> 2, mm = (g + j) & 3; f.apply(rows[j], col, rv[j], cv, rp[j], acc[ai][0][mm][0], acc[ai][0][mm][1], acc[ai][1][mm][0], acc[ai][1][mm][1]); }
;             asm volatile("" ::: "memory");
;         }
	v_pk_add_f32 v[78:79], v[78:79], v[82:83]
	v_cndmask_b32_e64 v65, v65, v67, s[36:37]
	v_rsq_f32_e32 v65, v65
	v_pk_add_f32 v[76:77], v[76:77], v[80:81]
	v_mul_f32_e32 v67, 0x45800000, v65
	v_cndmask_b32_e64 v70, v65, v67, s[36:37]
	v_mul_f32_e32 v65, 0x4b800000, v64
	v_cndmask_b32_e32 v64, v64, v65, vcc
	v_rsq_f32_e32 v64, v64
	v_pk_mov_b32 v[80:81], v[76:77], v[78:79] op_sel:[1,0]
	v_mov_b32_e32 v77, v79
	v_pk_add_f32 v[76:77], v[80:81], v[76:77]
	v_mov_b32_e32 v79, v84
	v_mov_b32_e32 v78, v76
	v_mov_b32_e32 v84, v77
	v_pk_add_f32 v[76:77], v[78:79], v[84:85]
	v_mul_f32_e32 v65, 0x45800000, v64
	v_pk_fma_f32 v[76:77], v[76:77], s[8:9], v[134:135] op_sel_hi:[1,0,0]
	v_cndmask_b32_e32 v64, v64, v65, vcc
	v_mul_f32_e32 v65, 0x4b800000, v77
	v_cmp_gt_f32_e64 s[36:37], s48, v77
	v_cmp_gt_f32_e32 vcc, s48, v76
	v_pk_mul_f32 v[62:63], v[62:63], v[70:71] op_sel_hi:[1,0]
	v_cndmask_b32_e64 v65, v77, v65, s[36:37]
	v_rsq_f32_e32 v65, v65
	v_pk_mul_f32 v[60:61], v[60:61], v[70:71] op_sel_hi:[1,0]
	v_pk_mul_f32 v[80:81], v[58:59], v[70:71] op_sel_hi:[1,0]
	v_pk_mul_f32 v[58:59], v[56:57], v[70:71] op_sel_hi:[1,0]
	v_mul_f32_e32 v67, 0x45800000, v65
	v_cndmask_b32_e64 v78, v65, v67, s[36:37]
	v_mul_f32_e32 v65, 0x4b800000, v76
	v_cndmask_b32_e32 v65, v76, v65, vcc
	v_rsq_f32_e32 v65, v65
	v_cvt_pk_bf16_f32 v56, v60, v61
	v_cvt_pk_bf16_f32 v57, v62, v63
	v_cvt_pk_bf16_f32 v58, v58, v59
	v_cvt_pk_bf16_f32 v59, v80, v81
	global_store_dwordx4 v[68:69], v[56:59], off sc1
	v_pk_mul_f32 v[54:55], v[54:55], v[70:71] op_sel_hi:[1,0]
	v_pk_mul_f32 v[52:53], v[52:53], v[70:71] op_sel_hi:[1,0]
	v_pk_mul_f32 v[56:57], v[50:51], v[70:71] op_sel_hi:[1,0]
	v_pk_mul_f32 v[50:51], v[48:49], v[70:71] op_sel_hi:[1,0]
	v_cvt_pk_bf16_f32 v48, v52, v53
	v_cvt_pk_bf16_f32 v49, v54, v55
	v_pk_mul_f32 v[46:47], v[46:47], v[64:65] op_sel_hi:[1,0]
	v_cvt_pk_bf16_f32 v50, v50, v51
	v_cvt_pk_bf16_f32 v51, v56, v57
	global_store_dwordx4 v[68:69], v[48:51], off offset:256 sc1
	v_pk_mul_f32 v[44:45], v[44:45], v[64:65] op_sel_hi:[1,0]
	v_pk_mul_f32 v[38:39], v[38:39], v[64:65] op_sel_hi:[1,0]
	v_mad_i64_i32 v[48:49], s[14:15], v66, s3, v[136:137]
	v_lshl_add_u64 v[48:49], v[48:49], 0, v[138:139]
	v_pk_mul_f32 v[50:51], v[42:43], v[64:65] op_sel_hi:[1,0]
	v_pk_mul_f32 v[42:43], v[40:41], v[64:65] op_sel_hi:[1,0]
	v_cvt_pk_bf16_f32 v40, v44, v45
	v_cvt_pk_bf16_f32 v41, v46, v47
	v_pk_mul_f32 v[36:37], v[36:37], v[64:65] op_sel_hi:[1,0]
	v_cvt_pk_bf16_f32 v42, v42, v43
	v_cvt_pk_bf16_f32 v43, v50, v51
	global_store_dwordx4 v[48:49], v[40:43], off sc1
	v_pk_mul_f32 v[30:31], v[30:31], v[78:79] op_sel_hi:[1,0]
	v_pk_mul_f32 v[28:29], v[28:29], v[78:79] op_sel_hi:[1,0]
	v_pk_mul_f32 v[40:41], v[34:35], v[64:65] op_sel_hi:[1,0]
	v_pk_mul_f32 v[34:35], v[32:33], v[64:65] op_sel_hi:[1,0]
	v_cvt_pk_bf16_f32 v32, v36, v37
	v_cvt_pk_bf16_f32 v33, v38, v39
	v_mul_f32_e32 v67, 0x45800000, v65
	v_cvt_pk_bf16_f32 v34, v34, v35
	v_cvt_pk_bf16_f32 v35, v40, v41
	global_store_dwordx4 v[48:49], v[32:35], off offset:256 sc1
	v_pk_mul_f32 v[22:23], v[22:23], v[78:79] op_sel_hi:[1,0]
	v_pk_mul_f32 v[20:21], v[20:21], v[78:79] op_sel_hi:[1,0]
	v_mad_i64_i32 v[32:33], s[14:15], v74, s3, v[136:137]
	v_lshl_add_u64 v[32:33], v[32:33], 0, v[138:139]
	v_pk_mul_f32 v[34:35], v[26:27], v[78:79] op_sel_hi:[1,0]
	v_pk_mul_f32 v[26:27], v[24:25], v[78:79] op_sel_hi:[1,0]
	v_cvt_pk_bf16_f32 v24, v28, v29
	v_cvt_pk_bf16_f32 v25, v30, v31
	v_cndmask_b32_e32 v76, v65, v67, vcc
	v_cvt_pk_bf16_f32 v26, v26, v27
	v_cvt_pk_bf16_f32 v27, v34, v35
	global_store_dwordx4 v[32:33], v[24:27], off sc1
	v_pk_mul_f32 v[14:15], v[14:15], v[76:77] op_sel_hi:[1,0]
	v_pk_mul_f32 v[12:13], v[12:13], v[76:77] op_sel_hi:[1,0]
	v_pk_mul_f32 v[24:25], v[18:19], v[78:79] op_sel_hi:[1,0]
	v_pk_mul_f32 v[18:19], v[16:17], v[78:79] op_sel_hi:[1,0]
	v_cvt_pk_bf16_f32 v16, v20, v21
	v_cvt_pk_bf16_f32 v17, v22, v23
	v_pk_mul_f32 v[6:7], v[6:7], v[76:77] op_sel_hi:[1,0]
	v_cvt_pk_bf16_f32 v18, v18, v19
	v_cvt_pk_bf16_f32 v19, v24, v25
	global_store_dwordx4 v[32:33], v[16:19], off offset:256 sc1
	v_pk_mul_f32 v[4:5], v[4:5], v[76:77] op_sel_hi:[1,0]
	s_mov_b64 s[36:37], -1
	v_mad_i64_i32 v[16:17], s[14:15], v72, s3, v[136:137]
	v_lshl_add_u64 v[16:17], v[16:17], 0, v[138:139]
	v_pk_mul_f32 v[18:19], v[10:11], v[76:77] op_sel_hi:[1,0]
	v_pk_mul_f32 v[10:11], v[8:9], v[76:77] op_sel_hi:[1,0]
	v_cvt_pk_bf16_f32 v8, v12, v13
	v_cvt_pk_bf16_f32 v9, v14, v15
	s_and_b64 vcc, exec, s[34:35]
	v_cvt_pk_bf16_f32 v10, v10, v11
	v_cvt_pk_bf16_f32 v11, v18, v19
	global_store_dwordx4 v[16:17], v[8:11], off sc1
	s_nop 1
	v_pk_mul_f32 v[8:9], v[2:3], v[76:77] op_sel_hi:[1,0]
	v_pk_mul_f32 v[2:3], v[0:1], v[76:77] op_sel_hi:[1,0]
	v_cvt_pk_bf16_f32 v0, v4, v5
	v_cvt_pk_bf16_f32 v1, v6, v7
	s_nop 0
	v_cvt_pk_bf16_f32 v2, v2, v3
	v_cvt_pk_bf16_f32 v3, v8, v9
	global_store_dwordx4 v[16:17], v[0:3], off offset:256 sc1
	s_cbranch_vccnz .LBB0_552
	s_andn2_b64 vcc, exec, s[38:39]
	s_cbranch_vccnz .LBB0_551
	s_barrier
	s_branch .LBB0_551

;     __device__ __forceinline__ RowPre pre_row(int row, int) const { const float ss = NSLOT == 8 ? sum8(part + (size_t)row * 8) : sum4(part + (size_t)row * 4); return PreRs{rsqrtf(ss * inv_k + EPS)}; }
;     __device__ __forceinline__ void operator()(const pg8::f32x4 (&acc)[2][2][4][2], const pg8::Unit& u, int wr, int wc, int, int, int ui) const {
;     ...
;         for (int g = 0; g < 8; g += NB) {
;             typename F::RowPre rp[NB]; int rows[NB]; float rv[NB];
; #pragma unroll
;             for (int j = 0; j < NB; ++j) { const int ai = (g + j) >> 2, mm = (g + j) & 3; const int rl = ai * 128 + wr * 64 + mm * 16 + fr; int row = u.pm * 256 + rl; asm volatile("" : "+v"(row)); rows[j] = row;
;                 rv[j] = F::USE_TAB ? tab[rl] : 0.f; rp[j] = f.pre_row(row, col); }
; #pragma unroll
;             for (int j = 0; j < NB; ++j) { const int ai = (g + j) >> 2, mm = (g + j) & 3; f.apply(rows[j], col, rv[j], cv, rp[j], acc[ai][0][mm][0], acc[ai][0][mm][1], acc[ai][1][mm][0], acc[ai][1][mm][1]); }
;             asm volatile("" ::: "memory");
;         }
.LBB0_579:
	v_mbcnt_lo_u32_b32 v134, -1, 0
	v_mbcnt_hi_u32_b32 v134, -1, v134
	s_lshl_b32 s12, s12, 8
	v_ashrrev_i32_e32 v135, 1, v134
	v_and_or_b32 v134, v134, 15, s71
	s_or_b32 s12, s12, s78
	v_and_b32_e32 v135, -8, v135
	v_lshl_add_u32 v147, s3, 8, v134
	v_add_u32_e32 v136, s12, v135
	v_mov_b32_e32 v150, v147
	v_or_b32_e32 v148, 16, v147
	v_ashrrev_i32_e32 v151, 31, v150
	v_lshl_add_u64 v[134:135], v[150:151], 4, s[92:93]
	global_load_dwordx4 v[142:145], v[134:135], off
	s_mov_b32 s8, 0x358637bd
	v_ashrrev_i32_e32 v149, 31, v148
	v_ashrrev_i32_e32 v137, 31, v136
	v_lshlrev_b64 v[150:151], 10, v[150:151]
	v_lshl_add_u64 v[150:151], s[18:19], 0, v[150:151]
	v_lshlrev_b64 v[136:137], 1, v[136:137]
	v_lshl_add_u64 v[150:151], v[150:151], 0, v[136:137]
	s_waitcnt vmcnt(0)
	v_mov_b32_e32 v134, v143
	v_mov_b32_e32 v135, v144
	v_mov_b32_e32 v143, v145
	v_pk_add_f32 v[134:135], v[134:135], v[142:143]
	v_lshl_add_u64 v[142:143], v[148:149], 4, s[92:93]
	global_load_dwordx4 v[142:145], v[142:143], off
	s_waitcnt vmcnt(0)
	v_mov_b32_e32 v152, v143
	v_mov_b32_e32 v153, v144
	v_mov_b32_e32 v143, v145
	v_pk_add_f32 v[142:143], v[152:153], v[142:143]
	v_mov_b32_e32 v145, v134
	v_mov_b32_e32 v144, v142
	v_mov_b32_e32 v134, v143
	v_pk_add_f32 v[142:143], v[144:145], v[134:135]
	v_mov_b64_e32 v[134:135], s[8:9]
	v_pk_fma_f32 v[142:143], v[142:143], s[82:83], v[134:135] op_sel_hi:[1,0,0]
	v_or_b32_e32 v144, 32, v147
	v_mul_f32_e32 v138, 0x4b800000, v143
	v_cmp_gt_f32_e64 s[38:39], s48, v143
	v_cmp_gt_f32_e32 vcc, s48, v142
	s_nop 0
	v_cndmask_b32_e64 v138, v143, v138, s[38:39]
	v_rsq_f32_e32 v138, v138
	v_ashrrev_i32_e32 v145, 31, v144
	v_mul_f32_e32 v140, 0x45800000, v138
	v_cndmask_b32_e64 v152, v138, v140, s[38:39]
	v_mul_f32_e32 v138, 0x4b800000, v142
	v_cndmask_b32_e32 v138, v142, v138, vcc
	v_lshl_add_u64 v[142:143], v[144:145], 4, s[92:93]
	global_load_dwordx4 v[154:157], v[142:143], off
	v_rsq_f32_e32 v138, v138
	s_waitcnt vmcnt(0)
	v_mov_b32_e32 v142, v155
	v_mov_b32_e32 v143, v156
	v_mov_b32_e32 v155, v157
	v_pk_add_f32 v[158:159], v[142:143], v[154:155]
	v_or_b32_e32 v142, 48, v147
	v_mul_f32_e32 v140, 0x45800000, v138
	v_ashrrev_i32_e32 v143, 31, v142
	v_lshl_add_u64 v[154:155], v[142:143], 4, s[92:93]
	global_load_dwordx4 v[154:157], v[154:155], off
	v_cndmask_b32_e32 v138, v138, v140, vcc
	v_pk_mul_f32 v[110:111], v[110:111], v[138:139] op_sel_hi:[1,0]
	v_pk_mul_f32 v[108:109], v[108:109], v[138:139] op_sel_hi:[1,0]
	v_pk_mul_f32 v[102:103], v[102:103], v[138:139] op_sel_hi:[1,0]
	v_pk_mul_f32 v[100:101], v[100:101], v[138:139] op_sel_hi:[1,0]
	s_waitcnt vmcnt(0)
	v_mov_b32_e32 v160, v155
	v_mov_b32_e32 v161, v156
	v_mov_b32_e32 v155, v157
	v_pk_add_f32 v[154:155], v[160:161], v[154:155]
	v_mov_b32_e32 v157, v158
	v_mov_b32_e32 v156, v154
	v_mov_b32_e32 v158, v155
	v_pk_add_f32 v[154:155], v[156:157], v[158:159]
	s_nop 0
	v_pk_fma_f32 v[154:155], v[154:155], s[82:83], v[134:135] op_sel_hi:[1,0,0]
	s_nop 0
	v_mul_f32_e32 v140, 0x4b800000, v155
	v_cmp_gt_f32_e64 s[38:39], s48, v155
	v_cmp_gt_f32_e32 vcc, s48, v154
	s_nop 0
	v_cndmask_b32_e64 v140, v155, v140, s[38:39]
	v_rsq_f32_e32 v140, v140
	s_nop 0
	v_mul_f32_e32 v146, 0x45800000, v140
	v_cndmask_b32_e64 v146, v140, v146, s[38:39]
	v_mul_f32_e32 v140, 0x4b800000, v154
	v_cndmask_b32_e32 v140, v154, v140, vcc
	v_rsq_f32_e32 v140, v140
	v_pk_mul_f32 v[94:95], v[94:95], v[146:147] op_sel_hi:[1,0]
	v_pk_mul_f32 v[92:93], v[92:93], v[146:147] op_sel_hi:[1,0]
	v_pk_mul_f32 v[86:87], v[86:87], v[146:147] op_sel_hi:[1,0]
	v_mul_f32_e32 v153, 0x45800000, v140
	v_pk_mul_f32 v[112:113], v[112:113], v[152:153] op_sel_hi:[1,0]
	v_pk_mul_f32 v[114:115], v[114:115], v[152:153] op_sel_hi:[1,0]
	v_cvt_pk_bf16_f32 v112, v112, v113
	v_pk_mul_f32 v[118:119], v[118:119], v[152:153] op_sel_hi:[1,0]
	v_cvt_pk_bf16_f32 v113, v114, v115
	v_pk_mul_f32 v[116:117], v[116:117], v[152:153] op_sel_hi:[1,0]
	v_pk_mul_f32 v[84:85], v[84:85], v[146:147] op_sel_hi:[1,0]
	v_cvt_pk_bf16_f32 v114, v116, v117
	v_cvt_pk_bf16_f32 v115, v118, v119
	global_store_dwordx4 v[150:151], v[112:115], off sc1
	v_pk_mul_f32 v[116:117], v[126:127], v[152:153] op_sel_hi:[1,0]
	v_pk_mul_f32 v[118:119], v[124:125], v[152:153] op_sel_hi:[1,0]
	v_pk_mul_f32 v[112:113], v[120:121], v[152:153] op_sel_hi:[1,0]
	v_pk_mul_f32 v[114:115], v[122:123], v[152:153] op_sel_hi:[1,0]
	v_cvt_pk_bf16_f32 v112, v112, v113
	v_cndmask_b32_e32 v140, v140, v153, vcc
	v_cvt_pk_bf16_f32 v113, v114, v115
	v_cvt_pk_bf16_f32 v114, v118, v119
	v_cvt_pk_bf16_f32 v115, v116, v117
	global_store_dwordx4 v[150:151], v[112:115], off offset:256 sc1
	v_pk_mul_f32 v[78:79], v[78:79], v[140:141] op_sel_hi:[1,0]
	v_pk_mul_f32 v[76:77], v[76:77], v[140:141] op_sel_hi:[1,0]
	v_lshlrev_b64 v[112:113], 10, v[148:149]
	v_lshl_add_u64 v[112:113], s[18:19], 0, v[112:113]
	v_lshl_add_u64 v[112:113], v[112:113], 0, v[136:137]
	v_pk_mul_f32 v[114:115], v[106:107], v[138:139] op_sel_hi:[1,0]
	v_pk_mul_f32 v[106:107], v[104:105], v[138:139] op_sel_hi:[1,0]
	v_cvt_pk_bf16_f32 v104, v108, v109
	v_cvt_pk_bf16_f32 v105, v110, v111
	v_pk_mul_f32 v[68:69], v[68:69], v[140:141] op_sel_hi:[1,0]
	v_cvt_pk_bf16_f32 v106, v106, v107
	v_cvt_pk_bf16_f32 v107, v114, v115
	global_store_dwordx4 v[112:113], v[104:107], off sc1
	v_pk_mul_f32 v[70:71], v[70:71], v[140:141] op_sel_hi:[1,0]
	s_nop 0
	v_pk_mul_f32 v[104:105], v[98:99], v[138:139] op_sel_hi:[1,0]
	v_pk_mul_f32 v[98:99], v[96:97], v[138:139] op_sel_hi:[1,0]
	v_cvt_pk_bf16_f32 v96, v100, v101
	v_cvt_pk_bf16_f32 v97, v102, v103
	s_nop 0
	v_cvt_pk_bf16_f32 v98, v98, v99
	v_cvt_pk_bf16_f32 v99, v104, v105
	global_store_dwordx4 v[112:113], v[96:99], off offset:256 sc1
;     __device__ __forceinline__ RowPre pre_row(int row, int) const { const float ss = NSLOT == 8 ? sum8(part + (size_t)row * 8) : sum4(part + (size_t)row * 4); return PreRs{rsqrtf(ss * inv_k + EPS)}; }
;     __device__ __forceinline__ void operator()(const pg8::f32x4 (&acc)[2][2][4][2], const pg8::Unit& u, int wr, int wc, int, int, int ui) const {
;     ...
;         for (int g = 0; g < 8; g += NB) {
;             typename F::RowPre rp[NB]; int rows[NB]; float rv[NB];
; #pragma unroll
;             for (int j = 0; j < NB; ++j) { const int ai = (g + j) >> 2, mm = (g + j) & 3; const int rl = ai * 128 + wr * 64 + mm * 16 + fr; int row = u.pm * 256 + rl; asm volatile("" : "+v"(row)); rows[j] = row;
;                 rv[j] = F::USE_TAB ? tab[rl] : 0.f; rp[j] = f.pre_row(row, col); }
; #pragma unroll
;             for (int j = 0; j < NB; ++j) { const int ai = (g + j) >> 2, mm = (g + j) & 3; f.apply(rows[j], col, rv[j], cv, rp[j], acc[ai][0][mm][0], acc[ai][0][mm][1], acc[ai][1][mm][0], acc[ai][1][mm][1]); }
;             asm volatile("" ::: "memory");
;         }
	s_nop 1
	v_lshlrev_b64 v[96:97], 10, v[144:145]
	v_lshl_add_u64 v[96:97], s[18:19], 0, v[96:97]
	v_lshl_add_u64 v[96:97], v[96:97], 0, v[136:137]
	v_pk_mul_f32 v[98:99], v[90:91], v[146:147] op_sel_hi:[1,0]
	v_pk_mul_f32 v[90:91], v[88:89], v[146:147] op_sel_hi:[1,0]
	v_cvt_pk_bf16_f32 v88, v92, v93
	v_cvt_pk_bf16_f32 v89, v94, v95
	s_nop 0
	v_cvt_pk_bf16_f32 v90, v90, v91
	v_cvt_pk_bf16_f32 v91, v98, v99
	global_store_dwordx4 v[96:97], v[88:91], off sc1
	s_nop 1
	v_pk_mul_f32 v[88:89], v[82:83], v[146:147] op_sel_hi:[1,0]
	v_pk_mul_f32 v[82:83], v[80:81], v[146:147] op_sel_hi:[1,0]
	v_cvt_pk_bf16_f32 v80, v84, v85
	v_cvt_pk_bf16_f32 v81, v86, v87
	s_nop 0
	v_cvt_pk_bf16_f32 v82, v82, v83
	v_cvt_pk_bf16_f32 v83, v88, v89
	global_store_dwordx4 v[96:97], v[80:83], off offset:256 sc1
	s_nop 1
	v_lshlrev_b64 v[80:81], 10, v[142:143]
	v_lshl_add_u64 v[80:81], s[18:19], 0, v[80:81]
	v_lshl_add_u64 v[80:81], v[80:81], 0, v[136:137]
	v_pk_mul_f32 v[82:83], v[74:75], v[140:141] op_sel_hi:[1,0]
	v_pk_mul_f32 v[74:75], v[72:73], v[140:141] op_sel_hi:[1,0]
	v_cvt_pk_bf16_f32 v72, v76, v77
	v_cvt_pk_bf16_f32 v73, v78, v79
	s_nop 0
	v_cvt_pk_bf16_f32 v74, v74, v75
	v_cvt_pk_bf16_f32 v75, v82, v83
	global_store_dwordx4 v[80:81], v[72:75], off sc1
	s_nop 1
	v_pk_mul_f32 v[72:73], v[66:67], v[140:141] op_sel_hi:[1,0]
	v_pk_mul_f32 v[66:67], v[64:65], v[140:141] op_sel_hi:[1,0]
	v_cvt_pk_bf16_f32 v64, v68, v69
	v_cvt_pk_bf16_f32 v65, v70, v71
	v_add_u32_e32 v68, 0x80, v147
	v_cvt_pk_bf16_f32 v66, v66, v67
	v_cvt_pk_bf16_f32 v67, v72, v73
	global_store_dwordx4 v[80:81], v[64:67], off offset:256 sc1
	s_nop 0
	v_ashrrev_i32_e32 v69, 31, v68
	v_lshl_add_u64 v[64:65], v[68:69], 4, s[92:93]
	global_load_dwordx4 v[64:67], v[64:65], off
	v_lshlrev_b64 v[68:69], 10, v[68:69]
	v_lshl_add_u64 v[68:69], s[18:19], 0, v[68:69]
	v_lshl_add_u64 v[68:69], v[68:69], 0, v[136:137]
	s_waitcnt vmcnt(0)
	v_mov_b32_e32 v71, v66
	v_add_u32_e32 v66, 0x90, v147
	v_mov_b32_e32 v70, v65
	v_mov_b32_e32 v65, v67
	v_pk_add_f32 v[64:65], v[70:71], v[64:65]
	v_ashrrev_i32_e32 v67, 31, v66
	v_lshl_add_u64 v[70:71], v[66:67], 4, s[92:93]
	global_load_dwordx4 v[70:73], v[70:71], off
	s_waitcnt vmcnt(0)
	v_mov_b32_e32 v74, v71
	v_mov_b32_e32 v75, v72
	v_mov_b32_e32 v71, v73
	v_pk_add_f32 v[70:71], v[74:75], v[70:71]
	v_add_u32_e32 v74, 0xa0, v147
	v_mov_b32_e32 v72, v70
	v_mov_b32_e32 v73, v64
	v_mov_b32_e32 v64, v71
	v_pk_add_f32 v[64:65], v[72:73], v[64:65]
	v_ashrrev_i32_e32 v75, 31, v74
	v_lshl_add_u64 v[72:73], v[74:75], 4, s[92:93]
	global_load_dwordx4 v[76:79], v[72:73], off
	v_pk_fma_f32 v[64:65], v[64:65], s[82:83], v[134:135] op_sel_hi:[1,0,0]
	s_waitcnt vmcnt(0)
	v_mov_b32_e32 v72, v77
	v_mov_b32_e32 v73, v78
	v_mov_b32_e32 v77, v79
	v_pk_add_f32 v[80:81], v[72:73], v[76:77]
	v_add_u32_e32 v72, 0xb0, v147
	v_mul_f32_e32 v70, 0x4b800000, v65
	v_ashrrev_i32_e32 v73, 31, v72
	v_lshl_add_u64 v[76:77], v[72:73], 4, s[92:93]
	global_load_dwordx4 v[76:79], v[76:77], off
	v_cmp_gt_f32_e64 s[38:39], s48, v65
	v_cmp_gt_f32_e32 vcc, s48, v64
	s_waitcnt vmcnt(0)
;     __device__ __forceinline__ RowPre pre_row(int row, int) const { const float ss = NSLOT == 8 ? sum8(part + (size_t)row * 8) : sum4(part + (size_t)row * 4); return PreRs{rsqrtf(ss * inv_k + EPS)}; }
;     __device__ __forceinline__ void operator()(const pg8::f32x4 (&acc)[2][2][4][2], const pg8::Unit& u, int wr, int wc, int, int, int ui) const {
;     ...
;         for (int g = 0; g < 8; g += NB) {
;             typename F::RowPre rp[NB]; int rows[NB]; float rv[NB];
; #pragma unroll
;             for (int j = 0; j < NB; ++j) { const int ai = (g + j) >> 2, mm = (g + j) & 3; const int rl = ai * 128 + wr * 64 + mm * 16 + fr; int row = u.pm * 256 + rl; asm volatile("" : "+v"(row)); rows[j] = row;
;                 rv[j] = F::USE_TAB ? tab[rl] : 0.f; rp[j] = f.pre_row(row, col); }
; #pragma unroll
;             for (int j = 0; j < NB; ++j) { const int ai = (g + j) >> 2, mm = (g + j) & 3; f.apply(rows[j], col, rv[j], cv, rp[j], acc[ai][0][mm][0], acc[ai][0][mm][1], acc[ai][1][mm][0], acc[ai][1][mm][1]); }
;             asm volatile("" ::: "memory");
;         }
	v_mov_b32_e32 v82, v77
	v_cndmask_b32_e64 v65, v65, v70, s[38:39]
	v_rsq_f32_e32 v65, v65
	v_mov_b32_e32 v83, v78
	v_mov_b32_e32 v77, v79
	v_pk_add_f32 v[76:77], v[82:83], v[76:77]
	v_mul_f32_e32 v70, 0x45800000, v65
	v_cndmask_b32_e64 v70, v65, v70, s[38:39]
	v_mul_f32_e32 v65, 0x4b800000, v64
	v_cndmask_b32_e32 v64, v64, v65, vcc
	v_rsq_f32_e32 v64, v64
	v_mov_b32_e32 v78, v76
	v_mov_b32_e32 v79, v80
	v_mov_b32_e32 v80, v77
	v_pk_add_f32 v[76:77], v[78:79], v[80:81]
	v_mul_f32_e32 v65, 0x45800000, v64
	v_pk_fma_f32 v[76:77], v[76:77], s[82:83], v[134:135] op_sel_hi:[1,0,0]
	v_cndmask_b32_e32 v64, v64, v65, vcc
	v_mul_f32_e32 v65, 0x4b800000, v77
	v_cmp_gt_f32_e64 s[38:39], s48, v77
	v_cmp_gt_f32_e32 vcc, s48, v76
	s_nop 0
	v_cndmask_b32_e64 v65, v77, v65, s[38:39]
	v_rsq_f32_e32 v65, v65
	s_nop 0
	v_mul_f32_e32 v71, 0x45800000, v65
	v_cndmask_b32_e64 v78, v65, v71, s[38:39]
	v_mul_f32_e32 v65, 0x4b800000, v76
	v_cndmask_b32_e32 v65, v76, v65, vcc
	v_rsq_f32_e32 v65, v65
	v_pk_mul_f32 v[30:31], v[30:31], v[78:79] op_sel_hi:[1,0]
	v_pk_mul_f32 v[28:29], v[28:29], v[78:79] op_sel_hi:[1,0]
	v_pk_mul_f32 v[22:23], v[22:23], v[78:79] op_sel_hi:[1,0]
	v_mul_f32_e32 v71, 0x45800000, v65
	v_pk_mul_f32 v[62:63], v[62:63], v[70:71] op_sel_hi:[1,0]
	v_pk_mul_f32 v[60:61], v[60:61], v[70:71] op_sel_hi:[1,0]
	v_pk_mul_f32 v[80:81], v[58:59], v[70:71] op_sel_hi:[1,0]
	v_pk_mul_f32 v[58:59], v[56:57], v[70:71] op_sel_hi:[1,0]
	v_cvt_pk_bf16_f32 v56, v60, v61
	v_cvt_pk_bf16_f32 v57, v62, v63
	v_pk_mul_f32 v[54:55], v[54:55], v[70:71] op_sel_hi:[1,0]
	v_cvt_pk_bf16_f32 v58, v58, v59
	v_cvt_pk_bf16_f32 v59, v80, v81
	global_store_dwordx4 v[68:69], v[56:59], off sc1
	v_pk_mul_f32 v[52:53], v[52:53], v[70:71] op_sel_hi:[1,0]
	v_pk_mul_f32 v[46:47], v[46:47], v[64:65] op_sel_hi:[1,0]
	v_pk_mul_f32 v[56:57], v[50:51], v[70:71] op_sel_hi:[1,0]
	v_pk_mul_f32 v[50:51], v[48:49], v[70:71] op_sel_hi:[1,0]
	v_cvt_pk_bf16_f32 v48, v52, v53
	v_cvt_pk_bf16_f32 v49, v54, v55
	v_pk_mul_f32 v[44:45], v[44:45], v[64:65] op_sel_hi:[1,0]
	v_cvt_pk_bf16_f32 v50, v50, v51
	v_cvt_pk_bf16_f32 v51, v56, v57
	global_store_dwordx4 v[68:69], v[48:51], off offset:256 sc1
	v_pk_mul_f32 v[38:39], v[38:39], v[64:65] op_sel_hi:[1,0]
	v_pk_mul_f32 v[36:37], v[36:37], v[64:65] op_sel_hi:[1,0]
	v_lshlrev_b64 v[48:49], 10, v[66:67]
	v_lshl_add_u64 v[48:49], s[18:19], 0, v[48:49]
	v_lshl_add_u64 v[48:49], v[48:49], 0, v[136:137]
	v_pk_mul_f32 v[50:51], v[42:43], v[64:65] op_sel_hi:[1,0]
	v_pk_mul_f32 v[42:43], v[40:41], v[64:65] op_sel_hi:[1,0]
	v_cvt_pk_bf16_f32 v40, v44, v45
	v_cvt_pk_bf16_f32 v41, v46, v47
	v_pk_mul_f32 v[20:21], v[20:21], v[78:79] op_sel_hi:[1,0]
	v_cvt_pk_bf16_f32 v42, v42, v43
	v_cvt_pk_bf16_f32 v43, v50, v51
	global_store_dwordx4 v[48:49], v[40:43], off sc1
	v_cndmask_b32_e32 v76, v65, v71, vcc
	v_pk_mul_f32 v[14:15], v[14:15], v[76:77] op_sel_hi:[1,0]
	v_pk_mul_f32 v[40:41], v[34:35], v[64:65] op_sel_hi:[1,0]
	v_pk_mul_f32 v[34:35], v[32:33], v[64:65] op_sel_hi:[1,0]
	v_cvt_pk_bf16_f32 v32, v36, v37
	v_cvt_pk_bf16_f32 v33, v38, v39
	v_pk_mul_f32 v[12:13], v[12:13], v[76:77] op_sel_hi:[1,0]
	v_cvt_pk_bf16_f32 v34, v34, v35
	v_cvt_pk_bf16_f32 v35, v40, v41
	global_store_dwordx4 v[48:49], v[32:35], off offset:256 sc1
	v_pk_mul_f32 v[6:7], v[6:7], v[76:77] op_sel_hi:[1,0]
	v_pk_mul_f32 v[4:5], v[4:5], v[76:77] op_sel_hi:[1,0]
	v_lshlrev_b64 v[32:33], 10, v[74:75]
	v_lshl_add_u64 v[32:33], s[18:19], 0, v[32:33]
	v_lshl_add_u64 v[32:33], v[32:33], 0, v[136:137]
	v_pk_mul_f32 v[34:35], v[26:27], v[78:79] op_sel_hi:[1,0]
	v_pk_mul_f32 v[26:27], v[24:25], v[78:79] op_sel_hi:[1,0]
	v_cvt_pk_bf16_f32 v24, v28, v29
	v_cvt_pk_bf16_f32 v25, v30, v31
	s_mov_b64 s[38:39], -1
	v_cvt_pk_bf16_f32 v26, v26, v27
	v_cvt_pk_bf16_f32 v27, v34, v35
	global_store_dwordx4 v[32:33], v[24:27], off sc1
	s_andn2_b64 vcc, exec, s[36:37]
	s_nop 0
	v_pk_mul_f32 v[24:25], v[18:19], v[78:79] op_sel_hi:[1,0]
	v_pk_mul_f32 v[18:19], v[16:17], v[78:79] op_sel_hi:[1,0]
	v_cvt_pk_bf16_f32 v16, v20, v21
	v_cvt_pk_bf16_f32 v17, v22, v23
	s_nop 0
	v_cvt_pk_bf16_f32 v18, v18, v19
	v_cvt_pk_bf16_f32 v19, v24, v25
	global_store_dwordx4 v[32:33], v[16:19], off offset:256 sc1
	s_nop 1
	v_lshlrev_b64 v[16:17], 10, v[72:73]
	v_lshl_add_u64 v[16:17], s[18:19], 0, v[16:17]
	v_lshl_add_u64 v[16:17], v[16:17], 0, v[136:137]
	v_pk_mul_f32 v[18:19], v[10:11], v[76:77] op_sel_hi:[1,0]
	v_pk_mul_f32 v[10:11], v[8:9], v[76:77] op_sel_hi:[1,0]
	v_cvt_pk_bf16_f32 v8, v12, v13
	v_cvt_pk_bf16_f32 v9, v14, v15
	s_nop 0
	v_cvt_pk_bf16_f32 v10, v10, v11
	v_cvt_pk_bf16_f32 v11, v18, v19
	global_store_dwordx4 v[16:17], v[8:11], off sc1
	s_nop 1
	v_pk_mul_f32 v[8:9], v[2:3], v[76:77] op_sel_hi:[1,0]
	v_pk_mul_f32 v[2:3], v[0:1], v[76:77] op_sel_hi:[1,0]
	v_cvt_pk_bf16_f32 v0, v4, v5
	v_cvt_pk_bf16_f32 v1, v6, v7
	s_nop 0
	v_cvt_pk_bf16_f32 v2, v2, v3
	v_cvt_pk_bf16_f32 v3, v8, v9
	global_store_dwordx4 v[16:17], v[0:3], off offset:256 sc1
	s_cbranch_vccnz .LBB0_570
	s_andn2_b64 vcc, exec, s[40:41]
	s_cbranch_vccnz .LBB0_569
	s_barrier
	s_branch .LBB0_569

; __device__ __forceinline__ float sum4(const float* p) { return hsum4(*(const f32x4*)p); }
;     __device__ __forceinline__ Pre4 pre_col(int col) const { Pre4 p;
; #pragma unroll
;         for (int i = 0; i < 4; ++i) { p.v[0][i] = rsqrtf(sum4(pckv + (size_t)(col + i) * 4) * (1.f / 256.f) + EPS); p.v[1][i] = rsqrtf(sum4(pckv + (size_t)(col + 4 + i) * 4) * (1.f / 256.f) + EPS);
;             p.v[2][i] = rsqrtf(sum4(pckv + (size_t)(col + 128 + i) * 4) * (1.f / 256.f) + EPS); p.v[3][i] = rsqrtf(sum4(pckv + (size_t)(col + 132 + i) * 4) * (1.f / 256.f) + EPS); }
;         return p; }
.LBB0_597:
	v_mbcnt_lo_u32_b32 v166, -1, 0
	v_mbcnt_hi_u32_b32 v166, -1, v166
	s_lshl_b32 s3, s3, 8
	v_ashrrev_i32_e32 v128, 1, v166
	s_or_b32 s3, s3, s70
	v_and_b32_e32 v128, -8, v128
	v_add_u32_e32 v152, s3, v128
	s_mov_b32 s6, 0x358637bd
	v_ashrrev_i32_e32 v153, 31, v152
	v_lshl_add_u64 v[162:163], v[152:153], 4, s[92:93]
	global_load_dwordx4 v[144:147], v[162:163], off
	global_load_dwordx4 v[148:151], v[162:163], off offset:64
	global_load_dwordx4 v[132:135], v[162:163], off offset:2048
	global_load_dwordx4 v[128:131], v[162:163], off offset:2112
	global_load_dwordx4 v[154:157], v[162:163], off offset:16
	s_mov_b32 s77, s55
	s_waitcnt vmcnt(0)
	v_mov_b32_e32 v158, v144
	v_mov_b32_e32 v159, v154
	v_mov_b32_e32 v154, v145
	v_pk_add_f32 v[144:145], v[158:159], v[154:155]
	v_mov_b32_e32 v154, v146
	v_mov_b32_e32 v155, v156
	v_mov_b32_e32 v156, v147
	v_pk_add_f32 v[146:147], v[154:155], v[156:157]
	global_load_dwordx4 v[156:159], v[162:163], off offset:80
	v_pk_add_f32 v[144:145], v[144:145], v[146:147]
	v_mov_b64_e32 v[154:155], s[6:7]
	v_pk_fma_f32 v[144:145], v[144:145], s[82:83], v[154:155] op_sel_hi:[1,0,0]
	s_mov_b32 s6, 0x45800000
	v_mul_f32_e32 v146, 0x4b800000, v144
	v_cmp_gt_f32_e64 s[36:37], s48, v144
	v_cmp_gt_f32_e32 vcc, s48, v145
	s_nop 0
	v_cndmask_b32_e64 v144, v144, v146, s[36:37]
	v_mul_f32_e32 v146, 0x4b800000, v145
	v_cndmask_b32_e32 v145, v145, v146, vcc
	v_rsq_f32_e32 v144, v144
	v_rsq_f32_e32 v145, v145
	s_nop 0
	v_pk_mul_f32 v[146:147], v[144:145], s[6:7] op_sel_hi:[1,0]
	s_nop 0
	v_cndmask_b32_e32 v145, v145, v147, vcc
	v_cndmask_b32_e64 v144, v144, v146, s[36:37]
	v_mov_b32_e32 v146, v148
	v_mov_b32_e32 v148, v150
	v_pk_mul_f32 v[124:125], v[124:125], v[144:145]
	v_pk_mul_f32 v[108:109], v[108:109], v[144:145]
	v_pk_mul_f32 v[92:93], v[92:93], v[144:145]
	v_pk_mul_f32 v[76:77], v[76:77], v[144:145]
	v_pk_mul_f32 v[60:61], v[60:61], v[144:145]
	v_pk_mul_f32 v[44:45], v[44:45], v[144:145]
	v_pk_mul_f32 v[28:29], v[28:29], v[144:145]
	v_pk_mul_f32 v[12:13], v[12:13], v[144:145]
	s_waitcnt vmcnt(0)
	v_mov_b32_e32 v147, v156
	v_mov_b32_e32 v156, v149
	v_mov_b32_e32 v149, v158
	v_mov_b32_e32 v158, v151
	v_pk_add_f32 v[146:147], v[146:147], v[156:157]
	v_pk_add_f32 v[148:149], v[148:149], v[158:159]
	v_mov_b32_e32 v156, v132
	v_pk_add_f32 v[146:147], v[146:147], v[148:149]
	s_nop 0
	v_pk_fma_f32 v[146:147], v[146:147], s[82:83], v[154:155] op_sel_hi:[1,0,0]
	s_nop 0
	v_mul_f32_e32 v148, 0x4b800000, v146
	v_cmp_gt_f32_e64 s[36:37], s48, v146
	v_cmp_gt_f32_e32 vcc, s48, v147
	s_nop 0
	v_cndmask_b32_e64 v146, v146, v148, s[36:37]
	v_mul_f32_e32 v148, 0x4b800000, v147
	v_cndmask_b32_e32 v147, v147, v148, vcc
	v_rsq_f32_e32 v146, v146
	v_rsq_f32_e32 v147, v147
	s_nop 0
	v_pk_mul_f32 v[148:149], v[146:147], s[6:7] op_sel_hi:[1,0]
	s_nop 0
	v_cndmask_b32_e32 v147, v147, v149, vcc
	v_cndmask_b32_e64 v146, v146, v148, s[36:37]
	global_load_dwordx4 v[148:151], v[162:163], off offset:2064
	s_waitcnt vmcnt(0)
	v_mov_b32_e32 v157, v148
	v_mov_b32_e32 v148, v133
	v_pk_add_f32 v[132:133], v[156:157], v[148:149]
	v_mov_b32_e32 v148, v134
	v_mov_b32_e32 v149, v150
	v_mov_b32_e32 v150, v135
	v_pk_add_f32 v[134:135], v[148:149], v[150:151]
	v_mov_b32_e32 v150, v128
	v_pk_add_f32 v[132:133], v[132:133], v[134:135]
	s_nop 0
	v_pk_fma_f32 v[132:133], v[132:133], s[82:83], v[154:155] op_sel_hi:[1,0,0]
	s_nop 0
	v_mul_f32_e32 v134, 0x4b800000, v132
	v_cmp_gt_f32_e64 s[36:37], s48, v132
	v_cmp_gt_f32_e32 vcc, s48, v133
	s_nop 0
	v_cndmask_b32_e64 v132, v132, v134, s[36:37]
	v_mul_f32_e32 v134, 0x4b800000, v133
	v_cndmask_b32_e32 v133, v133, v134, vcc
	v_rsq_f32_e32 v132, v132
	v_rsq_f32_e32 v133, v133
	s_nop 0
	v_pk_mul_f32 v[134:135], v[132:133], s[6:7] op_sel_hi:[1,0]
	s_nop 0
	v_cndmask_b32_e32 v149, v133, v135, vcc
	v_cndmask_b32_e64 v148, v132, v134, s[36:37]
	global_load_dwordx4 v[132:135], v[162:163], off offset:2128
	v_pk_mul_f32 v[116:117], v[116:117], v[148:149]
	v_pk_mul_f32 v[100:101], v[100:101], v[148:149]
	v_pk_mul_f32 v[84:85], v[84:85], v[148:149]
	v_pk_mul_f32 v[68:69], v[68:69], v[148:149]
	v_pk_mul_f32 v[52:53], v[52:53], v[148:149]
	v_pk_mul_f32 v[36:37], v[36:37], v[148:149]
	v_pk_mul_f32 v[20:21], v[20:21], v[148:149]
	v_pk_mul_f32 v[4:5], v[4:5], v[148:149]
	s_waitcnt vmcnt(0)
	v_mov_b32_e32 v151, v132
	v_mov_b32_e32 v132, v129
	v_pk_add_f32 v[128:129], v[150:151], v[132:133]
	v_mov_b32_e32 v132, v130
	v_mov_b32_e32 v133, v134
	v_mov_b32_e32 v134, v131
	v_pk_add_f32 v[130:131], v[132:133], v[134:135]
	s_nop 0
	v_pk_add_f32 v[128:129], v[128:129], v[130:131]
	s_nop 0
	v_pk_fma_f32 v[128:129], v[128:129], s[82:83], v[154:155] op_sel_hi:[1,0,0]
	s_nop 0
	v_mul_f32_e32 v130, 0x4b800000, v128
	v_cmp_gt_f32_e64 s[36:37], s48, v128
	v_cmp_gt_f32_e32 vcc, s48, v129
	s_nop 0
	v_cndmask_b32_e64 v128, v128, v130, s[36:37]
	v_mul_f32_e32 v130, 0x4b800000, v129
	v_cndmask_b32_e32 v129, v129, v130, vcc
	v_rsq_f32_e32 v128, v128
	v_rsq_f32_e32 v129, v129
	s_nop 0
	v_pk_mul_f32 v[130:131], v[128:129], s[6:7] op_sel_hi:[1,0]
	s_nop 0
	v_cndmask_b32_e32 v151, v129, v131, vcc
	v_cndmask_b32_e64 v150, v128, v130, s[36:37]
	global_load_dwordx4 v[156:159], v[162:163], off offset:32
	global_load_dwordx4 v[168:171], v[162:163], off offset:96
	global_load_dwordx4 v[132:135], v[162:163], off offset:2080
	global_load_dwordx4 v[128:131], v[162:163], off offset:2144
	global_load_dwordx4 v[172:175], v[162:163], off offset:48
	s_waitcnt vmcnt(4)
	v_mov_b32_e32 v160, v156
	s_waitcnt vmcnt(0)
; __device__ __forceinline__ float sum4(const float* p) { return hsum4(*(const f32x4*)p); }
;     __device__ __forceinline__ Pre4 pre_col(int col) const { Pre4 p;
; #pragma unroll
;         for (int i = 0; i < 4; ++i) { p.v[0][i] = rsqrtf(sum4(pckv + (size_t)(col + i) * 4) * (1.f / 256.f) + EPS); p.v[1][i] = rsqrtf(sum4(pckv + (size_t)(col + 4 + i) * 4) * (1.f / 256.f) + EPS);
;             p.v[2][i] = rsqrtf(sum4(pckv + (size_t)(col + 128 + i) * 4) * (1.f / 256.f) + EPS); p.v[3][i] = rsqrtf(sum4(pckv + (size_t)(col + 132 + i) * 4) * (1.f / 256.f) + EPS); }
;         return p; }
	v_mov_b32_e32 v161, v172
	v_mov_b32_e32 v172, v157
	v_pk_add_f32 v[156:157], v[160:161], v[172:173]
	v_mov_b32_e32 v160, v158
	v_mov_b32_e32 v161, v174
	v_mov_b32_e32 v174, v159
	v_pk_add_f32 v[158:159], v[160:161], v[174:175]
	v_mov_b32_e32 v172, v168
	v_pk_add_f32 v[156:157], v[156:157], v[158:159]
	v_mov_b32_e32 v168, v170
	v_pk_fma_f32 v[156:157], v[156:157], s[82:83], v[154:155] op_sel_hi:[1,0,0]
	s_nop 0
	v_mul_f32_e32 v153, 0x4b800000, v156
	v_cmp_gt_f32_e64 s[36:37], s48, v156
	v_cmp_gt_f32_e32 vcc, s48, v157
	s_nop 0
	v_cndmask_b32_e64 v153, v156, v153, s[36:37]
	v_rsq_f32_e32 v156, v153
	v_mul_f32_e32 v153, 0x4b800000, v157
	v_cndmask_b32_e32 v153, v157, v153, vcc
	v_rsq_f32_e32 v157, v153
	s_nop 0
	v_pk_mul_f32 v[158:159], v[156:157], s[6:7] op_sel_hi:[1,0]
	s_nop 0
	v_cndmask_b32_e32 v157, v157, v159, vcc
	v_cndmask_b32_e64 v156, v156, v158, s[36:37]
	global_load_dwordx4 v[158:161], v[162:163], off offset:112
	v_pk_mul_f32 v[126:127], v[126:127], v[156:157]
	v_pk_mul_f32 v[110:111], v[110:111], v[156:157]
	v_pk_mul_f32 v[94:95], v[94:95], v[156:157]
	v_pk_mul_f32 v[78:79], v[78:79], v[156:157]
	v_pk_mul_f32 v[62:63], v[62:63], v[156:157]
	v_pk_mul_f32 v[46:47], v[46:47], v[156:157]
	v_pk_mul_f32 v[30:31], v[30:31], v[156:157]
	v_pk_mul_f32 v[14:15], v[14:15], v[156:157]
	s_waitcnt vmcnt(0)
	v_mov_b32_e32 v173, v158
	v_mov_b32_e32 v158, v169
	v_mov_b32_e32 v169, v160
	v_mov_b32_e32 v160, v171
	v_pk_add_f32 v[160:161], v[168:169], v[160:161]
	global_load_dwordx4 v[168:171], v[162:163], off offset:2096
	v_pk_add_f32 v[158:159], v[172:173], v[158:159]
	s_nop 0
	v_pk_add_f32 v[158:159], v[158:159], v[160:161]
	s_nop 0
	v_pk_fma_f32 v[158:159], v[158:159], s[82:83], v[154:155] op_sel_hi:[1,0,0]
	s_nop 0
	v_mul_f32_e32 v153, 0x4b800000, v158
	v_cmp_gt_f32_e64 s[36:37], s48, v158
	v_cmp_gt_f32_e32 vcc, s48, v159
	s_nop 0
	v_cndmask_b32_e64 v153, v158, v153, s[36:37]
	v_rsq_f32_e32 v158, v153
	v_mul_f32_e32 v153, 0x4b800000, v159
	v_cndmask_b32_e32 v153, v159, v153, vcc
	v_rsq_f32_e32 v159, v153
	s_nop 0
	v_pk_mul_f32 v[160:161], v[158:159], s[6:7] op_sel_hi:[1,0]
	s_nop 0
	v_cndmask_b32_e32 v159, v159, v161, vcc
	v_cndmask_b32_e64 v158, v158, v160, s[36:37]
	v_mov_b32_e32 v160, v132
	s_waitcnt vmcnt(0)
	v_mov_b32_e32 v161, v168
	v_mov_b32_e32 v168, v133
	v_pk_add_f32 v[132:133], v[160:161], v[168:169]
	v_mov_b32_e32 v160, v134
	v_mov_b32_e32 v161, v170
	v_mov_b32_e32 v170, v135
	v_pk_add_f32 v[134:135], v[160:161], v[170:171]
	s_nop 0
	v_pk_add_f32 v[132:133], v[132:133], v[134:135]
	s_nop 0
	v_pk_fma_f32 v[132:133], v[132:133], s[82:83], v[154:155] op_sel_hi:[1,0,0]
	s_nop 0
	v_mul_f32_e32 v134, 0x4b800000, v132
	v_cmp_gt_f32_e64 s[36:37], s48, v132
	v_cmp_gt_f32_e32 vcc, s48, v133
	s_nop 0
	v_cndmask_b32_e64 v132, v132, v134, s[36:37]
	v_mul_f32_e32 v134, 0x4b800000, v133
	v_cndmask_b32_e32 v133, v133, v134, vcc
	v_rsq_f32_e32 v132, v132
	v_rsq_f32_e32 v133, v133
	s_nop 0
	v_pk_mul_f32 v[134:135], v[132:133], s[6:7] op_sel_hi:[1,0]
	s_nop 0
	v_cndmask_b32_e32 v161, v133, v135, vcc
	v_cndmask_b32_e64 v160, v132, v134, s[36:37]
	global_load_dwordx4 v[132:135], v[162:163], off offset:2160
	v_mov_b32_e32 v162, v128
	v_pk_mul_f32 v[118:119], v[118:119], v[160:161]
	v_pk_mul_f32 v[102:103], v[102:103], v[160:161]
	v_pk_mul_f32 v[86:87], v[86:87], v[160:161]
	v_pk_mul_f32 v[70:71], v[70:71], v[160:161]
	v_pk_mul_f32 v[54:55], v[54:55], v[160:161]
	v_pk_mul_f32 v[38:39], v[38:39], v[160:161]
	v_pk_mul_f32 v[22:23], v[22:23], v[160:161]
	v_pk_mul_f32 v[6:7], v[6:7], v[160:161]
	s_waitcnt vmcnt(0)
	v_mov_b32_e32 v163, v132
	v_mov_b32_e32 v132, v129
	v_pk_add_f32 v[128:129], v[162:163], v[132:133]
	v_mov_b32_e32 v132, v130
	v_mov_b32_e32 v133, v134
	v_mov_b32_e32 v134, v131
	v_pk_add_f32 v[130:131], v[132:133], v[134:135]
	v_and_b32_e32 v132, 0x1fff, v152
	v_pk_add_f32 v[128:129], v[128:129], v[130:131]
	v_lshlrev_b32_e32 v184, 1, v132
	v_pk_fma_f32 v[128:129], v[128:129], s[82:83], v[154:155] op_sel_hi:[1,0,0]
	v_pk_mul_f32 v[132:133], v[122:123], v[158:159]
	v_mul_f32_e32 v130, 0x4b800000, v128
	v_cmp_gt_f32_e64 s[36:37], s48, v128
	v_cmp_gt_f32_e32 vcc, s48, v129
	v_pk_mul_f32 v[122:123], v[120:121], v[146:147]
	v_cndmask_b32_e64 v128, v128, v130, s[36:37]
	v_mul_f32_e32 v130, 0x4b800000, v129
	v_cndmask_b32_e32 v129, v129, v130, vcc
	v_rsq_f32_e32 v128, v128
	v_rsq_f32_e32 v129, v129
	s_nop 0
	v_pk_mul_f32 v[130:131], v[128:129], s[6:7] op_sel_hi:[1,0]
	s_nop 0
	v_cndmask_b32_e64 v128, v128, v130, s[36:37]
	v_and_or_b32 v130, v166, 15, s69
	v_lshl_add_u32 v135, s78, 8, v130
	v_cndmask_b32_e32 v129, v129, v131, vcc
	v_ashrrev_i32_e32 v131, 4, v152
	v_mov_b32_e32 v130, v135
	v_and_b32_e32 v134, 0xfffffe00, v131
	v_or_b32_e32 v152, 16, v135
	v_add_u32_e32 v130, v130, v134
	v_ashrrev_i32_e32 v131, 31, v130
	v_lshlrev_b64 v[130:131], 14, v[130:131]
	v_or_b32_e32 v153, 32, v135
	v_or_b32_e32 v154, 48, v135
	v_lshl_add_u64 v[130:131], s[20:21], 0, v[130:131]
	v_lshl_add_u64 v[130:131], v[130:131], 0, v[184:185]
	v_cvt_pk_bf16_f32 v120, v124, v125
	v_cvt_pk_bf16_f32 v121, v126, v127
	v_cvt_pk_bf16_f32 v122, v122, v123
	v_cvt_pk_bf16_f32 v123, v132, v133
	global_store_dwordx4 v[130:131], v[120:123], off sc1
	s_mov_b64 s[36:37], -1
	s_andn2_b64 vcc, exec, s[34:35]
	v_pk_mul_f32 v[120:121], v[114:115], v[128:129]
	v_pk_mul_f32 v[114:115], v[112:113], v[150:151]
	v_cvt_pk_bf16_f32 v112, v116, v117
	v_cvt_pk_bf16_f32 v113, v118, v119
	s_nop 0
	v_cvt_pk_bf16_f32 v114, v114, v115
	v_cvt_pk_bf16_f32 v115, v120, v121
	global_store_dwordx4 v[130:131], v[112:115], off offset:256 sc1
	s_nop 1
	v_add_u32_e32 v112, v152, v134
	v_ashrrev_i32_e32 v113, 31, v112
;     __device__ __forceinline__ RowPre pre_row(int row, int) const { const float ss = NSLOT == 8 ? sum8(part + (size_t)row * 8) : sum4(part + (size_t)row * 4); return PreRs{rsqrtf(ss * inv_k + EPS)}; }
;     __device__ __forceinline__ void operator()(const pg8::f32x4 (&acc)[2][2][4][2], const pg8::Unit& u, int wr, int wc, int, int, int ui) const {
;     ...
;             for (int j = 0; j < NB; ++j) { const int ai = (g + j) >> 2, mm = (g + j) & 3; const int rl = ai * 128 + wr * 64 + mm * 16 + fr; int row = u.pm * 256 + rl; asm volatile("" : "+v"(row)); rows[j] = row;
;                 rv[j] = F::USE_TAB ? tab[rl] : 0.f; rp[j] = f.pre_row(row, col); }
; #pragma unroll
;             for (int j = 0; j < NB; ++j) { const int ai = (g + j) >> 2, mm = (g + j) & 3; f.apply(rows[j], col, rv[j], cv, rp[j], acc[ai][0][mm][0], acc[ai][0][mm][1], acc[ai][1][mm][0], acc[ai][1][mm][1]); }
;             asm volatile("" ::: "memory");
;         }
	v_lshlrev_b64 v[112:113], 14, v[112:113]
	v_lshl_add_u64 v[112:113], s[20:21], 0, v[112:113]
	v_lshl_add_u64 v[112:113], v[112:113], 0, v[184:185]
	v_pk_mul_f32 v[114:115], v[106:107], v[158:159]
	v_pk_mul_f32 v[106:107], v[104:105], v[146:147]
	v_cvt_pk_bf16_f32 v104, v108, v109
	v_cvt_pk_bf16_f32 v105, v110, v111
	s_nop 0
	v_cvt_pk_bf16_f32 v106, v106, v107
	v_cvt_pk_bf16_f32 v107, v114, v115
	global_store_dwordx4 v[112:113], v[104:107], off sc1
	s_nop 1
	v_pk_mul_f32 v[104:105], v[98:99], v[128:129]
	v_pk_mul_f32 v[98:99], v[96:97], v[150:151]
	v_cvt_pk_bf16_f32 v96, v100, v101
	v_cvt_pk_bf16_f32 v97, v102, v103
	s_nop 0
	v_cvt_pk_bf16_f32 v98, v98, v99
	v_cvt_pk_bf16_f32 v99, v104, v105
	global_store_dwordx4 v[112:113], v[96:99], off offset:256 sc1
	s_nop 1
	v_add_u32_e32 v96, v153, v134
	v_ashrrev_i32_e32 v97, 31, v96
	v_lshlrev_b64 v[96:97], 14, v[96:97]
	v_lshl_add_u64 v[96:97], s[20:21], 0, v[96:97]
	v_lshl_add_u64 v[96:97], v[96:97], 0, v[184:185]
	v_pk_mul_f32 v[98:99], v[90:91], v[158:159]
	v_pk_mul_f32 v[90:91], v[88:89], v[146:147]
	v_cvt_pk_bf16_f32 v88, v92, v93
	v_cvt_pk_bf16_f32 v89, v94, v95
	s_nop 0
	v_cvt_pk_bf16_f32 v90, v90, v91
	v_cvt_pk_bf16_f32 v91, v98, v99
	global_store_dwordx4 v[96:97], v[88:91], off sc1
	s_nop 1
	v_pk_mul_f32 v[88:89], v[82:83], v[128:129]
	v_pk_mul_f32 v[82:83], v[80:81], v[150:151]
	v_cvt_pk_bf16_f32 v80, v84, v85
	v_cvt_pk_bf16_f32 v81, v86, v87
	s_nop 0
	v_cvt_pk_bf16_f32 v82, v82, v83
	v_cvt_pk_bf16_f32 v83, v88, v89
	global_store_dwordx4 v[96:97], v[80:83], off offset:256 sc1
	s_nop 1
	v_add_u32_e32 v80, v154, v134
	v_ashrrev_i32_e32 v81, 31, v80
	v_lshlrev_b64 v[80:81], 14, v[80:81]
	v_lshl_add_u64 v[80:81], s[20:21], 0, v[80:81]
	v_lshl_add_u64 v[80:81], v[80:81], 0, v[184:185]
	v_pk_mul_f32 v[82:83], v[74:75], v[158:159]
	v_pk_mul_f32 v[74:75], v[72:73], v[146:147]
	v_cvt_pk_bf16_f32 v72, v76, v77
	v_cvt_pk_bf16_f32 v73, v78, v79
	s_nop 0
	v_cvt_pk_bf16_f32 v74, v74, v75
	v_cvt_pk_bf16_f32 v75, v82, v83
	global_store_dwordx4 v[80:81], v[72:75], off sc1
	s_nop 1
	v_pk_mul_f32 v[72:73], v[66:67], v[128:129]
	v_pk_mul_f32 v[66:67], v[64:65], v[150:151]
	v_cvt_pk_bf16_f32 v64, v68, v69
	v_cvt_pk_bf16_f32 v65, v70, v71
	v_add_u32_e32 v68, 0x90, v135
	v_cvt_pk_bf16_f32 v66, v66, v67
	v_cvt_pk_bf16_f32 v67, v72, v73
	global_store_dwordx4 v[80:81], v[64:67], off offset:256 sc1
	v_add_u32_e32 v69, 0xa0, v135
	v_add_u32_e32 v70, 0xb0, v135
	v_add_u32_e32 v64, 0x80, v135
	v_pk_mul_f32 v[66:67], v[58:59], v[158:159]
	v_add_u32_e32 v64, v64, v134
	v_ashrrev_i32_e32 v65, 31, v64
	v_lshlrev_b64 v[64:65], 14, v[64:65]
	v_lshl_add_u64 v[64:65], s[20:21], 0, v[64:65]
	v_lshl_add_u64 v[64:65], v[64:65], 0, v[184:185]
	v_pk_mul_f32 v[58:59], v[56:57], v[146:147]
	v_cvt_pk_bf16_f32 v56, v60, v61
	v_cvt_pk_bf16_f32 v57, v62, v63
	s_nop 0
	v_cvt_pk_bf16_f32 v58, v58, v59
	v_cvt_pk_bf16_f32 v59, v66, v67
	global_store_dwordx4 v[64:65], v[56:59], off sc1
	s_nop 1
	v_pk_mul_f32 v[56:57], v[50:51], v[128:129]
	v_pk_mul_f32 v[50:51], v[48:49], v[150:151]
	v_cvt_pk_bf16_f32 v48, v52, v53
	v_cvt_pk_bf16_f32 v49, v54, v55
	s_nop 0
	v_cvt_pk_bf16_f32 v50, v50, v51
	v_cvt_pk_bf16_f32 v51, v56, v57
	global_store_dwordx4 v[64:65], v[48:51], off offset:256 sc1
	s_nop 1
	v_add_u32_e32 v48, v68, v134
	v_ashrrev_i32_e32 v49, 31, v48
	v_lshlrev_b64 v[48:49], 14, v[48:49]
	v_lshl_add_u64 v[48:49], s[20:21], 0, v[48:49]
	v_lshl_add_u64 v[48:49], v[48:49], 0, v[184:185]
	v_pk_mul_f32 v[50:51], v[42:43], v[158:159]
	v_pk_mul_f32 v[42:43], v[40:41], v[146:147]
	v_cvt_pk_bf16_f32 v40, v44, v45
	v_cvt_pk_bf16_f32 v41, v46, v47
	s_nop 0
	v_cvt_pk_bf16_f32 v42, v42, v43
	v_cvt_pk_bf16_f32 v43, v50, v51
	global_store_dwordx4 v[48:49], v[40:43], off sc1
	s_nop 1
	v_pk_mul_f32 v[40:41], v[34:35], v[128:129]
	v_pk_mul_f32 v[34:35], v[32:33], v[150:151]
	v_cvt_pk_bf16_f32 v32, v36, v37
	v_cvt_pk_bf16_f32 v33, v38, v39
	s_nop 0
	v_cvt_pk_bf16_f32 v34, v34, v35
	v_cvt_pk_bf16_f32 v35, v40, v41
	global_store_dwordx4 v[48:49], v[32:35], off offset:256 sc1
	s_nop 1
	v_add_u32_e32 v32, v69, v134
	v_ashrrev_i32_e32 v33, 31, v32
	v_lshlrev_b64 v[32:33], 14, v[32:33]
	v_lshl_add_u64 v[32:33], s[20:21], 0, v[32:33]
	v_lshl_add_u64 v[32:33], v[32:33], 0, v[184:185]
	v_pk_mul_f32 v[34:35], v[26:27], v[158:159]
	v_pk_mul_f32 v[26:27], v[24:25], v[146:147]
	v_cvt_pk_bf16_f32 v24, v28, v29
	v_cvt_pk_bf16_f32 v25, v30, v31
	s_nop 0
	v_cvt_pk_bf16_f32 v26, v26, v27
	v_cvt_pk_bf16_f32 v27, v34, v35
	global_store_dwordx4 v[32:33], v[24:27], off sc1
	s_nop 1
	v_pk_mul_f32 v[24:25], v[18:19], v[128:129]
	v_pk_mul_f32 v[18:19], v[16:17], v[150:151]
	v_cvt_pk_bf16_f32 v16, v20, v21
	v_cvt_pk_bf16_f32 v17, v22, v23
	s_nop 0
	v_cvt_pk_bf16_f32 v18, v18, v19
	v_cvt_pk_bf16_f32 v19, v24, v25
	global_store_dwordx4 v[32:33], v[16:19], off offset:256 sc1
	s_nop 1
	v_add_u32_e32 v16, v70, v134
	v_ashrrev_i32_e32 v17, 31, v16
	v_lshlrev_b64 v[16:17], 14, v[16:17]
	v_lshl_add_u64 v[16:17], s[20:21], 0, v[16:17]
	v_lshl_add_u64 v[16:17], v[16:17], 0, v[184:185]
	v_pk_mul_f32 v[18:19], v[10:11], v[158:159]
	v_pk_mul_f32 v[10:11], v[8:9], v[146:147]
	v_cvt_pk_bf16_f32 v8, v12, v13
	v_cvt_pk_bf16_f32 v9, v14, v15
	s_nop 0
	v_cvt_pk_bf16_f32 v10, v10, v11
	v_cvt_pk_bf16_f32 v11, v18, v19
	global_store_dwordx4 v[16:17], v[8:11], off sc1
	s_nop 1
	v_pk_mul_f32 v[8:9], v[2:3], v[128:129]
	v_pk_mul_f32 v[2:3], v[0:1], v[150:151]
	v_cvt_pk_bf16_f32 v0, v4, v5
	v_cvt_pk_bf16_f32 v1, v6, v7
	s_nop 0
	v_cvt_pk_bf16_f32 v2, v2, v3
	v_cvt_pk_bf16_f32 v3, v8, v9
	global_store_dwordx4 v[16:17], v[0:3], off offset:256 sc1
	s_cbranch_vccnz .LBB0_588
	s_andn2_b64 vcc, exec, s[38:39]
	s_cbranch_vccnz .LBB0_587
	s_barrier
	s_branch .LBB0_587

; #define LAS __attribute__((address_space(3)))
; __device__ __forceinline__ void ssm_a_task(unsigned char* ws, LAS unsigned char* lds, int task, int tid) {
;     ...
;         for (int ks = 0; ks < 16; ++ks) {
;             bf16x8 bfr[4], afr[2];
; #pragma unroll
;             for (int a = 0; a < 2; ++a) afr[a] = *(const bf16x8*)(WA + (size_t)a * 16 * 1024 + (hh * 16 + ks) * 32);
; #pragma unroll
;             for (int c = 0; c < 4; ++c) bfr[c] = *(const LAS bf16x8*)(lds + SS_UB + (((2 * ks + (kk >> 1)) * 64 + c * 16 + rr) * 32 + (kk & 1) * 16));
; #pragma unroll
;             for (int a = 0; a < 2; ++a)
; #pragma unroll
;                 for (int c = 0; c < 4; ++c) acc[a][c] = __builtin_amdgcn_mfma_f32_16x16x32_bf16(afr[a], bfr[c], acc[a][c], 0, 0, 0);
;         }
.LBB0_606:
	v_add_co_u32_e32 v164, vcc, 0xffff8000, v38
	s_nop 1
	v_addc_co_u32_e32 v165, vcc, -1, v39, vcc
	v_add_u32_e32 v166, 0x10000, v47
	global_load_dwordx4 v[100:103], v[38:39], off offset:-192
	global_load_dwordx4 v[104:107], v[164:165], off offset:-192
	global_load_dwordx4 v[108:111], v[38:39], off offset:-128
	global_load_dwordx4 v[112:115], v[164:165], off offset:-128
	global_load_dwordx4 v[116:119], v[38:39], off offset:-64
	global_load_dwordx4 v[120:123], v[164:165], off offset:-64
	global_load_dwordx4 v[124:127], v[38:39], off offset:0
	global_load_dwordx4 v[128:131], v[164:165], off offset:0
	ds_read_b128 v[132:135], v166 offset:0
	ds_read_b128 v[136:139], v166 offset:512
	ds_read_b128 v[140:143], v166 offset:1024
	ds_read_b128 v[144:147], v166 offset:1536
	ds_read_b128 v[148:151], v166 offset:4096
	ds_read_b128 v[152:155], v166 offset:4608
	ds_read_b128 v[156:159], v166 offset:5120
	ds_read_b128 v[160:163], v166 offset:5632
	s_waitcnt lgkmcnt(4)
	s_waitcnt vmcnt(7)
	v_mfma_f32_16x16x32_bf16 v[12:15], v[100:103], v[132:135], v[12:15]
	v_mfma_f32_16x16x32_bf16 v[8:11], v[100:103], v[136:139], v[8:11]
	v_mfma_f32_16x16x32_bf16 v[4:7], v[100:103], v[140:143], v[4:7]
	v_mfma_f32_16x16x32_bf16 v[0:3], v[100:103], v[144:147], v[0:3]
	s_waitcnt vmcnt(6)
	v_mfma_f32_16x16x32_bf16 v[28:31], v[104:107], v[132:135], v[28:31]
	v_mfma_f32_16x16x32_bf16 v[24:27], v[104:107], v[136:139], v[24:27]
	v_mfma_f32_16x16x32_bf16 v[20:23], v[104:107], v[140:143], v[20:23]
	v_mfma_f32_16x16x32_bf16 v[16:19], v[104:107], v[144:147], v[16:19]
	global_load_dwordx4 v[100:103], v[38:39], off offset:64
	global_load_dwordx4 v[104:107], v[164:165], off offset:64
	ds_read_b128 v[132:135], v166 offset:8192
	ds_read_b128 v[136:139], v166 offset:8704
	ds_read_b128 v[140:143], v166 offset:9216
	ds_read_b128 v[144:147], v166 offset:9728
	s_waitcnt lgkmcnt(4)
	s_waitcnt vmcnt(7)
	v_mfma_f32_16x16x32_bf16 v[12:15], v[108:111], v[148:151], v[12:15]
	v_mfma_f32_16x16x32_bf16 v[8:11], v[108:111], v[152:155], v[8:11]
	v_mfma_f32_16x16x32_bf16 v[4:7], v[108:111], v[156:159], v[4:7]
	v_mfma_f32_16x16x32_bf16 v[0:3], v[108:111], v[160:163], v[0:3]
	s_waitcnt vmcnt(6)
	v_mfma_f32_16x16x32_bf16 v[28:31], v[112:115], v[148:151], v[28:31]
	v_mfma_f32_16x16x32_bf16 v[24:27], v[112:115], v[152:155], v[24:27]
	v_mfma_f32_16x16x32_bf16 v[20:23], v[112:115], v[156:159], v[20:23]
	v_mfma_f32_16x16x32_bf16 v[16:19], v[112:115], v[160:163], v[16:19]
	global_load_dwordx4 v[108:111], v[38:39], off offset:128
	global_load_dwordx4 v[112:115], v[164:165], off offset:128
	ds_read_b128 v[148:151], v166 offset:12288
	ds_read_b128 v[152:155], v166 offset:12800
	ds_read_b128 v[156:159], v166 offset:13312
	ds_read_b128 v[160:163], v166 offset:13824
	s_waitcnt lgkmcnt(4)
	s_waitcnt vmcnt(7)
	v_mfma_f32_16x16x32_bf16 v[12:15], v[116:119], v[132:135], v[12:15]
	v_mfma_f32_16x16x32_bf16 v[8:11], v[116:119], v[136:139], v[8:11]
	v_mfma_f32_16x16x32_bf16 v[4:7], v[116:119], v[140:143], v[4:7]
	v_mfma_f32_16x16x32_bf16 v[0:3], v[116:119], v[144:147], v[0:3]
	s_waitcnt vmcnt(6)
	v_mfma_f32_16x16x32_bf16 v[28:31], v[120:123], v[132:135], v[28:31]
	v_mfma_f32_16x16x32_bf16 v[24:27], v[120:123], v[136:139], v[24:27]
	v_mfma_f32_16x16x32_bf16 v[20:23], v[120:123], v[140:143], v[20:23]
	v_mfma_f32_16x16x32_bf16 v[16:19], v[120:123], v[144:147], v[16:19]
	global_load_dwordx4 v[116:119], v[38:39], off offset:192
	global_load_dwordx4 v[120:123], v[164:165], off offset:192
	ds_read_b128 v[132:135], v166 offset:16384
	ds_read_b128 v[136:139], v166 offset:16896
	ds_read_b128 v[140:143], v166 offset:17408
	ds_read_b128 v[144:147], v166 offset:17920
	s_waitcnt lgkmcnt(4)
	s_waitcnt vmcnt(7)
	v_mfma_f32_16x16x32_bf16 v[12:15], v[124:127], v[148:151], v[12:15]
	v_mfma_f32_16x16x32_bf16 v[8:11], v[124:127], v[152:155], v[8:11]
	v_mfma_f32_16x16x32_bf16 v[4:7], v[124:127], v[156:159], v[4:7]
	v_mfma_f32_16x16x32_bf16 v[0:3], v[124:127], v[160:163], v[0:3]
	s_waitcnt vmcnt(6)
	v_mfma_f32_16x16x32_bf16 v[28:31], v[128:131], v[148:151], v[28:31]
	v_mfma_f32_16x16x32_bf16 v[24:27], v[128:131], v[152:155], v[24:27]
	v_mfma_f32_16x16x32_bf16 v[20:23], v[128:131], v[156:159], v[20:23]
	v_mfma_f32_16x16x32_bf16 v[16:19], v[128:131], v[160:163], v[16:19]
	global_load_dwordx4 v[124:127], v[38:39], off offset:256
	global_load_dwordx4 v[128:131], v[164:165], off offset:256
	ds_read_b128 v[148:151], v166 offset:20480
	ds_read_b128 v[152:155], v166 offset:20992
	ds_read_b128 v[156:159], v166 offset:21504
	ds_read_b128 v[160:163], v166 offset:22016
	s_waitcnt lgkmcnt(4)
	s_waitcnt vmcnt(7)
	v_mfma_f32_16x16x32_bf16 v[12:15], v[100:103], v[132:135], v[12:15]
	v_mfma_f32_16x16x32_bf16 v[8:11], v[100:103], v[136:139], v[8:11]
	v_mfma_f32_16x16x32_bf16 v[4:7], v[100:103], v[140:143], v[4:7]
	v_mfma_f32_16x16x32_bf16 v[0:3], v[100:103], v[144:147], v[0:3]
	s_waitcnt vmcnt(6)
	v_mfma_f32_16x16x32_bf16 v[28:31], v[104:107], v[132:135], v[28:31]
	v_mfma_f32_16x16x32_bf16 v[24:27], v[104:107], v[136:139], v[24:27]
	v_mfma_f32_16x16x32_bf16 v[20:23], v[104:107], v[140:143], v[20:23]
	v_mfma_f32_16x16x32_bf16 v[16:19], v[104:107], v[144:147], v[16:19]
	global_load_dwordx4 v[100:103], v[38:39], off offset:320
	global_load_dwordx4 v[104:107], v[164:165], off offset:320
	ds_read_b128 v[132:135], v166 offset:24576
	ds_read_b128 v[136:139], v166 offset:25088
	ds_read_b128 v[140:143], v166 offset:25600
	ds_read_b128 v[144:147], v166 offset:26112
	s_waitcnt lgkmcnt(4)
	s_waitcnt vmcnt(7)
	v_mfma_f32_16x16x32_bf16 v[12:15], v[108:111], v[148:151], v[12:15]
	v_mfma_f32_16x16x32_bf16 v[8:11], v[108:111], v[152:155], v[8:11]
	v_mfma_f32_16x16x32_bf16 v[4:7], v[108:111], v[156:159], v[4:7]
	v_mfma_f32_16x16x32_bf16 v[0:3], v[108:111], v[160:163], v[0:3]
	s_waitcnt vmcnt(6)
; #define LAS __attribute__((address_space(3)))
; __device__ __forceinline__ void ssm_a_task(unsigned char* ws, LAS unsigned char* lds, int task, int tid) {
;     ...
;         for (int ks = 0; ks < 16; ++ks) {
;             bf16x8 bfr[4], afr[2];
; #pragma unroll
;             for (int a = 0; a < 2; ++a) afr[a] = *(const bf16x8*)(WA + (size_t)a * 16 * 1024 + (hh * 16 + ks) * 32);
; #pragma unroll
;             for (int c = 0; c < 4; ++c) bfr[c] = *(const LAS bf16x8*)(lds + SS_UB + (((2 * ks + (kk >> 1)) * 64 + c * 16 + rr) * 32 + (kk & 1) * 16));
; #pragma unroll
;             for (int a = 0; a < 2; ++a)
; #pragma unroll
;                 for (int c = 0; c < 4; ++c) acc[a][c] = __builtin_amdgcn_mfma_f32_16x16x32_bf16(afr[a], bfr[c], acc[a][c], 0, 0, 0);
;         }
	v_mfma_f32_16x16x32_bf16 v[28:31], v[112:115], v[148:151], v[28:31]
	v_mfma_f32_16x16x32_bf16 v[24:27], v[112:115], v[152:155], v[24:27]
	v_mfma_f32_16x16x32_bf16 v[20:23], v[112:115], v[156:159], v[20:23]
	v_mfma_f32_16x16x32_bf16 v[16:19], v[112:115], v[160:163], v[16:19]
	global_load_dwordx4 v[108:111], v[38:39], off offset:384
	global_load_dwordx4 v[112:115], v[164:165], off offset:384
	ds_read_b128 v[148:151], v166 offset:28672
	ds_read_b128 v[152:155], v166 offset:29184
	ds_read_b128 v[156:159], v166 offset:29696
	ds_read_b128 v[160:163], v166 offset:30208
	s_waitcnt lgkmcnt(4)
	s_waitcnt vmcnt(7)
	v_mfma_f32_16x16x32_bf16 v[12:15], v[116:119], v[132:135], v[12:15]
	v_mfma_f32_16x16x32_bf16 v[8:11], v[116:119], v[136:139], v[8:11]
	v_mfma_f32_16x16x32_bf16 v[4:7], v[116:119], v[140:143], v[4:7]
	v_mfma_f32_16x16x32_bf16 v[0:3], v[116:119], v[144:147], v[0:3]
	s_waitcnt vmcnt(6)
	v_mfma_f32_16x16x32_bf16 v[28:31], v[120:123], v[132:135], v[28:31]
	v_mfma_f32_16x16x32_bf16 v[24:27], v[120:123], v[136:139], v[24:27]
	v_mfma_f32_16x16x32_bf16 v[20:23], v[120:123], v[140:143], v[20:23]
	v_mfma_f32_16x16x32_bf16 v[16:19], v[120:123], v[144:147], v[16:19]
	global_load_dwordx4 v[116:119], v[38:39], off offset:448
	global_load_dwordx4 v[120:123], v[164:165], off offset:448
	ds_read_b128 v[132:135], v166 offset:32768
	ds_read_b128 v[136:139], v166 offset:33280
	ds_read_b128 v[140:143], v166 offset:33792
	ds_read_b128 v[144:147], v166 offset:34304
	s_waitcnt lgkmcnt(4)
	s_waitcnt vmcnt(7)
	v_mfma_f32_16x16x32_bf16 v[12:15], v[124:127], v[148:151], v[12:15]
	v_mfma_f32_16x16x32_bf16 v[8:11], v[124:127], v[152:155], v[8:11]
	v_mfma_f32_16x16x32_bf16 v[4:7], v[124:127], v[156:159], v[4:7]
	v_mfma_f32_16x16x32_bf16 v[0:3], v[124:127], v[160:163], v[0:3]
	s_waitcnt vmcnt(6)
	v_mfma_f32_16x16x32_bf16 v[28:31], v[128:131], v[148:151], v[28:31]
	v_mfma_f32_16x16x32_bf16 v[24:27], v[128:131], v[152:155], v[24:27]
	v_mfma_f32_16x16x32_bf16 v[20:23], v[128:131], v[156:159], v[20:23]
	v_mfma_f32_16x16x32_bf16 v[16:19], v[128:131], v[160:163], v[16:19]
	global_load_dwordx4 v[124:127], v[38:39], off offset:512
	global_load_dwordx4 v[128:131], v[164:165], off offset:512
	ds_read_b128 v[148:151], v166 offset:36864
	ds_read_b128 v[152:155], v166 offset:37376
	ds_read_b128 v[156:159], v166 offset:37888
	ds_read_b128 v[160:163], v166 offset:38400
	s_waitcnt lgkmcnt(4)
	s_waitcnt vmcnt(7)
	v_mfma_f32_16x16x32_bf16 v[12:15], v[100:103], v[132:135], v[12:15]
	v_mfma_f32_16x16x32_bf16 v[8:11], v[100:103], v[136:139], v[8:11]
	v_mfma_f32_16x16x32_bf16 v[4:7], v[100:103], v[140:143], v[4:7]
	v_mfma_f32_16x16x32_bf16 v[0:3], v[100:103], v[144:147], v[0:3]
	s_waitcnt vmcnt(6)
	v_mfma_f32_16x16x32_bf16 v[28:31], v[104:107], v[132:135], v[28:31]
	v_mfma_f32_16x16x32_bf16 v[24:27], v[104:107], v[136:139], v[24:27]
	v_mfma_f32_16x16x32_bf16 v[20:23], v[104:107], v[140:143], v[20:23]
	v_mfma_f32_16x16x32_bf16 v[16:19], v[104:107], v[144:147], v[16:19]
	global_load_dwordx4 v[100:103], v[38:39], off offset:576
	global_load_dwordx4 v[104:107], v[164:165], off offset:576
	ds_read_b128 v[132:135], v166 offset:40960
	ds_read_b128 v[136:139], v166 offset:41472
	ds_read_b128 v[140:143], v166 offset:41984
	ds_read_b128 v[144:147], v166 offset:42496
	s_waitcnt lgkmcnt(4)
	s_waitcnt vmcnt(7)
	v_mfma_f32_16x16x32_bf16 v[12:15], v[108:111], v[148:151], v[12:15]
	v_mfma_f32_16x16x32_bf16 v[8:11], v[108:111], v[152:155], v[8:11]
	v_mfma_f32_16x16x32_bf16 v[4:7], v[108:111], v[156:159], v[4:7]
	v_mfma_f32_16x16x32_bf16 v[0:3], v[108:111], v[160:163], v[0:3]
	s_waitcnt vmcnt(6)
	v_mfma_f32_16x16x32_bf16 v[28:31], v[112:115], v[148:151], v[28:31]
	v_mfma_f32_16x16x32_bf16 v[24:27], v[112:115], v[152:155], v[24:27]
	v_mfma_f32_16x16x32_bf16 v[20:23], v[112:115], v[156:159], v[20:23]
	v_mfma_f32_16x16x32_bf16 v[16:19], v[112:115], v[160:163], v[16:19]
	global_load_dwordx4 v[108:111], v[38:39], off offset:640
	global_load_dwordx4 v[112:115], v[164:165], off offset:640
	ds_read_b128 v[148:151], v166 offset:45056
	ds_read_b128 v[152:155], v166 offset:45568
	ds_read_b128 v[156:159], v166 offset:46080
	ds_read_b128 v[160:163], v166 offset:46592
	s_waitcnt lgkmcnt(4)
	s_waitcnt vmcnt(7)
	v_mfma_f32_16x16x32_bf16 v[12:15], v[116:119], v[132:135], v[12:15]
	v_mfma_f32_16x16x32_bf16 v[8:11], v[116:119], v[136:139], v[8:11]
	v_mfma_f32_16x16x32_bf16 v[4:7], v[116:119], v[140:143], v[4:7]
	v_mfma_f32_16x16x32_bf16 v[0:3], v[116:119], v[144:147], v[0:3]
	s_waitcnt vmcnt(6)
	v_mfma_f32_16x16x32_bf16 v[28:31], v[120:123], v[132:135], v[28:31]
	v_mfma_f32_16x16x32_bf16 v[24:27], v[120:123], v[136:139], v[24:27]
	v_mfma_f32_16x16x32_bf16 v[20:23], v[120:123], v[140:143], v[20:23]
	v_mfma_f32_16x16x32_bf16 v[16:19], v[120:123], v[144:147], v[16:19]
	global_load_dwordx4 v[116:119], v[38:39], off offset:704
	global_load_dwordx4 v[120:123], v[164:165], off offset:704
	ds_read_b128 v[132:135], v166 offset:49152
	ds_read_b128 v[136:139], v166 offset:49664
	ds_read_b128 v[140:143], v166 offset:50176
	ds_read_b128 v[144:147], v166 offset:50688
	s_waitcnt lgkmcnt(4)
; #define LAS __attribute__((address_space(3)))
; __device__ __forceinline__ void ssm_a_task(unsigned char* ws, LAS unsigned char* lds, int task, int tid) {
;     ...
;         for (int ks = 0; ks < 16; ++ks) {
;             bf16x8 bfr[4], afr[2];
; #pragma unroll
;             for (int a = 0; a < 2; ++a) afr[a] = *(const bf16x8*)(WA + (size_t)a * 16 * 1024 + (hh * 16 + ks) * 32);
; #pragma unroll
;             for (int c = 0; c < 4; ++c) bfr[c] = *(const LAS bf16x8*)(lds + SS_UB + (((2 * ks + (kk >> 1)) * 64 + c * 16 + rr) * 32 + (kk & 1) * 16));
; #pragma unroll
;             for (int a = 0; a < 2; ++a)
; #pragma unroll
;                 for (int c = 0; c < 4; ++c) acc[a][c] = __builtin_amdgcn_mfma_f32_16x16x32_bf16(afr[a], bfr[c], acc[a][c], 0, 0, 0);
;         }
;         __syncthreads();
;     }
;     float* S = (float*)(ws + AR_S);
; #pragma unroll
;     for (int a = 0; a < 2; ++a)
; #pragma unroll
;         for (int c = 0; c < 4; ++c) { const int col = cb * 64 + c * 16 + rr; *(f32x4*)(S + ((size_t)(col * NG + g) * 256 + wid * 32 + a * 16 + 4 * kk)) = acc[a][c]; }
	s_waitcnt vmcnt(7)
	v_mfma_f32_16x16x32_bf16 v[12:15], v[124:127], v[148:151], v[12:15]
	v_mfma_f32_16x16x32_bf16 v[8:11], v[124:127], v[152:155], v[8:11]
	v_mfma_f32_16x16x32_bf16 v[4:7], v[124:127], v[156:159], v[4:7]
	v_mfma_f32_16x16x32_bf16 v[0:3], v[124:127], v[160:163], v[0:3]
	s_waitcnt vmcnt(6)
	v_mfma_f32_16x16x32_bf16 v[28:31], v[128:131], v[148:151], v[28:31]
	v_mfma_f32_16x16x32_bf16 v[24:27], v[128:131], v[152:155], v[24:27]
	v_mfma_f32_16x16x32_bf16 v[20:23], v[128:131], v[156:159], v[20:23]
	v_mfma_f32_16x16x32_bf16 v[16:19], v[128:131], v[160:163], v[16:19]
	global_load_dwordx4 v[124:127], v[38:39], off offset:768
	global_load_dwordx4 v[128:131], v[164:165], off offset:768
	ds_read_b128 v[148:151], v166 offset:53248
	ds_read_b128 v[152:155], v166 offset:53760
	ds_read_b128 v[156:159], v166 offset:54272
	ds_read_b128 v[160:163], v166 offset:54784
	s_waitcnt lgkmcnt(4)
	s_waitcnt vmcnt(7)
	v_mfma_f32_16x16x32_bf16 v[12:15], v[100:103], v[132:135], v[12:15]
	v_mfma_f32_16x16x32_bf16 v[8:11], v[100:103], v[136:139], v[8:11]
	v_mfma_f32_16x16x32_bf16 v[4:7], v[100:103], v[140:143], v[4:7]
	v_mfma_f32_16x16x32_bf16 v[0:3], v[100:103], v[144:147], v[0:3]
	s_waitcnt vmcnt(6)
	v_mfma_f32_16x16x32_bf16 v[28:31], v[104:107], v[132:135], v[28:31]
	v_mfma_f32_16x16x32_bf16 v[24:27], v[104:107], v[136:139], v[24:27]
	v_mfma_f32_16x16x32_bf16 v[20:23], v[104:107], v[140:143], v[20:23]
	v_mfma_f32_16x16x32_bf16 v[16:19], v[104:107], v[144:147], v[16:19]
	ds_read_b128 v[132:135], v166 offset:57344
	ds_read_b128 v[136:139], v166 offset:57856
	ds_read_b128 v[140:143], v166 offset:58368
	ds_read_b128 v[144:147], v166 offset:58880
	s_waitcnt lgkmcnt(4)
	s_waitcnt vmcnt(5)
	v_mfma_f32_16x16x32_bf16 v[12:15], v[108:111], v[148:151], v[12:15]
	v_mfma_f32_16x16x32_bf16 v[8:11], v[108:111], v[152:155], v[8:11]
	v_mfma_f32_16x16x32_bf16 v[4:7], v[108:111], v[156:159], v[4:7]
	v_mfma_f32_16x16x32_bf16 v[0:3], v[108:111], v[160:163], v[0:3]
	s_waitcnt vmcnt(4)
	v_mfma_f32_16x16x32_bf16 v[28:31], v[112:115], v[148:151], v[28:31]
	v_mfma_f32_16x16x32_bf16 v[24:27], v[112:115], v[152:155], v[24:27]
	v_mfma_f32_16x16x32_bf16 v[20:23], v[112:115], v[156:159], v[20:23]
	v_mfma_f32_16x16x32_bf16 v[16:19], v[112:115], v[160:163], v[16:19]
	ds_read_b128 v[148:151], v166 offset:61440
	ds_read_b128 v[152:155], v166 offset:61952
	ds_read_b128 v[156:159], v166 offset:62464
	ds_read_b128 v[160:163], v166 offset:62976
	s_waitcnt lgkmcnt(4)
	s_waitcnt vmcnt(3)
	v_mfma_f32_16x16x32_bf16 v[12:15], v[116:119], v[132:135], v[12:15]
	v_mfma_f32_16x16x32_bf16 v[8:11], v[116:119], v[136:139], v[8:11]
	v_mfma_f32_16x16x32_bf16 v[4:7], v[116:119], v[140:143], v[4:7]
	v_mfma_f32_16x16x32_bf16 v[0:3], v[116:119], v[144:147], v[0:3]
	s_waitcnt vmcnt(2)
	v_mfma_f32_16x16x32_bf16 v[28:31], v[120:123], v[132:135], v[28:31]
	v_mfma_f32_16x16x32_bf16 v[24:27], v[120:123], v[136:139], v[24:27]
	v_mfma_f32_16x16x32_bf16 v[20:23], v[120:123], v[140:143], v[20:23]
	v_mfma_f32_16x16x32_bf16 v[16:19], v[120:123], v[144:147], v[16:19]
	s_waitcnt lgkmcnt(0)
	s_waitcnt vmcnt(1)
	v_mfma_f32_16x16x32_bf16 v[12:15], v[124:127], v[148:151], v[12:15]
	v_mfma_f32_16x16x32_bf16 v[8:11], v[124:127], v[152:155], v[8:11]
	v_mfma_f32_16x16x32_bf16 v[4:7], v[124:127], v[156:159], v[4:7]
	v_mfma_f32_16x16x32_bf16 v[0:3], v[124:127], v[160:163], v[0:3]
	s_waitcnt vmcnt(0)
	v_mfma_f32_16x16x32_bf16 v[28:31], v[128:131], v[148:151], v[28:31]
	v_mfma_f32_16x16x32_bf16 v[24:27], v[128:131], v[152:155], v[24:27]
	v_mfma_f32_16x16x32_bf16 v[20:23], v[128:131], v[156:159], v[20:23]
	v_mfma_f32_16x16x32_bf16 v[16:19], v[128:131], v[160:163], v[16:19]
	s_mov_b32 s3, 0x10000
	v_lshl_or_b32 v38, s17, 11, v45
	v_add_u32_e32 v38, s16, v38
	v_ashrrev_i32_e32 v39, 31, v38
	v_lshlrev_b64 v[40:41], 10, v[38:39]
	v_lshl_add_u64 v[40:41], v[32:33], 0, v[40:41]
	s_barrier
	global_store_dwordx4 v[40:41], v[28:31], off sc1
	s_add_i32 s54, s54, s76
	s_cmpk_gt_i32 s54, 0xff
	v_add_u32_e32 v28, 0x200, v38
	v_ashrrev_i32_e32 v29, 31, v28
	v_lshlrev_b64 v[28:29], 10, v[28:29]
	v_lshl_add_u64 v[28:29], v[32:33], 0, v[28:29]
	global_store_dwordx4 v[28:29], v[24:27], off sc1
	s_nop 1
	v_add_u32_e32 v24, 0x400, v38
	v_ashrrev_i32_e32 v25, 31, v24
	v_lshlrev_b64 v[24:25], 10, v[24:25]
	v_lshl_add_u64 v[24:25], v[32:33], 0, v[24:25]
	global_store_dwordx4 v[24:25], v[20:23], off sc1
	s_nop 1
	v_add_u32_e32 v20, 0x600, v38
	v_ashrrev_i32_e32 v21, 31, v20
	v_lshlrev_b64 v[20:21], 10, v[20:21]
	v_lshl_add_u64 v[20:21], v[32:33], 0, v[20:21]
	global_store_dwordx4 v[20:21], v[16:19], off sc1
	global_store_dwordx4 v[40:41], v[12:15], off offset:64 sc1
	global_store_dwordx4 v[28:29], v[8:11], off offset:64 sc1
	global_store_dwordx4 v[24:25], v[4:7], off offset:64 sc1
	global_store_dwordx4 v[20:21], v[0:3], off offset:64 sc1
	s_cbranch_scc0 .LBB0_603

; __device__ __forceinline__ void unpack8(u32x4 w, f32x4& a, f32x4& b) { a = (f32x4){bflo(w.x), bfhi(w.x), bflo(w.y), bfhi(w.y)}; b = (f32x4){bflo(w.z), bfhi(w.z), bflo(w.w), bfhi(w.w)}; }
; __device__ __forceinline__ float sumsq8(f32x4 a, f32x4 b) { return (a[0] * a[0] + a[1] * a[1]) + (a[2] * a[2] + a[3] * a[3]) + (b[0] * b[0] + b[1] * b[1]) + (b[2] * b[2] + b[3] * b[3]); }
; __device__ __forceinline__ void prep_item(unsigned char* ws, int l, int item, const int tid) {
;     ...
; #pragma unroll
;     for (int c = 0; c < 3; ++c) wraw[0][c] = *(const u32x4*)(Q + tok * 768 + h * 96 + (j + 4 * c) * 8);
; #pragma unroll
;     for (int c = 0; c < 2; ++c) wraw[1][c] = *(const u32x4*)(KN + tok * 512 + h * 64 + (j + 4 * c) * 8);
;     wraw[1][2] = *(const u32x4*)(KR + tok * 32 + j * 8);
; #pragma unroll
;     for (int e = 0; e < 8; ++e) csv[e] = rope[8 * (j & 1) + e];
; #pragma unroll
;     for (int which = 0; which < 2; ++which) {
;         f32x4 v[3][2];
; #pragma unroll
;         for (int c = 0; c < 3; ++c) unpack8(wraw[which][c], v[c][0], v[c][1]);
;         float ss = 0.f;
; #pragma unroll
;         for (int c = 0; c < 3; ++c) ss += sumsq8(v[c][0], v[c][1]);
;         ss += __shfl_xor(ss, 1); ss += __shfl_xor(ss, 2);
;         const float rs = rsqrtf(ss * (1.f / 96.f) + EPS);
;         const float* gn = which == 0 ? qg : kg;
; #pragma unroll
;         for (int c = 0; c < 3; ++c) { const f32x4 g0 = *(const f32x4*)(gn + (j + 4 * c) * 8), g1 = *(const f32x4*)(gn + (j + 4 * c) * 8 + 4); v[c][0] = v[c][0] * rs * g0; v[c][1] = v[c][1] * rs * g1; }
.LBB0_669:
	v_lshl_add_u64 v[56:57], v[52:53], 0, v[46:47]
	s_waitcnt vmcnt(0)
	v_add_co_u32_e32 v58, vcc, 0x13000000, v56
	v_lshl_add_u64 v[0:1], v[50:51], 0, v[46:47]
	s_nop 0
	v_addc_co_u32_e32 v59, vcc, 0, v57, vcc
	global_load_dwordx4 v[66:69], v[58:59], off
	global_load_dwordx4 v[90:93], v[58:59], off offset:64
	global_load_dwordx4 v[94:97], v[58:59], off offset:128
	v_and_b32_e32 v2, 0x1fff0, v54
	v_add_co_u32_e32 v0, vcc, s3, v0
	v_lshlrev_b32_e32 v184, 3, v2
	s_nop 0
	v_addc_co_u32_e32 v1, vcc, 0, v1, vcc
	global_load_dwordx4 v[20:23], v[0:1], off
	global_load_dwordx4 v[16:19], v[0:1], off offset:64
	v_lshl_add_u64 v[0:1], v[48:49], 0, v[46:47]
	v_lshl_add_u64 v[12:13], v[32:33], 0, v[184:185]
	global_load_dwordx4 v[24:27], v[0:1], off
	s_nop 0
	global_load_dwordx4 v[0:3], v[12:13], off offset:48
	global_load_dwordx4 v[4:7], v[12:13], off offset:32
	global_load_dwordx4 v[8:11], v[12:13], off offset:16
	s_nop 0
	global_load_dwordx4 v[12:15], v[12:13], off
	v_add_u32_e32 v30, s12, v30
	v_lshl_add_u64 v[48:49], v[48:49], 0, s[40:41]
	v_lshl_add_u64 v[50:51], v[50:51], 0, s[42:43]
	v_lshl_add_u64 v[52:53], v[52:53], 0, s[6:7]
	v_lshl_add_u64 v[54:55], v[54:55], 0, s[46:47]
	s_waitcnt vmcnt(9)
	v_and_b32_e32 v85, 0xffff0000, v67
	v_and_b32_e32 v83, 0xffff0000, v66
	v_and_b32_e32 v82, 0xffff0000, v68
	s_waitcnt vmcnt(7)
	v_and_b32_e32 v61, 0xffff0000, v97
	v_lshlrev_b32_e32 v84, 16, v67
	v_mul_f32_e32 v60, v85, v85
	v_lshlrev_b32_e32 v81, 16, v66
	v_lshlrev_b32_e32 v80, 16, v68
	v_pk_mul_f32 v[66:67], v[82:83], v[82:83]
	v_pk_fma_f32 v[70:71], v[84:85], v[84:85], v[60:61] op_sel_hi:[1,1,0]
	v_pk_fma_f32 v[66:67], v[80:81], v[80:81], v[66:67]
	v_and_b32_e32 v75, 0xffff0000, v90
	v_lshlrev_b32_e32 v78, 16, v69
	v_and_b32_e32 v79, 0xffff0000, v69
	v_pk_add_f32 v[68:69], v[66:67], v[70:71] op_sel:[1,0] op_sel_hi:[0,1]
	v_lshlrev_b32_e32 v74, 16, v90
	v_and_b32_e32 v77, 0xffff0000, v91
	v_mul_f32_e32 v60, v75, v75
	v_lshlrev_b32_e32 v64, 16, v95
	v_and_b32_e32 v65, 0xffff0000, v95
	v_pk_add_f32 v[98:99], v[66:67], v[68:69]
	v_lshlrev_b32_e32 v76, 16, v91
	v_lshlrev_b32_e32 v68, 16, v92
	v_and_b32_e32 v72, 0xffff0000, v92
	v_pk_mov_b32 v[70:71], v[92:93], v[96:97] op_sel:[1,0]
	v_lshlrev_b32_e32 v66, 16, v93
	v_pk_fma_f32 v[92:93], v[74:75], v[74:75], v[60:61] op_sel_hi:[1,1,0]
	v_mul_f32_e32 v60, v77, v77
	v_mul_f32_e32 v31, v64, v64
	v_mul_f32_e32 v89, v65, v65
	v_lshlrev_b32_e32 v69, 16, v94
	v_and_b32_e32 v73, 0xffff0000, v94
	v_pk_fma_f32 v[94:95], v[76:77], v[76:77], v[60:61] op_sel_hi:[1,1,0]
	v_pk_mul_f32 v[90:91], v[72:73], v[72:73]
	v_mov_b32_e32 v93, v31
	v_mov_b32_e32 v95, v89
	v_and_b32_e32 v71, 0xffff0000, v71
	v_and_b32_e32 v70, 0xffff0000, v70
	v_pk_fma_f32 v[90:91], v[68:69], v[68:69], v[90:91]
	v_pk_add_f32 v[92:93], v[92:93], v[94:95]
	v_lshlrev_b32_e32 v63, 16, v97
	v_lshlrev_b32_e32 v67, 16, v96
	v_pk_add_f32 v[90:91], v[90:91], v[92:93]
	v_pk_mul_f32 v[92:93], v[70:71], v[70:71]
	v_mul_f32_e32 v62, v78, v78
	v_mul_f32_e32 v100, v79, v79
	v_pk_fma_f32 v[92:93], v[66:67], v[66:67], v[92:93]
	v_mov_b32_e32 v101, v63
	v_pk_add_f32 v[90:91], v[92:93], v[90:91]
	v_pk_add_f32 v[92:93], v[62:63], v[100:101]
	v_pk_mul_f32 v[94:95], v[62:63], v[62:63]
	v_mul_f32_e32 v99, v61, v61
	v_mov_b32_e32 v93, v95
	v_pk_add_f32 v[92:93], v[92:93], v[98:99]
	v_mov_b32_e32 v98, v81
	v_pk_add_f32 v[90:91], v[92:93], v[90:91]
	v_mov_b32_e32 v81, v82
	v_add_f32_e32 v31, v90, v91
	global_load_dwordx4 v[90:93], v[34:35], off offset:16
	global_load_dwordx4 v[94:97], v[34:35], off
	ds_bpermute_b32 v60, v87, v31
	v_mov_b32_e32 v99, v83
	s_waitcnt lgkmcnt(0)
	v_add_f32_e32 v31, v31, v60
	ds_bpermute_b32 v60, v88, v31
	s_waitcnt lgkmcnt(0)
	v_add_f32_e32 v31, v31, v60
	v_fmamk_f32 v31, v31, 0x3c2aaaab, v248
	v_cmp_gt_f32_e32 vcc, s48, v31
	v_mul_f32_e32 v60, 0x4b800000, v31
	s_nop 0
	v_cndmask_b32_e32 v31, v31, v60, vcc
	v_rsq_f32_e32 v31, v31
	s_nop 0
	v_mul_f32_e32 v60, 0x45800000, v31
	v_cndmask_b32_e32 v62, v31, v60, vcc
	v_pk_mul_f32 v[84:85], v[84:85], v[62:63] op_sel_hi:[1,0]
	v_pk_mul_f32 v[78:79], v[62:63], v[78:79] op_sel_hi:[0,1]
	v_pk_mul_f32 v[80:81], v[62:63], v[80:81] op_sel_hi:[0,1]
	v_pk_mul_f32 v[76:77], v[62:63], v[76:77] op_sel_hi:[0,1]
	v_pk_mul_f32 v[74:75], v[62:63], v[74:75] op_sel_hi:[0,1]
	v_pk_mul_f32 v[98:99], v[98:99], v[62:63] op_sel_hi:[1,0]
	v_mov_b32_e32 v60, v63
	v_pk_mul_f32 v[64:65], v[62:63], v[64:65] op_sel_hi:[0,1]
	v_pk_mul_f32 v[60:61], v[60:61], v[62:63] op_sel_hi:[1,0]
	s_waitcnt vmcnt(1)
	v_pk_mul_f32 v[90:91], v[90:91], v[80:81]
	s_waitcnt vmcnt(0)
	v_pk_mul_f32 v[96:97], v[96:97], v[84:85]
	v_pk_mul_f32 v[92:93], v[92:93], v[78:79]
	global_load_dwordx4 v[78:81], v[36:37], off offset:16
	global_load_dwordx4 v[82:85], v[36:37], off
	v_pk_mul_f32 v[94:95], v[94:95], v[98:99]
	s_waitcnt vmcnt(0)
	v_pk_mul_f32 v[82:83], v[82:83], v[74:75]
	v_pk_mul_f32 v[84:85], v[84:85], v[76:77]
	v_mov_b32_e32 v74, v66
	v_mov_b32_e32 v75, v70
	v_mov_b32_e32 v76, v68
	v_mov_b32_e32 v77, v72
	v_pk_mul_f32 v[74:75], v[74:75], v[62:63] op_sel_hi:[1,0]
	v_pk_mul_f32 v[76:77], v[76:77], v[62:63] op_sel_hi:[1,0]
	v_pk_mul_f32 v[100:101], v[80:81], v[74:75]
	v_pk_mul_f32 v[98:99], v[78:79], v[76:77]
	global_load_dwordx4 v[74:77], v[38:39], off offset:16
	global_load_dwordx4 v[78:81], v[38:39], off
	v_mov_b32_e32 v72, v69
	v_pk_mul_f32 v[68:69], v[62:63], v[72:73] op_sel_hi:[0,1]
	v_mov_b32_e32 v70, v67
	v_pk_mul_f32 v[66:67], v[70:71], v[62:63] op_sel_hi:[1,0]
	s_waitcnt vmcnt(1)
	v_pk_mul_f32 v[60:61], v[76:77], v[60:61]
	s_waitcnt vmcnt(0)
; __device__ __forceinline__ u32x4 pack8(f32x4 a, f32x4 b) { u32x4 w; w.x = pk2(a[0], a[1]); w.y = pk2(a[2], a[3]); w.z = pk2(b[0], b[1]); w.w = pk2(b[2], b[3]); return w; }
; __device__ __forceinline__ void prep_item(unsigned char* ws, int l, int item, const int tid) {
;     ...
;         for (int c = 0; c < 3; ++c) { const f32x4 g0 = *(const f32x4*)(gn + (j + 4 * c) * 8), g1 = *(const f32x4*)(gn + (j + 4 * c) * 8 + 4); v[c][0] = v[c][0] * rs * g0; v[c][1] = v[c][1] * rs * g1; }
;         f32x4 o0, o1;
; #pragma unroll
;         for (int e = 0; e < 4; ++e) { o0[e] = __shfl_xor(v[2][0][e], 2); o1[e] = __shfl_xor(v[2][1][e], 2); }
; #pragma unroll
;         for (int e = 0; e < 8; ++e) { const f32x2 cs = csv[e]; const float mine = e < 4 ? v[2][0][e] : v[2][1][e - 4], oth = e < 4 ? o0[e] : o1[e - 4];
;             const float r = (j < 2) ? (mine * cs.x - oth * cs.y) : (oth * cs.y + mine * cs.x);
;             if (e < 4) v[2][0][e] = r; else v[2][1][e - 4] = r; }
;         if (which == 0) { const float sc = 0.10206207261596575f * 1.4426950408889634f;
; #pragma unroll
;             for (int c = 0; c < 3; ++c) { v[c][0] = v[c][0] * sc; v[c][1] = v[c][1] * sc; } }
;         bf16* dst = (which == 0 ? Q : K) + tok * 768 + h * 96;
; #pragma unroll
;         for (int c = 0; c < 3; ++c) *(u32x4*)(dst + (j + 4 * c) * 8) = pack8(v[c][0], v[c][1]);
	v_pk_mul_f32 v[68:69], v[78:79], v[68:69]
	v_pk_mul_f32 v[62:63], v[74:75], v[66:67]
	ds_bpermute_b32 v66, v88, v68
	ds_bpermute_b32 v67, v88, v69
	v_pk_mul_f32 v[64:65], v[80:81], v[64:65]
	ds_bpermute_b32 v72, v88, v64
	ds_bpermute_b32 v73, v88, v65
	v_mov_b32_e32 v78, v13
	v_mov_b32_e32 v79, v15
	s_waitcnt lgkmcnt(2)
	v_pk_mul_f32 v[66:67], v[78:79], v[66:67]
	ds_bpermute_b32 v70, v88, v62
	ds_bpermute_b32 v71, v88, v63
	v_mov_b32_e32 v76, v12
	v_mov_b32_e32 v77, v14
	v_cndmask_b32_e64 v67, v67, -v67, s[34:35]
	v_cndmask_b32_e64 v66, v66, -v66, s[34:35]
	v_pk_fma_f32 v[66:67], v[76:77], v[68:69], v[66:67]
	v_mov_b32_e32 v76, v9
	v_mov_b32_e32 v77, v11
	s_waitcnt lgkmcnt(2)
	v_pk_mul_f32 v[72:73], v[76:77], v[72:73]
	ds_bpermute_b32 v74, v88, v60
	ds_bpermute_b32 v75, v88, v61
	v_mov_b32_e32 v68, v8
	v_mov_b32_e32 v69, v10
	v_cndmask_b32_e64 v73, v73, -v73, s[34:35]
	v_cndmask_b32_e64 v72, v72, -v72, s[34:35]
	v_pk_fma_f32 v[64:65], v[68:69], v[64:65], v[72:73]
	v_mov_b32_e32 v72, v5
	v_mov_b32_e32 v73, v7
	s_waitcnt lgkmcnt(2)
	v_pk_mul_f32 v[70:71], v[72:73], v[70:71]
	v_mov_b32_e32 v68, v4
	v_mov_b32_e32 v69, v6
	v_cndmask_b32_e64 v71, v71, -v71, s[34:35]
	v_cndmask_b32_e64 v70, v70, -v70, s[34:35]
	v_pk_fma_f32 v[62:63], v[68:69], v[62:63], v[70:71]
	v_mov_b32_e32 v70, v1
	v_mov_b32_e32 v71, v3
	s_waitcnt lgkmcnt(0)
	v_pk_mul_f32 v[70:71], v[70:71], v[74:75]
	v_mov_b32_e32 v68, v0
	v_mov_b32_e32 v69, v2
	v_cndmask_b32_e64 v71, v71, -v71, s[34:35]
	v_cndmask_b32_e64 v70, v70, -v70, s[34:35]
	v_pk_fma_f32 v[60:61], v[68:69], v[60:61], v[70:71]
	v_pk_mul_f32 v[68:69], v[96:97], s[86:87] op_sel_hi:[1,0]
	v_pk_mul_f32 v[70:71], v[94:95], s[86:87] op_sel_hi:[1,0]
	v_pk_mul_f32 v[72:73], v[92:93], s[86:87] op_sel_hi:[1,0]
	v_pk_mul_f32 v[74:75], v[90:91], s[86:87] op_sel_hi:[1,0]
	v_pk_mul_f32 v[76:77], v[84:85], s[86:87] op_sel_hi:[1,0]
	v_pk_mul_f32 v[78:79], v[82:83], s[86:87] op_sel_hi:[1,0]
	v_pk_mul_f32 v[82:83], v[98:99], s[86:87] op_sel_hi:[1,0]
	v_pk_mul_f32 v[84:85], v[60:61], s[86:87] op_sel_hi:[1,0]
	v_pk_mul_f32 v[90:91], v[62:63], s[86:87] op_sel_hi:[1,0]
	v_cvt_pk_bf16_f32 v60, v70, v71
	v_cvt_pk_bf16_f32 v61, v68, v69
	v_cvt_pk_bf16_f32 v62, v74, v75
	v_cvt_pk_bf16_f32 v63, v72, v73
	v_pk_mul_f32 v[80:81], v[100:101], s[86:87] op_sel_hi:[1,0]
	global_store_dwordx4 v[58:59], v[60:63], off sc1
	v_pk_mul_f32 v[64:65], v[64:65], s[86:87] op_sel_hi:[1,0]
	v_pk_mul_f32 v[66:67], v[66:67], s[86:87] op_sel_hi:[1,0]
	v_cvt_pk_bf16_f32 v60, v78, v79
	v_cvt_pk_bf16_f32 v61, v76, v77
	v_cvt_pk_bf16_f32 v62, v82, v83
	v_cvt_pk_bf16_f32 v63, v80, v81
	v_and_b32_e32 v79, 0xffff0000, v21
	v_and_b32_e32 v83, 0xffff0000, v20
	v_and_b32_e32 v82, 0xffff0000, v22
	global_store_dwordx4 v[58:59], v[60:63], off offset:64 sc1
	v_lshlrev_b32_e32 v78, 16, v21
	v_lshlrev_b32_e32 v81, 16, v20
	v_cvt_pk_bf16_f32 v60, v66, v67
	v_cvt_pk_bf16_f32 v61, v64, v65
	v_cvt_pk_bf16_f32 v62, v90, v91
	v_cvt_pk_bf16_f32 v63, v84, v85
	global_store_dwordx4 v[58:59], v[60:63], off offset:128 sc1
	v_mul_f32_e32 v58, v79, v79
	v_lshlrev_b32_e32 v80, 16, v22
	v_pk_mul_f32 v[20:21], v[82:83], v[82:83]
	v_pk_fma_f32 v[58:59], v[78:79], v[78:79], v[58:59] op_sel_hi:[1,1,0]
	v_pk_fma_f32 v[20:21], v[80:81], v[80:81], v[20:21]
	v_and_b32_e32 v85, 0xffff0000, v16
	v_and_b32_e32 v91, 0xffff0000, v17
	v_lshlrev_b32_e32 v70, 16, v23
	v_and_b32_e32 v71, 0xffff0000, v23
	v_lshlrev_b32_e32 v72, 16, v25
	v_and_b32_e32 v73, 0xffff0000, v25
	v_pk_add_f32 v[22:23], v[20:21], v[58:59] op_sel:[1,0] op_sel_hi:[0,1]
	v_lshlrev_b32_e32 v84, 16, v16
	v_lshlrev_b32_e32 v90, 16, v17
	v_lshlrev_b32_e32 v92, 16, v18
	v_lshlrev_b32_e32 v93, 16, v24
	v_and_b32_e32 v95, 0xffff0000, v24
	v_and_b32_e32 v94, 0xffff0000, v18
	v_pk_mov_b32 v[16:17], v[18:19], v[26:27] op_sel:[1,0]
	v_mul_f32_e32 v18, v85, v85
	v_mul_f32_e32 v24, v91, v91
	v_pk_add_f32 v[20:21], v[20:21], v[22:23]
	v_mul_f32_e32 v23, v72, v72
	v_mul_f32_e32 v31, v73, v73
	v_lshlrev_b32_e32 v96, 16, v19
	v_pk_fma_f32 v[18:19], v[84:85], v[84:85], v[18:19] op_sel_hi:[1,1,0]
	v_pk_fma_f32 v[24:25], v[90:91], v[90:91], v[24:25] op_sel_hi:[1,1,0]
	v_and_b32_e32 v99, 0xffff0000, v17
	v_and_b32_e32 v98, 0xffff0000, v16
	v_pk_mul_f32 v[16:17], v[94:95], v[94:95]
	v_mov_b32_e32 v19, v23
	v_mov_b32_e32 v25, v31
	v_pk_fma_f32 v[16:17], v[92:93], v[92:93], v[16:17]
	v_pk_add_f32 v[18:19], v[18:19], v[24:25]
	v_lshlrev_b32_e32 v75, 16, v27
	v_lshlrev_b32_e32 v97, 16, v26
	v_pk_add_f32 v[16:17], v[16:17], v[18:19]
	v_pk_mul_f32 v[18:19], v[98:99], v[98:99]
	v_mul_f32_e32 v74, v70, v70
	v_mul_f32_e32 v22, v71, v71
	v_pk_fma_f32 v[18:19], v[96:97], v[96:97], v[18:19]
	v_mov_b32_e32 v23, v75
	v_and_b32_e32 v77, 0xffff0000, v27
	v_pk_add_f32 v[16:17], v[18:19], v[16:17]
	v_pk_add_f32 v[18:19], v[74:75], v[22:23]
	v_pk_mul_f32 v[22:23], v[74:75], v[74:75]
	v_mul_f32_e32 v21, v77, v77
	v_mov_b32_e32 v19, v23
	v_pk_add_f32 v[18:19], v[18:19], v[20:21]
	v_mov_b32_e32 v100, v93
	v_pk_add_f32 v[16:17], v[18:19], v[16:17]
	v_mov_b32_e32 v101, v95
	v_add_f32_e32 v16, v16, v17
	ds_bpermute_b32 v17, v87, v16
	v_mov_b32_e32 v76, v75
	v_mov_b32_e32 v93, v94
	s_waitcnt lgkmcnt(0)
; __device__ __forceinline__ u32x4 pack8(f32x4 a, f32x4 b) { u32x4 w; w.x = pk2(a[0], a[1]); w.y = pk2(a[2], a[3]); w.z = pk2(b[0], b[1]); w.w = pk2(b[2], b[3]); return w; }
; __device__ __forceinline__ float sumsq8(f32x4 a, f32x4 b) { return (a[0] * a[0] + a[1] * a[1]) + (a[2] * a[2] + a[3] * a[3]) + (b[0] * b[0] + b[1] * b[1]) + (b[2] * b[2] + b[3] * b[3]); }
; __device__ __forceinline__ void prep_item(unsigned char* ws, int l, int item, const int tid) {
;     ...
;         float ss = 0.f;
; #pragma unroll
;         for (int c = 0; c < 3; ++c) ss += sumsq8(v[c][0], v[c][1]);
;         ss += __shfl_xor(ss, 1); ss += __shfl_xor(ss, 2);
;         const float rs = rsqrtf(ss * (1.f / 96.f) + EPS);
;         const float* gn = which == 0 ? qg : kg;
; #pragma unroll
;         for (int c = 0; c < 3; ++c) { const f32x4 g0 = *(const f32x4*)(gn + (j + 4 * c) * 8), g1 = *(const f32x4*)(gn + (j + 4 * c) * 8 + 4); v[c][0] = v[c][0] * rs * g0; v[c][1] = v[c][1] * rs * g1; }
;         f32x4 o0, o1;
; #pragma unroll
;         for (int e = 0; e < 4; ++e) { o0[e] = __shfl_xor(v[2][0][e], 2); o1[e] = __shfl_xor(v[2][1][e], 2); }
; #pragma unroll
;         for (int e = 0; e < 8; ++e) { const f32x2 cs = csv[e]; const float mine = e < 4 ? v[2][0][e] : v[2][1][e - 4], oth = e < 4 ? o0[e] : o1[e - 4];
;             const float r = (j < 2) ? (mine * cs.x - oth * cs.y) : (oth * cs.y + mine * cs.x);
;             if (e < 4) v[2][0][e] = r; else v[2][1][e - 4] = r; }
;         if (which == 0) { const float sc = 0.10206207261596575f * 1.4426950408889634f;
; #pragma unroll
;             for (int c = 0; c < 3; ++c) { v[c][0] = v[c][0] * sc; v[c][1] = v[c][1] * sc; } }
;         bf16* dst = (which == 0 ? Q : K) + tok * 768 + h * 96;
; #pragma unroll
;         for (int c = 0; c < 3; ++c) *(u32x4*)(dst + (j + 4 * c) * 8) = pack8(v[c][0], v[c][1]);
	v_add_f32_e32 v16, v16, v17
	ds_bpermute_b32 v17, v88, v16
	s_waitcnt lgkmcnt(0)
	v_add_f32_e32 v16, v16, v17
	v_fmamk_f32 v16, v16, 0x3c2aaaab, v248
	v_cmp_gt_f32_e32 vcc, s48, v16
	v_mul_f32_e32 v17, 0x4b800000, v16
	s_nop 0
	v_cndmask_b32_e32 v16, v16, v17, vcc
	v_rsq_f32_e32 v16, v16
	s_nop 0
	v_mul_f32_e32 v17, 0x45800000, v16
	v_cndmask_b32_e32 v74, v16, v17, vcc
	global_load_dwordx4 v[16:19], v[40:41], off offset:16
	global_load_dwordx4 v[20:23], v[40:41], off
	global_load_dwordx4 v[24:27], v[42:43], off offset:16
	global_load_dwordx4 v[58:61], v[42:43], off
	global_load_dwordx4 v[62:65], v[44:45], off offset:16
	global_load_dwordx4 v[66:69], v[44:45], off
	v_pk_mul_f32 v[72:73], v[74:75], v[72:73] op_sel_hi:[0,1]
	v_pk_mul_f32 v[100:101], v[74:75], v[100:101] op_sel_hi:[0,1]
	v_pk_mul_f32 v[76:77], v[76:77], v[74:75] op_sel_hi:[1,0]
	s_waitcnt vmcnt(0)
	v_pk_mul_f32 v[68:69], v[68:69], v[72:73]
	v_mov_b32_e32 v73, v98
	v_mov_b32_e32 v98, v97
	v_mov_b32_e32 v72, v96
	v_pk_mul_f32 v[96:97], v[98:99], v[74:75] op_sel_hi:[1,0]
	ds_bpermute_b32 v98, v88, v69
	v_pk_mul_f32 v[62:63], v[62:63], v[96:97]
	ds_bpermute_b32 v96, v88, v68
	ds_bpermute_b32 v75, v88, v62
	v_pk_mul_f32 v[64:65], v[64:65], v[76:77]
	ds_bpermute_b32 v95, v88, v63
	ds_bpermute_b32 v97, v88, v64
	s_waitcnt lgkmcnt(3)
	v_mul_f32_e32 v9, v9, v96
	v_cndmask_b32_e64 v9, v9, -v9, s[34:35]
	v_pk_mul_f32 v[66:67], v[66:67], v[100:101]
	v_fmac_f32_e32 v9, v8, v68
	v_mul_f32_e32 v8, v11, v98
	ds_bpermute_b32 v31, v88, v66
	ds_bpermute_b32 v99, v88, v65
	v_cndmask_b32_e64 v8, v8, -v8, s[34:35]
	s_waitcnt lgkmcnt(4)
	v_mul_f32_e32 v5, v5, v75
	v_fmac_f32_e32 v8, v10, v69
	v_cndmask_b32_e64 v10, v5, -v5, s[34:35]
	ds_bpermute_b32 v89, v88, v67
	v_fmac_f32_e32 v10, v4, v62
	s_waitcnt lgkmcnt(4)
	v_mul_f32_e32 v4, v7, v95
	v_cndmask_b32_e64 v7, v4, -v4, s[34:35]
	s_waitcnt lgkmcnt(3)
	v_mul_f32_e32 v1, v1, v97
	v_fmac_f32_e32 v7, v6, v63
	v_cndmask_b32_e64 v6, v1, -v1, s[34:35]
	v_pk_mul_f32 v[76:77], v[78:79], v[74:75] op_sel_hi:[1,0]
	v_mov_b32_e32 v78, v81
	v_mov_b32_e32 v79, v83
	v_mov_b32_e32 v81, v82
	v_pk_mul_f32 v[70:71], v[74:75], v[70:71] op_sel_hi:[0,1]
	s_waitcnt lgkmcnt(2)
	v_mul_f32_e32 v13, v13, v31
	v_fmac_f32_e32 v6, v0, v64
	s_waitcnt lgkmcnt(1)
	v_mul_f32_e32 v0, v3, v99
	v_add_co_u32_e32 v4, vcc, s55, v56
	v_pk_mul_f32 v[78:79], v[78:79], v[74:75] op_sel_hi:[1,0]
	v_pk_mul_f32 v[22:23], v[22:23], v[76:77]
	v_pk_mul_f32 v[76:77], v[74:75], v[80:81] op_sel_hi:[0,1]
	v_pk_mul_f32 v[18:19], v[18:19], v[70:71]
	v_pk_mul_f32 v[70:71], v[74:75], v[84:85] op_sel_hi:[0,1]
	v_cndmask_b32_e64 v13, v13, -v13, s[34:35]
	v_cndmask_b32_e64 v11, v0, -v0, s[34:35]
	v_addc_co_u32_e32 v5, vcc, 0, v57, vcc
	v_pk_mul_f32 v[20:21], v[20:21], v[78:79]
	v_pk_mul_f32 v[16:17], v[16:17], v[76:77]
	v_pk_mul_f32 v[76:77], v[74:75], v[90:91] op_sel_hi:[0,1]
	v_pk_mul_f32 v[58:59], v[58:59], v[70:71]
	v_pk_mul_f32 v[70:71], v[92:93], v[74:75] op_sel_hi:[1,0]
	v_pk_mul_f32 v[72:73], v[72:73], v[74:75] op_sel_hi:[1,0]
	v_fmac_f32_e32 v13, v12, v66
	s_waitcnt lgkmcnt(0)
	v_mul_f32_e32 v12, v15, v89
	v_fmac_f32_e32 v11, v2, v65
	v_cvt_pk_bf16_f32 v0, v20, v21
	v_cvt_pk_bf16_f32 v1, v22, v23
	v_cvt_pk_bf16_f32 v2, v16, v17
	v_cvt_pk_bf16_f32 v3, v18, v19
	v_cmp_lt_i32_e32 vcc, s79, v30
	v_pk_mul_f32 v[60:61], v[60:61], v[76:77]
	v_pk_mul_f32 v[26:27], v[26:27], v[72:73]
	v_pk_mul_f32 v[24:25], v[24:25], v[70:71]
	v_cndmask_b32_e64 v12, v12, -v12, s[34:35]
	global_store_dwordx4 v[4:5], v[0:3], off sc1
	s_or_b64 s[38:39], vcc, s[38:39]
	v_fmac_f32_e32 v12, v14, v67
	v_cvt_pk_bf16_f32 v0, v58, v59
	v_cvt_pk_bf16_f32 v1, v60, v61
	v_cvt_pk_bf16_f32 v2, v24, v25
	v_cvt_pk_bf16_f32 v3, v26, v27
	global_store_dwordx4 v[4:5], v[0:3], off offset:64 sc1
	s_nop 1
	v_cvt_pk_bf16_f32 v0, v13, v12
	v_cvt_pk_bf16_f32 v1, v9, v8
	v_cvt_pk_bf16_f32 v2, v10, v7
	v_cvt_pk_bf16_f32 v3, v6, v11
	global_store_dwordx4 v[4:5], v[0:3], off offset:128 sc1
	s_andn2_b64 exec, exec, s[38:39]
	s_cbranch_execnz .LBB0_669

; __device__ __forceinline__ void unpack8(u32x4 w, f32x4& a, f32x4& b) { a = (f32x4){bflo(w.x), bfhi(w.x), bflo(w.y), bfhi(w.y)}; b = (f32x4){bflo(w.z), bfhi(w.z), bflo(w.w), bfhi(w.w)}; }
; __device__ __forceinline__ float sumsq8(f32x4 a, f32x4 b) { return (a[0] * a[0] + a[1] * a[1]) + (a[2] * a[2] + a[3] * a[3]) + (b[0] * b[0] + b[1] * b[1]) + (b[2] * b[2] + b[3] * b[3]); }
; __device__ __forceinline__ void prep_item(unsigned char* ws, int l, int item, const int tid) {
;     ...
; #pragma unroll
;     for (int c = 0; c < 3; ++c) wraw[0][c] = *(const u32x4*)(Q + tok * 768 + h * 96 + (j + 4 * c) * 8);
; #pragma unroll
;     for (int c = 0; c < 2; ++c) wraw[1][c] = *(const u32x4*)(KN + tok * 512 + h * 64 + (j + 4 * c) * 8);
;     wraw[1][2] = *(const u32x4*)(KR + tok * 32 + j * 8);
; #pragma unroll
;     for (int e = 0; e < 8; ++e) csv[e] = rope[8 * (j & 1) + e];
; #pragma unroll
;     for (int which = 0; which < 2; ++which) {
;         f32x4 v[3][2];
; #pragma unroll
;         for (int c = 0; c < 3; ++c) unpack8(wraw[which][c], v[c][0], v[c][1]);
;         float ss = 0.f;
; #pragma unroll
;         for (int c = 0; c < 3; ++c) ss += sumsq8(v[c][0], v[c][1]);
;         ss += __shfl_xor(ss, 1); ss += __shfl_xor(ss, 2);
;         const float rs = rsqrtf(ss * (1.f / 96.f) + EPS);
;         const float* gn = which == 0 ? qg : kg;
; #pragma unroll
;         for (int c = 0; c < 3; ++c) { const f32x4 g0 = *(const f32x4*)(gn + (j + 4 * c) * 8), g1 = *(const f32x4*)(gn + (j + 4 * c) * 8 + 4); v[c][0] = v[c][0] * rs * g0; v[c][1] = v[c][1] * rs * g1; }
.LBB0_681:
	v_lshl_add_u64 v[54:55], v[50:51], 0, v[44:45]
	v_add_co_u32_e32 v56, vcc, 0x13000000, v54
	v_lshl_add_u64 v[0:1], v[48:49], 0, v[44:45]
	s_nop 0
	v_addc_co_u32_e32 v57, vcc, 0, v55, vcc
	global_load_dwordx4 v[64:67], v[56:57], off
	global_load_dwordx4 v[86:89], v[56:57], off offset:64
	global_load_dwordx4 v[90:93], v[56:57], off offset:128
	v_and_b32_e32 v2, 0x1fff0, v52
	v_add_co_u32_e32 v0, vcc, s3, v0
	v_lshlrev_b32_e32 v184, 3, v2
	s_nop 0
	v_addc_co_u32_e32 v1, vcc, 0, v1, vcc
	global_load_dwordx4 v[20:23], v[0:1], off
	global_load_dwordx4 v[16:19], v[0:1], off offset:64
	v_lshl_add_u64 v[0:1], v[46:47], 0, v[44:45]
	v_lshl_add_u64 v[12:13], v[30:31], 0, v[184:185]
	global_load_dwordx4 v[24:27], v[0:1], off
	s_nop 0
	global_load_dwordx4 v[0:3], v[12:13], off offset:48
	global_load_dwordx4 v[4:7], v[12:13], off offset:32
	global_load_dwordx4 v[8:11], v[12:13], off offset:16
	s_nop 0
	global_load_dwordx4 v[12:15], v[12:13], off
	v_add_u32_e32 v28, s78, v28
	v_lshl_add_u64 v[46:47], v[46:47], 0, s[16:17]
	v_lshl_add_u64 v[48:49], v[48:49], 0, s[40:41]
	v_lshl_add_u64 v[50:51], v[50:51], 0, s[6:7]
	v_lshl_add_u64 v[52:53], v[52:53], 0, s[42:43]
	s_waitcnt vmcnt(9)
	v_and_b32_e32 v83, 0xffff0000, v65
	v_and_b32_e32 v81, 0xffff0000, v64
	v_and_b32_e32 v80, 0xffff0000, v66
	s_waitcnt vmcnt(7)
	v_and_b32_e32 v59, 0xffff0000, v93
	v_lshlrev_b32_e32 v82, 16, v65
	v_mul_f32_e32 v58, v83, v83
	v_lshlrev_b32_e32 v79, 16, v64
	v_lshlrev_b32_e32 v78, 16, v66
	v_pk_mul_f32 v[64:65], v[80:81], v[80:81]
	v_pk_fma_f32 v[68:69], v[82:83], v[82:83], v[58:59] op_sel_hi:[1,1,0]
	v_pk_fma_f32 v[64:65], v[78:79], v[78:79], v[64:65]
	v_and_b32_e32 v73, 0xffff0000, v86
	v_lshlrev_b32_e32 v76, 16, v67
	v_and_b32_e32 v77, 0xffff0000, v67
	v_pk_add_f32 v[66:67], v[64:65], v[68:69] op_sel:[1,0] op_sel_hi:[0,1]
	v_lshlrev_b32_e32 v72, 16, v86
	v_and_b32_e32 v75, 0xffff0000, v87
	v_mul_f32_e32 v58, v73, v73
	v_lshlrev_b32_e32 v62, 16, v91
	v_and_b32_e32 v63, 0xffff0000, v91
	v_pk_add_f32 v[94:95], v[64:65], v[66:67]
	v_lshlrev_b32_e32 v74, 16, v87
	v_lshlrev_b32_e32 v66, 16, v88
	v_and_b32_e32 v70, 0xffff0000, v88
	v_pk_mov_b32 v[68:69], v[88:89], v[92:93] op_sel:[1,0]
	v_lshlrev_b32_e32 v64, 16, v89
	v_pk_fma_f32 v[88:89], v[72:73], v[72:73], v[58:59] op_sel_hi:[1,1,0]
	v_mul_f32_e32 v58, v75, v75
	v_mul_f32_e32 v29, v62, v62
	v_mul_f32_e32 v97, v63, v63
	v_lshlrev_b32_e32 v67, 16, v90
	v_and_b32_e32 v71, 0xffff0000, v90
	v_pk_fma_f32 v[90:91], v[74:75], v[74:75], v[58:59] op_sel_hi:[1,1,0]
	v_pk_mul_f32 v[86:87], v[70:71], v[70:71]
	v_mov_b32_e32 v89, v29
	v_mov_b32_e32 v91, v97
	v_and_b32_e32 v69, 0xffff0000, v69
	v_and_b32_e32 v68, 0xffff0000, v68
	v_pk_fma_f32 v[86:87], v[66:67], v[66:67], v[86:87]
	v_pk_add_f32 v[88:89], v[88:89], v[90:91]
	v_lshlrev_b32_e32 v61, 16, v93
	v_lshlrev_b32_e32 v65, 16, v92
	v_pk_add_f32 v[86:87], v[86:87], v[88:89]
	v_pk_mul_f32 v[88:89], v[68:69], v[68:69]
	v_mul_f32_e32 v60, v76, v76
	v_mul_f32_e32 v96, v77, v77
	v_pk_fma_f32 v[88:89], v[64:65], v[64:65], v[88:89]
	v_mov_b32_e32 v97, v61
	v_pk_add_f32 v[86:87], v[88:89], v[86:87]
	v_pk_add_f32 v[88:89], v[60:61], v[96:97]
	v_pk_mul_f32 v[90:91], v[60:61], v[60:61]
	v_mul_f32_e32 v95, v59, v59
	v_mov_b32_e32 v89, v91
	v_pk_add_f32 v[88:89], v[88:89], v[94:95]
	v_mov_b32_e32 v94, v79
	v_pk_add_f32 v[86:87], v[88:89], v[86:87]
	v_mov_b32_e32 v79, v80
	v_add_f32_e32 v29, v86, v87
	global_load_dwordx4 v[86:89], v[32:33], off offset:16
	global_load_dwordx4 v[90:93], v[32:33], off
	ds_bpermute_b32 v58, v84, v29
	v_mov_b32_e32 v95, v81
	s_waitcnt lgkmcnt(0)
	v_add_f32_e32 v29, v29, v58
	ds_bpermute_b32 v58, v85, v29
	s_waitcnt lgkmcnt(0)
	v_add_f32_e32 v29, v29, v58
	v_fmamk_f32 v29, v29, 0x3c2aaaab, v248
	v_cmp_gt_f32_e32 vcc, s48, v29
	v_mul_f32_e32 v58, 0x4b800000, v29
	s_nop 0
	v_cndmask_b32_e32 v29, v29, v58, vcc
	v_rsq_f32_e32 v29, v29
	s_nop 0
	v_mul_f32_e32 v58, 0x45800000, v29
	v_cndmask_b32_e32 v60, v29, v58, vcc
	v_pk_mul_f32 v[82:83], v[82:83], v[60:61] op_sel_hi:[1,0]
	v_pk_mul_f32 v[76:77], v[60:61], v[76:77] op_sel_hi:[0,1]
	v_pk_mul_f32 v[78:79], v[60:61], v[78:79] op_sel_hi:[0,1]
	v_pk_mul_f32 v[74:75], v[60:61], v[74:75] op_sel_hi:[0,1]
	v_pk_mul_f32 v[72:73], v[60:61], v[72:73] op_sel_hi:[0,1]
	v_pk_mul_f32 v[94:95], v[94:95], v[60:61] op_sel_hi:[1,0]
	v_mov_b32_e32 v58, v61
	v_pk_mul_f32 v[62:63], v[60:61], v[62:63] op_sel_hi:[0,1]
	v_pk_mul_f32 v[58:59], v[58:59], v[60:61] op_sel_hi:[1,0]
	s_waitcnt vmcnt(1)
	v_pk_mul_f32 v[86:87], v[86:87], v[78:79]
	s_waitcnt vmcnt(0)
	v_pk_mul_f32 v[92:93], v[92:93], v[82:83]
	v_pk_mul_f32 v[88:89], v[88:89], v[76:77]
	global_load_dwordx4 v[76:79], v[34:35], off offset:16
	global_load_dwordx4 v[80:83], v[34:35], off
	v_pk_mul_f32 v[90:91], v[90:91], v[94:95]
	s_waitcnt vmcnt(0)
	v_pk_mul_f32 v[80:81], v[80:81], v[72:73]
	v_pk_mul_f32 v[82:83], v[82:83], v[74:75]
	v_mov_b32_e32 v72, v64
	v_mov_b32_e32 v73, v68
	v_mov_b32_e32 v74, v66
	v_mov_b32_e32 v75, v70
	v_pk_mul_f32 v[72:73], v[72:73], v[60:61] op_sel_hi:[1,0]
	v_pk_mul_f32 v[74:75], v[74:75], v[60:61] op_sel_hi:[1,0]
	v_pk_mul_f32 v[96:97], v[78:79], v[72:73]
	v_pk_mul_f32 v[94:95], v[76:77], v[74:75]
	global_load_dwordx4 v[72:75], v[36:37], off offset:16
	global_load_dwordx4 v[76:79], v[36:37], off
	v_mov_b32_e32 v70, v67
	v_pk_mul_f32 v[66:67], v[60:61], v[70:71] op_sel_hi:[0,1]
	v_mov_b32_e32 v68, v65
	v_pk_mul_f32 v[64:65], v[68:69], v[60:61] op_sel_hi:[1,0]
	s_waitcnt vmcnt(1)
	v_pk_mul_f32 v[58:59], v[74:75], v[58:59]
	s_waitcnt vmcnt(0)
; __device__ __forceinline__ u32x4 pack8(f32x4 a, f32x4 b) { u32x4 w; w.x = pk2(a[0], a[1]); w.y = pk2(a[2], a[3]); w.z = pk2(b[0], b[1]); w.w = pk2(b[2], b[3]); return w; }
; __device__ __forceinline__ void prep_item(unsigned char* ws, int l, int item, const int tid) {
;     ...
;         for (int c = 0; c < 3; ++c) { const f32x4 g0 = *(const f32x4*)(gn + (j + 4 * c) * 8), g1 = *(const f32x4*)(gn + (j + 4 * c) * 8 + 4); v[c][0] = v[c][0] * rs * g0; v[c][1] = v[c][1] * rs * g1; }
;         f32x4 o0, o1;
; #pragma unroll
;         for (int e = 0; e < 4; ++e) { o0[e] = __shfl_xor(v[2][0][e], 2); o1[e] = __shfl_xor(v[2][1][e], 2); }
; #pragma unroll
;         for (int e = 0; e < 8; ++e) { const f32x2 cs = csv[e]; const float mine = e < 4 ? v[2][0][e] : v[2][1][e - 4], oth = e < 4 ? o0[e] : o1[e - 4];
;             const float r = (j < 2) ? (mine * cs.x - oth * cs.y) : (oth * cs.y + mine * cs.x);
;             if (e < 4) v[2][0][e] = r; else v[2][1][e - 4] = r; }
;         if (which == 0) { const float sc = 0.10206207261596575f * 1.4426950408889634f;
; #pragma unroll
;             for (int c = 0; c < 3; ++c) { v[c][0] = v[c][0] * sc; v[c][1] = v[c][1] * sc; } }
;         bf16* dst = (which == 0 ? Q : K) + tok * 768 + h * 96;
; #pragma unroll
;         for (int c = 0; c < 3; ++c) *(u32x4*)(dst + (j + 4 * c) * 8) = pack8(v[c][0], v[c][1]);
	v_pk_mul_f32 v[66:67], v[76:77], v[66:67]
	v_pk_mul_f32 v[60:61], v[72:73], v[64:65]
	ds_bpermute_b32 v64, v85, v66
	ds_bpermute_b32 v65, v85, v67
	v_pk_mul_f32 v[62:63], v[78:79], v[62:63]
	ds_bpermute_b32 v70, v85, v62
	ds_bpermute_b32 v71, v85, v63
	v_mov_b32_e32 v76, v13
	v_mov_b32_e32 v77, v15
	s_waitcnt lgkmcnt(2)
	v_pk_mul_f32 v[64:65], v[76:77], v[64:65]
	ds_bpermute_b32 v68, v85, v60
	ds_bpermute_b32 v69, v85, v61
	v_mov_b32_e32 v74, v12
	v_mov_b32_e32 v75, v14
	v_cndmask_b32_e64 v65, v65, -v65, s[34:35]
	v_cndmask_b32_e64 v64, v64, -v64, s[34:35]
	v_pk_fma_f32 v[64:65], v[74:75], v[66:67], v[64:65]
	v_mov_b32_e32 v74, v9
	v_mov_b32_e32 v75, v11
	s_waitcnt lgkmcnt(2)
	v_pk_mul_f32 v[70:71], v[74:75], v[70:71]
	ds_bpermute_b32 v72, v85, v58
	ds_bpermute_b32 v73, v85, v59
	v_mov_b32_e32 v66, v8
	v_mov_b32_e32 v67, v10
	v_cndmask_b32_e64 v71, v71, -v71, s[34:35]
	v_cndmask_b32_e64 v70, v70, -v70, s[34:35]
	v_pk_fma_f32 v[62:63], v[66:67], v[62:63], v[70:71]
	v_mov_b32_e32 v70, v5
	v_mov_b32_e32 v71, v7
	s_waitcnt lgkmcnt(2)
	v_pk_mul_f32 v[68:69], v[70:71], v[68:69]
	v_mov_b32_e32 v66, v4
	v_mov_b32_e32 v67, v6
	v_cndmask_b32_e64 v69, v69, -v69, s[34:35]
	v_cndmask_b32_e64 v68, v68, -v68, s[34:35]
	v_pk_fma_f32 v[60:61], v[66:67], v[60:61], v[68:69]
	v_mov_b32_e32 v68, v1
	v_mov_b32_e32 v69, v3
	s_waitcnt lgkmcnt(0)
	v_pk_mul_f32 v[68:69], v[68:69], v[72:73]
	v_mov_b32_e32 v66, v0
	v_mov_b32_e32 v67, v2
	v_cndmask_b32_e64 v69, v69, -v69, s[34:35]
	v_cndmask_b32_e64 v68, v68, -v68, s[34:35]
	v_pk_fma_f32 v[58:59], v[66:67], v[58:59], v[68:69]
	v_pk_mul_f32 v[66:67], v[92:93], s[86:87] op_sel_hi:[1,0]
	v_pk_mul_f32 v[68:69], v[90:91], s[86:87] op_sel_hi:[1,0]
	v_pk_mul_f32 v[70:71], v[88:89], s[86:87] op_sel_hi:[1,0]
	v_pk_mul_f32 v[72:73], v[86:87], s[86:87] op_sel_hi:[1,0]
	v_pk_mul_f32 v[74:75], v[82:83], s[86:87] op_sel_hi:[1,0]
	v_pk_mul_f32 v[76:77], v[80:81], s[86:87] op_sel_hi:[1,0]
	v_pk_mul_f32 v[80:81], v[94:95], s[86:87] op_sel_hi:[1,0]
	v_pk_mul_f32 v[82:83], v[58:59], s[86:87] op_sel_hi:[1,0]
	v_pk_mul_f32 v[86:87], v[60:61], s[86:87] op_sel_hi:[1,0]
	v_cvt_pk_bf16_f32 v58, v68, v69
	v_cvt_pk_bf16_f32 v59, v66, v67
	v_cvt_pk_bf16_f32 v60, v72, v73
	v_cvt_pk_bf16_f32 v61, v70, v71
	v_pk_mul_f32 v[78:79], v[96:97], s[86:87] op_sel_hi:[1,0]
	global_store_dwordx4 v[56:57], v[58:61], off sc1
	v_pk_mul_f32 v[62:63], v[62:63], s[86:87] op_sel_hi:[1,0]
	v_pk_mul_f32 v[64:65], v[64:65], s[86:87] op_sel_hi:[1,0]
	v_cvt_pk_bf16_f32 v58, v76, v77
	v_cvt_pk_bf16_f32 v59, v74, v75
	v_cvt_pk_bf16_f32 v60, v80, v81
	v_cvt_pk_bf16_f32 v61, v78, v79
	v_and_b32_e32 v77, 0xffff0000, v21
	v_and_b32_e32 v81, 0xffff0000, v20
	v_and_b32_e32 v80, 0xffff0000, v22
	global_store_dwordx4 v[56:57], v[58:61], off offset:64 sc1
	v_lshlrev_b32_e32 v76, 16, v21
	v_lshlrev_b32_e32 v79, 16, v20
	v_cvt_pk_bf16_f32 v58, v64, v65
	v_cvt_pk_bf16_f32 v59, v62, v63
	v_cvt_pk_bf16_f32 v60, v86, v87
	v_cvt_pk_bf16_f32 v61, v82, v83
	global_store_dwordx4 v[56:57], v[58:61], off offset:128 sc1
	v_mul_f32_e32 v56, v77, v77
	v_lshlrev_b32_e32 v78, 16, v22
	v_pk_mul_f32 v[20:21], v[80:81], v[80:81]
	v_pk_fma_f32 v[56:57], v[76:77], v[76:77], v[56:57] op_sel_hi:[1,1,0]
	v_pk_fma_f32 v[20:21], v[78:79], v[78:79], v[20:21]
	v_and_b32_e32 v83, 0xffff0000, v16
	v_and_b32_e32 v87, 0xffff0000, v17
	v_lshlrev_b32_e32 v68, 16, v23
	v_and_b32_e32 v69, 0xffff0000, v23
	v_lshlrev_b32_e32 v70, 16, v25
	v_and_b32_e32 v71, 0xffff0000, v25
	v_pk_add_f32 v[22:23], v[20:21], v[56:57] op_sel:[1,0] op_sel_hi:[0,1]
	v_lshlrev_b32_e32 v82, 16, v16
	v_lshlrev_b32_e32 v86, 16, v17
	v_lshlrev_b32_e32 v88, 16, v18
	v_lshlrev_b32_e32 v89, 16, v24
	v_and_b32_e32 v91, 0xffff0000, v24
	v_and_b32_e32 v90, 0xffff0000, v18
	v_pk_mov_b32 v[16:17], v[18:19], v[26:27] op_sel:[1,0]
	v_mul_f32_e32 v18, v83, v83
	v_mul_f32_e32 v24, v87, v87
	v_pk_add_f32 v[20:21], v[20:21], v[22:23]
	v_mul_f32_e32 v23, v70, v70
	v_mul_f32_e32 v29, v71, v71
	v_lshlrev_b32_e32 v92, 16, v19
	v_pk_fma_f32 v[18:19], v[82:83], v[82:83], v[18:19] op_sel_hi:[1,1,0]
	v_pk_fma_f32 v[24:25], v[86:87], v[86:87], v[24:25] op_sel_hi:[1,1,0]
	v_and_b32_e32 v95, 0xffff0000, v17
	v_and_b32_e32 v94, 0xffff0000, v16
	v_pk_mul_f32 v[16:17], v[90:91], v[90:91]
	v_mov_b32_e32 v19, v23
	v_mov_b32_e32 v25, v29
	v_pk_fma_f32 v[16:17], v[88:89], v[88:89], v[16:17]
	v_pk_add_f32 v[18:19], v[18:19], v[24:25]
	v_lshlrev_b32_e32 v73, 16, v27
	v_lshlrev_b32_e32 v93, 16, v26
	v_pk_add_f32 v[16:17], v[16:17], v[18:19]
	v_pk_mul_f32 v[18:19], v[94:95], v[94:95]
	v_mul_f32_e32 v72, v68, v68
	v_mul_f32_e32 v22, v69, v69
	v_pk_fma_f32 v[18:19], v[92:93], v[92:93], v[18:19]
	v_mov_b32_e32 v23, v73
	v_and_b32_e32 v75, 0xffff0000, v27
	v_pk_add_f32 v[16:17], v[18:19], v[16:17]
	v_pk_add_f32 v[18:19], v[72:73], v[22:23]
	v_pk_mul_f32 v[22:23], v[72:73], v[72:73]
	v_mul_f32_e32 v21, v75, v75
	v_mov_b32_e32 v19, v23
	v_pk_add_f32 v[18:19], v[18:19], v[20:21]
	v_mov_b32_e32 v96, v89
	v_pk_add_f32 v[16:17], v[18:19], v[16:17]
	v_mov_b32_e32 v97, v91
	v_add_f32_e32 v16, v16, v17
	ds_bpermute_b32 v17, v84, v16
	v_mov_b32_e32 v74, v73
	v_mov_b32_e32 v89, v90
	s_waitcnt lgkmcnt(0)
; __device__ __forceinline__ u32x4 pack8(f32x4 a, f32x4 b) { u32x4 w; w.x = pk2(a[0], a[1]); w.y = pk2(a[2], a[3]); w.z = pk2(b[0], b[1]); w.w = pk2(b[2], b[3]); return w; }
; __device__ __forceinline__ float sumsq8(f32x4 a, f32x4 b) { return (a[0] * a[0] + a[1] * a[1]) + (a[2] * a[2] + a[3] * a[3]) + (b[0] * b[0] + b[1] * b[1]) + (b[2] * b[2] + b[3] * b[3]); }
; __device__ __forceinline__ void prep_item(unsigned char* ws, int l, int item, const int tid) {
;     ...
;         float ss = 0.f;
; #pragma unroll
;         for (int c = 0; c < 3; ++c) ss += sumsq8(v[c][0], v[c][1]);
;         ss += __shfl_xor(ss, 1); ss += __shfl_xor(ss, 2);
;         const float rs = rsqrtf(ss * (1.f / 96.f) + EPS);
;         const float* gn = which == 0 ? qg : kg;
; #pragma unroll
;         for (int c = 0; c < 3; ++c) { const f32x4 g0 = *(const f32x4*)(gn + (j + 4 * c) * 8), g1 = *(const f32x4*)(gn + (j + 4 * c) * 8 + 4); v[c][0] = v[c][0] * rs * g0; v[c][1] = v[c][1] * rs * g1; }
;         f32x4 o0, o1;
; #pragma unroll
;         for (int e = 0; e < 4; ++e) { o0[e] = __shfl_xor(v[2][0][e], 2); o1[e] = __shfl_xor(v[2][1][e], 2); }
; #pragma unroll
;         for (int e = 0; e < 8; ++e) { const f32x2 cs = csv[e]; const float mine = e < 4 ? v[2][0][e] : v[2][1][e - 4], oth = e < 4 ? o0[e] : o1[e - 4];
;             const float r = (j < 2) ? (mine * cs.x - oth * cs.y) : (oth * cs.y + mine * cs.x);
;             if (e < 4) v[2][0][e] = r; else v[2][1][e - 4] = r; }
;         if (which == 0) { const float sc = 0.10206207261596575f * 1.4426950408889634f;
; #pragma unroll
;             for (int c = 0; c < 3; ++c) { v[c][0] = v[c][0] * sc; v[c][1] = v[c][1] * sc; } }
;         bf16* dst = (which == 0 ? Q : K) + tok * 768 + h * 96;
; #pragma unroll
;         for (int c = 0; c < 3; ++c) *(u32x4*)(dst + (j + 4 * c) * 8) = pack8(v[c][0], v[c][1]);
	v_add_f32_e32 v16, v16, v17
	ds_bpermute_b32 v17, v85, v16
	s_waitcnt lgkmcnt(0)
	v_add_f32_e32 v16, v16, v17
	v_fmamk_f32 v16, v16, 0x3c2aaaab, v248
	v_cmp_gt_f32_e32 vcc, s48, v16
	v_mul_f32_e32 v17, 0x4b800000, v16
	s_nop 0
	v_cndmask_b32_e32 v16, v16, v17, vcc
	v_rsq_f32_e32 v16, v16
	s_nop 0
	v_mul_f32_e32 v17, 0x45800000, v16
	v_cndmask_b32_e32 v72, v16, v17, vcc
	global_load_dwordx4 v[16:19], v[38:39], off offset:16
	global_load_dwordx4 v[20:23], v[38:39], off
	global_load_dwordx4 v[24:27], v[40:41], off offset:16
	global_load_dwordx4 v[56:59], v[40:41], off
	global_load_dwordx4 v[60:63], v[42:43], off offset:16
	global_load_dwordx4 v[64:67], v[42:43], off
	v_pk_mul_f32 v[70:71], v[72:73], v[70:71] op_sel_hi:[0,1]
	v_pk_mul_f32 v[96:97], v[72:73], v[96:97] op_sel_hi:[0,1]
	v_pk_mul_f32 v[74:75], v[74:75], v[72:73] op_sel_hi:[1,0]
	s_waitcnt vmcnt(0)
	v_pk_mul_f32 v[66:67], v[66:67], v[70:71]
	v_mov_b32_e32 v71, v94
	v_mov_b32_e32 v94, v93
	v_mov_b32_e32 v70, v92
	v_pk_mul_f32 v[92:93], v[94:95], v[72:73] op_sel_hi:[1,0]
	ds_bpermute_b32 v95, v85, v67
	v_pk_mul_f32 v[60:61], v[60:61], v[92:93]
	ds_bpermute_b32 v93, v85, v66
	ds_bpermute_b32 v73, v85, v60
	v_pk_mul_f32 v[62:63], v[62:63], v[74:75]
	ds_bpermute_b32 v92, v85, v61
	ds_bpermute_b32 v94, v85, v62
	s_waitcnt lgkmcnt(3)
	v_mul_f32_e32 v9, v9, v93
	v_cndmask_b32_e64 v9, v9, -v9, s[34:35]
	v_pk_mul_f32 v[64:65], v[64:65], v[96:97]
	v_fmac_f32_e32 v9, v8, v66
	v_mul_f32_e32 v8, v11, v95
	ds_bpermute_b32 v29, v85, v64
	ds_bpermute_b32 v96, v85, v63
	v_cndmask_b32_e64 v8, v8, -v8, s[34:35]
	s_waitcnt lgkmcnt(4)
	v_mul_f32_e32 v5, v5, v73
	v_fmac_f32_e32 v8, v10, v67
	v_cndmask_b32_e64 v10, v5, -v5, s[34:35]
	ds_bpermute_b32 v91, v85, v65
	v_fmac_f32_e32 v10, v4, v60
	s_waitcnt lgkmcnt(4)
	v_mul_f32_e32 v4, v7, v92
	v_cndmask_b32_e64 v7, v4, -v4, s[34:35]
	s_waitcnt lgkmcnt(3)
	v_mul_f32_e32 v1, v1, v94
	v_fmac_f32_e32 v7, v6, v61
	v_cndmask_b32_e64 v6, v1, -v1, s[34:35]
	v_pk_mul_f32 v[74:75], v[76:77], v[72:73] op_sel_hi:[1,0]
	v_mov_b32_e32 v76, v79
	v_mov_b32_e32 v77, v81
	v_mov_b32_e32 v79, v80
	v_pk_mul_f32 v[68:69], v[72:73], v[68:69] op_sel_hi:[0,1]
	s_waitcnt lgkmcnt(2)
	v_mul_f32_e32 v13, v13, v29
	v_fmac_f32_e32 v6, v0, v62
	s_waitcnt lgkmcnt(1)
	v_mul_f32_e32 v0, v3, v96
	v_add_co_u32_e32 v4, vcc, s55, v54
	v_pk_mul_f32 v[76:77], v[76:77], v[72:73] op_sel_hi:[1,0]
	v_pk_mul_f32 v[22:23], v[22:23], v[74:75]
	v_pk_mul_f32 v[74:75], v[72:73], v[78:79] op_sel_hi:[0,1]
	v_pk_mul_f32 v[18:19], v[18:19], v[68:69]
	v_pk_mul_f32 v[68:69], v[72:73], v[82:83] op_sel_hi:[0,1]
	v_cndmask_b32_e64 v13, v13, -v13, s[34:35]
	v_cndmask_b32_e64 v11, v0, -v0, s[34:35]
	v_addc_co_u32_e32 v5, vcc, 0, v55, vcc
	v_pk_mul_f32 v[20:21], v[20:21], v[76:77]
	v_pk_mul_f32 v[16:17], v[16:17], v[74:75]
	v_pk_mul_f32 v[74:75], v[72:73], v[86:87] op_sel_hi:[0,1]
	v_pk_mul_f32 v[56:57], v[56:57], v[68:69]
	v_pk_mul_f32 v[68:69], v[88:89], v[72:73] op_sel_hi:[1,0]
	v_pk_mul_f32 v[70:71], v[70:71], v[72:73] op_sel_hi:[1,0]
	v_fmac_f32_e32 v13, v12, v64
	s_waitcnt lgkmcnt(0)
	v_mul_f32_e32 v12, v15, v91
	v_fmac_f32_e32 v11, v2, v63
	v_cvt_pk_bf16_f32 v0, v20, v21
	v_cvt_pk_bf16_f32 v1, v22, v23
	v_cvt_pk_bf16_f32 v2, v16, v17
	v_cvt_pk_bf16_f32 v3, v18, v19
	v_cmp_lt_i32_e32 vcc, s79, v28
	v_pk_mul_f32 v[58:59], v[58:59], v[74:75]
	v_pk_mul_f32 v[26:27], v[26:27], v[70:71]
	v_pk_mul_f32 v[24:25], v[24:25], v[68:69]
	v_cndmask_b32_e64 v12, v12, -v12, s[34:35]
	global_store_dwordx4 v[4:5], v[0:3], off sc1
	s_or_b64 s[38:39], vcc, s[38:39]
	v_fmac_f32_e32 v12, v14, v65
	v_cvt_pk_bf16_f32 v0, v56, v57
	v_cvt_pk_bf16_f32 v1, v58, v59
	v_cvt_pk_bf16_f32 v2, v24, v25
	v_cvt_pk_bf16_f32 v3, v26, v27
	global_store_dwordx4 v[4:5], v[0:3], off offset:64 sc1
	s_nop 1
	v_cvt_pk_bf16_f32 v0, v13, v12
	v_cvt_pk_bf16_f32 v1, v9, v8
	v_cvt_pk_bf16_f32 v2, v10, v7
	v_cvt_pk_bf16_f32 v3, v6, v11
	global_store_dwordx4 v[4:5], v[0:3], off offset:128 sc1
	s_andn2_b64 exec, exec, s[38:39]
	s_cbranch_execnz .LBB0_681

; #define LAS __attribute__((address_space(3)))
; __device__ __forceinline__ float sum16(const float* p) { const f32x4* q = (const f32x4*)p; return hsum4((q[0] + q[1]) + (q[2] + q[3])); }
;     __device__ __forceinline__ float table_val(int pm, int, int t) const { return t < 256 ? rsqrtf(sum16(px + (size_t)(pm * 256 + t) * 16) * (1.f / 1024.f) + EPS) : 0.f; }
;     __device__ __forceinline__ RowPre pre_row(int row, int) const { const float ss = NSLOT == 8 ? sum8(part + (size_t)row * 8) : sum4(part + (size_t)row * 4); return PreRs{rsqrtf(ss * inv_k + EPS)}; }
;     __device__ __forceinline__ float table_val(int pm, int, int t) const { return t < 256 ? rsqrtf(sum16(px + (size_t)(pm * 256 + t) * 16) * (1.f / 1024.f) + EPS) : 0.f; }
;     __device__ __forceinline__ void operator()(const pg8::f32x4 (&acc)[2][2][4][2], const pg8::Unit& u, int wr, int wc, int, int, int ui) const {
;     ...
;         if (F::USE_TAB) { const LAS float* tc = tab + 256 + wc * 32 + 8 * fq; cv.v[0] = *(const LAS f32x4*)tc; cv.v[1] = *(const LAS f32x4*)(tc + 4); cv.v[2] = *(const LAS f32x4*)(tc + 128); cv.v[3] = *(const LAS f32x4*)(tc + 132); }
;         constexpr int NB = F::BATCH;
; #pragma unroll
;         for (int g = 0; g < 8; g += NB) {
;             typename F::RowPre rp[NB]; int rows[NB]; float rv[NB];
; #pragma unroll
;             for (int j = 0; j < NB; ++j) { const int ai = (g + j) >> 2, mm = (g + j) & 3; const int rl = ai * 128 + wr * 64 + mm * 16 + fr; int row = u.pm * 256 + rl; asm volatile("" : "+v"(row)); rows[j] = row;
;                 rv[j] = F::USE_TAB ? tab[rl] : 0.f; rp[j] = f.pre_row(row, col); }
; #pragma unroll
;             for (int j = 0; j < NB; ++j) { const int ai = (g + j) >> 2, mm = (g + j) & 3; f.apply(rows[j], col, rv[j], cv, rp[j], acc[ai][0][mm][0], acc[ai][0][mm][1], acc[ai][1][mm][0], acc[ai][1][mm][1]); }
;     __device__ __forceinline__ float table_val(int pm, int pn, int t) const { return t < 256 ? rsqrtf(sum16(px + (size_t)(pm * 256 + t) * 16) * (1.f / 1024.f) + EPS) : bias[pn * 256 + t - 256]; }
.LBB0_923:
	v_mbcnt_lo_u32_b32 v156, -1, 0
	v_mbcnt_hi_u32_b32 v156, -1, v156
	s_lshl_b32 s3, s79, 8
	v_ashrrev_i32_e32 v104, 1, v156
	s_or_b32 s3, s3, s67
	v_and_b32_e32 v104, -8, v104
	v_add_u32_e32 v158, s3, v104
	s_lshl_b32 s3, s78, 11
	s_and_b32 s3, s3, 0x800
	s_add_i32 s3, s3, 0
	s_add_i32 s3, s3, 0x20040
	s_lshl_b32 s6, s67, 2
	v_and_or_b32 v156, v156, 15, s66
	s_add_i32 s6, s3, s6
	v_lshl_add_u32 v157, s71, 8, v156
	v_lshl_add_u32 v104, v104, 2, s6
	v_mov_b32_e32 v160, v157
	v_lshl_add_u32 v156, v156, 2, s3
	ds_read_b128 v[124:127], v104 offset:1024
	ds_read_b128 v[120:123], v104 offset:1040
	ds_read_b128 v[112:115], v104 offset:1536
	ds_read_b128 v[104:107], v104 offset:1552
	ds_read_b32 v161, v156
	v_add_u32_e32 v162, 16, v157
	ds_read_b32 v163, v156 offset:64
	v_ashrrev_i32_e32 v159, 31, v158
	s_waitcnt lgkmcnt(0)
	v_fma_f32 v132, v132, v161, v112
	v_mul_f32_e32 v132, 0xbfb8aa3b, v132
	v_exp_f32_e32 v132, v132
	v_fma_f32 v128, v128, v161, v104
	v_mul_f32_e32 v128, 0xbfb8aa3b, v128
	v_exp_f32_e32 v128, v128
	v_add_f32_e32 v132, 1.0, v132
	v_rcp_f32_e32 v164, v132
	v_fma_f32 v132, v141, v161, v125
	v_mul_f32_e32 v132, 0xbfb8aa3b, v132
	v_fma_f32 v137, v137, v161, v121
	v_exp_f32_e32 v132, v132
	v_mul_f32_e32 v137, 0xbfb8aa3b, v137
	v_fma_f32 v133, v133, v161, v113
	v_exp_f32_e32 v137, v137
	v_mul_f32_e32 v133, 0xbfb8aa3b, v133
	v_fma_f32 v129, v129, v161, v105
	v_exp_f32_e32 v133, v133
	v_mul_f32_e32 v129, 0xbfb8aa3b, v129
	v_add_f32_e32 v128, 1.0, v128
	v_exp_f32_e32 v129, v129
	v_rcp_f32_e32 v141, v128
	v_add_f32_e32 v128, 1.0, v132
	v_rcp_f32_e32 v132, v128
	v_add_f32_e32 v128, 1.0, v137
	v_rcp_f32_e32 v137, v128
	v_add_f32_e32 v128, 1.0, v133
	v_rcp_f32_e32 v165, v128
	v_add_f32_e32 v128, 1.0, v129
	v_fma_f32 v129, v142, v161, v126
	v_mul_f32_e32 v129, 0xbfb8aa3b, v129
	v_exp_f32_e32 v129, v129
	v_fma_f32 v133, v138, v161, v122
	v_mul_f32_e32 v133, 0xbfb8aa3b, v133
	v_rcp_f32_e32 v138, v128
	v_add_f32_e32 v128, 1.0, v129
	v_fma_f32 v129, v134, v161, v114
	v_exp_f32_e32 v133, v133
	v_mul_f32_e32 v129, 0xbfb8aa3b, v129
	v_fma_f32 v130, v130, v161, v106
	v_exp_f32_e32 v129, v129
	v_mul_f32_e32 v130, 0xbfb8aa3b, v130
	v_exp_f32_e32 v130, v130
	v_rcp_f32_e32 v142, v128
	v_add_f32_e32 v128, 1.0, v133
	v_rcp_f32_e32 v133, v128
	v_add_f32_e32 v128, 1.0, v129
	v_fma_f32 v129, v143, v161, v127
	v_rcp_f32_e32 v166, v128
	v_add_f32_e32 v128, 1.0, v130
	v_mul_f32_e32 v129, 0xbfb8aa3b, v129
	v_fma_f32 v130, v139, v161, v123
	v_exp_f32_e32 v129, v129
	v_mul_f32_e32 v130, 0xbfb8aa3b, v130
	v_exp_f32_e32 v130, v130
	v_rcp_f32_e32 v139, v128
	v_add_f32_e32 v128, 1.0, v129
	v_fma_f32 v129, v135, v161, v115
	v_rcp_f32_e32 v143, v128
	v_add_f32_e32 v128, 1.0, v130
	v_mul_f32_e32 v129, 0xbfb8aa3b, v129
	v_fma_f32 v130, v131, v161, v107
	v_exp_f32_e32 v129, v129
	v_mul_f32_e32 v130, 0xbfb8aa3b, v130
	v_fma_f32 v140, v140, v161, v124
	v_exp_f32_e32 v130, v130
	v_mul_f32_e32 v140, 0xbfb8aa3b, v140
	v_fma_f32 v136, v136, v161, v120
	v_exp_f32_e32 v140, v140
	v_mul_f32_e32 v136, 0xbfb8aa3b, v136
	v_fma_f32 v100, v100, v163, v112
	v_exp_f32_e32 v136, v136
	v_rcp_f32_e32 v167, v128
	v_add_f32_e32 v128, 1.0, v129
	v_mul_f32_e32 v100, 0xbfb8aa3b, v100
	v_rcp_f32_e32 v168, v128
	v_add_f32_e32 v128, 1.0, v130
	v_ashrrev_i32_e32 v161, 31, v160
	v_exp_f32_e32 v100, v100
	v_rcp_f32_e32 v169, v128
	v_lshlrev_b64 v[128:129], 12, v[160:161]
	v_add_f32_e32 v140, 1.0, v140
	v_lshl_add_u64 v[130:131], s[20:21], 0, v[128:129]
	v_lshlrev_b64 v[128:129], 1, v[158:159]
	v_rcp_f32_e32 v140, v140
	v_add_f32_e32 v136, 1.0, v136
	v_lshl_add_u64 v[134:135], v[130:131], 0, v[128:129]
	v_cvt_pk_bf16_f32 v130, v140, v132
	v_rcp_f32_e32 v136, v136
	v_cvt_pk_bf16_f32 v131, v142, v143
	v_cvt_pk_bf16_f32 v132, v136, v137
	v_cvt_pk_bf16_f32 v133, v133, v167
	global_store_dwordx4 v[134:135], v[130:133], off sc1
	v_fma_f32 v96, v96, v163, v104
	v_add_f32_e32 v100, 1.0, v100
	v_cvt_pk_bf16_f32 v130, v164, v165
	v_cvt_pk_bf16_f32 v131, v166, v168
	v_cvt_pk_bf16_f32 v132, v141, v138
	v_cvt_pk_bf16_f32 v133, v139, v169
	global_store_dwordx4 v[134:135], v[130:133], off offset:256 sc1
	v_mul_f32_e32 v96, 0xbfb8aa3b, v96
	v_exp_f32_e32 v96, v96
	v_rcp_f32_e32 v130, v100
	v_fma_f32 v100, v117, v163, v125
	v_mul_f32_e32 v100, 0xbfb8aa3b, v100
	v_exp_f32_e32 v100, v100
	v_add_f32_e32 v96, 1.0, v96
	v_fma_f32 v109, v109, v163, v121
	v_mul_f32_e32 v109, 0xbfb8aa3b, v109
	v_rcp_f32_e32 v117, v96
	v_add_f32_e32 v96, 1.0, v100
	v_fma_f32 v100, v101, v163, v113
	v_exp_f32_e32 v109, v109
	v_mul_f32_e32 v100, 0xbfb8aa3b, v100
	v_fma_f32 v97, v97, v163, v105
	v_exp_f32_e32 v100, v100
	v_mul_f32_e32 v97, 0xbfb8aa3b, v97
	v_exp_f32_e32 v97, v97
	v_rcp_f32_e32 v131, v96
	v_add_f32_e32 v96, 1.0, v109
	v_rcp_f32_e32 v109, v96
	v_add_f32_e32 v96, 1.0, v100
	v_rcp_f32_e32 v132, v96
	v_add_f32_e32 v96, 1.0, v97
	v_fma_f32 v97, v118, v163, v126
	v_mul_f32_e32 v97, 0xbfb8aa3b, v97
	v_exp_f32_e32 v97, v97
	v_fma_f32 v100, v110, v163, v122
	v_mul_f32_e32 v100, 0xbfb8aa3b, v100
	v_rcp_f32_e32 v110, v96
	v_add_f32_e32 v96, 1.0, v97
	v_fma_f32 v97, v102, v163, v114
	v_exp_f32_e32 v100, v100
	v_mul_f32_e32 v97, 0xbfb8aa3b, v97
	v_fma_f32 v98, v98, v163, v106
	v_exp_f32_e32 v97, v97
	v_mul_f32_e32 v98, 0xbfb8aa3b, v98
	v_exp_f32_e32 v98, v98
	v_rcp_f32_e32 v118, v96
	v_add_f32_e32 v96, 1.0, v100
	v_rcp_f32_e32 v102, v96
	v_add_f32_e32 v96, 1.0, v97
	v_fma_f32 v97, v119, v163, v127
	v_rcp_f32_e32 v133, v96
	v_add_f32_e32 v96, 1.0, v98
	v_mul_f32_e32 v97, 0xbfb8aa3b, v97
	v_fma_f32 v98, v111, v163, v123
	v_exp_f32_e32 v97, v97
	v_mul_f32_e32 v98, 0xbfb8aa3b, v98
	v_exp_f32_e32 v98, v98
	v_rcp_f32_e32 v111, v96
; #define LAS __attribute__((address_space(3)))
; __device__ __forceinline__ float sum16(const float* p) { const f32x4* q = (const f32x4*)p; return hsum4((q[0] + q[1]) + (q[2] + q[3])); }
;     __device__ __forceinline__ float table_val(int pm, int, int t) const { return t < 256 ? rsqrtf(sum16(px + (size_t)(pm * 256 + t) * 16) * (1.f / 1024.f) + EPS) : 0.f; }
;     __device__ __forceinline__ RowPre pre_row(int row, int) const { const float ss = NSLOT == 8 ? sum8(part + (size_t)row * 8) : sum4(part + (size_t)row * 4); return PreRs{rsqrtf(ss * inv_k + EPS)}; }
;     __device__ __forceinline__ float table_val(int pm, int, int t) const { return t < 256 ? rsqrtf(sum16(px + (size_t)(pm * 256 + t) * 16) * (1.f / 1024.f) + EPS) : 0.f; }
;     __device__ __forceinline__ void operator()(const pg8::f32x4 (&acc)[2][2][4][2], const pg8::Unit& u, int wr, int wc, int, int, int ui) const {
;     ...
;         if (F::USE_TAB) { const LAS float* tc = tab + 256 + wc * 32 + 8 * fq; cv.v[0] = *(const LAS f32x4*)tc; cv.v[1] = *(const LAS f32x4*)(tc + 4); cv.v[2] = *(const LAS f32x4*)(tc + 128); cv.v[3] = *(const LAS f32x4*)(tc + 132); }
;         constexpr int NB = F::BATCH;
; #pragma unroll
;         for (int g = 0; g < 8; g += NB) {
;             typename F::RowPre rp[NB]; int rows[NB]; float rv[NB];
; #pragma unroll
;             for (int j = 0; j < NB; ++j) { const int ai = (g + j) >> 2, mm = (g + j) & 3; const int rl = ai * 128 + wr * 64 + mm * 16 + fr; int row = u.pm * 256 + rl; asm volatile("" : "+v"(row)); rows[j] = row;
;                 rv[j] = F::USE_TAB ? tab[rl] : 0.f; rp[j] = f.pre_row(row, col); }
; #pragma unroll
;             for (int j = 0; j < NB; ++j) { const int ai = (g + j) >> 2, mm = (g + j) & 3; f.apply(rows[j], col, rv[j], cv, rp[j], acc[ai][0][mm][0], acc[ai][0][mm][1], acc[ai][1][mm][0], acc[ai][1][mm][1]); }
;     __device__ __forceinline__ float table_val(int pm, int pn, int t) const { return t < 256 ? rsqrtf(sum16(px + (size_t)(pm * 256 + t) * 16) * (1.f / 1024.f) + EPS) : bias[pn * 256 + t - 256]; }
	v_add_f32_e32 v96, 1.0, v97
	v_fma_f32 v97, v103, v163, v115
	v_rcp_f32_e32 v119, v96
	v_add_f32_e32 v96, 1.0, v98
	v_mul_f32_e32 v97, 0xbfb8aa3b, v97
	v_fma_f32 v98, v99, v163, v107
	v_exp_f32_e32 v97, v97
	v_mul_f32_e32 v98, 0xbfb8aa3b, v98
	v_fma_f32 v116, v116, v163, v124
	v_exp_f32_e32 v98, v98
	v_mul_f32_e32 v116, 0xbfb8aa3b, v116
	v_fma_f32 v108, v108, v163, v120
	v_exp_f32_e32 v116, v116
	v_mul_f32_e32 v108, 0xbfb8aa3b, v108
	v_exp_f32_e32 v108, v108
	v_rcp_f32_e32 v99, v96
	v_add_f32_e32 v96, 1.0, v97
	v_rcp_f32_e32 v103, v96
	v_add_f32_e32 v96, 1.0, v98
	v_ashrrev_i32_e32 v163, 31, v162
	v_rcp_f32_e32 v134, v96
	v_lshlrev_b64 v[96:97], 12, v[162:163]
	v_add_f32_e32 v116, 1.0, v116
	v_lshl_add_u64 v[96:97], s[20:21], 0, v[96:97]
	v_rcp_f32_e32 v116, v116
	v_add_f32_e32 v108, 1.0, v108
	v_lshl_add_u64 v[100:101], v[96:97], 0, v[128:129]
	v_cvt_pk_bf16_f32 v96, v116, v131
	v_rcp_f32_e32 v108, v108
	v_cvt_pk_bf16_f32 v97, v118, v119
	v_cvt_pk_bf16_f32 v98, v108, v109
	v_cvt_pk_bf16_f32 v99, v102, v99
	global_store_dwordx4 v[100:101], v[96:99], off sc1
	s_andn2_b64 vcc, exec, s[34:35]
	s_mov_b64 s[34:35], -1
	v_cvt_pk_bf16_f32 v96, v130, v132
	v_cvt_pk_bf16_f32 v97, v133, v103
	v_cvt_pk_bf16_f32 v98, v117, v110
	v_cvt_pk_bf16_f32 v99, v111, v134
	global_store_dwordx4 v[100:101], v[96:99], off offset:256 sc1
	s_nop 1
	v_add_u32_e32 v96, 32, v157
	ds_read_b32 v97, v156 offset:128
	v_add_u32_e32 v98, 48, v157
	ds_read_b32 v99, v156 offset:192
	s_waitcnt lgkmcnt(0)
	v_fma_f32 v84, v84, v97, v112
	v_mul_f32_e32 v84, 0xbfb8aa3b, v84
	v_exp_f32_e32 v84, v84
	v_fma_f32 v80, v80, v97, v104
	v_mul_f32_e32 v80, 0xbfb8aa3b, v80
	v_exp_f32_e32 v80, v80
	v_add_f32_e32 v84, 1.0, v84
	v_rcp_f32_e32 v100, v84
	v_fma_f32 v84, v93, v97, v125
	v_mul_f32_e32 v84, 0xbfb8aa3b, v84
	v_exp_f32_e32 v84, v84
	v_add_f32_e32 v80, 1.0, v80
	v_fma_f32 v89, v89, v97, v121
	v_mul_f32_e32 v89, 0xbfb8aa3b, v89
	v_rcp_f32_e32 v93, v80
	v_add_f32_e32 v80, 1.0, v84
	v_fma_f32 v84, v85, v97, v113
	v_exp_f32_e32 v89, v89
	v_mul_f32_e32 v84, 0xbfb8aa3b, v84
	v_fma_f32 v81, v81, v97, v105
	v_exp_f32_e32 v84, v84
	v_mul_f32_e32 v81, 0xbfb8aa3b, v81
	v_exp_f32_e32 v81, v81
	v_rcp_f32_e32 v101, v80
	v_add_f32_e32 v80, 1.0, v89
	v_rcp_f32_e32 v89, v80
	v_add_f32_e32 v80, 1.0, v84
	v_rcp_f32_e32 v102, v80
	v_add_f32_e32 v80, 1.0, v81
	v_fma_f32 v81, v94, v97, v126
	v_mul_f32_e32 v81, 0xbfb8aa3b, v81
	v_exp_f32_e32 v81, v81
	v_fma_f32 v84, v90, v97, v122
	v_mul_f32_e32 v84, 0xbfb8aa3b, v84
	v_rcp_f32_e32 v90, v80
	v_add_f32_e32 v80, 1.0, v81
	v_fma_f32 v81, v86, v97, v114
	v_exp_f32_e32 v84, v84
	v_mul_f32_e32 v81, 0xbfb8aa3b, v81
	v_fma_f32 v82, v82, v97, v106
	v_exp_f32_e32 v81, v81
	v_mul_f32_e32 v82, 0xbfb8aa3b, v82
	v_exp_f32_e32 v82, v82
	v_rcp_f32_e32 v94, v80
	v_add_f32_e32 v80, 1.0, v84
	v_rcp_f32_e32 v86, v80
	v_add_f32_e32 v80, 1.0, v81
	v_fma_f32 v81, v95, v97, v127
	v_rcp_f32_e32 v103, v80
	v_add_f32_e32 v80, 1.0, v82
	v_mul_f32_e32 v81, 0xbfb8aa3b, v81
	v_fma_f32 v82, v91, v97, v123
	v_exp_f32_e32 v81, v81
	v_mul_f32_e32 v82, 0xbfb8aa3b, v82
	v_exp_f32_e32 v82, v82
	v_rcp_f32_e32 v91, v80
	v_add_f32_e32 v80, 1.0, v81
	v_fma_f32 v81, v87, v97, v115
	v_rcp_f32_e32 v95, v80
	v_add_f32_e32 v80, 1.0, v82
	v_mul_f32_e32 v81, 0xbfb8aa3b, v81
	v_fma_f32 v82, v83, v97, v107
	v_exp_f32_e32 v81, v81
	v_mul_f32_e32 v82, 0xbfb8aa3b, v82
	v_fma_f32 v92, v92, v97, v124
	v_exp_f32_e32 v82, v82
	v_mul_f32_e32 v92, 0xbfb8aa3b, v92
	v_fma_f32 v88, v88, v97, v120
	v_exp_f32_e32 v92, v92
	v_mul_f32_e32 v88, 0xbfb8aa3b, v88
	v_fma_f32 v68, v68, v99, v112
	v_exp_f32_e32 v88, v88
	v_rcp_f32_e32 v83, v80
	v_add_f32_e32 v80, 1.0, v81
	v_mul_f32_e32 v68, 0xbfb8aa3b, v68
	v_rcp_f32_e32 v87, v80
	v_add_f32_e32 v80, 1.0, v82
	v_ashrrev_i32_e32 v97, 31, v96
	v_exp_f32_e32 v68, v68
	v_rcp_f32_e32 v108, v80
	v_lshlrev_b64 v[80:81], 12, v[96:97]
	v_add_f32_e32 v92, 1.0, v92
	v_lshl_add_u64 v[80:81], s[20:21], 0, v[80:81]
	v_rcp_f32_e32 v92, v92
	v_add_f32_e32 v88, 1.0, v88
	v_lshl_add_u64 v[84:85], v[80:81], 0, v[128:129]
	v_cvt_pk_bf16_f32 v80, v92, v101
	v_rcp_f32_e32 v88, v88
	v_cvt_pk_bf16_f32 v81, v94, v95
	v_cvt_pk_bf16_f32 v82, v88, v89
	v_cvt_pk_bf16_f32 v83, v86, v83
	global_store_dwordx4 v[84:85], v[80:83], off sc1
	v_fma_f32 v64, v64, v99, v104
	v_add_f32_e32 v68, 1.0, v68
	v_cvt_pk_bf16_f32 v80, v100, v102
	v_cvt_pk_bf16_f32 v81, v103, v87
	v_cvt_pk_bf16_f32 v82, v93, v90
	v_cvt_pk_bf16_f32 v83, v91, v108
	global_store_dwordx4 v[84:85], v[80:83], off offset:256 sc1
	v_mul_f32_e32 v64, 0xbfb8aa3b, v64
	v_exp_f32_e32 v64, v64
	v_rcp_f32_e32 v80, v68
	v_fma_f32 v68, v77, v99, v125
	v_mul_f32_e32 v68, 0xbfb8aa3b, v68
	v_exp_f32_e32 v68, v68
	v_add_f32_e32 v64, 1.0, v64
	v_fma_f32 v73, v73, v99, v121
	v_mul_f32_e32 v73, 0xbfb8aa3b, v73
	v_rcp_f32_e32 v77, v64
	v_add_f32_e32 v64, 1.0, v68
	v_fma_f32 v68, v69, v99, v113
	v_exp_f32_e32 v73, v73
	v_mul_f32_e32 v68, 0xbfb8aa3b, v68
	v_fma_f32 v65, v65, v99, v105
	v_exp_f32_e32 v68, v68
	v_mul_f32_e32 v65, 0xbfb8aa3b, v65
	v_exp_f32_e32 v65, v65
	v_rcp_f32_e32 v81, v64
	v_add_f32_e32 v64, 1.0, v73
	v_rcp_f32_e32 v73, v64
	v_add_f32_e32 v64, 1.0, v68
	v_rcp_f32_e32 v82, v64
	v_add_f32_e32 v64, 1.0, v65
	v_fma_f32 v65, v78, v99, v126
	v_mul_f32_e32 v65, 0xbfb8aa3b, v65
	v_exp_f32_e32 v65, v65
	v_fma_f32 v68, v74, v99, v122
	v_mul_f32_e32 v68, 0xbfb8aa3b, v68
	v_rcp_f32_e32 v74, v64
	v_add_f32_e32 v64, 1.0, v65
	v_fma_f32 v65, v70, v99, v114
	v_exp_f32_e32 v68, v68
	v_mul_f32_e32 v65, 0xbfb8aa3b, v65
	v_fma_f32 v66, v66, v99, v106
	v_exp_f32_e32 v65, v65
	v_mul_f32_e32 v66, 0xbfb8aa3b, v66
	v_exp_f32_e32 v66, v66
	v_rcp_f32_e32 v78, v64
; #define LAS __attribute__((address_space(3)))
; __device__ __forceinline__ float sum16(const float* p) { const f32x4* q = (const f32x4*)p; return hsum4((q[0] + q[1]) + (q[2] + q[3])); }
;     __device__ __forceinline__ float table_val(int pm, int, int t) const { return t < 256 ? rsqrtf(sum16(px + (size_t)(pm * 256 + t) * 16) * (1.f / 1024.f) + EPS) : 0.f; }
;     __device__ __forceinline__ RowPre pre_row(int row, int) const { const float ss = NSLOT == 8 ? sum8(part + (size_t)row * 8) : sum4(part + (size_t)row * 4); return PreRs{rsqrtf(ss * inv_k + EPS)}; }
;     __device__ __forceinline__ float table_val(int pm, int, int t) const { return t < 256 ? rsqrtf(sum16(px + (size_t)(pm * 256 + t) * 16) * (1.f / 1024.f) + EPS) : 0.f; }
;     __device__ __forceinline__ void operator()(const pg8::f32x4 (&acc)[2][2][4][2], const pg8::Unit& u, int wr, int wc, int, int, int ui) const {
;     ...
;         if (F::USE_TAB) { const LAS float* tc = tab + 256 + wc * 32 + 8 * fq; cv.v[0] = *(const LAS f32x4*)tc; cv.v[1] = *(const LAS f32x4*)(tc + 4); cv.v[2] = *(const LAS f32x4*)(tc + 128); cv.v[3] = *(const LAS f32x4*)(tc + 132); }
;         constexpr int NB = F::BATCH;
; #pragma unroll
;         for (int g = 0; g < 8; g += NB) {
;             typename F::RowPre rp[NB]; int rows[NB]; float rv[NB];
; #pragma unroll
;             for (int j = 0; j < NB; ++j) { const int ai = (g + j) >> 2, mm = (g + j) & 3; const int rl = ai * 128 + wr * 64 + mm * 16 + fr; int row = u.pm * 256 + rl; asm volatile("" : "+v"(row)); rows[j] = row;
;                 rv[j] = F::USE_TAB ? tab[rl] : 0.f; rp[j] = f.pre_row(row, col); }
; #pragma unroll
;             for (int j = 0; j < NB; ++j) { const int ai = (g + j) >> 2, mm = (g + j) & 3; f.apply(rows[j], col, rv[j], cv, rp[j], acc[ai][0][mm][0], acc[ai][0][mm][1], acc[ai][1][mm][0], acc[ai][1][mm][1]); }
;     __device__ __forceinline__ float table_val(int pm, int pn, int t) const { return t < 256 ? rsqrtf(sum16(px + (size_t)(pm * 256 + t) * 16) * (1.f / 1024.f) + EPS) : bias[pn * 256 + t - 256]; }
	v_add_f32_e32 v64, 1.0, v68
	v_rcp_f32_e32 v70, v64
	v_add_f32_e32 v64, 1.0, v65
	v_fma_f32 v65, v79, v99, v127
	v_rcp_f32_e32 v83, v64
	v_add_f32_e32 v64, 1.0, v66
	v_mul_f32_e32 v65, 0xbfb8aa3b, v65
	v_fma_f32 v66, v75, v99, v123
	v_exp_f32_e32 v65, v65
	v_mul_f32_e32 v66, 0xbfb8aa3b, v66
	v_exp_f32_e32 v66, v66
	v_rcp_f32_e32 v75, v64
	v_add_f32_e32 v64, 1.0, v65
	v_fma_f32 v65, v71, v99, v115
	v_rcp_f32_e32 v79, v64
	v_add_f32_e32 v64, 1.0, v66
	v_mul_f32_e32 v65, 0xbfb8aa3b, v65
	v_fma_f32 v66, v67, v99, v107
	v_exp_f32_e32 v65, v65
	v_mul_f32_e32 v66, 0xbfb8aa3b, v66
	v_fma_f32 v76, v76, v99, v124
	v_exp_f32_e32 v66, v66
	v_mul_f32_e32 v76, 0xbfb8aa3b, v76
	v_fma_f32 v72, v72, v99, v120
	v_exp_f32_e32 v76, v76
	v_mul_f32_e32 v72, 0xbfb8aa3b, v72
	v_exp_f32_e32 v72, v72
	v_rcp_f32_e32 v67, v64
	v_add_f32_e32 v64, 1.0, v65
	v_rcp_f32_e32 v71, v64
	v_add_f32_e32 v64, 1.0, v66
	v_ashrrev_i32_e32 v99, 31, v98
	v_rcp_f32_e32 v84, v64
	v_lshlrev_b64 v[64:65], 12, v[98:99]
	v_add_f32_e32 v76, 1.0, v76
	v_lshl_add_u64 v[64:65], s[20:21], 0, v[64:65]
	v_rcp_f32_e32 v76, v76
	v_add_f32_e32 v72, 1.0, v72
	v_lshl_add_u64 v[68:69], v[64:65], 0, v[128:129]
	v_cvt_pk_bf16_f32 v64, v76, v81
	v_rcp_f32_e32 v72, v72
	v_cvt_pk_bf16_f32 v65, v78, v79
	v_cvt_pk_bf16_f32 v66, v72, v73
	v_cvt_pk_bf16_f32 v67, v70, v67
	global_store_dwordx4 v[68:69], v[64:67], off sc1
	s_nop 1
	v_cvt_pk_bf16_f32 v64, v80, v82
	v_cvt_pk_bf16_f32 v65, v83, v71
	v_cvt_pk_bf16_f32 v66, v77, v74
	v_cvt_pk_bf16_f32 v67, v75, v84
	global_store_dwordx4 v[68:69], v[64:67], off offset:256 sc1
	s_nop 1
	v_add_u32_e32 v64, 0x80, v157
	ds_read_b32 v65, v156 offset:512
	v_add_u32_e32 v66, 0x90, v157
	ds_read_b32 v67, v156 offset:576
	s_waitcnt lgkmcnt(0)
	v_fma_f32 v52, v52, v65, v112
	v_mul_f32_e32 v52, 0xbfb8aa3b, v52
	v_exp_f32_e32 v52, v52
	v_fma_f32 v48, v48, v65, v104
	v_mul_f32_e32 v48, 0xbfb8aa3b, v48
	v_exp_f32_e32 v48, v48
	v_add_f32_e32 v52, 1.0, v52
	v_rcp_f32_e32 v68, v52
	v_fma_f32 v52, v61, v65, v125
	v_mul_f32_e32 v52, 0xbfb8aa3b, v52
	v_exp_f32_e32 v52, v52
	v_add_f32_e32 v48, 1.0, v48
	v_fma_f32 v57, v57, v65, v121
	v_mul_f32_e32 v57, 0xbfb8aa3b, v57
	v_rcp_f32_e32 v61, v48
	v_add_f32_e32 v48, 1.0, v52
	v_fma_f32 v52, v53, v65, v113
	v_exp_f32_e32 v57, v57
	v_mul_f32_e32 v52, 0xbfb8aa3b, v52
	v_fma_f32 v49, v49, v65, v105
	v_exp_f32_e32 v52, v52
	v_mul_f32_e32 v49, 0xbfb8aa3b, v49
	v_exp_f32_e32 v49, v49
	v_rcp_f32_e32 v69, v48
	v_add_f32_e32 v48, 1.0, v57
	v_rcp_f32_e32 v57, v48
	v_add_f32_e32 v48, 1.0, v52
	v_rcp_f32_e32 v70, v48
	v_add_f32_e32 v48, 1.0, v49
	v_fma_f32 v49, v62, v65, v126
	v_mul_f32_e32 v49, 0xbfb8aa3b, v49
	v_exp_f32_e32 v49, v49
	v_fma_f32 v52, v58, v65, v122
	v_mul_f32_e32 v52, 0xbfb8aa3b, v52
	v_rcp_f32_e32 v58, v48
	v_add_f32_e32 v48, 1.0, v49
	v_fma_f32 v49, v54, v65, v114
	v_exp_f32_e32 v52, v52
	v_mul_f32_e32 v49, 0xbfb8aa3b, v49
	v_fma_f32 v50, v50, v65, v106
	v_exp_f32_e32 v49, v49
	v_mul_f32_e32 v50, 0xbfb8aa3b, v50
	v_exp_f32_e32 v50, v50
	v_rcp_f32_e32 v62, v48
	v_add_f32_e32 v48, 1.0, v52
	v_rcp_f32_e32 v54, v48
	v_add_f32_e32 v48, 1.0, v49
	v_fma_f32 v49, v63, v65, v127
	v_rcp_f32_e32 v71, v48
	v_add_f32_e32 v48, 1.0, v50
	v_mul_f32_e32 v49, 0xbfb8aa3b, v49
	v_fma_f32 v50, v59, v65, v123
	v_exp_f32_e32 v49, v49
	v_mul_f32_e32 v50, 0xbfb8aa3b, v50
	v_exp_f32_e32 v50, v50
	v_rcp_f32_e32 v59, v48
	v_add_f32_e32 v48, 1.0, v49
	v_fma_f32 v49, v55, v65, v115
	v_rcp_f32_e32 v63, v48
	v_add_f32_e32 v48, 1.0, v50
	v_mul_f32_e32 v49, 0xbfb8aa3b, v49
	v_fma_f32 v50, v51, v65, v107
	v_exp_f32_e32 v49, v49
	v_mul_f32_e32 v50, 0xbfb8aa3b, v50
	v_fma_f32 v60, v60, v65, v124
	v_exp_f32_e32 v50, v50
	v_mul_f32_e32 v60, 0xbfb8aa3b, v60
	v_fma_f32 v56, v56, v65, v120
	v_exp_f32_e32 v60, v60
	v_mul_f32_e32 v56, 0xbfb8aa3b, v56
	v_fma_f32 v36, v36, v67, v112
	v_exp_f32_e32 v56, v56
	v_rcp_f32_e32 v51, v48
	v_add_f32_e32 v48, 1.0, v49
	v_mul_f32_e32 v36, 0xbfb8aa3b, v36
	v_rcp_f32_e32 v55, v48
	v_add_f32_e32 v48, 1.0, v50
	v_ashrrev_i32_e32 v65, 31, v64
	v_exp_f32_e32 v36, v36
	v_rcp_f32_e32 v72, v48
	v_lshlrev_b64 v[48:49], 12, v[64:65]
	v_add_f32_e32 v60, 1.0, v60
	v_lshl_add_u64 v[48:49], s[20:21], 0, v[48:49]
	v_rcp_f32_e32 v60, v60
	v_add_f32_e32 v56, 1.0, v56
	v_lshl_add_u64 v[52:53], v[48:49], 0, v[128:129]
	v_cvt_pk_bf16_f32 v48, v60, v69
	v_rcp_f32_e32 v56, v56
	v_cvt_pk_bf16_f32 v49, v62, v63
	v_cvt_pk_bf16_f32 v50, v56, v57
	v_cvt_pk_bf16_f32 v51, v54, v51
	global_store_dwordx4 v[52:53], v[48:51], off sc1
	v_fma_f32 v32, v32, v67, v104
	v_add_f32_e32 v36, 1.0, v36
	v_cvt_pk_bf16_f32 v48, v68, v70
	v_cvt_pk_bf16_f32 v49, v71, v55
	v_cvt_pk_bf16_f32 v50, v61, v58
	v_cvt_pk_bf16_f32 v51, v59, v72
	global_store_dwordx4 v[52:53], v[48:51], off offset:256 sc1
	v_mul_f32_e32 v32, 0xbfb8aa3b, v32
	v_exp_f32_e32 v32, v32
	v_rcp_f32_e32 v48, v36
	v_fma_f32 v36, v45, v67, v125
	v_mul_f32_e32 v36, 0xbfb8aa3b, v36
	v_exp_f32_e32 v36, v36
	v_add_f32_e32 v32, 1.0, v32
	v_fma_f32 v41, v41, v67, v121
	v_mul_f32_e32 v41, 0xbfb8aa3b, v41
	v_rcp_f32_e32 v45, v32
	v_add_f32_e32 v32, 1.0, v36
	v_fma_f32 v36, v37, v67, v113
	v_exp_f32_e32 v41, v41
	v_mul_f32_e32 v36, 0xbfb8aa3b, v36
	v_fma_f32 v33, v33, v67, v105
	v_exp_f32_e32 v36, v36
	v_mul_f32_e32 v33, 0xbfb8aa3b, v33
	v_exp_f32_e32 v33, v33
	v_rcp_f32_e32 v49, v32
	v_add_f32_e32 v32, 1.0, v41
	v_rcp_f32_e32 v41, v32
	v_add_f32_e32 v32, 1.0, v36
	v_rcp_f32_e32 v50, v32
	v_add_f32_e32 v32, 1.0, v33
	v_fma_f32 v33, v46, v67, v126
	v_mul_f32_e32 v33, 0xbfb8aa3b, v33
	v_exp_f32_e32 v33, v33
	v_fma_f32 v36, v42, v67, v122
	v_mul_f32_e32 v36, 0xbfb8aa3b, v36
	v_rcp_f32_e32 v42, v32
	v_add_f32_e32 v32, 1.0, v33
; #define LAS __attribute__((address_space(3)))
; __device__ __forceinline__ float sum16(const float* p) { const f32x4* q = (const f32x4*)p; return hsum4((q[0] + q[1]) + (q[2] + q[3])); }
;     __device__ __forceinline__ float table_val(int pm, int, int t) const { return t < 256 ? rsqrtf(sum16(px + (size_t)(pm * 256 + t) * 16) * (1.f / 1024.f) + EPS) : 0.f; }
;     __device__ __forceinline__ RowPre pre_row(int row, int) const { const float ss = NSLOT == 8 ? sum8(part + (size_t)row * 8) : sum4(part + (size_t)row * 4); return PreRs{rsqrtf(ss * inv_k + EPS)}; }
;     __device__ __forceinline__ float table_val(int pm, int, int t) const { return t < 256 ? rsqrtf(sum16(px + (size_t)(pm * 256 + t) * 16) * (1.f / 1024.f) + EPS) : 0.f; }
;     __device__ __forceinline__ void operator()(const pg8::f32x4 (&acc)[2][2][4][2], const pg8::Unit& u, int wr, int wc, int, int, int ui) const {
;     ...
;         if (F::USE_TAB) { const LAS float* tc = tab + 256 + wc * 32 + 8 * fq; cv.v[0] = *(const LAS f32x4*)tc; cv.v[1] = *(const LAS f32x4*)(tc + 4); cv.v[2] = *(const LAS f32x4*)(tc + 128); cv.v[3] = *(const LAS f32x4*)(tc + 132); }
;         constexpr int NB = F::BATCH;
; #pragma unroll
;         for (int g = 0; g < 8; g += NB) {
;             typename F::RowPre rp[NB]; int rows[NB]; float rv[NB];
; #pragma unroll
;             for (int j = 0; j < NB; ++j) { const int ai = (g + j) >> 2, mm = (g + j) & 3; const int rl = ai * 128 + wr * 64 + mm * 16 + fr; int row = u.pm * 256 + rl; asm volatile("" : "+v"(row)); rows[j] = row;
;                 rv[j] = F::USE_TAB ? tab[rl] : 0.f; rp[j] = f.pre_row(row, col); }
; #pragma unroll
;             for (int j = 0; j < NB; ++j) { const int ai = (g + j) >> 2, mm = (g + j) & 3; f.apply(rows[j], col, rv[j], cv, rp[j], acc[ai][0][mm][0], acc[ai][0][mm][1], acc[ai][1][mm][0], acc[ai][1][mm][1]); }
;     __device__ __forceinline__ float table_val(int pm, int pn, int t) const { return t < 256 ? rsqrtf(sum16(px + (size_t)(pm * 256 + t) * 16) * (1.f / 1024.f) + EPS) : bias[pn * 256 + t - 256]; }
	v_fma_f32 v33, v38, v67, v114
	v_exp_f32_e32 v36, v36
	v_mul_f32_e32 v33, 0xbfb8aa3b, v33
	v_fma_f32 v34, v34, v67, v106
	v_exp_f32_e32 v33, v33
	v_mul_f32_e32 v34, 0xbfb8aa3b, v34
	v_exp_f32_e32 v34, v34
	v_rcp_f32_e32 v46, v32
	v_add_f32_e32 v32, 1.0, v36
	v_rcp_f32_e32 v38, v32
	v_add_f32_e32 v32, 1.0, v33
	v_fma_f32 v33, v47, v67, v127
	v_rcp_f32_e32 v51, v32
	v_add_f32_e32 v32, 1.0, v34
	v_mul_f32_e32 v33, 0xbfb8aa3b, v33
	v_fma_f32 v34, v43, v67, v123
	v_exp_f32_e32 v33, v33
	v_mul_f32_e32 v34, 0xbfb8aa3b, v34
	v_exp_f32_e32 v34, v34
	v_rcp_f32_e32 v43, v32
	v_add_f32_e32 v32, 1.0, v33
	v_fma_f32 v33, v39, v67, v115
	v_rcp_f32_e32 v47, v32
	v_add_f32_e32 v32, 1.0, v34
	v_mul_f32_e32 v33, 0xbfb8aa3b, v33
	v_fma_f32 v34, v35, v67, v107
	v_exp_f32_e32 v33, v33
	v_mul_f32_e32 v34, 0xbfb8aa3b, v34
	v_fma_f32 v44, v44, v67, v124
	v_exp_f32_e32 v34, v34
	v_mul_f32_e32 v44, 0xbfb8aa3b, v44
	v_fma_f32 v40, v40, v67, v120
	v_exp_f32_e32 v44, v44
	v_mul_f32_e32 v40, 0xbfb8aa3b, v40
	v_exp_f32_e32 v40, v40
	v_rcp_f32_e32 v35, v32
	v_add_f32_e32 v32, 1.0, v33
	v_rcp_f32_e32 v39, v32
	v_add_f32_e32 v32, 1.0, v34
	v_ashrrev_i32_e32 v67, 31, v66
	v_rcp_f32_e32 v52, v32
	v_lshlrev_b64 v[32:33], 12, v[66:67]
	v_add_f32_e32 v44, 1.0, v44
	v_lshl_add_u64 v[32:33], s[20:21], 0, v[32:33]
	v_rcp_f32_e32 v44, v44
	v_add_f32_e32 v40, 1.0, v40
	v_lshl_add_u64 v[36:37], v[32:33], 0, v[128:129]
	v_cvt_pk_bf16_f32 v32, v44, v49
	v_rcp_f32_e32 v40, v40
	v_cvt_pk_bf16_f32 v33, v46, v47
	v_cvt_pk_bf16_f32 v34, v40, v41
	v_cvt_pk_bf16_f32 v35, v38, v35
	global_store_dwordx4 v[36:37], v[32:35], off sc1
	s_nop 1
	v_cvt_pk_bf16_f32 v32, v48, v50
	v_cvt_pk_bf16_f32 v33, v51, v39
	v_cvt_pk_bf16_f32 v34, v45, v42
	v_cvt_pk_bf16_f32 v35, v43, v52
	global_store_dwordx4 v[36:37], v[32:35], off offset:256 sc1
	s_nop 1
	v_add_u32_e32 v32, 0xa0, v157
	ds_read_b32 v33, v156 offset:640
	v_add_u32_e32 v34, 0xb0, v157
	ds_read_b32 v35, v156 offset:704
	s_waitcnt lgkmcnt(0)
;     __device__ __forceinline__ RowPre pre_row(int row, int) const { const float ss = NSLOT == 8 ? sum8(part + (size_t)row * 8) : sum4(part + (size_t)row * 4); return PreRs{rsqrtf(ss * inv_k + EPS)}; }
;     __device__ __forceinline__ void operator()(const pg8::f32x4 (&acc)[2][2][4][2], const pg8::Unit& u, int wr, int wc, int, int, int ui) const {
;     ...
;             for (int j = 0; j < NB; ++j) { const int ai = (g + j) >> 2, mm = (g + j) & 3; const int rl = ai * 128 + wr * 64 + mm * 16 + fr; int row = u.pm * 256 + rl; asm volatile("" : "+v"(row)); rows[j] = row;
;                 rv[j] = F::USE_TAB ? tab[rl] : 0.f; rp[j] = f.pre_row(row, col); }
; #pragma unroll
;             for (int j = 0; j < NB; ++j) { const int ai = (g + j) >> 2, mm = (g + j) & 3; f.apply(rows[j], col, rv[j], cv, rp[j], acc[ai][0][mm][0], acc[ai][0][mm][1], acc[ai][1][mm][0], acc[ai][1][mm][1]); }
;             asm volatile("" ::: "memory");
;         }
	v_fma_f32 v20, v20, v33, v112
	v_mul_f32_e32 v20, 0xbfb8aa3b, v20
	v_exp_f32_e32 v20, v20
	v_fma_f32 v16, v16, v33, v104
	v_mul_f32_e32 v16, 0xbfb8aa3b, v16
	v_exp_f32_e32 v16, v16
	v_add_f32_e32 v20, 1.0, v20
	v_rcp_f32_e32 v36, v20
	v_fma_f32 v20, v29, v33, v125
	v_mul_f32_e32 v20, 0xbfb8aa3b, v20
	v_exp_f32_e32 v20, v20
	v_add_f32_e32 v16, 1.0, v16
	v_fma_f32 v25, v25, v33, v121
	v_mul_f32_e32 v25, 0xbfb8aa3b, v25
	v_rcp_f32_e32 v29, v16
	v_add_f32_e32 v16, 1.0, v20
	v_fma_f32 v20, v21, v33, v113
	v_exp_f32_e32 v25, v25
	v_mul_f32_e32 v20, 0xbfb8aa3b, v20
	v_fma_f32 v17, v17, v33, v105
	v_exp_f32_e32 v20, v20
	v_mul_f32_e32 v17, 0xbfb8aa3b, v17
	v_exp_f32_e32 v17, v17
	v_rcp_f32_e32 v37, v16
	v_add_f32_e32 v16, 1.0, v25
	v_rcp_f32_e32 v25, v16
	v_add_f32_e32 v16, 1.0, v20
	v_rcp_f32_e32 v38, v16
	v_add_f32_e32 v16, 1.0, v17
	v_fma_f32 v17, v30, v33, v126
	v_mul_f32_e32 v17, 0xbfb8aa3b, v17
	v_exp_f32_e32 v17, v17
	v_fma_f32 v20, v26, v33, v122
	v_mul_f32_e32 v20, 0xbfb8aa3b, v20
	v_rcp_f32_e32 v26, v16
	v_add_f32_e32 v16, 1.0, v17
	v_fma_f32 v17, v22, v33, v114
	v_exp_f32_e32 v20, v20
	v_mul_f32_e32 v17, 0xbfb8aa3b, v17
	v_fma_f32 v18, v18, v33, v106
	v_exp_f32_e32 v17, v17
	v_mul_f32_e32 v18, 0xbfb8aa3b, v18
	v_exp_f32_e32 v18, v18
	v_rcp_f32_e32 v30, v16
	v_add_f32_e32 v16, 1.0, v20
	v_rcp_f32_e32 v22, v16
	v_add_f32_e32 v16, 1.0, v17
	v_fma_f32 v17, v31, v33, v127
	v_rcp_f32_e32 v39, v16
	v_add_f32_e32 v16, 1.0, v18
	v_mul_f32_e32 v17, 0xbfb8aa3b, v17
	v_fma_f32 v18, v27, v33, v123
	v_exp_f32_e32 v17, v17
	v_mul_f32_e32 v18, 0xbfb8aa3b, v18
	v_exp_f32_e32 v18, v18
	v_rcp_f32_e32 v27, v16
	v_add_f32_e32 v16, 1.0, v17
	v_fma_f32 v17, v23, v33, v115
	v_rcp_f32_e32 v31, v16
	v_add_f32_e32 v16, 1.0, v18
	v_mul_f32_e32 v17, 0xbfb8aa3b, v17
	v_fma_f32 v18, v19, v33, v107
	v_exp_f32_e32 v17, v17
	v_mul_f32_e32 v18, 0xbfb8aa3b, v18
	v_fma_f32 v28, v28, v33, v124
	v_exp_f32_e32 v18, v18
	v_mul_f32_e32 v28, 0xbfb8aa3b, v28
	v_fma_f32 v24, v24, v33, v120
	v_exp_f32_e32 v28, v28
	v_mul_f32_e32 v24, 0xbfb8aa3b, v24
	v_fma_f32 v4, v4, v35, v112
	v_exp_f32_e32 v24, v24
	v_rcp_f32_e32 v19, v16
	v_add_f32_e32 v16, 1.0, v17
	v_mul_f32_e32 v4, 0xbfb8aa3b, v4
	v_rcp_f32_e32 v23, v16
	v_add_f32_e32 v16, 1.0, v18
	v_ashrrev_i32_e32 v33, 31, v32
	v_exp_f32_e32 v4, v4
	v_rcp_f32_e32 v40, v16
	v_lshlrev_b64 v[16:17], 12, v[32:33]
	v_add_f32_e32 v28, 1.0, v28
	v_lshl_add_u64 v[16:17], s[20:21], 0, v[16:17]
	v_rcp_f32_e32 v28, v28
	v_add_f32_e32 v24, 1.0, v24
	v_lshl_add_u64 v[20:21], v[16:17], 0, v[128:129]
	v_cvt_pk_bf16_f32 v16, v28, v37
	v_rcp_f32_e32 v24, v24
	v_cvt_pk_bf16_f32 v17, v30, v31
	v_cvt_pk_bf16_f32 v18, v24, v25
	v_cvt_pk_bf16_f32 v19, v22, v19
	global_store_dwordx4 v[20:21], v[16:19], off sc1
	v_fma_f32 v0, v0, v35, v104
	v_add_f32_e32 v4, 1.0, v4
	v_cvt_pk_bf16_f32 v16, v36, v38
	v_cvt_pk_bf16_f32 v17, v39, v23
	v_cvt_pk_bf16_f32 v18, v29, v26
	v_cvt_pk_bf16_f32 v19, v27, v40
	global_store_dwordx4 v[20:21], v[16:19], off offset:256 sc1
	v_mul_f32_e32 v0, 0xbfb8aa3b, v0
	v_exp_f32_e32 v0, v0
	v_rcp_f32_e32 v16, v4
	v_fma_f32 v4, v13, v35, v125
	v_mul_f32_e32 v4, 0xbfb8aa3b, v4
	v_exp_f32_e32 v4, v4
	v_add_f32_e32 v0, 1.0, v0
	v_fma_f32 v9, v9, v35, v121
	v_mul_f32_e32 v9, 0xbfb8aa3b, v9
	v_rcp_f32_e32 v13, v0
	v_add_f32_e32 v0, 1.0, v4
	v_fma_f32 v4, v5, v35, v113
	v_exp_f32_e32 v9, v9
	v_mul_f32_e32 v4, 0xbfb8aa3b, v4
	v_fma_f32 v1, v1, v35, v105
	v_exp_f32_e32 v4, v4
	v_mul_f32_e32 v1, 0xbfb8aa3b, v1
	v_exp_f32_e32 v1, v1
	v_rcp_f32_e32 v17, v0
	v_add_f32_e32 v0, 1.0, v9
	v_rcp_f32_e32 v9, v0
	v_add_f32_e32 v0, 1.0, v4
	v_rcp_f32_e32 v18, v0
	v_add_f32_e32 v0, 1.0, v1
	v_fma_f32 v1, v14, v35, v126
	v_mul_f32_e32 v1, 0xbfb8aa3b, v1
	v_exp_f32_e32 v1, v1
	v_fma_f32 v4, v10, v35, v122
	v_mul_f32_e32 v4, 0xbfb8aa3b, v4
	v_rcp_f32_e32 v10, v0
	v_add_f32_e32 v0, 1.0, v1
	v_fma_f32 v1, v6, v35, v114
	v_exp_f32_e32 v4, v4
	v_mul_f32_e32 v1, 0xbfb8aa3b, v1
	v_fma_f32 v2, v2, v35, v106
	v_exp_f32_e32 v1, v1
	v_mul_f32_e32 v2, 0xbfb8aa3b, v2
	v_exp_f32_e32 v2, v2
	v_rcp_f32_e32 v14, v0
	v_add_f32_e32 v0, 1.0, v4
	v_fmac_f32_e32 v127, v15, v35
	v_rcp_f32_e32 v6, v0
	v_add_f32_e32 v0, 1.0, v1
	v_mul_f32_e32 v1, 0xbfb8aa3b, v127
	v_fmac_f32_e32 v123, v11, v35
	v_rcp_f32_e32 v19, v0
	v_add_f32_e32 v0, 1.0, v2
	v_exp_f32_e32 v1, v1
	v_mul_f32_e32 v2, 0xbfb8aa3b, v123
	v_exp_f32_e32 v2, v2
	v_fmac_f32_e32 v115, v7, v35
	v_rcp_f32_e32 v11, v0
	v_add_f32_e32 v0, 1.0, v1
	v_mul_f32_e32 v1, 0xbfb8aa3b, v115
	v_fmac_f32_e32 v107, v3, v35
	v_rcp_f32_e32 v15, v0
	v_add_f32_e32 v0, 1.0, v2
	v_exp_f32_e32 v1, v1
	v_mul_f32_e32 v2, 0xbfb8aa3b, v107
	v_fma_f32 v12, v12, v35, v124
	v_fma_f32 v8, v8, v35, v120
	v_exp_f32_e32 v2, v2
	v_mul_f32_e32 v12, 0xbfb8aa3b, v12
	v_mul_f32_e32 v8, 0xbfb8aa3b, v8
	v_exp_f32_e32 v12, v12
	v_exp_f32_e32 v8, v8
	v_rcp_f32_e32 v3, v0
	v_add_f32_e32 v0, 1.0, v1
	v_rcp_f32_e32 v7, v0
	v_add_f32_e32 v0, 1.0, v2
	v_ashrrev_i32_e32 v35, 31, v34
	v_rcp_f32_e32 v20, v0
	v_lshlrev_b64 v[0:1], 12, v[34:35]
	v_add_f32_e32 v12, 1.0, v12
	v_add_f32_e32 v8, 1.0, v8
	v_lshl_add_u64 v[0:1], s[20:21], 0, v[0:1]
	v_rcp_f32_e32 v12, v12
	v_rcp_f32_e32 v8, v8
	v_lshl_add_u64 v[4:5], v[0:1], 0, v[128:129]
	v_cvt_pk_bf16_f32 v0, v12, v17
	v_cvt_pk_bf16_f32 v1, v14, v15
	v_cvt_pk_bf16_f32 v2, v8, v9
	v_cvt_pk_bf16_f32 v3, v6, v3
	global_store_dwordx4 v[4:5], v[0:3], off sc1
	s_nop 1
	v_cvt_pk_bf16_f32 v0, v16, v18
	v_cvt_pk_bf16_f32 v1, v19, v7
	v_cvt_pk_bf16_f32 v2, v13, v10
	v_cvt_pk_bf16_f32 v3, v11, v20
	global_store_dwordx4 v[4:5], v[0:3], off offset:256 sc1
	s_cbranch_vccnz .LBB0_906
	s_andn2_b64 vcc, exec, s[38:39]
	s_cbranch_vccnz .LBB0_905
	s_barrier
	s_branch .LBB0_905

.LBB0_943:
	v_mbcnt_lo_u32_b32 v144, -1, 0
	v_mbcnt_hi_u32_b32 v144, -1, v144
	s_lshl_b32 s6, s12, 8
	v_ashrrev_i32_e32 v72, 1, v144
	s_or_b32 s6, s6, s71
	v_and_b32_e32 v72, -8, v72
	v_add_u32_e32 v194, s6, v72
	v_and_or_b32 v146, v144, 15, s70
	v_ashrrev_i32_e32 v195, 31, v194
	v_lshl_add_u64 v[80:81], v[194:195], 2, s[38:39]
	global_load_dwordx4 v[88:91], v[80:81], off offset:16
	global_load_dwordx4 v[92:95], v[80:81], off
	global_load_dwordx4 v[72:75], v[80:81], off offset:528
	s_nop 0
	global_load_dwordx4 v[80:83], v[80:81], off offset:512
	v_ashrrev_i32_e32 v144, 4, v194
	v_lshl_add_u32 v198, s3, 8, v146
	v_ashrrev_i32_e32 v145, 31, v144
	v_mov_b32_e32 v196, v198
	v_lshlrev_b64 v[144:145], 20, v[144:145]
	v_and_b32_e32 v147, 15, v194
	v_ashrrev_i32_e32 v197, 31, v196
	v_lshl_add_u64 v[176:177], s[18:19], 0, v[144:145]
	v_lshlrev_b64 v[144:145], 5, v[196:197]
	v_lshl_add_u64 v[144:145], v[176:177], 0, v[144:145]
	v_lshlrev_b32_e32 v184, 1, v147
	v_lshl_add_u64 v[144:145], v[144:145], 0, v[184:185]
	global_load_dwordx4 v[188:191], v[144:145], off
	v_add_co_u32_e32 v144, vcc, s48, v144
	v_or_b32_e32 v182, 16, v198
	s_nop 0
	v_addc_co_u32_e32 v145, vcc, 0, v145, vcc
	global_load_dwordx4 v[200:203], v[144:145], off
	v_or_b32_e32 v180, 32, v198
	v_ashrrev_i32_e32 v183, 31, v182
	v_lshlrev_b64 v[144:145], 5, v[182:183]
	v_lshl_add_u64 v[144:145], v[176:177], 0, v[144:145]
	v_lshl_add_u64 v[144:145], v[144:145], 0, v[184:185]
	v_add_co_u32_e32 v146, vcc, s48, v144
	v_or_b32_e32 v178, 48, v198
	s_nop 0
	v_addc_co_u32_e32 v147, vcc, 0, v145, vcc
	global_load_dwordx4 v[204:207], v[144:145], off
	global_load_dwordx4 v[160:163], v[146:147], off
	s_waitcnt vmcnt(0)
	v_add_f32_e32 v136, v136, v88
	v_ashrrev_i32_e32 v181, 31, v180
	v_lshlrev_b64 v[144:145], 5, v[180:181]
	v_lshl_add_u64 v[144:145], v[176:177], 0, v[144:145]
	v_lshl_add_u64 v[144:145], v[144:145], 0, v[184:185]
	v_add_co_u32_e32 v146, vcc, s48, v144
	v_add_f32_e32 v140, v140, v92
	s_nop 0
	v_addc_co_u32_e32 v147, vcc, 0, v145, vcc
	global_load_dwordx4 v[156:159], v[144:145], off
	global_load_dwordx4 v[152:155], v[146:147], off
	v_add_f32_e32 v132, v132, v80
	v_add_f32_e32 v128, v128, v72
	v_add_f32_e32 v141, v141, v93
	v_add_f32_e32 v129, v129, v73
	v_mul_f32_e32 v140, 0xbfb8aa3b, v140
	v_mul_f32_e32 v136, 0xbfb8aa3b, v136
	v_mul_f32_e32 v132, 0xbfb8aa3b, v132
	v_mul_f32_e32 v128, 0xbfb8aa3b, v128
	v_mul_f32_e32 v141, 0xbfb8aa3b, v141
	v_mul_f32_e32 v129, 0xbfb8aa3b, v129
	v_exp_f32_e32 v140, v140
	v_exp_f32_e32 v136, v136
	v_exp_f32_e32 v132, v132
	v_exp_f32_e32 v128, v128
	v_exp_f32_e32 v141, v141
	v_exp_f32_e32 v129, v129
	v_add_f32_e32 v137, v137, v89
	v_add_f32_e32 v140, 1.0, v140
	v_add_f32_e32 v136, 1.0, v136
	v_add_f32_e32 v132, 1.0, v132
	v_add_f32_e32 v128, 1.0, v128
	v_add_f32_e32 v141, 1.0, v141
	v_mul_f32_e32 v137, 0xbfb8aa3b, v137
	v_add_f32_e32 v129, 1.0, v129
	v_rcp_f32_e32 v140, v140
	v_rcp_f32_e32 v136, v136
	v_rcp_f32_e32 v132, v132
	v_rcp_f32_e32 v128, v128
	v_rcp_f32_e32 v141, v141
	v_exp_f32_e32 v137, v137
	v_rcp_f32_e32 v129, v129
	v_lshlrev_b32_e32 v192, 16, v188
	v_and_b32_e32 v188, 0xffff0000, v188
	v_lshlrev_b32_e32 v199, 16, v190
	v_lshlrev_b32_e32 v209, 16, v200
	v_lshlrev_b32_e32 v211, 16, v202
	v_and_b32_e32 v202, 0xffff0000, v202
	v_mul_f32_e32 v140, v140, v192
	v_mul_f32_e32 v136, v136, v199
	v_mul_f32_e32 v192, v132, v209
	v_mul_f32_e32 v199, v128, v211
	v_mul_f32_e32 v132, v141, v188
	v_add_f32_e32 v128, 1.0, v137
	v_add_f32_e32 v137, v142, v94
	v_mul_f32_e32 v188, v129, v202
	v_add_f32_e32 v129, v138, v90
	v_mul_f32_e32 v137, 0xbfb8aa3b, v137
	v_mul_f32_e32 v129, 0xbfb8aa3b, v129
	v_rcp_f32_e32 v128, v128
	v_exp_f32_e32 v137, v137
	v_exp_f32_e32 v129, v129
	v_and_b32_e32 v190, 0xffff0000, v190
	v_ashrrev_i32_e32 v179, 31, v178
	v_add_f32_e32 v133, v133, v81
	v_add_f32_e32 v130, v130, v74
	v_lshlrev_b64 v[144:145], 5, v[178:179]
	v_mul_f32_e32 v133, 0xbfb8aa3b, v133
	v_mul_f32_e32 v141, v128, v190
	v_add_f32_e32 v128, 1.0, v137
	v_add_f32_e32 v129, 1.0, v129
	v_mul_f32_e32 v130, 0xbfb8aa3b, v130
	v_lshl_add_u64 v[144:145], v[176:177], 0, v[144:145]
	v_exp_f32_e32 v133, v133
	v_rcp_f32_e32 v128, v128
	v_rcp_f32_e32 v129, v129
	v_exp_f32_e32 v130, v130
	v_lshl_add_u64 v[144:145], v[144:145], 0, v[184:185]
	v_add_co_u32_e32 v146, vcc, s48, v144
	v_lshlrev_b32_e32 v193, 16, v189
	s_nop 0
	v_addc_co_u32_e32 v147, vcc, 0, v145, vcc
	v_lshlrev_b32_e32 v208, 16, v191
	global_load_dwordx4 v[148:151], v[144:145], off
	s_nop 0
	global_load_dwordx4 v[144:147], v[146:147], off
	v_add_f32_e32 v133, 1.0, v133
	v_mul_f32_e32 v137, v128, v193
	v_mul_f32_e32 v138, v129, v208
	v_add_f32_e32 v128, 1.0, v130
	v_add_f32_e32 v129, v143, v95
	v_add_f32_e32 v130, v139, v91
	v_rcp_f32_e32 v133, v133
	v_mul_f32_e32 v129, 0xbfb8aa3b, v129
	v_mul_f32_e32 v130, 0xbfb8aa3b, v130
	v_rcp_f32_e32 v128, v128
	v_exp_f32_e32 v129, v129
	v_exp_f32_e32 v130, v130
	v_and_b32_e32 v200, 0xffff0000, v200
	v_lshlrev_b32_e32 v212, 16, v203
	v_mul_f32_e32 v142, v133, v200
	v_add_f32_e32 v133, v134, v82
	v_mul_f32_e32 v133, 0xbfb8aa3b, v133
	v_mul_f32_e32 v139, v128, v212
	v_add_f32_e32 v128, 1.0, v129
	v_add_f32_e32 v129, 1.0, v130
	v_add_f32_e32 v130, v135, v83
	v_add_f32_e32 v131, v131, v75
	v_exp_f32_e32 v133, v133
	v_mul_f32_e32 v130, 0xbfb8aa3b, v130
	v_mul_f32_e32 v131, 0xbfb8aa3b, v131
	v_exp_f32_e32 v130, v130
	v_exp_f32_e32 v131, v131
	v_add_f32_e32 v124, v124, v92
	v_add_f32_e32 v116, v116, v80
	v_add_f32_e32 v125, v125, v93
	v_add_f32_e32 v113, v113, v73
	v_add_f32_e32 v133, 1.0, v133
	v_mul_f32_e32 v124, 0xbfb8aa3b, v124
	v_add_f32_e32 v120, v120, v88
	v_mul_f32_e32 v116, 0xbfb8aa3b, v116
	v_add_f32_e32 v112, v112, v72
	v_mul_f32_e32 v125, 0xbfb8aa3b, v125
	v_mul_f32_e32 v113, 0xbfb8aa3b, v113
	v_rcp_f32_e32 v133, v133
	v_rcp_f32_e32 v128, v128
	v_rcp_f32_e32 v129, v129
	v_add_f32_e32 v130, 1.0, v130
	v_add_f32_e32 v131, 1.0, v131
	v_exp_f32_e32 v124, v124
	v_mul_f32_e32 v120, 0xbfb8aa3b, v120
	v_exp_f32_e32 v116, v116
	v_mul_f32_e32 v112, 0xbfb8aa3b, v112
	v_exp_f32_e32 v125, v125
	v_exp_f32_e32 v113, v113
	v_rcp_f32_e32 v130, v130
	v_rcp_f32_e32 v131, v131
	v_exp_f32_e32 v120, v120
	v_exp_f32_e32 v112, v112
	v_and_b32_e32 v189, 0xffff0000, v189
	v_and_b32_e32 v191, 0xffff0000, v191
	v_lshlrev_b32_e32 v210, 16, v201
	v_and_b32_e32 v201, 0xffff0000, v201
	v_and_b32_e32 v203, 0xffff0000, v203
	v_mul_f32_e32 v190, v133, v210
	v_mul_f32_e32 v133, v128, v189
	v_mul_f32_e32 v143, v129, v191
	v_lshlrev_b64 v[128:129], 10, v[196:197]
	v_add_f32_e32 v124, 1.0, v124
	v_add_f32_e32 v116, 1.0, v116
	v_add_f32_e32 v125, 1.0, v125
	v_add_f32_e32 v121, v121, v89
	v_add_f32_e32 v113, 1.0, v113
	v_mul_f32_e32 v189, v130, v201
	v_mul_f32_e32 v191, v131, v203
	v_lshl_add_u64 v[130:131], s[4:5], 0, v[128:129]
	v_lshlrev_b64 v[128:129], 1, v[194:195]
	v_rcp_f32_e32 v124, v124
	v_add_f32_e32 v120, 1.0, v120
	v_rcp_f32_e32 v116, v116
	v_add_f32_e32 v112, 1.0, v112
	v_rcp_f32_e32 v125, v125
	v_mul_f32_e32 v121, 0xbfb8aa3b, v121
	v_rcp_f32_e32 v113, v113
	v_lshl_add_u64 v[134:135], v[130:131], 0, v[128:129]
	v_cvt_pk_bf16_f32 v130, v140, v132
	v_cvt_pk_bf16_f32 v131, v137, v133
	v_rcp_f32_e32 v120, v120
	v_rcp_f32_e32 v112, v112
	v_exp_f32_e32 v121, v121
	v_cvt_pk_bf16_f32 v132, v136, v141
	v_cvt_pk_bf16_f32 v133, v138, v143
	global_store_dwordx4 v[134:135], v[130:133], off sc1
	v_lshlrev_b32_e32 v138, 16, v160
	v_and_b32_e32 v143, 0xffff0000, v162
	v_cvt_pk_bf16_f32 v130, v192, v142
	v_cvt_pk_bf16_f32 v131, v190, v189
	v_cvt_pk_bf16_f32 v132, v199, v188
	v_cvt_pk_bf16_f32 v133, v139, v191
	global_store_dwordx4 v[134:135], v[130:133], off offset:256 sc1
	v_lshlrev_b32_e32 v134, 16, v206
	v_lshlrev_b32_e32 v142, 16, v162
	v_lshlrev_b32_e32 v130, 16, v204
	v_and_b32_e32 v131, 0xffff0000, v204
	v_mul_f32_e32 v124, v124, v130
	v_mul_f32_e32 v130, v116, v138
	v_mul_f32_e32 v125, v125, v131
	v_add_f32_e32 v116, v117, v81
	v_add_f32_e32 v117, v126, v94
	v_mul_f32_e32 v131, v113, v143
	v_add_f32_e32 v113, v122, v90
	v_mul_f32_e32 v120, v120, v134
	v_mul_f32_e32 v134, v112, v142
	v_add_f32_e32 v112, 1.0, v121
	v_mul_f32_e32 v116, 0xbfb8aa3b, v116
	v_mul_f32_e32 v117, 0xbfb8aa3b, v117
	v_mul_f32_e32 v113, 0xbfb8aa3b, v113
	v_exp_f32_e32 v116, v116
	v_rcp_f32_e32 v112, v112
	v_exp_f32_e32 v117, v117
	v_exp_f32_e32 v113, v113
	v_and_b32_e32 v135, 0xffff0000, v206
	v_add_f32_e32 v114, v114, v74
	v_add_f32_e32 v116, 1.0, v116
	v_mul_f32_e32 v121, v112, v135
	v_add_f32_e32 v112, 1.0, v117
	v_add_f32_e32 v113, 1.0, v113
	v_mul_f32_e32 v114, 0xbfb8aa3b, v114
	v_rcp_f32_e32 v116, v116
	v_rcp_f32_e32 v112, v112
	v_rcp_f32_e32 v113, v113
	v_exp_f32_e32 v114, v114
	v_lshlrev_b32_e32 v132, 16, v205
	v_lshlrev_b32_e32 v136, 16, v207
	v_and_b32_e32 v139, 0xffff0000, v160
	v_mul_f32_e32 v126, v116, v139
	v_add_f32_e32 v116, v118, v82
	v_mul_f32_e32 v118, v112, v132
	v_mul_f32_e32 v122, v113, v136
	v_add_f32_e32 v112, 1.0, v114
	v_add_f32_e32 v113, v127, v95
	v_add_f32_e32 v114, v123, v91
	v_mul_f32_e32 v113, 0xbfb8aa3b, v113
	v_mul_f32_e32 v114, 0xbfb8aa3b, v114
	v_rcp_f32_e32 v112, v112
	v_exp_f32_e32 v113, v113
	v_exp_f32_e32 v114, v114
	v_lshlrev_b32_e32 v160, 16, v163
	v_mul_f32_e32 v116, 0xbfb8aa3b, v116
	v_mul_f32_e32 v123, v112, v160
	v_add_f32_e32 v112, 1.0, v113
	v_add_f32_e32 v113, 1.0, v114
	v_add_f32_e32 v114, v119, v83
	v_add_f32_e32 v115, v115, v75
	v_exp_f32_e32 v116, v116
	v_mul_f32_e32 v114, 0xbfb8aa3b, v114
	v_mul_f32_e32 v115, 0xbfb8aa3b, v115
	v_exp_f32_e32 v114, v114
	v_exp_f32_e32 v115, v115
	v_add_f32_e32 v108, v108, v92
	v_add_f32_e32 v100, v100, v80
	v_add_f32_e32 v109, v109, v93
	v_add_f32_e32 v97, v97, v73
	v_mul_f32_e32 v108, 0xbfb8aa3b, v108
	v_add_f32_e32 v104, v104, v88
	v_mul_f32_e32 v100, 0xbfb8aa3b, v100
	v_add_f32_e32 v96, v96, v72
	v_mul_f32_e32 v109, 0xbfb8aa3b, v109
	v_mul_f32_e32 v97, 0xbfb8aa3b, v97
	v_rcp_f32_e32 v112, v112
	v_rcp_f32_e32 v113, v113
	v_exp_f32_e32 v108, v108
	v_mul_f32_e32 v104, 0xbfb8aa3b, v104
	v_exp_f32_e32 v100, v100
	v_mul_f32_e32 v96, 0xbfb8aa3b, v96
	v_exp_f32_e32 v109, v109
	v_exp_f32_e32 v97, v97
	v_add_f32_e32 v116, 1.0, v116
	v_exp_f32_e32 v104, v104
	v_exp_f32_e32 v96, v96
	v_rcp_f32_e32 v116, v116
	v_add_f32_e32 v114, 1.0, v114
	v_add_f32_e32 v115, 1.0, v115
	v_and_b32_e32 v133, 0xffff0000, v205
	v_and_b32_e32 v137, 0xffff0000, v207
	v_rcp_f32_e32 v114, v114
	v_rcp_f32_e32 v115, v115
	v_mul_f32_e32 v119, v112, v133
	v_mul_f32_e32 v127, v113, v137
	v_lshlrev_b64 v[112:113], 10, v[182:183]
	v_add_f32_e32 v108, 1.0, v108
	v_add_f32_e32 v100, 1.0, v100
	v_add_f32_e32 v109, 1.0, v109
	v_add_f32_e32 v105, v105, v89
	v_add_f32_e32 v97, 1.0, v97
	v_lshlrev_b32_e32 v140, 16, v161
	v_lshl_add_u64 v[112:113], s[4:5], 0, v[112:113]
	v_rcp_f32_e32 v108, v108
	v_add_f32_e32 v104, 1.0, v104
	v_rcp_f32_e32 v100, v100
	v_add_f32_e32 v96, 1.0, v96
	v_rcp_f32_e32 v109, v109
	v_mul_f32_e32 v105, 0xbfb8aa3b, v105
	v_rcp_f32_e32 v97, v97
	v_and_b32_e32 v141, 0xffff0000, v161
	v_and_b32_e32 v161, 0xffff0000, v163
	v_mul_f32_e32 v132, v116, v140
	v_lshl_add_u64 v[116:117], v[112:113], 0, v[128:129]
	v_cvt_pk_bf16_f32 v112, v124, v125
	v_cvt_pk_bf16_f32 v113, v118, v119
	v_rcp_f32_e32 v104, v104
	v_rcp_f32_e32 v96, v96
	v_exp_f32_e32 v105, v105
	v_mul_f32_e32 v133, v114, v141
	v_mul_f32_e32 v135, v115, v161
	v_cvt_pk_bf16_f32 v114, v120, v121
	v_cvt_pk_bf16_f32 v115, v122, v127
	global_store_dwordx4 v[116:117], v[112:115], off sc1
	s_waitcnt vmcnt(5)
	v_lshlrev_b32_e32 v120, 16, v152
	v_and_b32_e32 v125, 0xffff0000, v154
	v_cvt_pk_bf16_f32 v112, v130, v126
	v_cvt_pk_bf16_f32 v113, v132, v133
	v_cvt_pk_bf16_f32 v114, v134, v131
	v_cvt_pk_bf16_f32 v115, v123, v135
	global_store_dwordx4 v[116:117], v[112:115], off offset:256 sc1
	v_lshlrev_b32_e32 v116, 16, v158
	v_lshlrev_b32_e32 v124, 16, v154
	v_lshlrev_b32_e32 v112, 16, v156
	v_and_b32_e32 v113, 0xffff0000, v156
	v_mul_f32_e32 v108, v108, v112
	v_mul_f32_e32 v112, v100, v120
	v_mul_f32_e32 v109, v109, v113
	v_add_f32_e32 v100, v101, v81
	v_add_f32_e32 v101, v110, v94
	v_mul_f32_e32 v113, v97, v125
	v_add_f32_e32 v97, v106, v90
	v_mul_f32_e32 v104, v104, v116
	v_mul_f32_e32 v116, v96, v124
	v_add_f32_e32 v96, 1.0, v105
	v_mul_f32_e32 v100, 0xbfb8aa3b, v100
	v_mul_f32_e32 v101, 0xbfb8aa3b, v101
	v_mul_f32_e32 v97, 0xbfb8aa3b, v97
	v_exp_f32_e32 v100, v100
	v_rcp_f32_e32 v96, v96
	v_exp_f32_e32 v101, v101
	v_exp_f32_e32 v97, v97
	v_and_b32_e32 v117, 0xffff0000, v158
	v_add_f32_e32 v98, v98, v74
	v_add_f32_e32 v100, 1.0, v100
	v_mul_f32_e32 v105, v96, v117
	v_add_f32_e32 v96, 1.0, v101
	v_add_f32_e32 v97, 1.0, v97
	v_mul_f32_e32 v98, 0xbfb8aa3b, v98
	v_rcp_f32_e32 v100, v100
	v_rcp_f32_e32 v96, v96
	v_rcp_f32_e32 v97, v97
	v_exp_f32_e32 v98, v98
	v_lshlrev_b32_e32 v114, 16, v157
	v_lshlrev_b32_e32 v118, 16, v159
	v_and_b32_e32 v121, 0xffff0000, v152
	v_mul_f32_e32 v110, v100, v121
	v_add_f32_e32 v100, v102, v82
	v_mul_f32_e32 v102, v96, v114
	v_mul_f32_e32 v106, v97, v118
	v_add_f32_e32 v96, 1.0, v98
	v_add_f32_e32 v97, v111, v95
	v_add_f32_e32 v98, v107, v91
	v_mul_f32_e32 v97, 0xbfb8aa3b, v97
	v_mul_f32_e32 v98, 0xbfb8aa3b, v98
	v_rcp_f32_e32 v96, v96
	v_exp_f32_e32 v97, v97
	v_exp_f32_e32 v98, v98
	v_lshlrev_b32_e32 v126, 16, v155
	v_mul_f32_e32 v100, 0xbfb8aa3b, v100
	v_mul_f32_e32 v107, v96, v126
	v_add_f32_e32 v96, 1.0, v97
	v_add_f32_e32 v97, 1.0, v98
	v_add_f32_e32 v98, v103, v83
	v_add_f32_e32 v99, v99, v75
	v_exp_f32_e32 v100, v100
	v_mul_f32_e32 v98, 0xbfb8aa3b, v98
	v_mul_f32_e32 v99, 0xbfb8aa3b, v99
	v_exp_f32_e32 v98, v98
	v_exp_f32_e32 v99, v99
	v_add_f32_e32 v84, v84, v92
	v_add_f32_e32 v68, v68, v80
	v_add_f32_e32 v85, v85, v93
	v_add_f32_e32 v65, v65, v73
	v_mul_f32_e32 v84, 0xbfb8aa3b, v84
	v_add_f32_e32 v76, v76, v88
	v_mul_f32_e32 v68, 0xbfb8aa3b, v68
	v_add_f32_e32 v64, v64, v72
	v_mul_f32_e32 v85, 0xbfb8aa3b, v85
	v_mul_f32_e32 v65, 0xbfb8aa3b, v65
	v_rcp_f32_e32 v96, v96
	v_rcp_f32_e32 v97, v97
	v_exp_f32_e32 v84, v84
	v_mul_f32_e32 v76, 0xbfb8aa3b, v76
	v_exp_f32_e32 v68, v68
	v_mul_f32_e32 v64, 0xbfb8aa3b, v64
	v_exp_f32_e32 v85, v85
	v_exp_f32_e32 v65, v65
	v_add_f32_e32 v100, 1.0, v100
	v_exp_f32_e32 v76, v76
	v_exp_f32_e32 v64, v64
	v_rcp_f32_e32 v100, v100
	v_add_f32_e32 v98, 1.0, v98
	v_add_f32_e32 v99, 1.0, v99
	v_and_b32_e32 v115, 0xffff0000, v157
	v_and_b32_e32 v119, 0xffff0000, v159
	v_rcp_f32_e32 v98, v98
	v_rcp_f32_e32 v99, v99
	v_mul_f32_e32 v103, v96, v115
	v_mul_f32_e32 v111, v97, v119
	v_lshlrev_b64 v[96:97], 10, v[180:181]
	v_add_f32_e32 v84, 1.0, v84
	v_add_f32_e32 v68, 1.0, v68
	v_add_f32_e32 v85, 1.0, v85
	v_add_f32_e32 v77, v77, v89
	v_add_f32_e32 v65, 1.0, v65
	v_lshlrev_b32_e32 v122, 16, v153
	v_lshl_add_u64 v[96:97], s[4:5], 0, v[96:97]
	v_rcp_f32_e32 v84, v84
	v_add_f32_e32 v76, 1.0, v76
	v_rcp_f32_e32 v68, v68
	v_add_f32_e32 v64, 1.0, v64
	v_rcp_f32_e32 v85, v85
	v_mul_f32_e32 v77, 0xbfb8aa3b, v77
	v_rcp_f32_e32 v65, v65
	v_and_b32_e32 v123, 0xffff0000, v153
	v_and_b32_e32 v127, 0xffff0000, v155
	v_mul_f32_e32 v114, v100, v122
	v_lshl_add_u64 v[100:101], v[96:97], 0, v[128:129]
	v_cvt_pk_bf16_f32 v96, v108, v109
	v_cvt_pk_bf16_f32 v97, v102, v103
	v_rcp_f32_e32 v76, v76
	v_rcp_f32_e32 v64, v64
	v_exp_f32_e32 v77, v77
	v_mul_f32_e32 v115, v98, v123
	v_mul_f32_e32 v117, v99, v127
	v_cvt_pk_bf16_f32 v98, v104, v105
	v_cvt_pk_bf16_f32 v99, v106, v111
	global_store_dwordx4 v[100:101], v[96:99], off sc1
	s_waitcnt vmcnt(5)
	v_lshlrev_b32_e32 v104, 16, v144
	v_and_b32_e32 v109, 0xffff0000, v146
	v_cvt_pk_bf16_f32 v96, v112, v110
	v_cvt_pk_bf16_f32 v97, v114, v115
	v_cvt_pk_bf16_f32 v98, v116, v113
	v_cvt_pk_bf16_f32 v99, v107, v117
	global_store_dwordx4 v[100:101], v[96:99], off offset:256 sc1
	v_lshlrev_b32_e32 v100, 16, v150
	v_lshlrev_b32_e32 v108, 16, v146
	v_lshlrev_b32_e32 v96, 16, v148
	v_and_b32_e32 v97, 0xffff0000, v148
	v_mul_f32_e32 v84, v84, v96
	v_mul_f32_e32 v96, v68, v104
	v_mul_f32_e32 v85, v85, v97
	v_add_f32_e32 v68, v69, v81
	v_add_f32_e32 v69, v86, v94
	v_mul_f32_e32 v97, v65, v109
	v_add_f32_e32 v65, v78, v90
	v_mul_f32_e32 v76, v76, v100
	v_mul_f32_e32 v100, v64, v108
	v_add_f32_e32 v64, 1.0, v77
	v_mul_f32_e32 v68, 0xbfb8aa3b, v68
	v_mul_f32_e32 v69, 0xbfb8aa3b, v69
	v_mul_f32_e32 v65, 0xbfb8aa3b, v65
	v_exp_f32_e32 v68, v68
	v_rcp_f32_e32 v64, v64
	v_exp_f32_e32 v69, v69
	v_exp_f32_e32 v65, v65
	v_and_b32_e32 v101, 0xffff0000, v150
	v_add_f32_e32 v66, v66, v74
	v_add_f32_e32 v68, 1.0, v68
	v_mul_f32_e32 v77, v64, v101
	v_add_f32_e32 v64, 1.0, v69
	v_add_f32_e32 v65, 1.0, v65
	v_mul_f32_e32 v66, 0xbfb8aa3b, v66
	v_rcp_f32_e32 v68, v68
	v_rcp_f32_e32 v64, v64
	v_rcp_f32_e32 v65, v65
	v_exp_f32_e32 v66, v66
	v_lshlrev_b32_e32 v98, 16, v149
	v_lshlrev_b32_e32 v102, 16, v151
	v_and_b32_e32 v105, 0xffff0000, v144
	v_mul_f32_e32 v86, v68, v105
	v_add_f32_e32 v68, v70, v82
	v_mul_f32_e32 v70, v64, v98
	v_mul_f32_e32 v78, v65, v102
	v_add_f32_e32 v64, 1.0, v66
	v_add_f32_e32 v65, v87, v95
	v_add_f32_e32 v66, v79, v91
	v_mul_f32_e32 v65, 0xbfb8aa3b, v65
	v_mul_f32_e32 v66, 0xbfb8aa3b, v66
	v_rcp_f32_e32 v64, v64
	v_exp_f32_e32 v65, v65
	v_exp_f32_e32 v66, v66
	v_lshlrev_b32_e32 v110, 16, v147
	v_mul_f32_e32 v79, v64, v110
	v_add_f32_e32 v64, 1.0, v65
	v_add_f32_e32 v65, 1.0, v66
	v_add_f32_e32 v66, v71, v83
	v_add_f32_e32 v67, v67, v75
	v_mul_f32_e32 v68, 0xbfb8aa3b, v68
	v_mul_f32_e32 v66, 0xbfb8aa3b, v66
	v_mul_f32_e32 v67, 0xbfb8aa3b, v67
	v_exp_f32_e32 v68, v68
	v_exp_f32_e32 v66, v66
	v_exp_f32_e32 v67, v67
	v_rcp_f32_e32 v64, v64
	v_rcp_f32_e32 v65, v65
	v_add_f32_e32 v68, 1.0, v68
	v_add_f32_e32 v66, 1.0, v66
	v_add_f32_e32 v67, 1.0, v67
	v_rcp_f32_e32 v68, v68
	v_rcp_f32_e32 v66, v66
	v_rcp_f32_e32 v67, v67
	v_and_b32_e32 v99, 0xffff0000, v149
	v_and_b32_e32 v103, 0xffff0000, v151
	v_mul_f32_e32 v71, v64, v99
	v_mul_f32_e32 v87, v65, v103
	v_lshlrev_b64 v[64:65], 10, v[178:179]
	v_lshlrev_b32_e32 v106, 16, v145
	v_and_b32_e32 v107, 0xffff0000, v145
	v_and_b32_e32 v111, 0xffff0000, v147
	v_lshl_add_u64 v[64:65], s[4:5], 0, v[64:65]
	v_mul_f32_e32 v98, v68, v106
	v_mul_f32_e32 v99, v66, v107
	v_mul_f32_e32 v101, v67, v111
	v_lshl_add_u64 v[68:69], v[64:65], 0, v[128:129]
	v_cvt_pk_bf16_f32 v64, v84, v85
	v_cvt_pk_bf16_f32 v65, v70, v71
	v_cvt_pk_bf16_f32 v66, v76, v77
	v_cvt_pk_bf16_f32 v67, v78, v87
	global_store_dwordx4 v[68:69], v[64:67], off sc1
	v_add_u32_e32 v118, 0x80, v198
	v_add_f32_e32 v60, v60, v92
	v_cvt_pk_bf16_f32 v64, v96, v86
	v_cvt_pk_bf16_f32 v65, v98, v99
	v_cvt_pk_bf16_f32 v66, v100, v97
	v_cvt_pk_bf16_f32 v67, v79, v101
	global_store_dwordx4 v[68:69], v[64:67], off offset:256 sc1
	v_add_u32_e32 v100, 0x90, v198
	v_ashrrev_i32_e32 v119, 31, v118
	v_lshlrev_b64 v[64:65], 5, v[118:119]
	v_lshl_add_u64 v[64:65], v[176:177], 0, v[64:65]
	v_lshl_add_u64 v[64:65], v[64:65], 0, v[184:185]
	global_load_dwordx4 v[102:105], v[64:65], off
	v_add_co_u32_e32 v64, vcc, s48, v64
	v_add_u32_e32 v98, 0xa0, v198
	s_nop 0
	v_addc_co_u32_e32 v65, vcc, 0, v65, vcc
	global_load_dwordx4 v[106:109], v[64:65], off
	v_add_f32_e32 v52, v52, v80
	v_ashrrev_i32_e32 v101, 31, v100
	v_lshlrev_b64 v[64:65], 5, v[100:101]
	v_lshl_add_u64 v[64:65], v[176:177], 0, v[64:65]
	v_lshl_add_u64 v[64:65], v[64:65], 0, v[184:185]
	v_add_co_u32_e32 v66, vcc, s48, v64
	v_add_f32_e32 v61, v61, v93
	s_nop 0
	v_addc_co_u32_e32 v67, vcc, 0, v65, vcc
	global_load_dwordx4 v[110:113], v[64:65], off
	global_load_dwordx4 v[114:117], v[66:67], off
	v_add_f32_e32 v49, v49, v73
	v_ashrrev_i32_e32 v99, 31, v98
	v_lshlrev_b64 v[64:65], 5, v[98:99]
	v_lshl_add_u64 v[64:65], v[176:177], 0, v[64:65]
	v_lshl_add_u64 v[64:65], v[64:65], 0, v[184:185]
	v_add_co_u32_e32 v66, vcc, s48, v64
	v_mul_f32_e32 v60, 0xbfb8aa3b, v60
	s_nop 0
	v_addc_co_u32_e32 v67, vcc, 0, v65, vcc
	global_load_dwordx4 v[84:87], v[64:65], off
	global_load_dwordx4 v[76:79], v[66:67], off
	v_add_f32_e32 v56, v56, v88
	v_mul_f32_e32 v52, 0xbfb8aa3b, v52
	v_add_f32_e32 v48, v48, v72
	v_mul_f32_e32 v61, 0xbfb8aa3b, v61
	v_mul_f32_e32 v49, 0xbfb8aa3b, v49
	v_exp_f32_e32 v60, v60
	v_mul_f32_e32 v56, 0xbfb8aa3b, v56
	v_exp_f32_e32 v52, v52
	v_mul_f32_e32 v48, 0xbfb8aa3b, v48
	v_exp_f32_e32 v61, v61
	v_exp_f32_e32 v49, v49
	v_exp_f32_e32 v56, v56
	v_exp_f32_e32 v48, v48
	v_add_f32_e32 v60, 1.0, v60
	v_add_f32_e32 v52, 1.0, v52
	v_add_f32_e32 v61, 1.0, v61
	v_add_f32_e32 v57, v57, v89
	v_add_f32_e32 v49, 1.0, v49
	v_rcp_f32_e32 v60, v60
	v_add_f32_e32 v56, 1.0, v56
	v_rcp_f32_e32 v52, v52
	v_add_f32_e32 v48, 1.0, v48
	v_rcp_f32_e32 v61, v61
	v_mul_f32_e32 v57, 0xbfb8aa3b, v57
	v_rcp_f32_e32 v49, v49
	v_rcp_f32_e32 v56, v56
	v_rcp_f32_e32 v48, v48
	v_exp_f32_e32 v57, v57
	v_add_u32_e32 v96, 0xb0, v198
	v_add_f32_e32 v50, v50, v74
	v_ashrrev_i32_e32 v97, 31, v96
	v_lshlrev_b64 v[64:65], 5, v[96:97]
	v_lshl_add_u64 v[64:65], v[176:177], 0, v[64:65]
	v_lshl_add_u64 v[64:65], v[64:65], 0, v[184:185]
	v_mul_f32_e32 v50, 0xbfb8aa3b, v50
	v_add_co_u32_e32 v66, vcc, s48, v64
	v_exp_f32_e32 v50, v50
	s_nop 0
	v_addc_co_u32_e32 v67, vcc, 0, v65, vcc
	global_load_dwordx4 v[68:71], v[64:65], off
	s_nop 0
	global_load_dwordx4 v[64:67], v[66:67], off
	v_add_f32_e32 v51, v51, v75
	v_mul_f32_e32 v51, 0xbfb8aa3b, v51
	v_exp_f32_e32 v51, v51
	v_add_f32_e32 v44, v44, v92
	v_add_f32_e32 v36, v36, v80
	v_add_f32_e32 v45, v45, v93
	v_add_f32_e32 v33, v33, v73
	s_waitcnt vmcnt(7)
	v_lshlrev_b32_e32 v120, 16, v102
	v_and_b32_e32 v102, 0xffff0000, v102
	v_lshlrev_b32_e32 v122, 16, v104
	v_mul_f32_e32 v60, v60, v120
	v_mul_f32_e32 v61, v61, v102
	v_mul_f32_e32 v56, v56, v122
	s_waitcnt vmcnt(6)
	v_lshlrev_b32_e32 v124, 16, v106
	v_lshlrev_b32_e32 v126, 16, v108
	v_and_b32_e32 v108, 0xffff0000, v108
	v_mul_f32_e32 v120, v52, v124
	v_add_f32_e32 v52, v53, v81
	v_add_f32_e32 v53, v62, v94
	v_mul_f32_e32 v102, v49, v108
	v_add_f32_e32 v49, v58, v90
	v_mul_f32_e32 v122, v48, v126
	v_add_f32_e32 v48, 1.0, v57
	v_mul_f32_e32 v52, 0xbfb8aa3b, v52
	v_mul_f32_e32 v53, 0xbfb8aa3b, v53
	v_mul_f32_e32 v49, 0xbfb8aa3b, v49
	v_exp_f32_e32 v52, v52
	v_rcp_f32_e32 v48, v48
	v_exp_f32_e32 v53, v53
	v_exp_f32_e32 v49, v49
	v_and_b32_e32 v104, 0xffff0000, v104
	v_add_f32_e32 v52, 1.0, v52
	v_mul_f32_e32 v57, v48, v104
	v_add_f32_e32 v48, 1.0, v53
	v_add_f32_e32 v49, 1.0, v49
	v_rcp_f32_e32 v52, v52
	v_rcp_f32_e32 v48, v48
	v_rcp_f32_e32 v49, v49
	v_lshlrev_b32_e32 v121, 16, v103
	v_lshlrev_b32_e32 v123, 16, v105
	v_and_b32_e32 v106, 0xffff0000, v106
	v_mul_f32_e32 v62, v52, v106
	v_add_f32_e32 v52, v54, v82
	v_mul_f32_e32 v54, v48, v121
	v_mul_f32_e32 v58, v49, v123
	v_add_f32_e32 v48, 1.0, v50
	v_add_f32_e32 v49, v63, v95
	v_add_f32_e32 v50, v59, v91
	v_mul_f32_e32 v49, 0xbfb8aa3b, v49
	v_mul_f32_e32 v50, 0xbfb8aa3b, v50
	v_rcp_f32_e32 v48, v48
	v_exp_f32_e32 v49, v49
	v_exp_f32_e32 v50, v50
	v_lshlrev_b32_e32 v127, 16, v109
	v_mul_f32_e32 v52, 0xbfb8aa3b, v52
	v_mul_f32_e32 v59, v48, v127
	v_add_f32_e32 v48, 1.0, v49
	v_add_f32_e32 v49, 1.0, v50
	v_add_f32_e32 v50, v55, v83
	v_exp_f32_e32 v52, v52
	v_mul_f32_e32 v50, 0xbfb8aa3b, v50
	v_exp_f32_e32 v50, v50
	v_mul_f32_e32 v44, 0xbfb8aa3b, v44
	v_add_f32_e32 v40, v40, v88
	v_mul_f32_e32 v36, 0xbfb8aa3b, v36
	v_add_f32_e32 v32, v32, v72
	v_mul_f32_e32 v45, 0xbfb8aa3b, v45
	v_mul_f32_e32 v33, 0xbfb8aa3b, v33
	v_rcp_f32_e32 v48, v48
	v_rcp_f32_e32 v49, v49
	v_exp_f32_e32 v44, v44
	v_mul_f32_e32 v40, 0xbfb8aa3b, v40
	v_exp_f32_e32 v36, v36
	v_mul_f32_e32 v32, 0xbfb8aa3b, v32
	v_exp_f32_e32 v45, v45
	v_exp_f32_e32 v33, v33
	v_add_f32_e32 v52, 1.0, v52
	v_exp_f32_e32 v40, v40
	v_exp_f32_e32 v32, v32
	v_rcp_f32_e32 v52, v52
	v_add_f32_e32 v50, 1.0, v50
	v_add_f32_e32 v51, 1.0, v51
	v_and_b32_e32 v103, 0xffff0000, v103
	v_and_b32_e32 v105, 0xffff0000, v105
	v_rcp_f32_e32 v50, v50
	v_rcp_f32_e32 v51, v51
	v_mul_f32_e32 v55, v48, v103
	v_mul_f32_e32 v63, v49, v105
	v_lshlrev_b64 v[48:49], 10, v[118:119]
	v_add_f32_e32 v44, 1.0, v44
	v_add_f32_e32 v36, 1.0, v36
	v_add_f32_e32 v45, 1.0, v45
	v_add_f32_e32 v41, v41, v89
	v_add_f32_e32 v33, 1.0, v33
	v_lshlrev_b32_e32 v125, 16, v107
	v_lshl_add_u64 v[48:49], s[4:5], 0, v[48:49]
	v_rcp_f32_e32 v44, v44
	v_add_f32_e32 v40, 1.0, v40
	v_rcp_f32_e32 v36, v36
	v_add_f32_e32 v32, 1.0, v32
	v_rcp_f32_e32 v45, v45
	v_mul_f32_e32 v41, 0xbfb8aa3b, v41
	v_rcp_f32_e32 v33, v33
	v_and_b32_e32 v107, 0xffff0000, v107
	v_and_b32_e32 v109, 0xffff0000, v109
	v_mul_f32_e32 v104, v52, v125
	v_lshl_add_u64 v[52:53], v[48:49], 0, v[128:129]
	v_cvt_pk_bf16_f32 v48, v60, v61
	v_cvt_pk_bf16_f32 v49, v54, v55
	v_rcp_f32_e32 v40, v40
	v_rcp_f32_e32 v32, v32
	v_exp_f32_e32 v41, v41
	v_mul_f32_e32 v103, v50, v107
	v_mul_f32_e32 v105, v51, v109
	v_cvt_pk_bf16_f32 v50, v56, v57
	v_cvt_pk_bf16_f32 v51, v58, v63
	global_store_dwordx4 v[52:53], v[48:51], off sc1
	s_waitcnt vmcnt(5)
	v_lshlrev_b32_e32 v56, 16, v114
	v_and_b32_e32 v61, 0xffff0000, v116
	v_cvt_pk_bf16_f32 v48, v120, v62
	v_cvt_pk_bf16_f32 v49, v104, v103
	v_cvt_pk_bf16_f32 v50, v122, v102
	v_cvt_pk_bf16_f32 v51, v59, v105
	global_store_dwordx4 v[52:53], v[48:51], off offset:256 sc1
	v_lshlrev_b32_e32 v52, 16, v112
	v_lshlrev_b32_e32 v60, 16, v116
	v_lshlrev_b32_e32 v48, 16, v110
	v_and_b32_e32 v49, 0xffff0000, v110
	v_mul_f32_e32 v44, v44, v48
	v_mul_f32_e32 v48, v36, v56
	v_mul_f32_e32 v45, v45, v49
	v_add_f32_e32 v36, v37, v81
	v_add_f32_e32 v37, v46, v94
	v_mul_f32_e32 v49, v33, v61
	v_add_f32_e32 v33, v42, v90
	v_mul_f32_e32 v40, v40, v52
	v_mul_f32_e32 v52, v32, v60
	v_add_f32_e32 v32, 1.0, v41
	v_mul_f32_e32 v36, 0xbfb8aa3b, v36
	v_mul_f32_e32 v37, 0xbfb8aa3b, v37
	v_mul_f32_e32 v33, 0xbfb8aa3b, v33
	v_exp_f32_e32 v36, v36
	v_rcp_f32_e32 v32, v32
	v_exp_f32_e32 v37, v37
	v_exp_f32_e32 v33, v33
	v_and_b32_e32 v53, 0xffff0000, v112
	v_add_f32_e32 v34, v34, v74
	v_add_f32_e32 v36, 1.0, v36
	v_mul_f32_e32 v41, v32, v53
	v_add_f32_e32 v32, 1.0, v37
	v_add_f32_e32 v33, 1.0, v33
	v_mul_f32_e32 v34, 0xbfb8aa3b, v34
	v_rcp_f32_e32 v36, v36
	v_rcp_f32_e32 v32, v32
	v_rcp_f32_e32 v33, v33
	v_exp_f32_e32 v34, v34
	v_lshlrev_b32_e32 v50, 16, v111
	v_lshlrev_b32_e32 v54, 16, v113
	v_and_b32_e32 v57, 0xffff0000, v114
	v_mul_f32_e32 v46, v36, v57
	v_add_f32_e32 v36, v38, v82
	v_mul_f32_e32 v38, v32, v50
	v_mul_f32_e32 v42, v33, v54
	v_add_f32_e32 v32, 1.0, v34
	v_add_f32_e32 v33, v47, v95
	v_add_f32_e32 v34, v43, v91
	v_mul_f32_e32 v33, 0xbfb8aa3b, v33
	v_mul_f32_e32 v34, 0xbfb8aa3b, v34
	v_rcp_f32_e32 v32, v32
	v_exp_f32_e32 v33, v33
	v_exp_f32_e32 v34, v34
	v_lshlrev_b32_e32 v62, 16, v117
	v_mul_f32_e32 v36, 0xbfb8aa3b, v36
	v_mul_f32_e32 v43, v32, v62
	v_add_f32_e32 v32, 1.0, v33
	v_add_f32_e32 v33, 1.0, v34
	v_add_f32_e32 v34, v39, v83
	v_add_f32_e32 v35, v35, v75
	v_exp_f32_e32 v36, v36
	v_mul_f32_e32 v34, 0xbfb8aa3b, v34
	v_mul_f32_e32 v35, 0xbfb8aa3b, v35
	v_exp_f32_e32 v34, v34
	v_exp_f32_e32 v35, v35
	v_add_f32_e32 v28, v28, v92
	v_add_f32_e32 v20, v20, v80
	v_add_f32_e32 v29, v29, v93
	v_add_f32_e32 v17, v17, v73
	v_mul_f32_e32 v28, 0xbfb8aa3b, v28
	v_add_f32_e32 v24, v24, v88
	v_mul_f32_e32 v20, 0xbfb8aa3b, v20
	v_add_f32_e32 v16, v16, v72
	v_mul_f32_e32 v29, 0xbfb8aa3b, v29
	v_mul_f32_e32 v17, 0xbfb8aa3b, v17
	v_rcp_f32_e32 v32, v32
	v_rcp_f32_e32 v33, v33
	v_exp_f32_e32 v28, v28
	v_mul_f32_e32 v24, 0xbfb8aa3b, v24
	v_exp_f32_e32 v20, v20
	v_mul_f32_e32 v16, 0xbfb8aa3b, v16
	v_exp_f32_e32 v29, v29
	v_exp_f32_e32 v17, v17
	v_add_f32_e32 v36, 1.0, v36
	v_exp_f32_e32 v24, v24
	v_exp_f32_e32 v16, v16
	v_rcp_f32_e32 v36, v36
	v_add_f32_e32 v34, 1.0, v34
	v_add_f32_e32 v35, 1.0, v35
	v_and_b32_e32 v51, 0xffff0000, v111
	v_and_b32_e32 v55, 0xffff0000, v113
	v_rcp_f32_e32 v34, v34
	v_rcp_f32_e32 v35, v35
	v_mul_f32_e32 v39, v32, v51
	v_mul_f32_e32 v47, v33, v55
	v_lshlrev_b64 v[32:33], 10, v[100:101]
	v_add_f32_e32 v28, 1.0, v28
	v_add_f32_e32 v20, 1.0, v20
	v_add_f32_e32 v29, 1.0, v29
	v_add_f32_e32 v25, v25, v89
	v_add_f32_e32 v17, 1.0, v17
	v_lshlrev_b32_e32 v58, 16, v115
	v_lshl_add_u64 v[32:33], s[4:5], 0, v[32:33]
	v_rcp_f32_e32 v28, v28
	v_add_f32_e32 v24, 1.0, v24
	v_rcp_f32_e32 v20, v20
	v_add_f32_e32 v16, 1.0, v16
	v_rcp_f32_e32 v29, v29
	v_mul_f32_e32 v25, 0xbfb8aa3b, v25
	v_rcp_f32_e32 v17, v17
	v_and_b32_e32 v59, 0xffff0000, v115
	v_and_b32_e32 v63, 0xffff0000, v117
	v_mul_f32_e32 v50, v36, v58
	v_lshl_add_u64 v[36:37], v[32:33], 0, v[128:129]
	v_cvt_pk_bf16_f32 v32, v44, v45
	v_cvt_pk_bf16_f32 v33, v38, v39
	v_rcp_f32_e32 v24, v24
	v_rcp_f32_e32 v16, v16
	v_exp_f32_e32 v25, v25
	v_mul_f32_e32 v51, v34, v59
	v_mul_f32_e32 v53, v35, v63
	v_cvt_pk_bf16_f32 v34, v40, v41
	v_cvt_pk_bf16_f32 v35, v42, v47
	global_store_dwordx4 v[36:37], v[32:35], off sc1
	s_waitcnt vmcnt(5)
	v_lshlrev_b32_e32 v40, 16, v76
	v_and_b32_e32 v45, 0xffff0000, v78
	v_cvt_pk_bf16_f32 v32, v48, v46
	v_cvt_pk_bf16_f32 v33, v50, v51
	v_cvt_pk_bf16_f32 v34, v52, v49
	v_cvt_pk_bf16_f32 v35, v43, v53
	global_store_dwordx4 v[36:37], v[32:35], off offset:256 sc1
	v_lshlrev_b32_e32 v36, 16, v86
	v_lshlrev_b32_e32 v44, 16, v78
	v_lshlrev_b32_e32 v32, 16, v84
	v_and_b32_e32 v33, 0xffff0000, v84
	v_mul_f32_e32 v28, v28, v32
	v_mul_f32_e32 v32, v20, v40
	v_mul_f32_e32 v29, v29, v33
	v_add_f32_e32 v20, v21, v81
	v_add_f32_e32 v21, v30, v94
	v_mul_f32_e32 v33, v17, v45
	v_add_f32_e32 v17, v26, v90
	v_mul_f32_e32 v24, v24, v36
	v_mul_f32_e32 v36, v16, v44
	v_add_f32_e32 v16, 1.0, v25
	v_mul_f32_e32 v20, 0xbfb8aa3b, v20
	v_mul_f32_e32 v21, 0xbfb8aa3b, v21
	v_mul_f32_e32 v17, 0xbfb8aa3b, v17
	v_exp_f32_e32 v20, v20
	v_rcp_f32_e32 v16, v16
	v_exp_f32_e32 v21, v21
	v_exp_f32_e32 v17, v17
	v_and_b32_e32 v37, 0xffff0000, v86
	v_add_f32_e32 v18, v18, v74
	v_add_f32_e32 v20, 1.0, v20
	v_mul_f32_e32 v25, v16, v37
	v_add_f32_e32 v16, 1.0, v21
	v_add_f32_e32 v17, 1.0, v17
	v_mul_f32_e32 v18, 0xbfb8aa3b, v18
	v_rcp_f32_e32 v20, v20
	v_rcp_f32_e32 v16, v16
	v_rcp_f32_e32 v17, v17
	v_exp_f32_e32 v18, v18
	v_lshlrev_b32_e32 v34, 16, v85
	v_lshlrev_b32_e32 v38, 16, v87
	v_and_b32_e32 v41, 0xffff0000, v76
	v_mul_f32_e32 v30, v20, v41
	v_add_f32_e32 v20, v22, v82
	v_mul_f32_e32 v22, v16, v34
	v_mul_f32_e32 v26, v17, v38
	v_add_f32_e32 v16, 1.0, v18
	v_add_f32_e32 v17, v31, v95
	v_add_f32_e32 v18, v27, v91
	v_mul_f32_e32 v17, 0xbfb8aa3b, v17
	v_mul_f32_e32 v18, 0xbfb8aa3b, v18
	v_rcp_f32_e32 v16, v16
	v_exp_f32_e32 v17, v17
	v_exp_f32_e32 v18, v18
	v_lshlrev_b32_e32 v46, 16, v79
	v_mul_f32_e32 v20, 0xbfb8aa3b, v20
	v_mul_f32_e32 v27, v16, v46
	v_add_f32_e32 v16, 1.0, v17
	v_add_f32_e32 v17, 1.0, v18
	v_add_f32_e32 v18, v23, v83
	v_add_f32_e32 v19, v19, v75
	v_exp_f32_e32 v20, v20
	v_mul_f32_e32 v18, 0xbfb8aa3b, v18
	v_mul_f32_e32 v19, 0xbfb8aa3b, v19
	v_exp_f32_e32 v18, v18
	v_exp_f32_e32 v19, v19
	v_add_f32_e32 v12, v12, v92
	v_add_f32_e32 v4, v4, v80
	v_add_f32_e32 v13, v13, v93
	v_add_f32_e32 v1, v1, v73
	v_mul_f32_e32 v12, 0xbfb8aa3b, v12
	v_add_f32_e32 v8, v8, v88
	v_mul_f32_e32 v4, 0xbfb8aa3b, v4
	v_add_f32_e32 v0, v0, v72
	v_mul_f32_e32 v13, 0xbfb8aa3b, v13
	v_mul_f32_e32 v1, 0xbfb8aa3b, v1
	v_rcp_f32_e32 v16, v16
	v_rcp_f32_e32 v17, v17
	v_exp_f32_e32 v12, v12
	v_mul_f32_e32 v8, 0xbfb8aa3b, v8
	v_exp_f32_e32 v4, v4
	v_mul_f32_e32 v0, 0xbfb8aa3b, v0
	v_exp_f32_e32 v13, v13
	v_exp_f32_e32 v1, v1
	v_add_f32_e32 v20, 1.0, v20
	v_exp_f32_e32 v8, v8
	v_exp_f32_e32 v0, v0
	v_rcp_f32_e32 v20, v20
	v_add_f32_e32 v18, 1.0, v18
	v_add_f32_e32 v19, 1.0, v19
	v_and_b32_e32 v35, 0xffff0000, v85
	v_and_b32_e32 v39, 0xffff0000, v87
	v_rcp_f32_e32 v18, v18
	v_rcp_f32_e32 v19, v19
	v_mul_f32_e32 v23, v16, v35
	v_mul_f32_e32 v31, v17, v39
	v_lshlrev_b64 v[16:17], 10, v[98:99]
	v_add_f32_e32 v12, 1.0, v12
	v_add_f32_e32 v4, 1.0, v4
	v_add_f32_e32 v13, 1.0, v13
	v_add_f32_e32 v9, v9, v89
	v_add_f32_e32 v1, 1.0, v1
	v_lshlrev_b32_e32 v42, 16, v77
	v_lshl_add_u64 v[16:17], s[4:5], 0, v[16:17]
	v_rcp_f32_e32 v12, v12
	v_add_f32_e32 v8, 1.0, v8
	v_rcp_f32_e32 v4, v4
	v_add_f32_e32 v0, 1.0, v0
	v_rcp_f32_e32 v13, v13
	v_mul_f32_e32 v9, 0xbfb8aa3b, v9
	v_rcp_f32_e32 v1, v1
	v_and_b32_e32 v43, 0xffff0000, v77
	v_and_b32_e32 v47, 0xffff0000, v79
	v_mul_f32_e32 v34, v20, v42
	v_lshl_add_u64 v[20:21], v[16:17], 0, v[128:129]
	v_cvt_pk_bf16_f32 v16, v28, v29
	v_cvt_pk_bf16_f32 v17, v22, v23
	v_rcp_f32_e32 v8, v8
	v_rcp_f32_e32 v0, v0
	v_exp_f32_e32 v9, v9
	v_mul_f32_e32 v35, v18, v43
	v_mul_f32_e32 v37, v19, v47
	v_cvt_pk_bf16_f32 v18, v24, v25
	v_cvt_pk_bf16_f32 v19, v26, v31
	global_store_dwordx4 v[20:21], v[16:19], off sc1
	s_waitcnt vmcnt(5)
	v_lshlrev_b32_e32 v24, 16, v64
	v_and_b32_e32 v29, 0xffff0000, v66
	v_cvt_pk_bf16_f32 v16, v32, v30
	v_cvt_pk_bf16_f32 v17, v34, v35
	v_cvt_pk_bf16_f32 v18, v36, v33
	v_cvt_pk_bf16_f32 v19, v27, v37
	global_store_dwordx4 v[20:21], v[16:19], off offset:256 sc1
	v_lshlrev_b32_e32 v20, 16, v70
	v_lshlrev_b32_e32 v28, 16, v66
	v_lshlrev_b32_e32 v16, 16, v68
	v_and_b32_e32 v17, 0xffff0000, v68
	v_mul_f32_e32 v12, v12, v16
	v_mul_f32_e32 v16, v4, v24
	v_mul_f32_e32 v13, v13, v17
	v_add_f32_e32 v4, v5, v81
	v_add_f32_e32 v5, v14, v94
	v_mul_f32_e32 v17, v1, v29
	v_add_f32_e32 v1, v10, v90
	v_mul_f32_e32 v8, v8, v20
	v_mul_f32_e32 v20, v0, v28
	v_add_f32_e32 v0, 1.0, v9
	v_mul_f32_e32 v4, 0xbfb8aa3b, v4
	v_mul_f32_e32 v5, 0xbfb8aa3b, v5
	v_mul_f32_e32 v1, 0xbfb8aa3b, v1
	v_exp_f32_e32 v4, v4
	v_rcp_f32_e32 v0, v0
	v_exp_f32_e32 v5, v5
	v_exp_f32_e32 v1, v1
	v_and_b32_e32 v21, 0xffff0000, v70
	v_add_f32_e32 v2, v2, v74
	v_add_f32_e32 v4, 1.0, v4
	v_mul_f32_e32 v9, v0, v21
	v_add_f32_e32 v0, 1.0, v5
	v_add_f32_e32 v1, 1.0, v1
	v_mul_f32_e32 v2, 0xbfb8aa3b, v2
	v_rcp_f32_e32 v4, v4
	v_rcp_f32_e32 v0, v0
	v_rcp_f32_e32 v1, v1
	v_exp_f32_e32 v2, v2
	v_lshlrev_b32_e32 v18, 16, v69
	v_lshlrev_b32_e32 v22, 16, v71
	v_and_b32_e32 v25, 0xffff0000, v64
	v_mul_f32_e32 v14, v4, v25
	v_add_f32_e32 v4, v6, v82
	v_mul_f32_e32 v6, v0, v18
	v_mul_f32_e32 v10, v1, v22
	v_add_f32_e32 v0, 1.0, v2
	v_add_f32_e32 v1, v15, v95
	v_add_f32_e32 v2, v11, v91
	v_mul_f32_e32 v1, 0xbfb8aa3b, v1
	v_mul_f32_e32 v2, 0xbfb8aa3b, v2
	v_rcp_f32_e32 v0, v0
	v_exp_f32_e32 v1, v1
	v_exp_f32_e32 v2, v2
	v_lshlrev_b32_e32 v30, 16, v67
	v_mul_f32_e32 v11, v0, v30
	v_add_f32_e32 v0, 1.0, v1
	v_add_f32_e32 v1, 1.0, v2
	v_add_f32_e32 v2, v7, v83
	v_add_f32_e32 v3, v3, v75
	v_mul_f32_e32 v4, 0xbfb8aa3b, v4
	v_mul_f32_e32 v2, 0xbfb8aa3b, v2
	v_mul_f32_e32 v3, 0xbfb8aa3b, v3
	v_exp_f32_e32 v4, v4
	v_exp_f32_e32 v2, v2
	v_exp_f32_e32 v3, v3
	v_rcp_f32_e32 v0, v0
	v_rcp_f32_e32 v1, v1
	v_add_f32_e32 v4, 1.0, v4
	v_add_f32_e32 v2, 1.0, v2
	v_add_f32_e32 v3, 1.0, v3
	v_rcp_f32_e32 v4, v4
	v_rcp_f32_e32 v2, v2
	v_rcp_f32_e32 v3, v3
	v_and_b32_e32 v19, 0xffff0000, v69
	v_and_b32_e32 v23, 0xffff0000, v71
	v_mul_f32_e32 v7, v0, v19
	v_mul_f32_e32 v15, v1, v23
	v_lshlrev_b64 v[0:1], 10, v[96:97]
	v_lshlrev_b32_e32 v26, 16, v65
	v_and_b32_e32 v27, 0xffff0000, v65
	v_and_b32_e32 v31, 0xffff0000, v67
	v_lshl_add_u64 v[0:1], s[4:5], 0, v[0:1]
	v_mul_f32_e32 v18, v4, v26
	v_mul_f32_e32 v19, v2, v27
	v_mul_f32_e32 v21, v3, v31
	v_lshl_add_u64 v[4:5], v[0:1], 0, v[128:129]
	v_cvt_pk_bf16_f32 v0, v12, v13
	v_cvt_pk_bf16_f32 v1, v6, v7
	v_cvt_pk_bf16_f32 v2, v8, v9
	v_cvt_pk_bf16_f32 v3, v10, v15
	global_store_dwordx4 v[4:5], v[0:3], off sc1
	s_andn2_b64 vcc, exec, s[34:35]
	s_mov_b64 s[34:35], -1
	v_cvt_pk_bf16_f32 v0, v16, v14
	v_cvt_pk_bf16_f32 v1, v18, v19
	v_cvt_pk_bf16_f32 v2, v20, v17
	v_cvt_pk_bf16_f32 v3, v11, v21
	global_store_dwordx4 v[4:5], v[0:3], off offset:256 sc1
	s_cbranch_vccnz .LBB0_932
	s_andn2_b64 vcc, exec, s[36:37]
	s_cbranch_vccnz .LBB0_931
	s_barrier
	s_branch .LBB0_931

;     __device__ __forceinline__ RowPre pre_row(int row, int) const { const float ss = NSLOT == 8 ? sum8(part + (size_t)row * 8) : sum4(part + (size_t)row * 4); return PreRs{rsqrtf(ss * inv_k + EPS)}; }
;     __device__ __forceinline__ void operator()(const pg8::f32x4 (&acc)[2][2][4][2], const pg8::Unit& u, int wr, int wc, int, int, int ui) const {
;     ...
;             for (int j = 0; j < NB; ++j) { const int ai = (g + j) >> 2, mm = (g + j) & 3; const int rl = ai * 128 + wr * 64 + mm * 16 + fr; int row = u.pm * 256 + rl; asm volatile("" : "+v"(row)); rows[j] = row;
;                 rv[j] = F::USE_TAB ? tab[rl] : 0.f; rp[j] = f.pre_row(row, col); }
; #pragma unroll
;             for (int j = 0; j < NB; ++j) { const int ai = (g + j) >> 2, mm = (g + j) & 3; f.apply(rows[j], col, rv[j], cv, rp[j], acc[ai][0][mm][0], acc[ai][0][mm][1], acc[ai][1][mm][0], acc[ai][1][mm][1]); }
.LBB0_1020:
	s_cmp_lg_u32 s79, 0
	s_cselect_b64 s[56:57], -1, 0
	s_lshl_b32 s3, s17, 8
	s_or_b32 s12, s3, s71
	s_lshl_b32 s3, s78, 8
	s_and_b64 vcc, exec, s[56:57]
	s_cbranch_vccz .LBB0_1028
	v_mbcnt_lo_u32_b32 v129, -1, 0
	v_mbcnt_hi_u32_b32 v129, -1, v129
	s_nop 0
	v_ashrrev_i32_e32 v128, 1, v129
	v_and_or_b32 v130, v129, 15, s70
	v_and_b32_e32 v128, -8, v128
	v_add_u32_e32 v194, s3, v130
	v_add_u32_e32 v128, s12, v128
	v_mov_b32_e32 v150, v194
	v_or_b32_e32 v162, 16, v194
	v_ashrrev_i32_e32 v151, 31, v150
	v_ashrrev_i32_e32 v129, 31, v128
	v_lshlrev_b64 v[130:131], 12, v[150:151]
	v_lshl_add_u64 v[130:131], s[20:21], 0, v[130:131]
	v_lshlrev_b64 v[136:137], 1, v[128:129]
	v_lshl_add_u64 v[128:129], v[130:131], 0, v[136:137]
	global_load_dwordx4 v[132:135], v[128:129], off offset:2048
	global_load_dwordx4 v[138:141], v[128:129], off offset:2304
	v_or_b32_e32 v130, 32, v194
	v_ashrrev_i32_e32 v163, 31, v162
	v_lshlrev_b64 v[128:129], 12, v[162:163]
	v_lshl_add_u64 v[128:129], s[20:21], 0, v[128:129]
	v_lshl_add_u64 v[128:129], v[128:129], 0, v[136:137]
	global_load_dwordx4 v[142:145], v[128:129], off offset:2048
	global_load_dwordx4 v[146:149], v[128:129], off offset:2304
	v_or_b32_e32 v128, 48, v194
	v_ashrrev_i32_e32 v131, 31, v130
	v_lshlrev_b64 v[166:167], 12, v[130:131]
	v_lshl_add_u64 v[166:167], s[20:21], 0, v[166:167]
	v_lshl_add_u64 v[170:171], v[166:167], 0, v[136:137]
	global_load_dwordx4 v[166:169], v[170:171], off offset:2048
	v_lshlrev_b64 v[150:151], 11, v[150:151]
	global_load_dwordx4 v[170:173], v[170:171], off offset:2304
	v_lshl_add_u64 v[150:151], s[24:25], 0, v[150:151]
	v_ashrrev_i32_e32 v129, 31, v128
	v_lshlrev_b64 v[174:175], 12, v[128:129]
	v_lshl_add_u64 v[174:175], s[20:21], 0, v[174:175]
	v_lshl_add_u64 v[178:179], v[174:175], 0, v[136:137]
	global_load_dwordx4 v[174:177], v[178:179], off offset:2048
	s_nop 0
	global_load_dwordx4 v[178:181], v[178:179], off offset:2304
	v_lshl_add_u64 v[150:151], v[150:151], 0, v[136:137]
	v_lshlrev_b64 v[162:163], 11, v[162:163]
	v_lshlrev_b64 v[130:131], 11, v[130:131]
	v_lshl_add_u64 v[130:131], s[24:25], 0, v[130:131]
	v_lshlrev_b64 v[128:129], 11, v[128:129]
	v_lshl_add_u64 v[128:129], s[24:25], 0, v[128:129]
	s_waitcnt vmcnt(0)
	v_lshlrev_b32_e32 v182, 16, v132
	v_and_b32_e32 v183, 0xffff0000, v132
	v_lshlrev_b32_e32 v132, 16, v133
	v_and_b32_e32 v133, 0xffff0000, v133
	v_lshlrev_b32_e32 v186, 16, v134
	v_and_b32_e32 v187, 0xffff0000, v134
	v_lshlrev_b32_e32 v134, 16, v135
	v_and_b32_e32 v135, 0xffff0000, v135
	v_pk_mul_f32 v[192:193], v[126:127], v[132:133]
	v_pk_mul_f32 v[132:133], v[124:125], v[182:183]
	v_lshlrev_b32_e32 v188, 16, v138
	v_and_b32_e32 v189, 0xffff0000, v138
	v_lshlrev_b32_e32 v138, 16, v139
	v_and_b32_e32 v139, 0xffff0000, v139
	v_pk_mul_f32 v[182:183], v[122:123], v[134:135]
	v_pk_mul_f32 v[134:135], v[120:121], v[186:187]
	v_cvt_pk_bf16_f32 v132, v132, v133
	v_cvt_pk_bf16_f32 v133, v192, v193
	v_lshlrev_b32_e32 v190, 16, v140
	v_and_b32_e32 v191, 0xffff0000, v140
	v_lshlrev_b32_e32 v140, 16, v141
	v_and_b32_e32 v141, 0xffff0000, v141
	v_pk_mul_f32 v[138:139], v[94:95], v[138:139]
	v_pk_mul_f32 v[186:187], v[92:93], v[188:189]
	v_cvt_pk_bf16_f32 v134, v134, v135
	v_cvt_pk_bf16_f32 v135, v182, v183
	global_store_dwordx4 v[150:151], v[132:135], off sc1
	v_pk_mul_f32 v[140:141], v[90:91], v[140:141]
	v_pk_mul_f32 v[188:189], v[88:89], v[190:191]
	v_cvt_pk_bf16_f32 v132, v186, v187
	v_cvt_pk_bf16_f32 v133, v138, v139
	v_lshlrev_b32_e32 v138, 16, v144
	v_cvt_pk_bf16_f32 v134, v188, v189
	v_cvt_pk_bf16_f32 v135, v140, v141
	global_store_dwordx4 v[150:151], v[132:135], off offset:256 sc1
	v_lshl_add_u64 v[150:151], s[24:25], 0, v[162:163]
	v_and_b32_e32 v139, 0xffff0000, v144
	v_lshlrev_b32_e32 v132, 16, v142
	v_and_b32_e32 v133, 0xffff0000, v142
	v_lshlrev_b32_e32 v134, 16, v143
	v_and_b32_e32 v135, 0xffff0000, v143
	v_pk_mul_f32 v[132:133], v[116:117], v[132:133]
	v_lshlrev_b32_e32 v140, 16, v145
	v_and_b32_e32 v141, 0xffff0000, v145
	v_lshlrev_b32_e32 v142, 16, v146
	v_and_b32_e32 v143, 0xffff0000, v146
	v_lshl_add_u64 v[150:151], v[150:151], 0, v[136:137]
	v_pk_mul_f32 v[134:135], v[118:119], v[134:135]
	v_cvt_pk_bf16_f32 v132, v132, v133
	v_lshlrev_b32_e32 v144, 16, v147
	v_cvt_pk_bf16_f32 v133, v134, v135
	v_and_b32_e32 v145, 0xffff0000, v147
	v_pk_mul_f32 v[140:141], v[114:115], v[140:141]
	v_pk_mul_f32 v[138:139], v[112:113], v[138:139]
	v_lshlrev_b32_e32 v146, 16, v148
	v_cvt_pk_bf16_f32 v134, v138, v139
	v_cvt_pk_bf16_f32 v135, v140, v141
	global_store_dwordx4 v[150:151], v[132:135], off sc1
	v_and_b32_e32 v147, 0xffff0000, v148
	v_lshlrev_b32_e32 v148, 16, v149
	v_pk_mul_f32 v[132:133], v[84:85], v[142:143]
	v_and_b32_e32 v149, 0xffff0000, v149
	v_pk_mul_f32 v[134:135], v[86:87], v[144:145]
	v_cvt_pk_bf16_f32 v132, v132, v133
	v_pk_mul_f32 v[138:139], v[82:83], v[148:149]
	v_cvt_pk_bf16_f32 v133, v134, v135
	v_pk_mul_f32 v[140:141], v[80:81], v[146:147]
	v_lshlrev_b32_e32 v142, 16, v170
	v_cvt_pk_bf16_f32 v134, v140, v141
	v_cvt_pk_bf16_f32 v135, v138, v139
	global_store_dwordx4 v[150:151], v[132:135], off offset:256 sc1
	v_lshlrev_b32_e32 v138, 16, v168
	v_and_b32_e32 v139, 0xffff0000, v168
	v_lshlrev_b32_e32 v132, 16, v166
	v_and_b32_e32 v133, 0xffff0000, v166
	v_lshlrev_b32_e32 v134, 16, v167
	v_and_b32_e32 v135, 0xffff0000, v167
	v_lshl_add_u64 v[150:151], v[130:131], 0, v[136:137]
	v_pk_mul_f32 v[130:131], v[108:109], v[132:133]
	v_lshlrev_b32_e32 v140, 16, v169
	v_and_b32_e32 v141, 0xffff0000, v169
	v_and_b32_e32 v143, 0xffff0000, v170
	v_pk_mul_f32 v[134:135], v[110:111], v[134:135]
	v_pk_mul_f32 v[132:133], v[104:105], v[138:139]
	v_cvt_pk_bf16_f32 v130, v130, v131
	v_cvt_pk_bf16_f32 v131, v134, v135
	v_lshlrev_b32_e32 v144, 16, v171
	v_and_b32_e32 v145, 0xffff0000, v171
	v_lshlrev_b32_e32 v148, 16, v173
	v_and_b32_e32 v149, 0xffff0000, v173
	v_pk_mul_f32 v[140:141], v[106:107], v[140:141]
	v_cvt_pk_bf16_f32 v132, v132, v133
	v_lshlrev_b32_e32 v146, 16, v172
	v_cvt_pk_bf16_f32 v133, v140, v141
	global_store_dwordx4 v[150:151], v[130:133], off sc1
	v_and_b32_e32 v147, 0xffff0000, v172
	v_pk_mul_f32 v[134:135], v[74:75], v[148:149]
	v_pk_mul_f32 v[130:131], v[76:77], v[142:143]
	v_pk_mul_f32 v[132:133], v[78:79], v[144:145]
	v_cvt_pk_bf16_f32 v130, v130, v131
	v_pk_mul_f32 v[138:139], v[72:73], v[146:147]
	v_cvt_pk_bf16_f32 v131, v132, v133
	v_lshl_add_u64 v[148:149], v[128:129], 0, v[136:137]
	v_cvt_pk_bf16_f32 v132, v138, v139
	v_cvt_pk_bf16_f32 v133, v134, v135
	global_store_dwordx4 v[150:151], v[130:133], off offset:256 sc1
	v_lshlrev_b32_e32 v134, 16, v176
	v_and_b32_e32 v135, 0xffff0000, v176
	v_lshlrev_b32_e32 v130, 16, v174
	v_and_b32_e32 v131, 0xffff0000, v174
	v_lshlrev_b32_e32 v132, 16, v175
	v_and_b32_e32 v133, 0xffff0000, v175
	v_lshlrev_b32_e32 v138, 16, v177
	v_and_b32_e32 v139, 0xffff0000, v177
	v_pk_mul_f32 v[128:129], v[100:101], v[130:131]
	v_pk_mul_f32 v[130:131], v[96:97], v[134:135]
	v_lshlrev_b32_e32 v140, 16, v178
	v_and_b32_e32 v141, 0xffff0000, v178
	v_lshlrev_b32_e32 v142, 16, v179
	v_and_b32_e32 v143, 0xffff0000, v179
	v_pk_mul_f32 v[132:133], v[102:103], v[132:133]
	v_pk_mul_f32 v[138:139], v[98:99], v[138:139]
	v_cvt_pk_bf16_f32 v128, v128, v129
	v_cvt_pk_bf16_f32 v129, v132, v133
	v_cvt_pk_bf16_f32 v130, v130, v131
	v_lshlrev_b32_e32 v144, 16, v180
	v_cvt_pk_bf16_f32 v131, v138, v139
	v_and_b32_e32 v145, 0xffff0000, v180
	v_lshlrev_b32_e32 v146, 16, v181
	v_and_b32_e32 v147, 0xffff0000, v181
	global_store_dwordx4 v[148:149], v[128:131], off sc1
	v_pk_mul_f32 v[132:133], v[66:67], v[146:147]
	v_pk_mul_f32 v[134:135], v[64:65], v[144:145]
	v_pk_mul_f32 v[130:131], v[70:71], v[142:143]
	v_pk_mul_f32 v[128:129], v[68:69], v[140:141]
	v_add_u32_e32 v162, 0x80, v194
	v_cvt_pk_bf16_f32 v128, v128, v129
	v_cvt_pk_bf16_f32 v129, v130, v131
	v_cvt_pk_bf16_f32 v130, v134, v135
	v_cvt_pk_bf16_f32 v131, v132, v133
	global_store_dwordx4 v[148:149], v[128:131], off offset:256 sc1
	v_add_u32_e32 v178, 0x90, v194
	v_ashrrev_i32_e32 v163, 31, v162
	v_lshlrev_b64 v[128:129], 12, v[162:163]
	v_lshl_add_u64 v[128:129], s[20:21], 0, v[128:129]
	v_lshl_add_u64 v[128:129], v[128:129], 0, v[136:137]
	global_load_dwordx4 v[140:143], v[128:129], off offset:2048
	global_load_dwordx4 v[144:147], v[128:129], off offset:2304
	v_add_u32_e32 v180, 0xa0, v194
	v_ashrrev_i32_e32 v179, 31, v178
	v_lshlrev_b64 v[128:129], 12, v[178:179]
	v_lshl_add_u64 v[128:129], s[20:21], 0, v[128:129]
	v_lshl_add_u64 v[128:129], v[128:129], 0, v[136:137]
	global_load_dwordx4 v[148:151], v[128:129], off offset:2048
	global_load_dwordx4 v[166:169], v[128:129], off offset:2304
	v_add_u32_e32 v138, 0xb0, v194
	v_ashrrev_i32_e32 v181, 31, v180
	v_lshlrev_b64 v[128:129], 12, v[180:181]
	v_lshl_add_u64 v[128:129], s[20:21], 0, v[128:129]
	v_lshl_add_u64 v[128:129], v[128:129], 0, v[136:137]
	global_load_dwordx4 v[170:173], v[128:129], off offset:2048
	global_load_dwordx4 v[174:177], v[128:129], off offset:2304
	v_lshlrev_b64 v[162:163], 11, v[162:163]
	v_ashrrev_i32_e32 v139, 31, v138
	v_lshlrev_b64 v[128:129], 12, v[138:139]
	v_lshl_add_u64 v[128:129], s[20:21], 0, v[128:129]
	v_lshl_add_u64 v[128:129], v[128:129], 0, v[136:137]
	global_load_dwordx4 v[132:135], v[128:129], off offset:2048
	s_nop 0
	global_load_dwordx4 v[128:131], v[128:129], off offset:2304
	v_lshl_add_u64 v[162:163], s[24:25], 0, v[162:163]
	v_lshl_add_u64 v[162:163], v[162:163], 0, v[136:137]
	s_waitcnt vmcnt(7)
	v_lshlrev_b32_e32 v182, 16, v140
	v_and_b32_e32 v183, 0xffff0000, v140
	v_lshlrev_b32_e32 v140, 16, v141
	v_and_b32_e32 v141, 0xffff0000, v141
	v_lshlrev_b32_e32 v186, 16, v142
	v_and_b32_e32 v187, 0xffff0000, v142
	v_lshlrev_b32_e32 v142, 16, v143
	v_and_b32_e32 v143, 0xffff0000, v143
	v_pk_mul_f32 v[192:193], v[62:63], v[140:141]
	v_pk_mul_f32 v[140:141], v[60:61], v[182:183]
	v_pk_mul_f32 v[182:183], v[58:59], v[142:143]
	v_pk_mul_f32 v[142:143], v[56:57], v[186:187]
	s_waitcnt vmcnt(6)
	v_lshlrev_b32_e32 v188, 16, v144
	v_and_b32_e32 v189, 0xffff0000, v144
	v_lshlrev_b32_e32 v144, 16, v145
	v_and_b32_e32 v145, 0xffff0000, v145
	v_cvt_pk_bf16_f32 v140, v140, v141
	v_cvt_pk_bf16_f32 v141, v192, v193
	v_cvt_pk_bf16_f32 v142, v142, v143
	v_cvt_pk_bf16_f32 v143, v182, v183
	v_lshlrev_b32_e32 v190, 16, v146
	v_and_b32_e32 v191, 0xffff0000, v146
	v_lshlrev_b32_e32 v146, 16, v147
	v_and_b32_e32 v147, 0xffff0000, v147
	global_store_dwordx4 v[162:163], v[140:143], off sc1
	s_nop 1
	v_pk_mul_f32 v[142:143], v[30:31], v[144:145]
	v_pk_mul_f32 v[140:141], v[28:29], v[188:189]
	v_pk_mul_f32 v[144:145], v[26:27], v[146:147]
	v_pk_mul_f32 v[146:147], v[24:25], v[190:191]
	v_cvt_pk_bf16_f32 v140, v140, v141
	v_cvt_pk_bf16_f32 v141, v142, v143
	s_nop 0
	v_cvt_pk_bf16_f32 v142, v146, v147
	v_cvt_pk_bf16_f32 v143, v144, v145
	global_store_dwordx4 v[162:163], v[140:143], off offset:256 sc1
	s_waitcnt vmcnt(7)
	v_lshlrev_b32_e32 v144, 16, v150
	v_and_b32_e32 v145, 0xffff0000, v150
	v_lshlrev_b32_e32 v140, 16, v148
	v_and_b32_e32 v141, 0xffff0000, v148
	v_lshlrev_b32_e32 v142, 16, v149
	v_and_b32_e32 v143, 0xffff0000, v149
	v_lshlrev_b32_e32 v146, 16, v151
	v_and_b32_e32 v147, 0xffff0000, v151
	s_waitcnt vmcnt(6)
	v_lshlrev_b32_e32 v148, 16, v166
	v_and_b32_e32 v149, 0xffff0000, v166
	v_lshlrev_b32_e32 v150, 16, v167
	v_and_b32_e32 v151, 0xffff0000, v167
	v_lshlrev_b32_e32 v162, 16, v168
	v_and_b32_e32 v163, 0xffff0000, v168
	v_lshlrev_b32_e32 v166, 16, v169
	v_and_b32_e32 v167, 0xffff0000, v169
	v_lshlrev_b64 v[168:169], 11, v[178:179]
	v_lshl_add_u64 v[168:169], s[24:25], 0, v[168:169]
	v_pk_mul_f32 v[142:143], v[54:55], v[142:143]
	v_pk_mul_f32 v[140:141], v[52:53], v[140:141]
	v_lshl_add_u64 v[168:169], v[168:169], 0, v[136:137]
	v_pk_mul_f32 v[146:147], v[50:51], v[146:147]
	v_pk_mul_f32 v[144:145], v[48:49], v[144:145]
	v_cvt_pk_bf16_f32 v140, v140, v141
	v_cvt_pk_bf16_f32 v141, v142, v143
	s_nop 0
	v_cvt_pk_bf16_f32 v142, v144, v145
	v_cvt_pk_bf16_f32 v143, v146, v147
	global_store_dwordx4 v[168:169], v[140:143], off sc1
	v_pk_mul_f32 v[144:145], v[18:19], v[166:167]
	v_pk_mul_f32 v[146:147], v[16:17], v[162:163]
	v_pk_mul_f32 v[142:143], v[22:23], v[150:151]
	v_pk_mul_f32 v[140:141], v[20:21], v[148:149]
	s_waitcnt vmcnt(5)
	v_lshlrev_b32_e32 v148, 16, v174
	v_cvt_pk_bf16_f32 v140, v140, v141
	v_cvt_pk_bf16_f32 v141, v142, v143
	v_cvt_pk_bf16_f32 v142, v146, v147
	v_cvt_pk_bf16_f32 v143, v144, v145
	global_store_dwordx4 v[168:169], v[140:143], off offset:256 sc1
	v_lshlrev_b64 v[168:169], 11, v[180:181]
	v_lshlrev_b32_e32 v144, 16, v172
	v_lshlrev_b32_e32 v140, 16, v170
	v_and_b32_e32 v141, 0xffff0000, v170
	v_lshlrev_b32_e32 v142, 16, v171
	v_and_b32_e32 v143, 0xffff0000, v171
	v_and_b32_e32 v145, 0xffff0000, v172
	v_lshlrev_b32_e32 v146, 16, v173
	v_and_b32_e32 v147, 0xffff0000, v173
	v_lshl_add_u64 v[168:169], s[24:25], 0, v[168:169]
	v_pk_mul_f32 v[142:143], v[46:47], v[142:143]
	v_pk_mul_f32 v[140:141], v[44:45], v[140:141]
	v_and_b32_e32 v149, 0xffff0000, v174
	v_lshlrev_b32_e32 v150, 16, v175
	v_and_b32_e32 v151, 0xffff0000, v175
	v_lshlrev_b32_e32 v162, 16, v176
	v_and_b32_e32 v163, 0xffff0000, v176
	v_lshlrev_b32_e32 v166, 16, v177
	v_and_b32_e32 v167, 0xffff0000, v177
	v_lshl_add_u64 v[168:169], v[168:169], 0, v[136:137]
	v_pk_mul_f32 v[146:147], v[42:43], v[146:147]
	v_pk_mul_f32 v[144:145], v[40:41], v[144:145]
	v_cvt_pk_bf16_f32 v140, v140, v141
	v_cvt_pk_bf16_f32 v141, v142, v143
	s_nop 0
	v_cvt_pk_bf16_f32 v142, v144, v145
	v_cvt_pk_bf16_f32 v143, v146, v147
	global_store_dwordx4 v[168:169], v[140:143], off sc1
	v_pk_mul_f32 v[144:145], v[10:11], v[166:167]
	v_pk_mul_f32 v[146:147], v[8:9], v[162:163]
	v_pk_mul_f32 v[142:143], v[14:15], v[150:151]
	v_pk_mul_f32 v[140:141], v[12:13], v[148:149]
	s_waitcnt vmcnt(5)
	v_lshlrev_b32_e32 v148, 16, v130
	v_cvt_pk_bf16_f32 v140, v140, v141
	v_cvt_pk_bf16_f32 v141, v142, v143
	v_cvt_pk_bf16_f32 v142, v146, v147
	v_cvt_pk_bf16_f32 v143, v144, v145
	v_lshlrev_b32_e32 v144, 16, v128
	v_and_b32_e32 v145, 0xffff0000, v128
	v_lshlrev_b32_e32 v146, 16, v129
	v_and_b32_e32 v147, 0xffff0000, v129
	v_lshlrev_b64 v[128:129], 11, v[138:139]
	global_store_dwordx4 v[168:169], v[140:143], off offset:256 sc1
	v_lshl_add_u64 v[128:129], s[24:25], 0, v[128:129]
	v_and_b32_e32 v149, 0xffff0000, v130
	v_lshlrev_b32_e32 v140, 16, v132
	v_and_b32_e32 v141, 0xffff0000, v132
	v_lshlrev_b32_e32 v132, 16, v133
	v_and_b32_e32 v133, 0xffff0000, v133
	v_lshlrev_b32_e32 v142, 16, v134
	v_and_b32_e32 v143, 0xffff0000, v134
	v_lshlrev_b32_e32 v134, 16, v135
	v_and_b32_e32 v135, 0xffff0000, v135
	v_lshlrev_b32_e32 v150, 16, v131
	v_and_b32_e32 v151, 0xffff0000, v131
	v_lshl_add_u64 v[136:137], v[128:129], 0, v[136:137]
	v_pk_mul_f32 v[130:131], v[38:39], v[132:133]
	v_pk_mul_f32 v[128:129], v[36:37], v[140:141]
	v_pk_mul_f32 v[132:133], v[34:35], v[134:135]
	v_pk_mul_f32 v[134:135], v[32:33], v[142:143]
	v_cvt_pk_bf16_f32 v128, v128, v129
	v_cvt_pk_bf16_f32 v129, v130, v131
	s_nop 0
	v_cvt_pk_bf16_f32 v130, v134, v135
	v_cvt_pk_bf16_f32 v131, v132, v133
	global_store_dwordx4 v[136:137], v[128:131], off sc1
	v_pk_mul_f32 v[132:133], v[2:3], v[150:151]
	v_pk_mul_f32 v[134:135], v[0:1], v[148:149]
	v_pk_mul_f32 v[130:131], v[6:7], v[146:147]
	v_pk_mul_f32 v[128:129], v[4:5], v[144:145]
	s_nop 0
	v_cvt_pk_bf16_f32 v128, v128, v129
	v_cvt_pk_bf16_f32 v129, v130, v131
	v_cvt_pk_bf16_f32 v130, v134, v135
	v_cvt_pk_bf16_f32 v131, v132, v133
	global_store_dwordx4 v[136:137], v[128:131], off offset:256 sc1
	s_cbranch_execnz .LBB0_1023

;     __device__ __forceinline__ RowPre pre_row(int row, int) const { const float ss = NSLOT == 8 ? sum8(part + (size_t)row * 8) : sum4(part + (size_t)row * 4); return PreRs{rsqrtf(ss * inv_k + EPS)}; }
;     __device__ __forceinline__ void operator()(const pg8::f32x4 (&acc)[2][2][4][2], const pg8::Unit& u, int wr, int wc, int, int, int ui) const {
;     ...
;             for (int j = 0; j < NB; ++j) { const int ai = (g + j) >> 2, mm = (g + j) & 3; const int rl = ai * 128 + wr * 64 + mm * 16 + fr; int row = u.pm * 256 + rl; asm volatile("" : "+v"(row)); rows[j] = row;
;                 rv[j] = F::USE_TAB ? tab[rl] : 0.f; rp[j] = f.pre_row(row, col); }
; #pragma unroll
;             for (int j = 0; j < NB; ++j) { const int ai = (g + j) >> 2, mm = (g + j) & 3; f.apply(rows[j], col, rv[j], cv, rp[j], acc[ai][0][mm][0], acc[ai][0][mm][1], acc[ai][1][mm][0], acc[ai][1][mm][1]); }
.LBB0_1242:
	v_mbcnt_lo_u32_b32 v141, -1, 0
	v_mbcnt_hi_u32_b32 v141, -1, v141
	s_lshl_b32 s3, s71, 8
	v_ashrrev_i32_e32 v140, 1, v141
	s_or_b32 s3, s3, s65
	v_and_b32_e32 v140, -8, v140
	v_add_u32_e32 v140, s3, v140
	s_lshl_b32 s3, s70, 11
	s_and_b32 s3, s3, 0x800
	s_add_i32 s3, s3, 0
	v_and_or_b32 v141, v141, 15, s64
	v_lshl_add_u32 v143, v141, 2, s3
	v_lshl_add_u32 v146, s69, 8, v141
	v_mov_b32_e32 v142, v146
	v_add_u32_e32 v147, 0x20040, v143
	ds_read_b32 v143, v147
	v_add_u32_e32 v144, 16, v146
	ds_read_b32 v145, v147 offset:64
	v_ashrrev_i32_e32 v141, 31, v140
	s_waitcnt lgkmcnt(0)
	v_mul_f32_e32 v112, v112, v143
	v_max_f32_e32 v112, 0, v112
	v_mul_f32_e32 v116, v116, v143
	v_mul_f32_e32 v149, v112, v112
	v_mul_f32_e32 v112, v125, v143
	v_max_f32_e32 v116, 0, v116
	v_max_f32_e32 v112, 0, v112
	v_mul_f32_e32 v148, v116, v116
	v_mul_f32_e32 v116, v112, v112
	v_mul_f32_e32 v112, v121, v143
	v_max_f32_e32 v112, 0, v112
	v_mul_f32_e32 v121, v112, v112
	v_mul_f32_e32 v112, v117, v143
	v_max_f32_e32 v112, 0, v112
	v_mul_f32_e32 v125, v112, v112
	v_mul_f32_e32 v112, v113, v143
	v_max_f32_e32 v112, 0, v112
	v_mul_f32_e32 v150, v112, v112
	v_mul_f32_e32 v112, v126, v143
	v_max_f32_e32 v112, 0, v112
	v_mul_f32_e32 v117, v112, v112
	v_mul_f32_e32 v112, v122, v143
	v_max_f32_e32 v112, 0, v112
	v_mul_f32_e32 v122, v112, v112
	v_mul_f32_e32 v112, v118, v143
	v_max_f32_e32 v112, 0, v112
	v_mul_f32_e32 v126, v112, v112
	v_mul_f32_e32 v112, v114, v143
	v_max_f32_e32 v112, 0, v112
	v_mul_f32_e32 v151, v112, v112
	v_mul_f32_e32 v112, v127, v143
	v_max_f32_e32 v112, 0, v112
	v_mul_f32_e32 v127, v112, v112
	v_mul_f32_e32 v112, v123, v143
	v_max_f32_e32 v112, 0, v112
	v_mul_f32_e32 v123, v112, v112
	v_mul_f32_e32 v112, v119, v143
	v_max_f32_e32 v112, 0, v112
	v_mul_f32_e32 v152, v112, v112
	v_mul_f32_e32 v112, v115, v143
	v_mul_f32_e32 v124, v124, v143
	v_mul_f32_e32 v120, v120, v143
	v_max_f32_e32 v112, 0, v112
	v_ashrrev_i32_e32 v143, 31, v142
	v_mul_f32_e32 v153, v112, v112
	v_lshlrev_b64 v[112:113], 13, v[142:143]
	v_max_f32_e32 v124, 0, v124
	v_lshl_add_u64 v[114:115], s[4:5], 0, v[112:113]
	v_lshlrev_b64 v[112:113], 1, v[140:141]
	v_mul_f32_e32 v124, v124, v124
	v_max_f32_e32 v120, 0, v120
	v_lshl_add_u64 v[118:119], v[114:115], 0, v[112:113]
	v_cvt_pk_bf16_f32 v114, v124, v116
	v_cvt_pk_bf16_f32 v115, v117, v127
	v_mul_f32_e32 v96, v96, v145
	v_mul_f32_e32 v120, v120, v120
	v_cvt_pk_bf16_f32 v116, v120, v121
	v_cvt_pk_bf16_f32 v117, v122, v123
	global_store_dwordx4 v[118:119], v[114:117], off sc1
	v_max_f32_e32 v96, 0, v96
	v_mul_f32_e32 v108, v108, v145
	v_cvt_pk_bf16_f32 v114, v148, v125
	v_cvt_pk_bf16_f32 v115, v126, v152
	v_cvt_pk_bf16_f32 v116, v149, v150
	v_cvt_pk_bf16_f32 v117, v151, v153
	global_store_dwordx4 v[118:119], v[114:117], off offset:256 sc1
	v_mul_f32_e32 v104, v104, v145
	v_mul_f32_e32 v100, v100, v145
	v_mul_f32_e32 v115, v96, v96
	v_mul_f32_e32 v96, v109, v145
	v_max_f32_e32 v96, 0, v96
	v_mul_f32_e32 v109, v96, v96
	v_mul_f32_e32 v96, v105, v145
	v_max_f32_e32 v96, 0, v96
	v_mul_f32_e32 v105, v96, v96
	v_mul_f32_e32 v96, v101, v145
	v_max_f32_e32 v96, 0, v96
	v_mul_f32_e32 v116, v96, v96
	v_mul_f32_e32 v96, v97, v145
	v_max_f32_e32 v96, 0, v96
	v_mul_f32_e32 v117, v96, v96
	v_mul_f32_e32 v96, v110, v145
	v_max_f32_e32 v96, 0, v96
	v_mul_f32_e32 v110, v96, v96
	v_mul_f32_e32 v96, v106, v145
	v_max_f32_e32 v96, 0, v96
	v_mul_f32_e32 v106, v96, v96
	v_mul_f32_e32 v96, v102, v145
	v_max_f32_e32 v96, 0, v96
	v_mul_f32_e32 v102, v96, v96
	v_mul_f32_e32 v96, v98, v145
	v_max_f32_e32 v96, 0, v96
	v_mul_f32_e32 v118, v96, v96
	v_mul_f32_e32 v96, v111, v145
	v_max_f32_e32 v96, 0, v96
	v_mul_f32_e32 v98, v96, v96
	v_mul_f32_e32 v96, v107, v145
	v_max_f32_e32 v96, 0, v96
	v_mul_f32_e32 v107, v96, v96
	v_mul_f32_e32 v96, v103, v145
	v_max_f32_e32 v96, 0, v96
	v_mul_f32_e32 v103, v96, v96
	v_mul_f32_e32 v96, v99, v145
	v_max_f32_e32 v96, 0, v96
	v_ashrrev_i32_e32 v145, 31, v144
	v_mul_f32_e32 v111, v96, v96
	v_lshlrev_b64 v[96:97], 13, v[144:145]
	v_max_f32_e32 v108, 0, v108
	v_max_f32_e32 v100, 0, v100
	v_lshl_add_u64 v[96:97], s[4:5], 0, v[96:97]
	v_mul_f32_e32 v108, v108, v108
	v_max_f32_e32 v104, 0, v104
	v_mul_f32_e32 v114, v100, v100
	v_lshl_add_u64 v[100:101], v[96:97], 0, v[112:113]
	v_cvt_pk_bf16_f32 v96, v108, v109
	v_mul_f32_e32 v104, v104, v104
	v_cvt_pk_bf16_f32 v97, v110, v98
	v_cvt_pk_bf16_f32 v98, v104, v105
	v_cvt_pk_bf16_f32 v99, v106, v107
	global_store_dwordx4 v[100:101], v[96:99], off sc1
	s_andn2_b64 vcc, exec, s[36:37]
	s_mov_b64 s[36:37], -1
	v_cvt_pk_bf16_f32 v96, v114, v116
	v_cvt_pk_bf16_f32 v97, v102, v103
	v_cvt_pk_bf16_f32 v98, v115, v117
	v_cvt_pk_bf16_f32 v99, v118, v111
	global_store_dwordx4 v[100:101], v[96:99], off offset:256 sc1
	v_readlane_b32 s77, v251, 5
	v_readlane_b32 s78, v252, 15
	v_add_u32_e32 v96, 32, v146
	ds_read_b32 v97, v147 offset:128
	v_add_u32_e32 v98, 48, v146
	ds_read_b32 v99, v147 offset:192
	v_readlane_b32 s79, v252, 16
	s_waitcnt lgkmcnt(0)
	v_mul_f32_e32 v80, v80, v97
	v_max_f32_e32 v80, 0, v80
	v_mul_f32_e32 v101, v80, v80
	v_mul_f32_e32 v80, v93, v97
	v_max_f32_e32 v80, 0, v80
	v_mul_f32_e32 v93, v80, v80
	v_mul_f32_e32 v80, v89, v97
	v_max_f32_e32 v80, 0, v80
	v_mul_f32_e32 v89, v80, v80
	v_mul_f32_e32 v80, v85, v97
	v_max_f32_e32 v80, 0, v80
	v_mul_f32_e32 v102, v80, v80
	v_mul_f32_e32 v80, v81, v97
	v_max_f32_e32 v80, 0, v80
	v_mul_f32_e32 v103, v80, v80
	v_mul_f32_e32 v80, v94, v97
	v_max_f32_e32 v80, 0, v80
	v_mul_f32_e32 v94, v80, v80
	v_mul_f32_e32 v80, v90, v97
	v_max_f32_e32 v80, 0, v80
	v_mul_f32_e32 v90, v80, v80
	v_mul_f32_e32 v80, v86, v97
	v_max_f32_e32 v80, 0, v80
	v_mul_f32_e32 v86, v80, v80
	v_mul_f32_e32 v80, v82, v97
	v_max_f32_e32 v80, 0, v80
	v_mul_f32_e32 v104, v80, v80
	v_mul_f32_e32 v80, v95, v97
	v_max_f32_e32 v80, 0, v80
	v_mul_f32_e32 v82, v80, v80
	v_mul_f32_e32 v80, v91, v97
	v_max_f32_e32 v80, 0, v80
	v_mul_f32_e32 v91, v80, v80
	v_mul_f32_e32 v80, v87, v97
	v_max_f32_e32 v80, 0, v80
	v_mul_f32_e32 v87, v80, v80
	v_mul_f32_e32 v80, v83, v97
	v_mul_f32_e32 v92, v92, v97
	v_mul_f32_e32 v88, v88, v97
	v_mul_f32_e32 v84, v84, v97
	v_max_f32_e32 v80, 0, v80
	v_ashrrev_i32_e32 v97, 31, v96
	v_mul_f32_e32 v95, v80, v80
	v_lshlrev_b64 v[80:81], 13, v[96:97]
	v_max_f32_e32 v92, 0, v92
	v_max_f32_e32 v84, 0, v84
	v_lshl_add_u64 v[80:81], s[4:5], 0, v[80:81]
	v_mul_f32_e32 v92, v92, v92
	v_max_f32_e32 v88, 0, v88
	v_mul_f32_e32 v100, v84, v84
	v_lshl_add_u64 v[84:85], v[80:81], 0, v[112:113]
	v_cvt_pk_bf16_f32 v80, v92, v93
	v_cvt_pk_bf16_f32 v81, v94, v82
	v_mul_f32_e32 v64, v64, v99
	v_mul_f32_e32 v88, v88, v88
	v_cvt_pk_bf16_f32 v82, v88, v89
	v_cvt_pk_bf16_f32 v83, v90, v91
	global_store_dwordx4 v[84:85], v[80:83], off sc1
	v_max_f32_e32 v64, 0, v64
	v_mul_f32_e32 v76, v76, v99
	v_cvt_pk_bf16_f32 v80, v100, v102
	v_cvt_pk_bf16_f32 v81, v86, v87
	v_cvt_pk_bf16_f32 v82, v101, v103
	v_cvt_pk_bf16_f32 v83, v104, v95
	global_store_dwordx4 v[84:85], v[80:83], off offset:256 sc1
	v_mul_f32_e32 v72, v72, v99
	v_mul_f32_e32 v68, v68, v99
	v_mul_f32_e32 v81, v64, v64
	v_mul_f32_e32 v64, v77, v99
	v_max_f32_e32 v64, 0, v64
	v_mul_f32_e32 v77, v64, v64
	v_mul_f32_e32 v64, v73, v99
	v_max_f32_e32 v64, 0, v64
	v_mul_f32_e32 v73, v64, v64
	v_mul_f32_e32 v64, v69, v99
	v_max_f32_e32 v64, 0, v64
	v_mul_f32_e32 v82, v64, v64
	v_mul_f32_e32 v64, v65, v99
	v_max_f32_e32 v64, 0, v64
	v_mul_f32_e32 v83, v64, v64
	v_mul_f32_e32 v64, v78, v99
	v_max_f32_e32 v64, 0, v64
	v_mul_f32_e32 v78, v64, v64
	v_mul_f32_e32 v64, v74, v99
	v_max_f32_e32 v64, 0, v64
	v_mul_f32_e32 v74, v64, v64
	v_mul_f32_e32 v64, v70, v99
	v_max_f32_e32 v64, 0, v64
	v_mul_f32_e32 v70, v64, v64
	v_mul_f32_e32 v64, v66, v99
	v_max_f32_e32 v64, 0, v64
	v_mul_f32_e32 v84, v64, v64
	v_mul_f32_e32 v64, v79, v99
	v_max_f32_e32 v64, 0, v64
	v_mul_f32_e32 v66, v64, v64
	v_mul_f32_e32 v64, v75, v99
	v_max_f32_e32 v64, 0, v64
	v_mul_f32_e32 v75, v64, v64
	v_mul_f32_e32 v64, v71, v99
	v_max_f32_e32 v64, 0, v64
	v_mul_f32_e32 v71, v64, v64
	v_mul_f32_e32 v64, v67, v99
	v_max_f32_e32 v64, 0, v64
	v_ashrrev_i32_e32 v99, 31, v98
	v_mul_f32_e32 v79, v64, v64
	v_lshlrev_b64 v[64:65], 13, v[98:99]
	v_max_f32_e32 v76, 0, v76
	v_max_f32_e32 v68, 0, v68
	v_lshl_add_u64 v[64:65], s[4:5], 0, v[64:65]
	v_mul_f32_e32 v76, v76, v76
	v_max_f32_e32 v72, 0, v72
	v_mul_f32_e32 v80, v68, v68
	v_lshl_add_u64 v[68:69], v[64:65], 0, v[112:113]
	v_cvt_pk_bf16_f32 v64, v76, v77
	v_mul_f32_e32 v72, v72, v72
	v_cvt_pk_bf16_f32 v65, v78, v66
	v_cvt_pk_bf16_f32 v66, v72, v73
	v_cvt_pk_bf16_f32 v67, v74, v75
	global_store_dwordx4 v[68:69], v[64:67], off sc1
	s_nop 1
	v_cvt_pk_bf16_f32 v64, v80, v82
	v_cvt_pk_bf16_f32 v65, v70, v71
	v_cvt_pk_bf16_f32 v66, v81, v83
	v_cvt_pk_bf16_f32 v67, v84, v79
	global_store_dwordx4 v[68:69], v[64:67], off offset:256 sc1
	s_nop 1
	v_add_u32_e32 v64, 0x80, v146
	ds_read_b32 v65, v147 offset:512
	v_add_u32_e32 v66, 0x90, v146
	ds_read_b32 v67, v147 offset:576
	s_waitcnt lgkmcnt(0)
	v_mul_f32_e32 v48, v48, v65
	v_max_f32_e32 v48, 0, v48
	v_mul_f32_e32 v69, v48, v48
	v_mul_f32_e32 v48, v61, v65
	v_max_f32_e32 v48, 0, v48
	v_mul_f32_e32 v61, v48, v48
	v_mul_f32_e32 v48, v57, v65
	v_max_f32_e32 v48, 0, v48
	v_mul_f32_e32 v57, v48, v48
	v_mul_f32_e32 v48, v53, v65
	v_max_f32_e32 v48, 0, v48
	v_mul_f32_e32 v70, v48, v48
	v_mul_f32_e32 v48, v49, v65
	v_max_f32_e32 v48, 0, v48
	v_mul_f32_e32 v71, v48, v48
	v_mul_f32_e32 v48, v62, v65
	v_max_f32_e32 v48, 0, v48
	v_mul_f32_e32 v62, v48, v48
	v_mul_f32_e32 v48, v58, v65
	v_max_f32_e32 v48, 0, v48
	v_mul_f32_e32 v58, v48, v48
	v_mul_f32_e32 v48, v54, v65
	v_max_f32_e32 v48, 0, v48
	v_mul_f32_e32 v54, v48, v48
	v_mul_f32_e32 v48, v50, v65
	v_max_f32_e32 v48, 0, v48
	v_mul_f32_e32 v72, v48, v48
	v_mul_f32_e32 v48, v63, v65
	v_max_f32_e32 v48, 0, v48
	v_mul_f32_e32 v50, v48, v48
	v_mul_f32_e32 v48, v59, v65
	v_max_f32_e32 v48, 0, v48
	v_mul_f32_e32 v59, v48, v48
	v_mul_f32_e32 v48, v55, v65
	v_max_f32_e32 v48, 0, v48
	v_mul_f32_e32 v55, v48, v48
	v_mul_f32_e32 v48, v51, v65
	v_mul_f32_e32 v60, v60, v65
	v_mul_f32_e32 v56, v56, v65
	v_mul_f32_e32 v52, v52, v65
	v_max_f32_e32 v48, 0, v48
	v_ashrrev_i32_e32 v65, 31, v64
	v_mul_f32_e32 v63, v48, v48
	v_lshlrev_b64 v[48:49], 13, v[64:65]
	v_max_f32_e32 v60, 0, v60
	v_max_f32_e32 v52, 0, v52
	v_lshl_add_u64 v[48:49], s[4:5], 0, v[48:49]
	v_mul_f32_e32 v60, v60, v60
	v_max_f32_e32 v56, 0, v56
	v_mul_f32_e32 v68, v52, v52
	v_lshl_add_u64 v[52:53], v[48:49], 0, v[112:113]
	v_cvt_pk_bf16_f32 v48, v60, v61
	v_cvt_pk_bf16_f32 v49, v62, v50
	v_mul_f32_e32 v32, v32, v67
	v_mul_f32_e32 v56, v56, v56
	v_cvt_pk_bf16_f32 v50, v56, v57
	v_cvt_pk_bf16_f32 v51, v58, v59
	global_store_dwordx4 v[52:53], v[48:51], off sc1
	v_max_f32_e32 v32, 0, v32
	v_mul_f32_e32 v44, v44, v67
	v_cvt_pk_bf16_f32 v48, v68, v70
	v_cvt_pk_bf16_f32 v49, v54, v55
	v_cvt_pk_bf16_f32 v50, v69, v71
	v_cvt_pk_bf16_f32 v51, v72, v63
	global_store_dwordx4 v[52:53], v[48:51], off offset:256 sc1
	v_mul_f32_e32 v40, v40, v67
	v_mul_f32_e32 v36, v36, v67
	v_mul_f32_e32 v49, v32, v32
	v_mul_f32_e32 v32, v45, v67
	v_max_f32_e32 v32, 0, v32
	v_mul_f32_e32 v45, v32, v32
	v_mul_f32_e32 v32, v41, v67
	v_max_f32_e32 v32, 0, v32
	v_mul_f32_e32 v41, v32, v32
	v_mul_f32_e32 v32, v37, v67
	v_max_f32_e32 v32, 0, v32
	v_mul_f32_e32 v50, v32, v32
	v_mul_f32_e32 v32, v33, v67
	v_max_f32_e32 v32, 0, v32
	v_mul_f32_e32 v51, v32, v32
	v_mul_f32_e32 v32, v46, v67
	v_max_f32_e32 v32, 0, v32
	v_mul_f32_e32 v46, v32, v32
	v_mul_f32_e32 v32, v42, v67
	v_max_f32_e32 v32, 0, v32
	v_mul_f32_e32 v42, v32, v32
	v_mul_f32_e32 v32, v38, v67
	v_max_f32_e32 v32, 0, v32
	v_mul_f32_e32 v38, v32, v32
	v_mul_f32_e32 v32, v34, v67
	v_max_f32_e32 v32, 0, v32
	v_mul_f32_e32 v52, v32, v32
	v_mul_f32_e32 v32, v47, v67
	v_max_f32_e32 v32, 0, v32
	v_mul_f32_e32 v34, v32, v32
	v_mul_f32_e32 v32, v43, v67
	v_max_f32_e32 v32, 0, v32
	v_mul_f32_e32 v43, v32, v32
	v_mul_f32_e32 v32, v39, v67
	v_max_f32_e32 v32, 0, v32
	v_mul_f32_e32 v39, v32, v32
	v_mul_f32_e32 v32, v35, v67
	v_max_f32_e32 v32, 0, v32
	v_ashrrev_i32_e32 v67, 31, v66
	v_mul_f32_e32 v47, v32, v32
	v_lshlrev_b64 v[32:33], 13, v[66:67]
	v_max_f32_e32 v44, 0, v44
	v_max_f32_e32 v36, 0, v36
	v_lshl_add_u64 v[32:33], s[4:5], 0, v[32:33]
	v_mul_f32_e32 v44, v44, v44
	v_max_f32_e32 v40, 0, v40
	v_mul_f32_e32 v48, v36, v36
	v_lshl_add_u64 v[36:37], v[32:33], 0, v[112:113]
	v_cvt_pk_bf16_f32 v32, v44, v45
	v_mul_f32_e32 v40, v40, v40
	v_cvt_pk_bf16_f32 v33, v46, v34
	v_cvt_pk_bf16_f32 v34, v40, v41
	v_cvt_pk_bf16_f32 v35, v42, v43
	global_store_dwordx4 v[36:37], v[32:35], off sc1
	s_nop 1
	v_cvt_pk_bf16_f32 v32, v48, v50
	v_cvt_pk_bf16_f32 v33, v38, v39
	v_cvt_pk_bf16_f32 v34, v49, v51
	v_cvt_pk_bf16_f32 v35, v52, v47
	global_store_dwordx4 v[36:37], v[32:35], off offset:256 sc1
	s_nop 1
	v_add_u32_e32 v32, 0xa0, v146
	ds_read_b32 v33, v147 offset:640
	v_add_u32_e32 v34, 0xb0, v146
	ds_read_b32 v35, v147 offset:704
	s_waitcnt lgkmcnt(0)
	v_mul_f32_e32 v16, v16, v33
	v_max_f32_e32 v16, 0, v16
	v_mul_f32_e32 v37, v16, v16
	v_mul_f32_e32 v16, v29, v33
	v_max_f32_e32 v16, 0, v16
	v_mul_f32_e32 v29, v16, v16
	v_mul_f32_e32 v16, v25, v33
	v_max_f32_e32 v16, 0, v16
	v_mul_f32_e32 v25, v16, v16
	v_mul_f32_e32 v16, v21, v33
	v_max_f32_e32 v16, 0, v16
	v_mul_f32_e32 v38, v16, v16
	v_mul_f32_e32 v16, v17, v33
	v_max_f32_e32 v16, 0, v16
	v_mul_f32_e32 v39, v16, v16
	v_mul_f32_e32 v16, v30, v33
	v_max_f32_e32 v16, 0, v16
	v_mul_f32_e32 v30, v16, v16
	v_mul_f32_e32 v16, v26, v33
	v_max_f32_e32 v16, 0, v16
	v_mul_f32_e32 v26, v16, v16
	v_mul_f32_e32 v16, v22, v33
	v_max_f32_e32 v16, 0, v16
	v_mul_f32_e32 v22, v16, v16
	v_mul_f32_e32 v16, v18, v33
	v_max_f32_e32 v16, 0, v16
	v_mul_f32_e32 v40, v16, v16
	v_mul_f32_e32 v16, v31, v33
	v_max_f32_e32 v16, 0, v16
	v_mul_f32_e32 v18, v16, v16
	v_mul_f32_e32 v16, v27, v33
	v_max_f32_e32 v16, 0, v16
	v_mul_f32_e32 v27, v16, v16
	v_mul_f32_e32 v16, v23, v33
	v_max_f32_e32 v16, 0, v16
	v_mul_f32_e32 v23, v16, v16
	v_mul_f32_e32 v16, v19, v33
	v_mul_f32_e32 v28, v28, v33
	v_mul_f32_e32 v24, v24, v33
	v_mul_f32_e32 v20, v20, v33
	v_max_f32_e32 v16, 0, v16
	v_ashrrev_i32_e32 v33, 31, v32
	v_mul_f32_e32 v31, v16, v16
	v_lshlrev_b64 v[16:17], 13, v[32:33]
	v_max_f32_e32 v28, 0, v28
	v_max_f32_e32 v20, 0, v20
	v_lshl_add_u64 v[16:17], s[4:5], 0, v[16:17]
	v_mul_f32_e32 v28, v28, v28
	v_max_f32_e32 v24, 0, v24
	v_mul_f32_e32 v36, v20, v20
	v_lshl_add_u64 v[20:21], v[16:17], 0, v[112:113]
	v_cvt_pk_bf16_f32 v16, v28, v29
	v_cvt_pk_bf16_f32 v17, v30, v18
	v_mul_f32_e32 v0, v0, v35
	v_mul_f32_e32 v24, v24, v24
	v_cvt_pk_bf16_f32 v18, v24, v25
	v_cvt_pk_bf16_f32 v19, v26, v27
	global_store_dwordx4 v[20:21], v[16:19], off sc1
	v_max_f32_e32 v0, 0, v0
	v_mul_f32_e32 v12, v12, v35
	v_cvt_pk_bf16_f32 v16, v36, v38
	v_cvt_pk_bf16_f32 v17, v22, v23
	v_cvt_pk_bf16_f32 v18, v37, v39
	v_cvt_pk_bf16_f32 v19, v40, v31
	global_store_dwordx4 v[20:21], v[16:19], off offset:256 sc1
	v_mul_f32_e32 v8, v8, v35
	v_mul_f32_e32 v4, v4, v35
	v_mul_f32_e32 v17, v0, v0
	v_mul_f32_e32 v0, v13, v35
	v_max_f32_e32 v0, 0, v0
	v_mul_f32_e32 v13, v0, v0
	v_mul_f32_e32 v0, v9, v35
	v_max_f32_e32 v0, 0, v0
	v_mul_f32_e32 v9, v0, v0
	v_mul_f32_e32 v0, v5, v35
	v_max_f32_e32 v0, 0, v0
	v_mul_f32_e32 v18, v0, v0
	v_mul_f32_e32 v0, v1, v35
	v_max_f32_e32 v0, 0, v0
	v_mul_f32_e32 v19, v0, v0
	v_mul_f32_e32 v0, v14, v35
	v_max_f32_e32 v0, 0, v0
	v_mul_f32_e32 v14, v0, v0
	v_mul_f32_e32 v0, v10, v35
	v_max_f32_e32 v0, 0, v0
	v_mul_f32_e32 v10, v0, v0
	v_mul_f32_e32 v0, v6, v35
	v_max_f32_e32 v0, 0, v0
	v_mul_f32_e32 v6, v0, v0
	v_mul_f32_e32 v0, v2, v35
	v_max_f32_e32 v0, 0, v0
	v_mul_f32_e32 v20, v0, v0
	v_mul_f32_e32 v0, v15, v35
	v_max_f32_e32 v0, 0, v0
	v_mul_f32_e32 v2, v0, v0
	v_mul_f32_e32 v0, v11, v35
	v_max_f32_e32 v0, 0, v0
	v_mul_f32_e32 v11, v0, v0
	v_mul_f32_e32 v0, v7, v35
	v_max_f32_e32 v0, 0, v0
	v_mul_f32_e32 v7, v0, v0
	v_mul_f32_e32 v0, v3, v35
	v_max_f32_e32 v0, 0, v0
	v_ashrrev_i32_e32 v35, 31, v34
	v_mul_f32_e32 v15, v0, v0
	v_lshlrev_b64 v[0:1], 13, v[34:35]
	v_max_f32_e32 v12, 0, v12
	v_max_f32_e32 v8, 0, v8
	v_max_f32_e32 v4, 0, v4
	v_lshl_add_u64 v[0:1], s[4:5], 0, v[0:1]
	v_mul_f32_e32 v12, v12, v12
	v_mul_f32_e32 v8, v8, v8
	v_mul_f32_e32 v16, v4, v4
	v_lshl_add_u64 v[4:5], v[0:1], 0, v[112:113]
	v_cvt_pk_bf16_f32 v0, v12, v13
	v_cvt_pk_bf16_f32 v1, v14, v2
	v_cvt_pk_bf16_f32 v2, v8, v9
	v_cvt_pk_bf16_f32 v3, v10, v11
	global_store_dwordx4 v[4:5], v[0:3], off sc1
	s_nop 1
	v_cvt_pk_bf16_f32 v0, v16, v18
	v_cvt_pk_bf16_f32 v1, v6, v7
	v_cvt_pk_bf16_f32 v2, v17, v19
	v_cvt_pk_bf16_f32 v3, v20, v15
	global_store_dwordx4 v[4:5], v[0:3], off offset:256 sc1
	s_cbranch_vccnz .LBB0_1227
	s_andn2_b64 vcc, exec, s[38:39]
	s_cbranch_vccnz .LBB0_1226
	s_barrier
	s_branch .LBB0_1226
